# plus input-projection epilogues (phases 3, 4): eight row-statistic loads issued together, per-row vmcnt(0) waits dropped
# speedup vs baseline: 1.0150x; 1.0049x over previous
; __device__ __forceinline__ unsigned cvt_pk_bf16(float lo, float hi) { cvf32x2_t v = {lo, hi}; cvbf16x2_t b = __builtin_convertvector(v, cvbf16x2_t); return __builtin_bit_cast(unsigned, b); }
; __device__ __forceinline__ float fsilu(float x) { return x * fsigm(x); }
; __device__ __forceinline__ float row_rs(const float* ssq, int row) { return ssq ? rsqrtf(ssq[row] * (1.f / 1024.f) + RMS_EPS) : 1.f; }
;     __device__ __forceinline__ void operator()(const f32x4 (&acc)[2][2][4][2], const Unit& u, int wr, int wc, int fr, int fq) const {
;     ...
;         bf16_t* dst = grp == 0 ? QS : (grp == 2 ? VV : (grp == 3 ? GS : BC)); const bool act = (grp == 0) || (grp == 3);
; #pragma unroll
;         for (int ai = 0; ai < 2; ++ai)
; #pragma unroll
;             for (int m = 0; m < 4; ++m) { const int row = row0 + ai * HALF + m * 16; const float rs = row_rs(ssq, row);
; #pragma unroll
;                 for (int bj = 0; bj < 2; ++bj) { f32x4 p0 = acc[ai][bj][m][0] * rs, p1 = acc[ai][bj][m][1] * rs;
;                     if (act) { p0[0] = fsilu(p0[0]); p0[1] = fsilu(p0[1]); p0[2] = fsilu(p0[2]); p0[3] = fsilu(p0[3]); p1[0] = fsilu(p1[0]); p1[1] = fsilu(p1[1]); p1[2] = fsilu(p1[2]); p1[3] = fsilu(p1[3]); }
;                     u32x4 w; w.x = cvt_pk_bf16(p0[0], p0[1]); w.y = cvt_pk_bf16(p0[2], p0[3]); w.z = cvt_pk_bf16(p1[0], p1[1]); w.w = cvt_pk_bf16(p1[2], p1[3]);
;                     *(u32x4*)(dst + (size_t)row * 512 + cbase + bj * HALF) = w; } }
.LBB0_478:
	v_ashrrev_i32_e32 v149, 31, v148
	v_lshl_add_u64 v[150:151], v[148:149], 2, s[30:31]
	global_load_dword v136, v[150:151], off
	global_load_dword v210, v[150:151], off offset:64
	global_load_dword v211, v[150:151], off offset:128
	global_load_dword v212, v[150:151], off offset:192
	global_load_dword v213, v[150:151], off offset:512
	global_load_dword v214, v[150:151], off offset:576
	global_load_dword v215, v[150:151], off offset:640
	global_load_dword v216, v[150:151], off offset:704
	s_cmp_eq_u32 s65, 3
	s_cselect_b64 s[52:53], -1, 0
	s_or_b64 s[52:53], s[6:7], s[52:53]
	s_andn2_b64 vcc, exec, s[52:53]
	s_waitcnt vmcnt(0)
	v_fmamk_f32 v136, v136, 0x3a800000, v170
	v_mul_f32_e32 v152, 0x4b800000, v136
	v_cmp_gt_f32_e64 s[8:9], s87, v136
	s_nop 1
	v_cndmask_b32_e64 v136, v136, v152, s[8:9]
	v_rsq_f32_e32 v136, v136
	v_cndmask_b32_e64 v152, 0, 1, s[52:53]
	v_cmp_ne_u32_e64 s[6:7], 1, v152
	v_mul_f32_e32 v152, 0x45800000, v136
	v_cndmask_b32_e64 v154, v136, v152, s[8:9]
	v_pk_mul_f32 v[160:161], v[126:127], v[154:155] op_sel_hi:[1,0]
	v_pk_mul_f32 v[164:165], v[124:125], v[154:155] op_sel_hi:[1,0]
	v_pk_mul_f32 v[158:159], v[122:123], v[154:155] op_sel_hi:[1,0]
	v_pk_mul_f32 v[162:163], v[120:121], v[154:155] op_sel_hi:[1,0]
	s_cbranch_vccnz .LBB0_480
	v_mul_f32_e32 v136, 0xbfb8aa3b, v164
	v_exp_f32_e32 v136, v136
	v_mul_f32_e32 v152, 0xbfb8aa3b, v165
	v_mul_f32_e32 v153, 0xbfb8aa3b, v160
	v_exp_f32_e32 v155, v152
	v_exp_f32_e32 v156, v153
	v_add_f32_e32 v136, 1.0, v136
	v_rcp_f32_e32 v152, v136
	v_add_f32_e32 v136, 1.0, v155
	v_mul_f32_e32 v155, 0xbfb8aa3b, v161
	v_rcp_f32_e32 v153, v136
	v_add_f32_e32 v136, 1.0, v156
	v_exp_f32_e32 v155, v155
	v_mul_f32_e32 v156, 0xbfb8aa3b, v162
	v_exp_f32_e32 v172, v156
	v_rcp_f32_e32 v156, v136
	v_add_f32_e32 v136, 1.0, v155
	v_rcp_f32_e32 v157, v136
	v_add_f32_e32 v136, 1.0, v172
	v_mul_f32_e32 v155, 0xbfb8aa3b, v158
	v_rcp_f32_e32 v172, v136
	v_mul_f32_e32 v136, 0xbfb8aa3b, v163
	v_exp_f32_e32 v155, v155
	v_mul_f32_e32 v173, 0xbfb8aa3b, v159
	v_exp_f32_e32 v136, v136
	v_exp_f32_e32 v173, v173
	v_add_f32_e32 v155, 1.0, v155
	v_rcp_f32_e32 v174, v155
	v_add_f32_e32 v136, 1.0, v136
	v_add_f32_e32 v155, 1.0, v173
	v_rcp_f32_e32 v175, v155
	v_rcp_f32_e32 v173, v136
	v_pk_mul_f32 v[160:161], v[160:161], v[156:157]
	v_pk_mul_f32 v[164:165], v[164:165], v[152:153]
	v_pk_mul_f32 v[158:159], v[158:159], v[174:175]
	v_pk_mul_f32 v[162:163], v[162:163], v[172:173]

; __device__ __forceinline__ unsigned cvt_pk_bf16(float lo, float hi) { cvf32x2_t v = {lo, hi}; cvbf16x2_t b = __builtin_convertvector(v, cvbf16x2_t); return __builtin_bit_cast(unsigned, b); }
; __device__ __forceinline__ float fsilu(float x) { return x * fsigm(x); }
; __device__ __forceinline__ float row_rs(const float* ssq, int row) { return ssq ? rsqrtf(ssq[row] * (1.f / 1024.f) + RMS_EPS) : 1.f; }
;     __device__ __forceinline__ void operator()(const f32x4 (&acc)[2][2][4][2], const Unit& u, int wr, int wc, int fr, int fq) const {
;     ...
;         bf16_t* dst = grp == 0 ? QS : (grp == 2 ? VV : (grp == 3 ? GS : BC)); const bool act = (grp == 0) || (grp == 3);
; #pragma unroll
;         for (int ai = 0; ai < 2; ++ai)
; #pragma unroll
;             for (int m = 0; m < 4; ++m) { const int row = row0 + ai * HALF + m * 16; const float rs = row_rs(ssq, row);
; #pragma unroll
;                 for (int bj = 0; bj < 2; ++bj) { f32x4 p0 = acc[ai][bj][m][0] * rs, p1 = acc[ai][bj][m][1] * rs;
;                     if (act) { p0[0] = fsilu(p0[0]); p0[1] = fsilu(p0[1]); p0[2] = fsilu(p0[2]); p0[3] = fsilu(p0[3]); p1[0] = fsilu(p1[0]); p1[1] = fsilu(p1[1]); p1[2] = fsilu(p1[2]); p1[3] = fsilu(p1[3]); }
;                     u32x4 w; w.x = cvt_pk_bf16(p0[0], p0[1]); w.y = cvt_pk_bf16(p0[2], p0[3]); w.z = cvt_pk_bf16(p1[0], p1[1]); w.w = cvt_pk_bf16(p1[2], p1[3]);
;                     *(u32x4*)(dst + (size_t)row * 512 + cbase + bj * HALF) = w; } }
.LBB0_482:
	s_nop 0
	v_cvt_pk_bf16_f32 v174, v154, v155
	v_or_b32_e32 v154, 16, v148
	v_cvt_pk_bf16_f32 v172, v160, v161
	v_cvt_pk_bf16_f32 v173, v158, v159
	v_cvt_pk_bf16_f32 v175, v162, v163
	v_ashrrev_i32_e32 v155, 31, v154
	global_store_dwordx4 v[156:157], v[172:175], off offset:256
	v_lshl_add_u64 v[156:157], v[154:155], 2, s[30:31]
	s_and_b64 vcc, exec, s[6:7]
	v_fmamk_f32 v136, v210, 0x3a800000, v170
	v_mul_f32_e32 v156, 0x4b800000, v136
	v_cmp_gt_f32_e64 s[8:9], s87, v136
	s_nop 1
	v_cndmask_b32_e64 v136, v136, v156, s[8:9]
	v_rsq_f32_e32 v136, v136
	s_nop 0
	v_mul_f32_e32 v156, 0x45800000, v136
	v_cndmask_b32_e64 v156, v136, v156, s[8:9]
	v_pk_mul_f32 v[160:161], v[110:111], v[156:157] op_sel_hi:[1,0]
	v_pk_mul_f32 v[164:165], v[108:109], v[156:157] op_sel_hi:[1,0]
	v_pk_mul_f32 v[158:159], v[106:107], v[156:157] op_sel_hi:[1,0]
	v_pk_mul_f32 v[162:163], v[104:105], v[156:157] op_sel_hi:[1,0]
	s_cbranch_vccnz .LBB0_484
	v_mul_f32_e32 v136, 0xbfb8aa3b, v164
	v_exp_f32_e32 v136, v136
	v_mul_f32_e32 v157, 0xbfb8aa3b, v165
	v_mul_f32_e32 v172, 0xbfb8aa3b, v160
	v_exp_f32_e32 v157, v157
	v_exp_f32_e32 v174, v172
	v_add_f32_e32 v136, 1.0, v136
	v_rcp_f32_e32 v172, v136
	v_add_f32_e32 v136, 1.0, v157
	v_mul_f32_e32 v157, 0xbfb8aa3b, v161
	v_rcp_f32_e32 v173, v136
	v_add_f32_e32 v136, 1.0, v174
	v_exp_f32_e32 v157, v157
	v_mul_f32_e32 v174, 0xbfb8aa3b, v162
	v_exp_f32_e32 v176, v174
	v_rcp_f32_e32 v174, v136
	v_add_f32_e32 v136, 1.0, v157
	v_rcp_f32_e32 v175, v136
	v_add_f32_e32 v136, 1.0, v176
	v_mul_f32_e32 v157, 0xbfb8aa3b, v158
	v_rcp_f32_e32 v176, v136
	v_mul_f32_e32 v136, 0xbfb8aa3b, v163
	v_exp_f32_e32 v157, v157
	v_mul_f32_e32 v177, 0xbfb8aa3b, v159
	v_exp_f32_e32 v136, v136
	v_exp_f32_e32 v177, v177
	v_add_f32_e32 v157, 1.0, v157
	v_rcp_f32_e32 v178, v157
	v_add_f32_e32 v136, 1.0, v136
	v_add_f32_e32 v157, 1.0, v177
	v_rcp_f32_e32 v179, v157
	v_rcp_f32_e32 v177, v136
	v_pk_mul_f32 v[160:161], v[160:161], v[174:175]
	v_pk_mul_f32 v[164:165], v[164:165], v[172:173]
	v_pk_mul_f32 v[158:159], v[158:159], v[178:179]
	v_pk_mul_f32 v[162:163], v[162:163], v[176:177]

; __device__ __forceinline__ unsigned cvt_pk_bf16(float lo, float hi) { cvf32x2_t v = {lo, hi}; cvbf16x2_t b = __builtin_convertvector(v, cvbf16x2_t); return __builtin_bit_cast(unsigned, b); }
; __device__ __forceinline__ float fsilu(float x) { return x * fsigm(x); }
; __device__ __forceinline__ float row_rs(const float* ssq, int row) { return ssq ? rsqrtf(ssq[row] * (1.f / 1024.f) + RMS_EPS) : 1.f; }
;     __device__ __forceinline__ void operator()(const f32x4 (&acc)[2][2][4][2], const Unit& u, int wr, int wc, int fr, int fq) const {
;     ...
;         bf16_t* dst = grp == 0 ? QS : (grp == 2 ? VV : (grp == 3 ? GS : BC)); const bool act = (grp == 0) || (grp == 3);
; #pragma unroll
;         for (int ai = 0; ai < 2; ++ai)
; #pragma unroll
;             for (int m = 0; m < 4; ++m) { const int row = row0 + ai * HALF + m * 16; const float rs = row_rs(ssq, row);
; #pragma unroll
;                 for (int bj = 0; bj < 2; ++bj) { f32x4 p0 = acc[ai][bj][m][0] * rs, p1 = acc[ai][bj][m][1] * rs;
;                     if (act) { p0[0] = fsilu(p0[0]); p0[1] = fsilu(p0[1]); p0[2] = fsilu(p0[2]); p0[3] = fsilu(p0[3]); p1[0] = fsilu(p1[0]); p1[1] = fsilu(p1[1]); p1[2] = fsilu(p1[2]); p1[3] = fsilu(p1[3]); }
;                     u32x4 w; w.x = cvt_pk_bf16(p0[0], p0[1]); w.y = cvt_pk_bf16(p0[2], p0[3]); w.z = cvt_pk_bf16(p1[0], p1[1]); w.w = cvt_pk_bf16(p1[2], p1[3]);
;                     *(u32x4*)(dst + (size_t)row * 512 + cbase + bj * HALF) = w; } }
.LBB0_486:
	s_nop 0
	v_cvt_pk_bf16_f32 v172, v160, v161
	v_cvt_pk_bf16_f32 v173, v158, v159
	v_cvt_pk_bf16_f32 v174, v156, v157
	v_cvt_pk_bf16_f32 v175, v162, v163
	global_store_dwordx4 v[154:155], v[172:175], off offset:256
	v_or_b32_e32 v154, 32, v148
	v_ashrrev_i32_e32 v155, 31, v154
	v_lshl_add_u64 v[156:157], v[154:155], 2, s[30:31]
	s_and_b64 vcc, exec, s[6:7]
	v_fmamk_f32 v136, v211, 0x3a800000, v170
	v_mul_f32_e32 v156, 0x4b800000, v136
	v_cmp_gt_f32_e64 s[8:9], s87, v136
	s_nop 1
	v_cndmask_b32_e64 v136, v136, v156, s[8:9]
	v_rsq_f32_e32 v136, v136
	s_nop 0
	v_mul_f32_e32 v156, 0x45800000, v136
	v_cndmask_b32_e64 v156, v136, v156, s[8:9]
	v_pk_mul_f32 v[160:161], v[94:95], v[156:157] op_sel_hi:[1,0]
	v_pk_mul_f32 v[164:165], v[92:93], v[156:157] op_sel_hi:[1,0]
	v_pk_mul_f32 v[158:159], v[90:91], v[156:157] op_sel_hi:[1,0]
	v_pk_mul_f32 v[162:163], v[88:89], v[156:157] op_sel_hi:[1,0]
	s_cbranch_vccnz .LBB0_488
	v_mul_f32_e32 v136, 0xbfb8aa3b, v164
	v_exp_f32_e32 v136, v136
	v_mul_f32_e32 v157, 0xbfb8aa3b, v165
	v_mul_f32_e32 v172, 0xbfb8aa3b, v160
	v_exp_f32_e32 v157, v157
	v_exp_f32_e32 v174, v172
	v_add_f32_e32 v136, 1.0, v136
	v_rcp_f32_e32 v172, v136
	v_add_f32_e32 v136, 1.0, v157
	v_mul_f32_e32 v157, 0xbfb8aa3b, v161
	v_rcp_f32_e32 v173, v136
	v_add_f32_e32 v136, 1.0, v174
	v_exp_f32_e32 v157, v157
	v_mul_f32_e32 v174, 0xbfb8aa3b, v162
	v_exp_f32_e32 v176, v174
	v_rcp_f32_e32 v174, v136
	v_add_f32_e32 v136, 1.0, v157
	v_rcp_f32_e32 v175, v136
	v_add_f32_e32 v136, 1.0, v176
	v_mul_f32_e32 v157, 0xbfb8aa3b, v158
	v_rcp_f32_e32 v176, v136
	v_mul_f32_e32 v136, 0xbfb8aa3b, v163
	v_exp_f32_e32 v157, v157
	v_mul_f32_e32 v177, 0xbfb8aa3b, v159
	v_exp_f32_e32 v136, v136
	v_exp_f32_e32 v177, v177
	v_add_f32_e32 v157, 1.0, v157
	v_rcp_f32_e32 v178, v157
	v_add_f32_e32 v136, 1.0, v136
	v_add_f32_e32 v157, 1.0, v177
	v_rcp_f32_e32 v179, v157
	v_rcp_f32_e32 v177, v136
	v_pk_mul_f32 v[160:161], v[160:161], v[174:175]
	v_pk_mul_f32 v[164:165], v[164:165], v[172:173]
	v_pk_mul_f32 v[158:159], v[158:159], v[178:179]
	v_pk_mul_f32 v[162:163], v[162:163], v[176:177]

; __device__ __forceinline__ unsigned cvt_pk_bf16(float lo, float hi) { cvf32x2_t v = {lo, hi}; cvbf16x2_t b = __builtin_convertvector(v, cvbf16x2_t); return __builtin_bit_cast(unsigned, b); }
; __device__ __forceinline__ float fsilu(float x) { return x * fsigm(x); }
; __device__ __forceinline__ float row_rs(const float* ssq, int row) { return ssq ? rsqrtf(ssq[row] * (1.f / 1024.f) + RMS_EPS) : 1.f; }
;     __device__ __forceinline__ void operator()(const f32x4 (&acc)[2][2][4][2], const Unit& u, int wr, int wc, int fr, int fq) const {
;     ...
;         bf16_t* dst = grp == 0 ? QS : (grp == 2 ? VV : (grp == 3 ? GS : BC)); const bool act = (grp == 0) || (grp == 3);
; #pragma unroll
;         for (int ai = 0; ai < 2; ++ai)
; #pragma unroll
;             for (int m = 0; m < 4; ++m) { const int row = row0 + ai * HALF + m * 16; const float rs = row_rs(ssq, row);
; #pragma unroll
;                 for (int bj = 0; bj < 2; ++bj) { f32x4 p0 = acc[ai][bj][m][0] * rs, p1 = acc[ai][bj][m][1] * rs;
;                     if (act) { p0[0] = fsilu(p0[0]); p0[1] = fsilu(p0[1]); p0[2] = fsilu(p0[2]); p0[3] = fsilu(p0[3]); p1[0] = fsilu(p1[0]); p1[1] = fsilu(p1[1]); p1[2] = fsilu(p1[2]); p1[3] = fsilu(p1[3]); }
;                     u32x4 w; w.x = cvt_pk_bf16(p0[0], p0[1]); w.y = cvt_pk_bf16(p0[2], p0[3]); w.z = cvt_pk_bf16(p1[0], p1[1]); w.w = cvt_pk_bf16(p1[2], p1[3]);
;                     *(u32x4*)(dst + (size_t)row * 512 + cbase + bj * HALF) = w; } }
.LBB0_490:
	s_nop 0
	v_cvt_pk_bf16_f32 v172, v160, v161
	v_cvt_pk_bf16_f32 v173, v158, v159
	v_cvt_pk_bf16_f32 v174, v156, v157
	v_cvt_pk_bf16_f32 v175, v162, v163
	global_store_dwordx4 v[154:155], v[172:175], off offset:256
	v_or_b32_e32 v154, 48, v148
	v_ashrrev_i32_e32 v155, 31, v154
	v_lshl_add_u64 v[156:157], v[154:155], 2, s[30:31]
	s_and_b64 vcc, exec, s[6:7]
	v_fmamk_f32 v136, v212, 0x3a800000, v170
	v_mul_f32_e32 v156, 0x4b800000, v136
	v_cmp_gt_f32_e64 s[8:9], s87, v136
	s_nop 1
	v_cndmask_b32_e64 v136, v136, v156, s[8:9]
	v_rsq_f32_e32 v136, v136
	s_nop 0
	v_mul_f32_e32 v156, 0x45800000, v136
	v_cndmask_b32_e64 v156, v136, v156, s[8:9]
	v_pk_mul_f32 v[160:161], v[78:79], v[156:157] op_sel_hi:[1,0]
	v_pk_mul_f32 v[164:165], v[76:77], v[156:157] op_sel_hi:[1,0]
	v_pk_mul_f32 v[158:159], v[74:75], v[156:157] op_sel_hi:[1,0]
	v_pk_mul_f32 v[162:163], v[72:73], v[156:157] op_sel_hi:[1,0]
	s_cbranch_vccnz .LBB0_492
	v_mul_f32_e32 v136, 0xbfb8aa3b, v164
	v_exp_f32_e32 v136, v136
	v_mul_f32_e32 v157, 0xbfb8aa3b, v165
	v_mul_f32_e32 v172, 0xbfb8aa3b, v160
	v_exp_f32_e32 v157, v157
	v_exp_f32_e32 v174, v172
	v_add_f32_e32 v136, 1.0, v136
	v_rcp_f32_e32 v172, v136
	v_add_f32_e32 v136, 1.0, v157
	v_mul_f32_e32 v157, 0xbfb8aa3b, v161
	v_rcp_f32_e32 v173, v136
	v_add_f32_e32 v136, 1.0, v174
	v_exp_f32_e32 v157, v157
	v_mul_f32_e32 v174, 0xbfb8aa3b, v162
	v_exp_f32_e32 v176, v174
	v_rcp_f32_e32 v174, v136
	v_add_f32_e32 v136, 1.0, v157
	v_rcp_f32_e32 v175, v136
	v_add_f32_e32 v136, 1.0, v176
	v_mul_f32_e32 v157, 0xbfb8aa3b, v158
	v_rcp_f32_e32 v176, v136
	v_mul_f32_e32 v136, 0xbfb8aa3b, v163
	v_exp_f32_e32 v157, v157
	v_mul_f32_e32 v177, 0xbfb8aa3b, v159
	v_exp_f32_e32 v136, v136
	v_exp_f32_e32 v177, v177
	v_add_f32_e32 v157, 1.0, v157
	v_rcp_f32_e32 v178, v157
	v_add_f32_e32 v136, 1.0, v136
	v_add_f32_e32 v157, 1.0, v177
	v_rcp_f32_e32 v179, v157
	v_rcp_f32_e32 v177, v136
	v_pk_mul_f32 v[160:161], v[160:161], v[174:175]
	v_pk_mul_f32 v[164:165], v[164:165], v[172:173]
	v_pk_mul_f32 v[158:159], v[158:159], v[178:179]
	v_pk_mul_f32 v[162:163], v[162:163], v[176:177]

; __device__ __forceinline__ unsigned cvt_pk_bf16(float lo, float hi) { cvf32x2_t v = {lo, hi}; cvbf16x2_t b = __builtin_convertvector(v, cvbf16x2_t); return __builtin_bit_cast(unsigned, b); }
; __device__ __forceinline__ float fsilu(float x) { return x * fsigm(x); }
; __device__ __forceinline__ float row_rs(const float* ssq, int row) { return ssq ? rsqrtf(ssq[row] * (1.f / 1024.f) + RMS_EPS) : 1.f; }
;     __device__ __forceinline__ void operator()(const f32x4 (&acc)[2][2][4][2], const Unit& u, int wr, int wc, int fr, int fq) const {
;     ...
;         bf16_t* dst = grp == 0 ? QS : (grp == 2 ? VV : (grp == 3 ? GS : BC)); const bool act = (grp == 0) || (grp == 3);
; #pragma unroll
;         for (int ai = 0; ai < 2; ++ai)
; #pragma unroll
;             for (int m = 0; m < 4; ++m) { const int row = row0 + ai * HALF + m * 16; const float rs = row_rs(ssq, row);
; #pragma unroll
;                 for (int bj = 0; bj < 2; ++bj) { f32x4 p0 = acc[ai][bj][m][0] * rs, p1 = acc[ai][bj][m][1] * rs;
;                     if (act) { p0[0] = fsilu(p0[0]); p0[1] = fsilu(p0[1]); p0[2] = fsilu(p0[2]); p0[3] = fsilu(p0[3]); p1[0] = fsilu(p1[0]); p1[1] = fsilu(p1[1]); p1[2] = fsilu(p1[2]); p1[3] = fsilu(p1[3]); }
;                     u32x4 w; w.x = cvt_pk_bf16(p0[0], p0[1]); w.y = cvt_pk_bf16(p0[2], p0[3]); w.z = cvt_pk_bf16(p1[0], p1[1]); w.w = cvt_pk_bf16(p1[2], p1[3]);
;                     *(u32x4*)(dst + (size_t)row * 512 + cbase + bj * HALF) = w; } }
.LBB0_494:
	s_nop 0
	v_cvt_pk_bf16_f32 v172, v160, v161
	v_cvt_pk_bf16_f32 v173, v158, v159
	v_cvt_pk_bf16_f32 v174, v156, v157
	v_cvt_pk_bf16_f32 v175, v162, v163
	global_store_dwordx4 v[154:155], v[172:175], off offset:256
	s_and_b64 vcc, exec, s[6:7]
	v_fmamk_f32 v136, v213, 0x3a800000, v170
	v_mul_f32_e32 v154, 0x4b800000, v136
	v_cmp_gt_f32_e64 s[8:9], s87, v136
	s_nop 1
	v_cndmask_b32_e64 v136, v136, v154, s[8:9]
	v_rsq_f32_e32 v136, v136
	s_nop 0
	v_mul_f32_e32 v154, 0x45800000, v136
	v_cndmask_b32_e64 v154, v136, v154, s[8:9]
	v_pk_mul_f32 v[160:161], v[62:63], v[154:155] op_sel_hi:[1,0]
	v_pk_mul_f32 v[164:165], v[60:61], v[154:155] op_sel_hi:[1,0]
	v_pk_mul_f32 v[158:159], v[58:59], v[154:155] op_sel_hi:[1,0]
	v_pk_mul_f32 v[162:163], v[56:57], v[154:155] op_sel_hi:[1,0]
	s_cbranch_vccnz .LBB0_496
	v_mul_f32_e32 v136, 0xbfb8aa3b, v164
	v_exp_f32_e32 v136, v136
	v_mul_f32_e32 v155, 0xbfb8aa3b, v165
	v_mul_f32_e32 v156, 0xbfb8aa3b, v160
	v_exp_f32_e32 v155, v155
	v_exp_f32_e32 v172, v156
	v_add_f32_e32 v136, 1.0, v136
	v_rcp_f32_e32 v156, v136
	v_add_f32_e32 v136, 1.0, v155
	v_mul_f32_e32 v155, 0xbfb8aa3b, v161
	v_rcp_f32_e32 v157, v136
	v_add_f32_e32 v136, 1.0, v172
	v_exp_f32_e32 v155, v155
	v_mul_f32_e32 v172, 0xbfb8aa3b, v162
	v_exp_f32_e32 v174, v172
	v_rcp_f32_e32 v172, v136
	v_add_f32_e32 v136, 1.0, v155
	v_rcp_f32_e32 v173, v136
	v_add_f32_e32 v136, 1.0, v174
	v_mul_f32_e32 v155, 0xbfb8aa3b, v158
	v_rcp_f32_e32 v174, v136
	v_mul_f32_e32 v136, 0xbfb8aa3b, v163
	v_exp_f32_e32 v155, v155
	v_mul_f32_e32 v175, 0xbfb8aa3b, v159
	v_exp_f32_e32 v136, v136
	v_exp_f32_e32 v175, v175
	v_add_f32_e32 v155, 1.0, v155
	v_rcp_f32_e32 v176, v155
	v_add_f32_e32 v136, 1.0, v136
	v_add_f32_e32 v155, 1.0, v175
	v_rcp_f32_e32 v177, v155
	v_rcp_f32_e32 v175, v136
	v_pk_mul_f32 v[160:161], v[160:161], v[172:173]
	v_pk_mul_f32 v[164:165], v[164:165], v[156:157]
	v_pk_mul_f32 v[158:159], v[158:159], v[176:177]
	v_pk_mul_f32 v[162:163], v[162:163], v[174:175]

; __device__ __forceinline__ unsigned cvt_pk_bf16(float lo, float hi) { cvf32x2_t v = {lo, hi}; cvbf16x2_t b = __builtin_convertvector(v, cvbf16x2_t); return __builtin_bit_cast(unsigned, b); }
; __device__ __forceinline__ float fsilu(float x) { return x * fsigm(x); }
; __device__ __forceinline__ float row_rs(const float* ssq, int row) { return ssq ? rsqrtf(ssq[row] * (1.f / 1024.f) + RMS_EPS) : 1.f; }
;     __device__ __forceinline__ void operator()(const f32x4 (&acc)[2][2][4][2], const Unit& u, int wr, int wc, int fr, int fq) const {
;     ...
;         bf16_t* dst = grp == 0 ? QS : (grp == 2 ? VV : (grp == 3 ? GS : BC)); const bool act = (grp == 0) || (grp == 3);
; #pragma unroll
;         for (int ai = 0; ai < 2; ++ai)
; #pragma unroll
;             for (int m = 0; m < 4; ++m) { const int row = row0 + ai * HALF + m * 16; const float rs = row_rs(ssq, row);
; #pragma unroll
;                 for (int bj = 0; bj < 2; ++bj) { f32x4 p0 = acc[ai][bj][m][0] * rs, p1 = acc[ai][bj][m][1] * rs;
;                     if (act) { p0[0] = fsilu(p0[0]); p0[1] = fsilu(p0[1]); p0[2] = fsilu(p0[2]); p0[3] = fsilu(p0[3]); p1[0] = fsilu(p1[0]); p1[1] = fsilu(p1[1]); p1[2] = fsilu(p1[2]); p1[3] = fsilu(p1[3]); }
;                     u32x4 w; w.x = cvt_pk_bf16(p0[0], p0[1]); w.y = cvt_pk_bf16(p0[2], p0[3]); w.z = cvt_pk_bf16(p1[0], p1[1]); w.w = cvt_pk_bf16(p1[2], p1[3]);
;                     *(u32x4*)(dst + (size_t)row * 512 + cbase + bj * HALF) = w; } }
.LBB0_498:
	v_lshl_add_u64 v[164:165], v[156:157], 0, s[38:39]
	v_cvt_pk_bf16_f32 v156, v160, v161
	v_cvt_pk_bf16_f32 v157, v158, v159
	v_cvt_pk_bf16_f32 v158, v154, v155
	v_cvt_pk_bf16_f32 v159, v162, v163
	global_store_dwordx4 v[164:165], v[156:159], off offset:256
	s_and_b64 vcc, exec, s[6:7]
	v_fmamk_f32 v136, v214, 0x3a800000, v170
	v_mul_f32_e32 v154, 0x4b800000, v136
	v_cmp_gt_f32_e64 s[8:9], s87, v136
	s_nop 1
	v_cndmask_b32_e64 v136, v136, v154, s[8:9]
	v_rsq_f32_e32 v136, v136
	s_nop 0
	v_mul_f32_e32 v154, 0x45800000, v136
	v_cndmask_b32_e64 v154, v136, v154, s[8:9]
	v_pk_mul_f32 v[160:161], v[46:47], v[154:155] op_sel_hi:[1,0]
	v_pk_mul_f32 v[164:165], v[44:45], v[154:155] op_sel_hi:[1,0]
	v_pk_mul_f32 v[158:159], v[42:43], v[154:155] op_sel_hi:[1,0]
	v_pk_mul_f32 v[162:163], v[40:41], v[154:155] op_sel_hi:[1,0]
	s_cbranch_vccnz .LBB0_500
	v_mul_f32_e32 v136, 0xbfb8aa3b, v164
	v_exp_f32_e32 v136, v136
	v_mul_f32_e32 v155, 0xbfb8aa3b, v165
	v_mul_f32_e32 v156, 0xbfb8aa3b, v160
	v_exp_f32_e32 v155, v155
	v_exp_f32_e32 v172, v156
	v_add_f32_e32 v136, 1.0, v136
	v_rcp_f32_e32 v156, v136
	v_add_f32_e32 v136, 1.0, v155
	v_mul_f32_e32 v155, 0xbfb8aa3b, v161
	v_rcp_f32_e32 v157, v136
	v_add_f32_e32 v136, 1.0, v172
	v_exp_f32_e32 v155, v155
	v_mul_f32_e32 v172, 0xbfb8aa3b, v162
	v_exp_f32_e32 v174, v172
	v_rcp_f32_e32 v172, v136
	v_add_f32_e32 v136, 1.0, v155
	v_rcp_f32_e32 v173, v136
	v_add_f32_e32 v136, 1.0, v174
	v_mul_f32_e32 v155, 0xbfb8aa3b, v158
	v_rcp_f32_e32 v174, v136
	v_mul_f32_e32 v136, 0xbfb8aa3b, v163
	v_exp_f32_e32 v155, v155
	v_mul_f32_e32 v175, 0xbfb8aa3b, v159
	v_exp_f32_e32 v136, v136
	v_exp_f32_e32 v175, v175
	v_add_f32_e32 v155, 1.0, v155
	v_rcp_f32_e32 v176, v155
	v_add_f32_e32 v136, 1.0, v136
	v_add_f32_e32 v155, 1.0, v175
	v_rcp_f32_e32 v177, v155
	v_rcp_f32_e32 v175, v136
	v_pk_mul_f32 v[160:161], v[160:161], v[172:173]
	v_pk_mul_f32 v[164:165], v[164:165], v[156:157]
	v_pk_mul_f32 v[158:159], v[158:159], v[176:177]
	v_pk_mul_f32 v[162:163], v[162:163], v[174:175]

; __device__ __forceinline__ unsigned cvt_pk_bf16(float lo, float hi) { cvf32x2_t v = {lo, hi}; cvbf16x2_t b = __builtin_convertvector(v, cvbf16x2_t); return __builtin_bit_cast(unsigned, b); }
; __device__ __forceinline__ float fsilu(float x) { return x * fsigm(x); }
; __device__ __forceinline__ float row_rs(const float* ssq, int row) { return ssq ? rsqrtf(ssq[row] * (1.f / 1024.f) + RMS_EPS) : 1.f; }
;     __device__ __forceinline__ void operator()(const f32x4 (&acc)[2][2][4][2], const Unit& u, int wr, int wc, int fr, int fq) const {
;     ...
;         bf16_t* dst = grp == 0 ? QS : (grp == 2 ? VV : (grp == 3 ? GS : BC)); const bool act = (grp == 0) || (grp == 3);
; #pragma unroll
;         for (int ai = 0; ai < 2; ++ai)
; #pragma unroll
;             for (int m = 0; m < 4; ++m) { const int row = row0 + ai * HALF + m * 16; const float rs = row_rs(ssq, row);
; #pragma unroll
;                 for (int bj = 0; bj < 2; ++bj) { f32x4 p0 = acc[ai][bj][m][0] * rs, p1 = acc[ai][bj][m][1] * rs;
;                     if (act) { p0[0] = fsilu(p0[0]); p0[1] = fsilu(p0[1]); p0[2] = fsilu(p0[2]); p0[3] = fsilu(p0[3]); p1[0] = fsilu(p1[0]); p1[1] = fsilu(p1[1]); p1[2] = fsilu(p1[2]); p1[3] = fsilu(p1[3]); }
;                     u32x4 w; w.x = cvt_pk_bf16(p0[0], p0[1]); w.y = cvt_pk_bf16(p0[2], p0[3]); w.z = cvt_pk_bf16(p1[0], p1[1]); w.w = cvt_pk_bf16(p1[2], p1[3]);
;                     *(u32x4*)(dst + (size_t)row * 512 + cbase + bj * HALF) = w; } }
.LBB0_502:
	v_lshl_add_u64 v[164:165], v[156:157], 0, s[40:41]
	v_cvt_pk_bf16_f32 v156, v160, v161
	v_cvt_pk_bf16_f32 v157, v158, v159
	v_cvt_pk_bf16_f32 v158, v154, v155
	v_cvt_pk_bf16_f32 v159, v162, v163
	global_store_dwordx4 v[164:165], v[156:159], off offset:256
	s_and_b64 vcc, exec, s[6:7]
	v_fmamk_f32 v136, v215, 0x3a800000, v170
	v_mul_f32_e32 v154, 0x4b800000, v136
	v_cmp_gt_f32_e64 s[8:9], s87, v136
	s_nop 1
	v_cndmask_b32_e64 v136, v136, v154, s[8:9]
	v_rsq_f32_e32 v136, v136
	s_nop 0
	v_mul_f32_e32 v154, 0x45800000, v136
	v_cndmask_b32_e64 v154, v136, v154, s[8:9]
	v_pk_mul_f32 v[160:161], v[30:31], v[154:155] op_sel_hi:[1,0]
	v_pk_mul_f32 v[164:165], v[28:29], v[154:155] op_sel_hi:[1,0]
	v_pk_mul_f32 v[158:159], v[26:27], v[154:155] op_sel_hi:[1,0]
	v_pk_mul_f32 v[162:163], v[24:25], v[154:155] op_sel_hi:[1,0]
	s_cbranch_vccnz .LBB0_504
	v_mul_f32_e32 v136, 0xbfb8aa3b, v164
	v_exp_f32_e32 v136, v136
	v_mul_f32_e32 v155, 0xbfb8aa3b, v165
	v_mul_f32_e32 v156, 0xbfb8aa3b, v160
	v_exp_f32_e32 v155, v155
	v_exp_f32_e32 v172, v156
	v_add_f32_e32 v136, 1.0, v136
	v_rcp_f32_e32 v156, v136
	v_add_f32_e32 v136, 1.0, v155
	v_mul_f32_e32 v155, 0xbfb8aa3b, v161
	v_rcp_f32_e32 v157, v136
	v_add_f32_e32 v136, 1.0, v172
	v_exp_f32_e32 v155, v155
	v_mul_f32_e32 v172, 0xbfb8aa3b, v162
	v_exp_f32_e32 v174, v172
	v_rcp_f32_e32 v172, v136
	v_add_f32_e32 v136, 1.0, v155
	v_rcp_f32_e32 v173, v136
	v_add_f32_e32 v136, 1.0, v174
	v_mul_f32_e32 v155, 0xbfb8aa3b, v158
	v_rcp_f32_e32 v174, v136
	v_mul_f32_e32 v136, 0xbfb8aa3b, v163
	v_exp_f32_e32 v155, v155
	v_mul_f32_e32 v175, 0xbfb8aa3b, v159
	v_exp_f32_e32 v136, v136
	v_exp_f32_e32 v175, v175
	v_add_f32_e32 v155, 1.0, v155
	v_rcp_f32_e32 v176, v155
	v_add_f32_e32 v136, 1.0, v136
	v_add_f32_e32 v155, 1.0, v175
	v_rcp_f32_e32 v177, v155
	v_rcp_f32_e32 v175, v136
	v_pk_mul_f32 v[160:161], v[160:161], v[172:173]
	v_pk_mul_f32 v[164:165], v[164:165], v[156:157]
	v_pk_mul_f32 v[158:159], v[158:159], v[176:177]
	v_pk_mul_f32 v[162:163], v[162:163], v[174:175]

; __device__ __forceinline__ unsigned cvt_pk_bf16(float lo, float hi) { cvf32x2_t v = {lo, hi}; cvbf16x2_t b = __builtin_convertvector(v, cvbf16x2_t); return __builtin_bit_cast(unsigned, b); }
; __device__ __forceinline__ float fsilu(float x) { return x * fsigm(x); }
; __device__ __forceinline__ float row_rs(const float* ssq, int row) { return ssq ? rsqrtf(ssq[row] * (1.f / 1024.f) + RMS_EPS) : 1.f; }
;     __device__ __forceinline__ void operator()(const f32x4 (&acc)[2][2][4][2], const Unit& u, int wr, int wc, int fr, int fq) const {
;     ...
;         bf16_t* dst = grp == 0 ? QS : (grp == 2 ? VV : (grp == 3 ? GS : BC)); const bool act = (grp == 0) || (grp == 3);
; #pragma unroll
;         for (int ai = 0; ai < 2; ++ai)
; #pragma unroll
;             for (int m = 0; m < 4; ++m) { const int row = row0 + ai * HALF + m * 16; const float rs = row_rs(ssq, row);
; #pragma unroll
;                 for (int bj = 0; bj < 2; ++bj) { f32x4 p0 = acc[ai][bj][m][0] * rs, p1 = acc[ai][bj][m][1] * rs;
;                     if (act) { p0[0] = fsilu(p0[0]); p0[1] = fsilu(p0[1]); p0[2] = fsilu(p0[2]); p0[3] = fsilu(p0[3]); p1[0] = fsilu(p1[0]); p1[1] = fsilu(p1[1]); p1[2] = fsilu(p1[2]); p1[3] = fsilu(p1[3]); }
;                     u32x4 w; w.x = cvt_pk_bf16(p0[0], p0[1]); w.y = cvt_pk_bf16(p0[2], p0[3]); w.z = cvt_pk_bf16(p1[0], p1[1]); w.w = cvt_pk_bf16(p1[2], p1[3]);
;                     *(u32x4*)(dst + (size_t)row * 512 + cbase + bj * HALF) = w; } }
.LBB0_506:
	v_lshl_add_u64 v[164:165], v[156:157], 0, s[42:43]
	v_cvt_pk_bf16_f32 v156, v160, v161
	v_cvt_pk_bf16_f32 v157, v158, v159
	v_cvt_pk_bf16_f32 v158, v154, v155
	v_cvt_pk_bf16_f32 v159, v162, v163
	global_store_dwordx4 v[164:165], v[156:159], off offset:256
	s_and_b64 vcc, exec, s[6:7]
	v_fmamk_f32 v136, v216, 0x3a800000, v170
	v_mul_f32_e32 v150, 0x4b800000, v136
	v_cmp_gt_f32_e64 s[8:9], s87, v136
	s_nop 1
	v_cndmask_b32_e64 v136, v136, v150, s[8:9]
	v_rsq_f32_e32 v136, v136
	s_nop 0
	v_mul_f32_e32 v150, 0x45800000, v136
	v_cndmask_b32_e64 v150, v136, v150, s[8:9]
	v_pk_mul_f32 v[156:157], v[14:15], v[150:151] op_sel_hi:[1,0]
	v_pk_mul_f32 v[160:161], v[12:13], v[150:151] op_sel_hi:[1,0]
	v_pk_mul_f32 v[154:155], v[10:11], v[150:151] op_sel_hi:[1,0]
	v_pk_mul_f32 v[158:159], v[8:9], v[150:151] op_sel_hi:[1,0]
	s_cbranch_vccnz .LBB0_508
	v_mul_f32_e32 v136, 0xbfb8aa3b, v160
	v_exp_f32_e32 v136, v136
	v_mul_f32_e32 v151, 0xbfb8aa3b, v161
	v_mul_f32_e32 v162, 0xbfb8aa3b, v156
	v_exp_f32_e32 v151, v151
	v_exp_f32_e32 v164, v162
	v_add_f32_e32 v136, 1.0, v136
	v_rcp_f32_e32 v162, v136
	v_add_f32_e32 v136, 1.0, v151
	v_mul_f32_e32 v151, 0xbfb8aa3b, v157
	v_rcp_f32_e32 v163, v136
	v_add_f32_e32 v136, 1.0, v164
	v_exp_f32_e32 v151, v151
	v_mul_f32_e32 v164, 0xbfb8aa3b, v158
	v_exp_f32_e32 v172, v164
	v_rcp_f32_e32 v164, v136
	v_add_f32_e32 v136, 1.0, v151
	v_rcp_f32_e32 v165, v136
	v_add_f32_e32 v136, 1.0, v172
	v_mul_f32_e32 v151, 0xbfb8aa3b, v154
	v_rcp_f32_e32 v172, v136
	v_mul_f32_e32 v136, 0xbfb8aa3b, v159
	v_exp_f32_e32 v151, v151
	v_mul_f32_e32 v173, 0xbfb8aa3b, v155
	v_exp_f32_e32 v136, v136
	v_exp_f32_e32 v173, v173
	v_add_f32_e32 v151, 1.0, v151
	v_rcp_f32_e32 v174, v151
	v_add_f32_e32 v136, 1.0, v136
	v_add_f32_e32 v151, 1.0, v173
	v_rcp_f32_e32 v175, v151
	v_rcp_f32_e32 v173, v136
	v_pk_mul_f32 v[156:157], v[156:157], v[164:165]
	v_pk_mul_f32 v[160:161], v[160:161], v[162:163]
	v_pk_mul_f32 v[154:155], v[154:155], v[174:175]
	v_pk_mul_f32 v[158:159], v[158:159], v[172:173]

; __device__ __forceinline__ float fsigm(float x) { return __builtin_amdgcn_rcpf(1.f + __expf(-x)); }
; __device__ __forceinline__ float row_rs(const float* ssq, int row) { return ssq ? rsqrtf(ssq[row] * (1.f / 1024.f) + RMS_EPS) : 1.f; }
;     __device__ __forceinline__ void operator()(const f32x4 (&acc)[2][2][4][2], const Unit& u, int wr, int wc, int fr, int fq) const {
;     ...
;         if (grp == 1) {
;             float lb[2][2][4];
; #pragma unroll
;             for (int bj = 0; bj < 2; ++bj)
; #pragma unroll
;                 for (int n = 0; n < 2; ++n) { const int c = cbase + bj * HALF + n * 4; const f32x4 l0 = *(const f32x4*)(lbl + c), l1 = *(const f32x4*)(lbl + 512 + c);
; #pragma unroll
;                     for (int j = 0; j < 4; ++j) lb[bj][n][j] = fsigm(l0[j] - l1[j]); }
; #pragma unroll
;             for (int ai = 0; ai < 2; ++ai)
; #pragma unroll
;                 for (int m = 0; m < 4; ++m) { const int row = row0 + ai * HALF + m * 16; const float rs = row_rs(ssq, row);
; #pragma unroll
;                     for (int bj = 0; bj < 2; ++bj) { f16x4 o[2];
; #pragma unroll
;                         for (int n = 0; n < 2; ++n) { const f32x4 p = acc[ai][bj][m][n] * rs;
; #pragma unroll
;                             for (int j = 0; j < 4; ++j) { const float l = lb[bj][n][j]; const float f = l + (1.f - l) * fsigm(p[j]); o[n][j] = (_Float16)__logf(f); } }
;                         const u32x2 a0 = __builtin_bit_cast(u32x2, o[0]), a1 = __builtin_bit_cast(u32x2, o[1]); u32x4 w; w.x = a0.x; w.y = a0.y; w.z = a1.x; w.w = a1.y;
;                         *(u32x4*)(LF + (size_t)row * 512 + cbase + bj * HALF) = w; } }
.LBB0_511:
	s_and_b64 vcc, exec, s[6:7]
	s_cbranch_vccz .LBB0_513
	v_ashrrev_i32_e32 v149, 31, v148
	v_lshlrev_b32_e32 v136, 2, v181
	v_lshl_add_u64 v[150:151], v[148:149], 2, s[30:31]
	global_load_dwordx4 v[152:155], v136, s[12:13] offset:2048
	global_load_dwordx4 v[156:159], v136, s[12:13]
	global_load_dwordx4 v[160:163], v136, s[12:13] offset:16
	global_load_dwordx4 v[172:175], v136, s[12:13] offset:2064
	global_load_dwordx4 v[176:179], v136, s[12:13] offset:2560
	global_load_dwordx4 v[182:185], v136, s[12:13] offset:512
	global_load_dwordx4 v[186:189], v136, s[12:13] offset:528
	global_load_dwordx4 v[190:193], v136, s[12:13] offset:2576
	s_waitcnt vmcnt(0)
	v_sub_f32_e32 v152, v156, v152
	global_load_dword v136, v[150:151], off
	global_load_dword v210, v[150:151], off offset:64
	global_load_dword v211, v[150:151], off offset:128
	global_load_dword v212, v[150:151], off offset:192
	global_load_dword v213, v[150:151], off offset:512
	global_load_dword v214, v[150:151], off offset:576
	global_load_dword v215, v[150:151], off offset:640
	global_load_dword v216, v[150:151], off offset:704
	v_sub_f32_e32 v153, v157, v153
	v_sub_f32_e32 v156, v160, v172
	v_sub_f32_e32 v160, v182, v176
	v_mul_f32_e32 v153, 0xbfb8aa3b, v153
	v_sub_f32_e32 v172, v188, v192
	v_mul_f32_e32 v176, 0xbfb8aa3b, v172
	v_exp_f32_e32 v153, v153
	v_sub_f32_e32 v154, v158, v154
	v_sub_f32_e32 v158, v162, v174
	v_mul_f32_e32 v152, 0xbfb8aa3b, v152
	v_add_f32_e32 v153, 1.0, v153
	v_rcp_f32_e32 v174, v153
	v_exp_f32_e32 v152, v152
	v_sub_f32_e32 v157, v161, v173
	v_sub_f32_e32 v161, v183, v177
	v_sub_f32_e32 v155, v159, v155
	v_mul_f32_e32 v160, 0xbfb8aa3b, v160
	v_mul_f32_e32 v161, 0xbfb8aa3b, v161
	v_add_f32_e32 v152, 1.0, v152
	v_sub_f32_e32 v159, v163, v175
	v_mul_f32_e32 v155, 0xbfb8aa3b, v155
	v_exp_f32_e32 v160, v160
	v_exp_f32_e32 v161, v161
	v_rcp_f32_e32 v175, v152
	v_exp_f32_e32 v155, v155
	v_exp_f32_e32 v152, v176
	v_add_f32_e32 v160, 1.0, v160
	v_add_f32_e32 v177, 1.0, v161
	v_sub_f32_e32 v176, 1.0, v175
	v_sub_f32_e32 v162, v184, v178
	v_add_f32_e32 v155, 1.0, v155
	v_rcp_f32_e32 v161, v160
	v_rcp_f32_e32 v160, v177
	v_add_f32_e32 v152, 1.0, v152
	v_mul_f32_e32 v159, 0xbfb8aa3b, v159
	v_mul_f32_e32 v162, 0xbfb8aa3b, v162
	v_mul_f32_e32 v154, 0xbfb8aa3b, v154
	v_exp_f32_e32 v159, v159
	v_exp_f32_e32 v162, v162
	v_exp_f32_e32 v154, v154
	v_sub_f32_e32 v163, v185, v179
	v_add_f32_e32 v159, 1.0, v159
	v_add_f32_e32 v178, 1.0, v162
	v_mul_f32_e32 v158, 0xbfb8aa3b, v158
	v_mul_f32_e32 v163, 0xbfb8aa3b, v163
	v_add_f32_e32 v154, 1.0, v154
	v_rcp_f32_e32 v162, v159
	v_rcp_f32_e32 v159, v178
	v_exp_f32_e32 v158, v158
	v_exp_f32_e32 v163, v163
	v_rcp_f32_e32 v173, v154
	v_sub_f32_e32 v164, v186, v190
	v_add_f32_e32 v158, 1.0, v158
	v_add_f32_e32 v179, 1.0, v163
	v_rcp_f32_e32 v163, v158
	v_rcp_f32_e32 v158, v179
	v_mul_f32_e32 v157, 0xbfb8aa3b, v157
	v_mul_f32_e32 v164, 0xbfb8aa3b, v164
	v_exp_f32_e32 v157, v157
	v_exp_f32_e32 v164, v164
	v_sub_f32_e32 v165, v187, v191
	v_mul_f32_e32 v156, 0xbfb8aa3b, v156
	v_add_f32_e32 v157, 1.0, v157
	v_add_f32_e32 v180, 1.0, v164
	v_mul_f32_e32 v165, 0xbfb8aa3b, v165
	v_rcp_f32_e32 v164, v157
	v_rcp_f32_e32 v157, v180
	v_exp_f32_e32 v156, v156
	v_exp_f32_e32 v165, v165
	v_add_f32_e32 v156, 1.0, v156
	v_add_f32_e32 v182, 1.0, v165
	v_rcp_f32_e32 v165, v156
	v_rcp_f32_e32 v156, v182
	s_waitcnt vmcnt(0)
	v_fmamk_f32 v136, v136, 0x3a800000, v170
	v_mul_f32_e32 v172, 0x4b800000, v136
	v_cmp_gt_f32_e32 vcc, s87, v136
	s_nop 1
	v_cndmask_b32_e32 v136, v136, v172, vcc
	v_rsq_f32_e32 v136, v136
	v_rcp_f32_e32 v172, v155
	v_rcp_f32_e32 v155, v152
	v_sub_f32_e32 v152, v189, v193
	v_mul_f32_e32 v153, 0x45800000, v136
	v_cndmask_b32_e32 v194, v136, v153, vcc
	v_mul_f32_e32 v136, v124, v194
	v_mul_f32_e32 v136, 0xbfb8aa3b, v136
	v_exp_f32_e32 v136, v136
	v_mul_f32_e32 v177, v125, v194
	v_mul_f32_e32 v177, 0xbfb8aa3b, v177
	v_mul_f32_e32 v152, 0xbfb8aa3b, v152
	v_add_f32_e32 v136, 1.0, v136
	v_rcp_f32_e32 v136, v136
	v_exp_f32_e32 v177, v177
	v_exp_f32_e32 v152, v152
	v_sub_f32_e32 v183, 1.0, v172
	v_fma_f32 v136, v176, v136, v175
	v_cmp_gt_f32_e32 vcc, s87, v136
	v_add_f32_e32 v177, 1.0, v177
	v_add_f32_e32 v152, 1.0, v152
	v_cndmask_b32_e64 v153, 0, 32, vcc
	v_ldexp_f32 v136, v136, v153
	v_log_f32_e32 v136, v136
	v_rcp_f32_e32 v178, v177
	v_rcp_f32_e32 v154, v152
	v_lshlrev_b64 v[152:153], 10, v[148:149]
	v_mul_f32_e32 v149, 0x3f317217, v136
	v_fma_f32 v149, v136, s92, -v149
	v_fmac_f32_e32 v149, 0x3377d1cf, v136
	v_sub_f32_e32 v177, 1.0, v174
	v_fmac_f32_e32 v149, 0x3f317217, v136
	v_cmp_lt_f32_e64 s[6:7], |v136|, s93
	v_fma_f32 v178, v177, v178, v174
	v_lshl_add_u64 v[152:153], s[28:29], 0, v[152:153]
	v_cndmask_b32_e64 v136, v136, v149, s[6:7]
	v_cndmask_b32_e32 v149, 0, v171, vcc
	v_cmp_gt_f32_e32 vcc, s87, v178
	v_sub_f32_e32 v136, v136, v149
	s_nop 0
	v_cndmask_b32_e64 v179, 0, 32, vcc
	v_ldexp_f32 v178, v178, v179
	v_log_f32_e32 v179, v178
	v_mul_f32_e32 v178, v126, v194
	v_mul_f32_e32 v178, 0xbfb8aa3b, v178
	v_exp_f32_e32 v178, v178
	v_mul_f32_e32 v149, 0x3f317217, v179
	v_fma_f32 v149, v179, s92, -v149
	v_fmac_f32_e32 v149, 0x3377d1cf, v179
	v_add_f32_e32 v178, 1.0, v178
	v_rcp_f32_e32 v180, v178
	v_sub_f32_e32 v178, 1.0, v173
	v_fmac_f32_e32 v149, 0x3f317217, v179
	v_cmp_lt_f32_e64 s[8:9], |v179|, s93
	v_fma_f32 v180, v178, v180, v173
	v_cmp_gt_f32_e64 s[6:7], s87, v180
	v_cndmask_b32_e64 v149, v179, v149, s[8:9]
	v_cndmask_b32_e32 v179, 0, v171, vcc
	v_cndmask_b32_e64 v182, 0, 32, s[6:7]
	v_ldexp_f32 v180, v180, v182
	v_sub_f32_e32 v182, v149, v179
	v_mul_f32_e32 v179, v127, v194
	v_mul_f32_e32 v179, 0xbfb8aa3b, v179
	v_exp_f32_e32 v179, v179
; __device__ __forceinline__ float fsigm(float x) { return __builtin_amdgcn_rcpf(1.f + __expf(-x)); }
; __device__ __forceinline__ float row_rs(const float* ssq, int row) { return ssq ? rsqrtf(ssq[row] * (1.f / 1024.f) + RMS_EPS) : 1.f; }
;     __device__ __forceinline__ void operator()(const f32x4 (&acc)[2][2][4][2], const Unit& u, int wr, int wc, int fr, int fq) const {
;     ...
;                 for (int m = 0; m < 4; ++m) { const int row = row0 + ai * HALF + m * 16; const float rs = row_rs(ssq, row);
; #pragma unroll
;                     for (int bj = 0; bj < 2; ++bj) { f16x4 o[2];
; #pragma unroll
;                         for (int n = 0; n < 2; ++n) { const f32x4 p = acc[ai][bj][m][n] * rs;
; #pragma unroll
;                             for (int j = 0; j < 4; ++j) { const float l = lb[bj][n][j]; const float f = l + (1.f - l) * fsigm(p[j]); o[n][j] = (_Float16)__logf(f); } }
;                         const u32x2 a0 = __builtin_bit_cast(u32x2, o[0]), a1 = __builtin_bit_cast(u32x2, o[1]); u32x4 w; w.x = a0.x; w.y = a0.y; w.z = a1.x; w.w = a1.y;
;                         *(u32x4*)(LF + (size_t)row * 512 + cbase + bj * HALF) = w; } }
	v_log_f32_e32 v180, v180
	v_add_f32_e32 v179, 1.0, v179
	v_rcp_f32_e32 v179, v179
	v_mul_f32_e32 v149, 0x3f317217, v180
	v_fma_f32 v149, v180, s92, -v149
	v_fmac_f32_e32 v149, 0x3377d1cf, v180
	v_fmac_f32_e32 v149, 0x3f317217, v180
	v_cmp_lt_f32_e64 vcc, |v180|, s93
	v_fma_f32 v179, v183, v179, v172
	s_nop 0
	v_cndmask_b32_e32 v149, v180, v149, vcc
	v_cmp_gt_f32_e32 vcc, s87, v179
	v_cndmask_b32_e64 v180, 0, v171, s[6:7]
	v_sub_f32_e32 v185, v149, v180
	v_cndmask_b32_e64 v184, 0, 32, vcc
	v_ldexp_f32 v179, v179, v184
	v_mul_f32_e32 v184, v120, v194
	v_log_f32_e32 v179, v179
	v_mul_f32_e32 v184, 0xbfb8aa3b, v184
	v_exp_f32_e32 v184, v184
	v_mul_f32_e32 v149, 0x3f317217, v179
	v_fma_f32 v180, v179, s92, -v149
	v_add_f32_e32 v149, 1.0, v184
	v_rcp_f32_e32 v184, v149
	v_sub_f32_e32 v149, 1.0, v165
	v_fmac_f32_e32 v180, 0x3377d1cf, v179
	v_fmac_f32_e32 v180, 0x3f317217, v179
	v_fma_f32 v184, v149, v184, v165
	v_cmp_gt_f32_e64 s[6:7], s87, v184
	v_cmp_lt_f32_e64 s[8:9], |v179|, s93
	s_nop 0
	v_cndmask_b32_e64 v186, 0, 32, s[6:7]
	v_cndmask_b32_e64 v179, v179, v180, s[8:9]
	v_cndmask_b32_e32 v180, 0, v171, vcc
	v_ldexp_f32 v184, v184, v186
	v_sub_f32_e32 v186, v179, v180
	v_mul_f32_e32 v180, v121, v194
	v_mul_f32_e32 v180, 0xbfb8aa3b, v180
	v_log_f32_e32 v184, v184
	v_exp_f32_e32 v180, v180
	v_cndmask_b32_e64 v187, 0, v171, s[6:7]
	v_mul_f32_e32 v179, 0x3f317217, v184
	v_add_f32_e32 v180, 1.0, v180
	v_fma_f32 v179, v184, s92, -v179
	v_rcp_f32_e32 v180, v180
	v_fmac_f32_e32 v179, 0x3377d1cf, v184
	v_fmac_f32_e32 v179, 0x3f317217, v184
	v_cmp_lt_f32_e64 vcc, |v184|, s93
	s_nop 1
	v_cndmask_b32_e32 v184, v184, v179, vcc
	v_sub_f32_e32 v179, 1.0, v164
	v_fma_f32 v180, v179, v180, v164
	v_cmp_gt_f32_e32 vcc, s87, v180
	v_sub_f32_e32 v184, v184, v187
	s_nop 0
	v_cndmask_b32_e64 v188, 0, 32, vcc
	v_ldexp_f32 v180, v180, v188
	v_log_f32_e32 v188, v180
	v_mul_f32_e32 v180, v122, v194
	v_mul_f32_e32 v180, 0xbfb8aa3b, v180
	v_exp_f32_e32 v180, v180
	v_mul_f32_e32 v187, 0x3f317217, v188
	v_fma_f32 v187, v188, s92, -v187
	v_fmac_f32_e32 v187, 0x3377d1cf, v188
	v_add_f32_e32 v180, 1.0, v180
	v_rcp_f32_e32 v189, v180
	v_sub_f32_e32 v180, 1.0, v163
	v_fmac_f32_e32 v187, 0x3f317217, v188
	v_cmp_lt_f32_e64 s[8:9], |v188|, s93
	v_fma_f32 v189, v180, v189, v163
	v_cmp_gt_f32_e64 s[6:7], s87, v189
	v_cndmask_b32_e64 v187, v188, v187, s[8:9]
	v_cndmask_b32_e32 v188, 0, v171, vcc
	v_cndmask_b32_e64 v190, 0, 32, s[6:7]
	v_ldexp_f32 v189, v189, v190
	v_mul_f32_e32 v190, v123, v194
	v_mul_f32_e32 v190, 0xbfb8aa3b, v190
	v_log_f32_e32 v189, v189
	v_exp_f32_e32 v190, v190
	v_sub_f32_e32 v187, v187, v188
	v_cndmask_b32_e64 v191, 0, v171, s[6:7]
	v_mul_f32_e32 v188, 0x3f317217, v189
	v_add_f32_e32 v190, 1.0, v190
	v_fma_f32 v188, v189, s92, -v188
	v_rcp_f32_e32 v190, v190
	v_fmac_f32_e32 v188, 0x3377d1cf, v189
	v_fmac_f32_e32 v188, 0x3f317217, v189
	v_cmp_lt_f32_e64 vcc, |v189|, s93
	s_nop 1
	v_cndmask_b32_e32 v189, v189, v188, vcc
	v_sub_f32_e32 v188, 1.0, v162
	v_fma_f32 v190, v188, v190, v162
	v_cmp_gt_f32_e32 vcc, s87, v190
	v_sub_f32_e32 v189, v189, v191
	v_cvt_pk_f16_f32 v191, v185, v186
	v_cndmask_b32_e64 v192, 0, 32, vcc
	v_ldexp_f32 v190, v190, v192
	v_log_f32_e32 v192, v190
	v_cvt_pk_f16_f32 v190, v136, v182
	v_cndmask_b32_e32 v182, 0, v171, vcc
	v_mul_f32_e32 v136, 0x3f317217, v192
	v_fma_f32 v136, v192, s92, -v136
	v_fmac_f32_e32 v136, 0x3377d1cf, v192
	v_fmac_f32_e32 v136, 0x3f317217, v192
	v_cmp_lt_f32_e64 s[6:7], |v192|, s93
	s_nop 1
	v_cndmask_b32_e64 v136, v192, v136, s[6:7]
	v_sub_f32_e32 v136, v136, v182
	v_mul_f32_e32 v182, v116, v194
	v_mul_f32_e32 v182, 0xbfb8aa3b, v182
	v_exp_f32_e32 v182, v182
	v_cvt_pk_f16_f32 v193, v189, v136
	v_cvt_pk_f16_f32 v192, v184, v187
	v_sub_f32_e32 v184, 1.0, v161
	v_add_f32_e32 v136, 1.0, v182
	v_rcp_f32_e32 v182, v136
	v_lshlrev_b32_e32 v136, 1, v181
	v_lshl_add_u64 v[152:153], v[152:153], 0, v[136:137]
	global_store_dwordx4 v[152:153], v[190:193], off
	v_fma_f32 v181, v184, v182, v161
	v_cmp_gt_f32_e32 vcc, s87, v181
	s_nop 1
	v_cndmask_b32_e64 v182, 0, 32, vcc
	v_ldexp_f32 v181, v181, v182
	v_log_f32_e32 v182, v181
	v_mul_f32_e32 v181, v117, v194
	v_mul_f32_e32 v181, 0xbfb8aa3b, v181
	v_exp_f32_e32 v181, v181
	v_mul_f32_e32 v185, 0x3f317217, v182
	v_fma_f32 v185, v182, s92, -v185
	v_fmac_f32_e32 v185, 0x3377d1cf, v182
	v_add_f32_e32 v181, 1.0, v181
	v_rcp_f32_e32 v186, v181
	v_sub_f32_e32 v181, 1.0, v160
	v_fmac_f32_e32 v185, 0x3f317217, v182
	v_cmp_lt_f32_e64 s[8:9], |v182|, s93
	v_fma_f32 v186, v181, v186, v160
	v_cmp_gt_f32_e64 s[6:7], s87, v186
	v_cndmask_b32_e64 v182, v182, v185, s[8:9]
	v_cndmask_b32_e32 v185, 0, v171, vcc
	v_cndmask_b32_e64 v187, 0, 32, s[6:7]
	v_ldexp_f32 v186, v186, v187
	v_mul_f32_e32 v187, v118, v194
	v_mul_f32_e32 v187, 0xbfb8aa3b, v187
	v_log_f32_e32 v186, v186
	v_exp_f32_e32 v187, v187
	v_sub_f32_e32 v182, v182, v185
	v_cndmask_b32_e64 v189, 0, v171, s[6:7]
	v_mul_f32_e32 v185, 0x3f317217, v186
	v_add_f32_e32 v187, 1.0, v187
	v_fma_f32 v185, v186, s92, -v185
	v_rcp_f32_e32 v187, v187
	v_fmac_f32_e32 v185, 0x3377d1cf, v186
	v_fmac_f32_e32 v185, 0x3f317217, v186
	v_cmp_lt_f32_e64 vcc, |v186|, s93
	s_nop 1
	v_cndmask_b32_e32 v186, v186, v185, vcc
	v_sub_f32_e32 v185, 1.0, v159
	v_fma_f32 v187, v185, v187, v159
	v_cmp_gt_f32_e32 vcc, s87, v187
	v_sub_f32_e32 v189, v186, v189
	s_nop 0
	v_cndmask_b32_e64 v190, 0, 32, vcc
	v_ldexp_f32 v187, v187, v190
	v_mul_f32_e32 v190, v119, v194
	v_log_f32_e32 v187, v187
	v_mul_f32_e32 v190, 0xbfb8aa3b, v190
	v_exp_f32_e32 v190, v190
	v_mul_f32_e32 v186, 0x3f317217, v187
	v_fma_f32 v191, v187, s92, -v186
	v_add_f32_e32 v186, 1.0, v190
	v_rcp_f32_e32 v190, v186
; __device__ __forceinline__ float fsigm(float x) { return __builtin_amdgcn_rcpf(1.f + __expf(-x)); }
; __device__ __forceinline__ float row_rs(const float* ssq, int row) { return ssq ? rsqrtf(ssq[row] * (1.f / 1024.f) + RMS_EPS) : 1.f; }
;     __device__ __forceinline__ void operator()(const f32x4 (&acc)[2][2][4][2], const Unit& u, int wr, int wc, int fr, int fq) const {
;     ...
;                 for (int m = 0; m < 4; ++m) { const int row = row0 + ai * HALF + m * 16; const float rs = row_rs(ssq, row);
; #pragma unroll
;                     for (int bj = 0; bj < 2; ++bj) { f16x4 o[2];
; #pragma unroll
;                         for (int n = 0; n < 2; ++n) { const f32x4 p = acc[ai][bj][m][n] * rs;
; #pragma unroll
;                             for (int j = 0; j < 4; ++j) { const float l = lb[bj][n][j]; const float f = l + (1.f - l) * fsigm(p[j]); o[n][j] = (_Float16)__logf(f); } }
;                         const u32x2 a0 = __builtin_bit_cast(u32x2, o[0]), a1 = __builtin_bit_cast(u32x2, o[1]); u32x4 w; w.x = a0.x; w.y = a0.y; w.z = a1.x; w.w = a1.y;
;                         *(u32x4*)(LF + (size_t)row * 512 + cbase + bj * HALF) = w; } }
	v_sub_f32_e32 v186, 1.0, v158
	v_fmac_f32_e32 v191, 0x3377d1cf, v187
	v_fmac_f32_e32 v191, 0x3f317217, v187
	v_fma_f32 v190, v186, v190, v158
	v_cmp_gt_f32_e64 s[6:7], s87, v190
	v_cmp_lt_f32_e64 s[8:9], |v187|, s93
	s_nop 0
	v_cndmask_b32_e64 v192, 0, 32, s[6:7]
	v_ldexp_f32 v190, v190, v192
	v_log_f32_e32 v190, v190
	v_mul_f32_e32 v192, v112, v194
	v_mul_f32_e32 v192, 0xbfb8aa3b, v192
	v_exp_f32_e32 v192, v192
	v_cndmask_b32_e64 v187, v187, v191, s[8:9]
	v_cndmask_b32_e32 v191, 0, v171, vcc
	v_sub_f32_e32 v187, v187, v191
	v_mul_f32_e32 v191, 0x3f317217, v190
	v_fma_f32 v191, v190, s92, -v191
	v_fmac_f32_e32 v191, 0x3377d1cf, v190
	v_add_f32_e32 v192, 1.0, v192
	v_fmac_f32_e32 v191, 0x3f317217, v190
	v_cmp_lt_f32_e64 vcc, |v190|, s93
	v_rcp_f32_e32 v192, v192
	s_nop 0
	v_cndmask_b32_e32 v190, v190, v191, vcc
	v_cndmask_b32_e64 v191, 0, v171, s[6:7]
	v_sub_f32_e32 v190, v190, v191
	v_cvt_pk_f16_f32 v193, v187, v190
	v_sub_f32_e32 v187, 1.0, v157
	v_fma_f32 v190, v187, v192, v157
	v_cmp_gt_f32_e32 vcc, s87, v190
	v_cvt_pk_f16_f32 v192, v182, v189
	s_nop 0
	v_cndmask_b32_e64 v191, 0, 32, vcc
	v_ldexp_f32 v190, v190, v191
	v_mul_f32_e32 v191, v113, v194
	v_log_f32_e32 v190, v190
	v_mul_f32_e32 v191, 0xbfb8aa3b, v191
	v_exp_f32_e32 v191, v191
	v_mul_f32_e32 v182, 0x3f317217, v190
	v_fma_f32 v189, v190, s92, -v182
	v_add_f32_e32 v182, 1.0, v191
	v_rcp_f32_e32 v191, v182
	v_fmac_f32_e32 v189, 0x3377d1cf, v190
	v_sub_f32_e32 v182, 1.0, v156
	v_fmac_f32_e32 v189, 0x3f317217, v190
	v_fma_f32 v191, v182, v191, v156
	v_cmp_lt_f32_e64 s[8:9], |v190|, s93
	v_cmp_gt_f32_e64 s[6:7], s87, v191
	s_nop 0
	v_cndmask_b32_e64 v189, v190, v189, s[8:9]
	v_cndmask_b32_e32 v190, 0, v171, vcc
	v_cndmask_b32_e64 v195, 0, 32, s[6:7]
	v_sub_f32_e32 v196, v189, v190
	v_mul_f32_e32 v190, v114, v194
	v_ldexp_f32 v191, v191, v195
	v_mul_f32_e32 v190, 0xbfb8aa3b, v190
	v_log_f32_e32 v191, v191
	v_exp_f32_e32 v190, v190
	v_cndmask_b32_e64 v195, 0, v171, s[6:7]
	v_mul_f32_e32 v189, 0x3f317217, v191
	v_add_f32_e32 v190, 1.0, v190
	v_fma_f32 v189, v191, s92, -v189
	v_rcp_f32_e32 v190, v190
	v_fmac_f32_e32 v189, 0x3377d1cf, v191
	v_fmac_f32_e32 v189, 0x3f317217, v191
	v_cmp_lt_f32_e64 vcc, |v191|, s93
	s_nop 1
	v_cndmask_b32_e32 v191, v191, v189, vcc
	v_sub_f32_e32 v189, 1.0, v155
	v_fma_f32 v190, v189, v190, v155
	v_cmp_gt_f32_e32 vcc, s87, v190
	v_sub_f32_e32 v191, v191, v195
	s_nop 0
	v_cndmask_b32_e64 v197, 0, 32, vcc
	v_ldexp_f32 v190, v190, v197
	v_log_f32_e32 v197, v190
	v_mul_f32_e32 v190, v115, v194
	v_mul_f32_e32 v190, 0xbfb8aa3b, v190
	v_exp_f32_e32 v190, v190
	v_mul_f32_e32 v194, 0x3f317217, v197
	v_fma_f32 v194, v197, s92, -v194
	v_fmac_f32_e32 v194, 0x3377d1cf, v197
	v_add_f32_e32 v190, 1.0, v190
	v_rcp_f32_e32 v195, v190
	v_sub_f32_e32 v190, 1.0, v154
	v_fmac_f32_e32 v194, 0x3f317217, v197
	v_cmp_lt_f32_e64 s[8:9], |v197|, s93
	v_fma_f32 v195, v190, v195, v154
	v_cmp_gt_f32_e64 s[6:7], s87, v195
	v_cndmask_b32_e64 v194, v197, v194, s[8:9]
	v_cndmask_b32_e32 v197, 0, v171, vcc
	v_cndmask_b32_e64 v198, 0, 32, s[6:7]
	v_ldexp_f32 v195, v195, v198
	v_log_f32_e32 v195, v195
	v_sub_f32_e32 v194, v194, v197
	v_mul_f32_e32 v197, 0x3f317217, v195
	v_fma_f32 v197, v195, s92, -v197
	v_fmac_f32_e32 v197, 0x3377d1cf, v195
	v_fmac_f32_e32 v197, 0x3f317217, v195
	v_cmp_lt_f32_e64 vcc, |v195|, s93
	s_nop 1
	v_cndmask_b32_e32 v195, v195, v197, vcc
	v_cndmask_b32_e64 v197, 0, v171, s[6:7]
	v_sub_f32_e32 v195, v195, v197
	v_cvt_pk_f16_f32 v195, v194, v195
	v_cvt_pk_f16_f32 v194, v196, v191
	global_store_dwordx4 v[152:153], v[192:195], off offset:256
	s_nop 1
	v_or_b32_e32 v192, 16, v148
	v_ashrrev_i32_e32 v193, 31, v192
	v_lshl_add_u64 v[194:195], v[192:193], 2, s[30:31]
	v_lshlrev_b64 v[196:197], 10, v[192:193]
	v_lshl_add_u64 v[196:197], s[28:29], 0, v[196:197]
	v_lshl_add_u64 v[196:197], v[196:197], 0, v[136:137]
	v_fmamk_f32 v191, v210, 0x3a800000, v170
	v_mul_f32_e32 v194, 0x4b800000, v191
	v_cmp_gt_f32_e32 vcc, s87, v191
	s_nop 1
	v_cndmask_b32_e32 v191, v191, v194, vcc
	v_rsq_f32_e32 v191, v191
	s_nop 0
	v_mul_f32_e32 v194, 0x45800000, v191
	v_cndmask_b32_e32 v191, v191, v194, vcc
	v_mul_f32_e32 v194, v108, v191
	v_mul_f32_e32 v194, 0xbfb8aa3b, v194
	v_exp_f32_e32 v194, v194
	v_mul_f32_e32 v193, v109, v191
	v_mul_f32_e32 v193, 0xbfb8aa3b, v193
	v_exp_f32_e32 v193, v193
	v_add_f32_e32 v194, 1.0, v194
	v_rcp_f32_e32 v194, v194
	v_add_f32_e32 v193, 1.0, v193
	v_rcp_f32_e32 v193, v193
	v_fma_f32 v194, v176, v194, v175
	v_cmp_gt_f32_e32 vcc, s87, v194
	v_fma_f32 v193, v177, v193, v174
	s_nop 0
	v_cndmask_b32_e64 v195, 0, 32, vcc
	v_ldexp_f32 v194, v194, v195
	v_log_f32_e32 v194, v194
	s_nop 0
	v_mul_f32_e32 v192, 0x3f317217, v194
	v_fma_f32 v192, v194, s92, -v192
	v_fmac_f32_e32 v192, 0x3377d1cf, v194
	v_fmac_f32_e32 v192, 0x3f317217, v194
	v_cmp_lt_f32_e64 s[6:7], |v194|, s93
	s_nop 1
	v_cndmask_b32_e64 v192, v194, v192, s[6:7]
	v_cndmask_b32_e32 v194, 0, v171, vcc
	v_cmp_gt_f32_e32 vcc, s87, v193
	v_sub_f32_e32 v192, v192, v194
	s_nop 0
	v_cndmask_b32_e64 v194, 0, 32, vcc
	v_ldexp_f32 v193, v193, v194
	v_mul_f32_e32 v194, v110, v191
	v_mul_f32_e32 v194, 0xbfb8aa3b, v194
	v_exp_f32_e32 v194, v194
	v_log_f32_e32 v193, v193
	v_cndmask_b32_e32 v198, 0, v171, vcc
	v_add_f32_e32 v194, 1.0, v194
	v_rcp_f32_e32 v194, v194
	v_mul_f32_e32 v195, 0x3f317217, v193
	v_fma_f32 v195, v193, s92, -v195
	v_fmac_f32_e32 v195, 0x3377d1cf, v193
	v_fmac_f32_e32 v195, 0x3f317217, v193
	v_cmp_lt_f32_e64 s[6:7], |v193|, s93
	v_fma_f32 v194, v178, v194, v173
	s_nop 0
	v_cndmask_b32_e64 v193, v193, v195, s[6:7]
	v_cmp_gt_f32_e64 s[6:7], s87, v194
	v_sub_f32_e32 v198, v193, v198
	v_cvt_pk_f16_f32 v192, v192, v198
; __device__ __forceinline__ float fsigm(float x) { return __builtin_amdgcn_rcpf(1.f + __expf(-x)); }
; __device__ __forceinline__ float row_rs(const float* ssq, int row) { return ssq ? rsqrtf(ssq[row] * (1.f / 1024.f) + RMS_EPS) : 1.f; }
;     __device__ __forceinline__ void operator()(const f32x4 (&acc)[2][2][4][2], const Unit& u, int wr, int wc, int fr, int fq) const {
;     ...
;                 for (int m = 0; m < 4; ++m) { const int row = row0 + ai * HALF + m * 16; const float rs = row_rs(ssq, row);
; #pragma unroll
;                     for (int bj = 0; bj < 2; ++bj) { f16x4 o[2];
; #pragma unroll
;                         for (int n = 0; n < 2; ++n) { const f32x4 p = acc[ai][bj][m][n] * rs;
; #pragma unroll
;                             for (int j = 0; j < 4; ++j) { const float l = lb[bj][n][j]; const float f = l + (1.f - l) * fsigm(p[j]); o[n][j] = (_Float16)__logf(f); } }
;                         const u32x2 a0 = __builtin_bit_cast(u32x2, o[0]), a1 = __builtin_bit_cast(u32x2, o[1]); u32x4 w; w.x = a0.x; w.y = a0.y; w.z = a1.x; w.w = a1.y;
;                         *(u32x4*)(LF + (size_t)row * 512 + cbase + bj * HALF) = w; } }
	v_cndmask_b32_e64 v195, 0, 32, s[6:7]
	v_ldexp_f32 v194, v194, v195
	v_mul_f32_e32 v195, v111, v191
	v_mul_f32_e32 v195, 0xbfb8aa3b, v195
	v_exp_f32_e32 v195, v195
	v_log_f32_e32 v194, v194
	v_add_f32_e32 v195, 1.0, v195
	v_rcp_f32_e32 v195, v195
	v_mul_f32_e32 v193, 0x3f317217, v194
	v_fma_f32 v193, v194, s92, -v193
	v_fmac_f32_e32 v193, 0x3377d1cf, v194
	v_fma_f32 v195, v183, v195, v172
	v_cmp_gt_f32_e32 vcc, s87, v195
	v_fmac_f32_e32 v193, 0x3f317217, v194
	v_cmp_lt_f32_e64 s[8:9], |v194|, s93
	v_cndmask_b32_e64 v199, 0, 32, vcc
	v_ldexp_f32 v195, v195, v199
	v_mul_f32_e32 v199, v104, v191
	v_mul_f32_e32 v199, 0xbfb8aa3b, v199
	v_log_f32_e32 v195, v195
	v_exp_f32_e32 v199, v199
	v_cndmask_b32_e64 v193, v194, v193, s[8:9]
	v_cndmask_b32_e64 v194, 0, v171, s[6:7]
	v_sub_f32_e32 v193, v193, v194
	v_mul_f32_e32 v194, 0x3f317217, v195
	v_add_f32_e32 v199, 1.0, v199
	v_fma_f32 v194, v195, s92, -v194
	v_rcp_f32_e32 v199, v199
	v_fmac_f32_e32 v194, 0x3377d1cf, v195
	v_fmac_f32_e32 v194, 0x3f317217, v195
	v_cmp_lt_f32_e64 s[6:7], |v195|, s93
	v_fma_f32 v199, v149, v199, v165
	s_nop 0
	v_cndmask_b32_e64 v194, v195, v194, s[6:7]
	v_cndmask_b32_e32 v195, 0, v171, vcc
	v_sub_f32_e32 v194, v194, v195
	v_mul_f32_e32 v195, v105, v191
	v_cmp_gt_f32_e32 vcc, s87, v199
	v_mul_f32_e32 v195, 0xbfb8aa3b, v195
	v_exp_f32_e32 v195, v195
	v_cndmask_b32_e64 v200, 0, 32, vcc
	v_ldexp_f32 v199, v199, v200
	v_log_f32_e32 v199, v199
	v_add_f32_e32 v195, 1.0, v195
	v_rcp_f32_e32 v195, v195
	v_cvt_pk_f16_f32 v193, v193, v194
	v_mul_f32_e32 v194, 0x3f317217, v199
	v_fma_f32 v194, v199, s92, -v194
	v_fmac_f32_e32 v194, 0x3377d1cf, v199
	v_fmac_f32_e32 v194, 0x3f317217, v199
	v_cmp_lt_f32_e64 s[6:7], |v199|, s93
	v_fma_f32 v195, v179, v195, v164
	v_cndmask_b32_e32 v198, 0, v171, vcc
	v_cndmask_b32_e64 v194, v199, v194, s[6:7]
	v_cmp_gt_f32_e32 vcc, s87, v195
	v_sub_f32_e32 v194, v194, v198
	s_nop 0
	v_cndmask_b32_e64 v198, 0, 32, vcc
	v_ldexp_f32 v195, v195, v198
	v_mul_f32_e32 v198, v106, v191
	v_mul_f32_e32 v198, 0xbfb8aa3b, v198
	v_exp_f32_e32 v198, v198
	v_log_f32_e32 v195, v195
	v_cndmask_b32_e32 v200, 0, v171, vcc
	v_add_f32_e32 v198, 1.0, v198
	v_rcp_f32_e32 v198, v198
	v_mul_f32_e32 v199, 0x3f317217, v195
	v_fma_f32 v199, v195, s92, -v199
	v_fmac_f32_e32 v199, 0x3377d1cf, v195
	v_fmac_f32_e32 v199, 0x3f317217, v195
	v_cmp_lt_f32_e64 s[6:7], |v195|, s93
	v_fma_f32 v198, v180, v198, v163
	s_nop 0
	v_cndmask_b32_e64 v195, v195, v199, s[6:7]
	v_cmp_gt_f32_e64 s[6:7], s87, v198
	v_sub_f32_e32 v200, v195, v200
	v_cvt_pk_f16_f32 v194, v194, v200
	v_cndmask_b32_e64 v199, 0, 32, s[6:7]
	v_ldexp_f32 v198, v198, v199
	v_mul_f32_e32 v199, v107, v191
	v_mul_f32_e32 v199, 0xbfb8aa3b, v199
	v_exp_f32_e32 v199, v199
	v_log_f32_e32 v198, v198
	v_add_f32_e32 v199, 1.0, v199
	v_rcp_f32_e32 v199, v199
	v_mul_f32_e32 v195, 0x3f317217, v198
	v_fma_f32 v195, v198, s92, -v195
	v_fmac_f32_e32 v195, 0x3377d1cf, v198
	v_fma_f32 v199, v188, v199, v162
	v_cmp_gt_f32_e32 vcc, s87, v199
	v_fmac_f32_e32 v195, 0x3f317217, v198
	v_cmp_lt_f32_e64 s[8:9], |v198|, s93
	v_cndmask_b32_e64 v201, 0, 32, vcc
	v_ldexp_f32 v199, v199, v201
	v_log_f32_e32 v199, v199
	v_mul_f32_e32 v201, v100, v191
	v_mul_f32_e32 v201, 0xbfb8aa3b, v201
	v_exp_f32_e32 v201, v201
	v_cndmask_b32_e64 v195, v198, v195, s[8:9]
	v_cndmask_b32_e64 v198, 0, v171, s[6:7]
	v_sub_f32_e32 v195, v195, v198
	v_mul_f32_e32 v198, 0x3f317217, v199
	v_fma_f32 v198, v199, s92, -v198
	v_fmac_f32_e32 v198, 0x3377d1cf, v199
	v_add_f32_e32 v201, 1.0, v201
	v_fmac_f32_e32 v198, 0x3f317217, v199
	v_cmp_lt_f32_e64 s[6:7], |v199|, s93
	v_rcp_f32_e32 v201, v201
	s_nop 0
	v_cndmask_b32_e64 v198, v199, v198, s[6:7]
	v_cndmask_b32_e32 v199, 0, v171, vcc
	v_sub_f32_e32 v198, v198, v199
	v_cvt_pk_f16_f32 v195, v195, v198
	v_fma_f32 v198, v184, v201, v161
	global_store_dwordx4 v[196:197], v[192:195], off
	v_cmp_gt_f32_e32 vcc, s87, v198
	s_nop 0
	v_mul_f32_e32 v193, v101, v191
	v_mul_f32_e32 v193, 0xbfb8aa3b, v193
	v_cndmask_b32_e64 v199, 0, 32, vcc
	v_exp_f32_e32 v193, v193
	v_ldexp_f32 v198, v198, v199
	v_log_f32_e32 v198, v198
	v_cndmask_b32_e32 v194, 0, v171, vcc
	v_add_f32_e32 v193, 1.0, v193
	v_rcp_f32_e32 v193, v193
	v_mul_f32_e32 v192, 0x3f317217, v198
	v_fma_f32 v192, v198, s92, -v192
	v_fmac_f32_e32 v192, 0x3377d1cf, v198
	v_fmac_f32_e32 v192, 0x3f317217, v198
	v_cmp_lt_f32_e64 s[6:7], |v198|, s93
	v_fma_f32 v193, v181, v193, v160
	v_cmp_gt_f32_e32 vcc, s87, v193
	v_cndmask_b32_e64 v192, v198, v192, s[6:7]
	v_sub_f32_e32 v192, v192, v194
	v_cndmask_b32_e64 v194, 0, 32, vcc
	v_ldexp_f32 v193, v193, v194
	v_mul_f32_e32 v194, v102, v191
	v_mul_f32_e32 v194, 0xbfb8aa3b, v194
	v_exp_f32_e32 v194, v194
	v_log_f32_e32 v193, v193
	v_cndmask_b32_e32 v198, 0, v171, vcc
	v_add_f32_e32 v194, 1.0, v194
	v_rcp_f32_e32 v194, v194
	v_mul_f32_e32 v195, 0x3f317217, v193
	v_fma_f32 v195, v193, s92, -v195
	v_fmac_f32_e32 v195, 0x3377d1cf, v193
	v_fmac_f32_e32 v195, 0x3f317217, v193
	v_cmp_lt_f32_e64 s[6:7], |v193|, s93
	v_fma_f32 v194, v185, v194, v159
	s_nop 0
	v_cndmask_b32_e64 v193, v193, v195, s[6:7]
	v_cmp_gt_f32_e64 s[6:7], s87, v194
	v_sub_f32_e32 v198, v193, v198
	v_cvt_pk_f16_f32 v192, v192, v198
	v_cndmask_b32_e64 v195, 0, 32, s[6:7]
	v_ldexp_f32 v194, v194, v195
	v_mul_f32_e32 v195, v103, v191
	v_mul_f32_e32 v195, 0xbfb8aa3b, v195
	v_exp_f32_e32 v195, v195
	v_log_f32_e32 v194, v194
	v_add_f32_e32 v195, 1.0, v195
	v_rcp_f32_e32 v195, v195
	v_mul_f32_e32 v193, 0x3f317217, v194
	v_fma_f32 v193, v194, s92, -v193
	v_fmac_f32_e32 v193, 0x3377d1cf, v194
	v_fma_f32 v195, v186, v195, v158
	v_cmp_gt_f32_e32 vcc, s87, v195
	v_fmac_f32_e32 v193, 0x3f317217, v194
; __device__ __forceinline__ float fsigm(float x) { return __builtin_amdgcn_rcpf(1.f + __expf(-x)); }
; __device__ __forceinline__ float row_rs(const float* ssq, int row) { return ssq ? rsqrtf(ssq[row] * (1.f / 1024.f) + RMS_EPS) : 1.f; }
;     __device__ __forceinline__ void operator()(const f32x4 (&acc)[2][2][4][2], const Unit& u, int wr, int wc, int fr, int fq) const {
;     ...
;                 for (int m = 0; m < 4; ++m) { const int row = row0 + ai * HALF + m * 16; const float rs = row_rs(ssq, row);
; #pragma unroll
;                     for (int bj = 0; bj < 2; ++bj) { f16x4 o[2];
; #pragma unroll
;                         for (int n = 0; n < 2; ++n) { const f32x4 p = acc[ai][bj][m][n] * rs;
; #pragma unroll
;                             for (int j = 0; j < 4; ++j) { const float l = lb[bj][n][j]; const float f = l + (1.f - l) * fsigm(p[j]); o[n][j] = (_Float16)__logf(f); } }
;                         const u32x2 a0 = __builtin_bit_cast(u32x2, o[0]), a1 = __builtin_bit_cast(u32x2, o[1]); u32x4 w; w.x = a0.x; w.y = a0.y; w.z = a1.x; w.w = a1.y;
;                         *(u32x4*)(LF + (size_t)row * 512 + cbase + bj * HALF) = w; } }
	v_cmp_lt_f32_e64 s[8:9], |v194|, s93
	v_cndmask_b32_e64 v199, 0, 32, vcc
	v_ldexp_f32 v195, v195, v199
	v_mul_f32_e32 v199, v96, v191
	v_mul_f32_e32 v199, 0xbfb8aa3b, v199
	v_log_f32_e32 v195, v195
	v_exp_f32_e32 v199, v199
	v_cndmask_b32_e64 v193, v194, v193, s[8:9]
	v_cndmask_b32_e64 v194, 0, v171, s[6:7]
	v_sub_f32_e32 v193, v193, v194
	v_mul_f32_e32 v194, 0x3f317217, v195
	v_add_f32_e32 v199, 1.0, v199
	v_fma_f32 v194, v195, s92, -v194
	v_rcp_f32_e32 v199, v199
	v_fmac_f32_e32 v194, 0x3377d1cf, v195
	v_fmac_f32_e32 v194, 0x3f317217, v195
	v_cmp_lt_f32_e64 s[6:7], |v195|, s93
	v_fma_f32 v199, v187, v199, v157
	s_nop 0
	v_cndmask_b32_e64 v194, v195, v194, s[6:7]
	v_cndmask_b32_e32 v195, 0, v171, vcc
	v_sub_f32_e32 v194, v194, v195
	v_mul_f32_e32 v195, v97, v191
	v_cmp_gt_f32_e32 vcc, s87, v199
	v_mul_f32_e32 v195, 0xbfb8aa3b, v195
	v_exp_f32_e32 v195, v195
	v_cndmask_b32_e64 v200, 0, 32, vcc
	v_ldexp_f32 v199, v199, v200
	v_log_f32_e32 v199, v199
	v_add_f32_e32 v195, 1.0, v195
	v_rcp_f32_e32 v195, v195
	v_cvt_pk_f16_f32 v193, v193, v194
	v_mul_f32_e32 v194, 0x3f317217, v199
	v_fma_f32 v194, v199, s92, -v194
	v_fmac_f32_e32 v194, 0x3377d1cf, v199
	v_fmac_f32_e32 v194, 0x3f317217, v199
	v_cmp_lt_f32_e64 s[6:7], |v199|, s93
	v_fma_f32 v195, v182, v195, v156
	v_cndmask_b32_e32 v198, 0, v171, vcc
	v_cndmask_b32_e64 v194, v199, v194, s[6:7]
	v_cmp_gt_f32_e32 vcc, s87, v195
	v_sub_f32_e32 v194, v194, v198
	s_nop 0
	v_cndmask_b32_e64 v198, 0, 32, vcc
	v_ldexp_f32 v195, v195, v198
	v_mul_f32_e32 v198, v98, v191
	v_mul_f32_e32 v198, 0xbfb8aa3b, v198
	v_exp_f32_e32 v198, v198
	v_log_f32_e32 v195, v195
	v_mul_f32_e32 v191, v99, v191
	v_mul_f32_e32 v191, 0xbfb8aa3b, v191
	v_add_f32_e32 v198, 1.0, v198
	v_rcp_f32_e32 v198, v198
	v_exp_f32_e32 v191, v191
	v_mul_f32_e32 v199, 0x3f317217, v195
	v_fma_f32 v199, v195, s92, -v199
	v_fmac_f32_e32 v199, 0x3377d1cf, v195
	v_fmac_f32_e32 v199, 0x3f317217, v195
	v_cmp_lt_f32_e64 s[6:7], |v195|, s93
	v_fma_f32 v198, v189, v198, v155
	v_add_f32_e32 v191, 1.0, v191
	v_cndmask_b32_e64 v195, v195, v199, s[6:7]
	v_cmp_gt_f32_e64 s[6:7], s87, v198
	v_rcp_f32_e32 v191, v191
	s_nop 0
	v_cndmask_b32_e64 v199, 0, 32, s[6:7]
	v_ldexp_f32 v198, v198, v199
	v_log_f32_e32 v198, v198
	v_fma_f32 v191, v190, v191, v154
	v_cndmask_b32_e32 v199, 0, v171, vcc
	v_cmp_gt_f32_e32 vcc, s87, v191
	v_sub_f32_e32 v199, v195, v199
	v_mul_f32_e32 v195, 0x3f317217, v198
	v_cndmask_b32_e64 v200, 0, 32, vcc
	v_ldexp_f32 v191, v191, v200
	v_fma_f32 v195, v198, s92, -v195
	v_log_f32_e32 v191, v191
	v_fmac_f32_e32 v195, 0x3377d1cf, v198
	v_fmac_f32_e32 v195, 0x3f317217, v198
	v_cmp_lt_f32_e64 s[8:9], |v198|, s93
	v_cvt_pk_f16_f32 v194, v194, v199
	s_nop 0
	v_cndmask_b32_e64 v195, v198, v195, s[8:9]
	v_cndmask_b32_e64 v198, 0, v171, s[6:7]
	v_sub_f32_e32 v195, v195, v198
	v_mul_f32_e32 v198, 0x3f317217, v191
	v_fma_f32 v198, v191, s92, -v198
	v_fmac_f32_e32 v198, 0x3377d1cf, v191
	v_fmac_f32_e32 v198, 0x3f317217, v191
	v_cmp_lt_f32_e64 s[6:7], |v191|, s93
	s_nop 1
	v_cndmask_b32_e64 v191, v191, v198, s[6:7]
	v_cndmask_b32_e32 v198, 0, v171, vcc
	v_sub_f32_e32 v191, v191, v198
	v_cvt_pk_f16_f32 v195, v195, v191
	global_store_dwordx4 v[196:197], v[192:195], off offset:256
	s_nop 1
	v_or_b32_e32 v192, 32, v148
	v_ashrrev_i32_e32 v193, 31, v192
	v_lshl_add_u64 v[194:195], v[192:193], 2, s[30:31]
	v_lshlrev_b64 v[196:197], 10, v[192:193]
	v_lshl_add_u64 v[196:197], s[28:29], 0, v[196:197]
	v_lshl_add_u64 v[196:197], v[196:197], 0, v[136:137]
	v_fmamk_f32 v191, v211, 0x3a800000, v170
	v_mul_f32_e32 v194, 0x4b800000, v191
	v_cmp_gt_f32_e32 vcc, s87, v191
	s_nop 1
	v_cndmask_b32_e32 v191, v191, v194, vcc
	v_rsq_f32_e32 v191, v191
	s_nop 0
	v_mul_f32_e32 v194, 0x45800000, v191
	v_cndmask_b32_e32 v191, v191, v194, vcc
	v_mul_f32_e32 v194, v92, v191
	v_mul_f32_e32 v194, 0xbfb8aa3b, v194
	v_exp_f32_e32 v194, v194
	v_mul_f32_e32 v193, v93, v191
	v_mul_f32_e32 v193, 0xbfb8aa3b, v193
	v_exp_f32_e32 v193, v193
	v_add_f32_e32 v194, 1.0, v194
	v_rcp_f32_e32 v194, v194
	v_add_f32_e32 v193, 1.0, v193
	v_rcp_f32_e32 v193, v193
	v_fma_f32 v194, v176, v194, v175
	v_cmp_gt_f32_e32 vcc, s87, v194
	v_fma_f32 v193, v177, v193, v174
	s_nop 0
	v_cndmask_b32_e64 v195, 0, 32, vcc
	v_ldexp_f32 v194, v194, v195
	v_log_f32_e32 v194, v194
	s_nop 0
	v_mul_f32_e32 v192, 0x3f317217, v194
	v_fma_f32 v192, v194, s92, -v192
	v_fmac_f32_e32 v192, 0x3377d1cf, v194
	v_fmac_f32_e32 v192, 0x3f317217, v194
	v_cmp_lt_f32_e64 s[6:7], |v194|, s93
	s_nop 1
	v_cndmask_b32_e64 v192, v194, v192, s[6:7]
	v_cndmask_b32_e32 v194, 0, v171, vcc
	v_cmp_gt_f32_e32 vcc, s87, v193
	v_sub_f32_e32 v192, v192, v194
	s_nop 0
	v_cndmask_b32_e64 v194, 0, 32, vcc
	v_ldexp_f32 v193, v193, v194
	v_mul_f32_e32 v194, v94, v191
	v_mul_f32_e32 v194, 0xbfb8aa3b, v194
	v_exp_f32_e32 v194, v194
	v_log_f32_e32 v193, v193
	v_cndmask_b32_e32 v198, 0, v171, vcc
	v_add_f32_e32 v194, 1.0, v194
	v_rcp_f32_e32 v194, v194
	v_mul_f32_e32 v195, 0x3f317217, v193
	v_fma_f32 v195, v193, s92, -v195
	v_fmac_f32_e32 v195, 0x3377d1cf, v193
	v_fmac_f32_e32 v195, 0x3f317217, v193
	v_cmp_lt_f32_e64 s[6:7], |v193|, s93
	v_fma_f32 v194, v178, v194, v173
	s_nop 0
	v_cndmask_b32_e64 v193, v193, v195, s[6:7]
	v_cmp_gt_f32_e64 s[6:7], s87, v194
	v_sub_f32_e32 v198, v193, v198
	v_cvt_pk_f16_f32 v192, v192, v198
	v_cndmask_b32_e64 v195, 0, 32, s[6:7]
	v_ldexp_f32 v194, v194, v195
	v_mul_f32_e32 v195, v95, v191
	v_mul_f32_e32 v195, 0xbfb8aa3b, v195
	v_exp_f32_e32 v195, v195
	v_log_f32_e32 v194, v194
	v_add_f32_e32 v195, 1.0, v195
	v_rcp_f32_e32 v195, v195
	v_mul_f32_e32 v193, 0x3f317217, v194
	v_fma_f32 v193, v194, s92, -v193
	v_fmac_f32_e32 v193, 0x3377d1cf, v194
; __device__ __forceinline__ float fsigm(float x) { return __builtin_amdgcn_rcpf(1.f + __expf(-x)); }
; __device__ __forceinline__ float row_rs(const float* ssq, int row) { return ssq ? rsqrtf(ssq[row] * (1.f / 1024.f) + RMS_EPS) : 1.f; }
;     __device__ __forceinline__ void operator()(const f32x4 (&acc)[2][2][4][2], const Unit& u, int wr, int wc, int fr, int fq) const {
;     ...
;                 for (int m = 0; m < 4; ++m) { const int row = row0 + ai * HALF + m * 16; const float rs = row_rs(ssq, row);
; #pragma unroll
;                     for (int bj = 0; bj < 2; ++bj) { f16x4 o[2];
; #pragma unroll
;                         for (int n = 0; n < 2; ++n) { const f32x4 p = acc[ai][bj][m][n] * rs;
; #pragma unroll
;                             for (int j = 0; j < 4; ++j) { const float l = lb[bj][n][j]; const float f = l + (1.f - l) * fsigm(p[j]); o[n][j] = (_Float16)__logf(f); } }
;                         const u32x2 a0 = __builtin_bit_cast(u32x2, o[0]), a1 = __builtin_bit_cast(u32x2, o[1]); u32x4 w; w.x = a0.x; w.y = a0.y; w.z = a1.x; w.w = a1.y;
;                         *(u32x4*)(LF + (size_t)row * 512 + cbase + bj * HALF) = w; } }
	v_fma_f32 v195, v183, v195, v172
	v_cmp_gt_f32_e32 vcc, s87, v195
	v_fmac_f32_e32 v193, 0x3f317217, v194
	v_cmp_lt_f32_e64 s[8:9], |v194|, s93
	v_cndmask_b32_e64 v199, 0, 32, vcc
	v_ldexp_f32 v195, v195, v199
	v_mul_f32_e32 v199, v88, v191
	v_mul_f32_e32 v199, 0xbfb8aa3b, v199
	v_log_f32_e32 v195, v195
	v_exp_f32_e32 v199, v199
	v_cndmask_b32_e64 v193, v194, v193, s[8:9]
	v_cndmask_b32_e64 v194, 0, v171, s[6:7]
	v_sub_f32_e32 v193, v193, v194
	v_mul_f32_e32 v194, 0x3f317217, v195
	v_add_f32_e32 v199, 1.0, v199
	v_fma_f32 v194, v195, s92, -v194
	v_rcp_f32_e32 v199, v199
	v_fmac_f32_e32 v194, 0x3377d1cf, v195
	v_fmac_f32_e32 v194, 0x3f317217, v195
	v_cmp_lt_f32_e64 s[6:7], |v195|, s93
	v_fma_f32 v199, v149, v199, v165
	s_nop 0
	v_cndmask_b32_e64 v194, v195, v194, s[6:7]
	v_cndmask_b32_e32 v195, 0, v171, vcc
	v_sub_f32_e32 v194, v194, v195
	v_mul_f32_e32 v195, v89, v191
	v_cmp_gt_f32_e32 vcc, s87, v199
	v_mul_f32_e32 v195, 0xbfb8aa3b, v195
	v_exp_f32_e32 v195, v195
	v_cndmask_b32_e64 v200, 0, 32, vcc
	v_ldexp_f32 v199, v199, v200
	v_log_f32_e32 v199, v199
	v_add_f32_e32 v195, 1.0, v195
	v_rcp_f32_e32 v195, v195
	v_cvt_pk_f16_f32 v193, v193, v194
	v_mul_f32_e32 v194, 0x3f317217, v199
	v_fma_f32 v194, v199, s92, -v194
	v_fmac_f32_e32 v194, 0x3377d1cf, v199
	v_fmac_f32_e32 v194, 0x3f317217, v199
	v_cmp_lt_f32_e64 s[6:7], |v199|, s93
	v_fma_f32 v195, v179, v195, v164
	v_cndmask_b32_e32 v198, 0, v171, vcc
	v_cndmask_b32_e64 v194, v199, v194, s[6:7]
	v_cmp_gt_f32_e32 vcc, s87, v195
	v_sub_f32_e32 v194, v194, v198
	s_nop 0
	v_cndmask_b32_e64 v198, 0, 32, vcc
	v_ldexp_f32 v195, v195, v198
	v_mul_f32_e32 v198, v90, v191
	v_mul_f32_e32 v198, 0xbfb8aa3b, v198
	v_exp_f32_e32 v198, v198
	v_log_f32_e32 v195, v195
	v_cndmask_b32_e32 v200, 0, v171, vcc
	v_add_f32_e32 v198, 1.0, v198
	v_rcp_f32_e32 v198, v198
	v_mul_f32_e32 v199, 0x3f317217, v195
	v_fma_f32 v199, v195, s92, -v199
	v_fmac_f32_e32 v199, 0x3377d1cf, v195
	v_fmac_f32_e32 v199, 0x3f317217, v195
	v_cmp_lt_f32_e64 s[6:7], |v195|, s93
	v_fma_f32 v198, v180, v198, v163
	s_nop 0
	v_cndmask_b32_e64 v195, v195, v199, s[6:7]
	v_cmp_gt_f32_e64 s[6:7], s87, v198
	v_sub_f32_e32 v200, v195, v200
	v_cvt_pk_f16_f32 v194, v194, v200
	v_cndmask_b32_e64 v199, 0, 32, s[6:7]
	v_ldexp_f32 v198, v198, v199
	v_mul_f32_e32 v199, v91, v191
	v_mul_f32_e32 v199, 0xbfb8aa3b, v199
	v_exp_f32_e32 v199, v199
	v_log_f32_e32 v198, v198
	v_add_f32_e32 v199, 1.0, v199
	v_rcp_f32_e32 v199, v199
	v_mul_f32_e32 v195, 0x3f317217, v198
	v_fma_f32 v195, v198, s92, -v195
	v_fmac_f32_e32 v195, 0x3377d1cf, v198
	v_fma_f32 v199, v188, v199, v162
	v_cmp_gt_f32_e32 vcc, s87, v199
	v_fmac_f32_e32 v195, 0x3f317217, v198
	v_cmp_lt_f32_e64 s[8:9], |v198|, s93
	v_cndmask_b32_e64 v201, 0, 32, vcc
	v_ldexp_f32 v199, v199, v201
	v_log_f32_e32 v199, v199
	v_mul_f32_e32 v201, v84, v191
	v_mul_f32_e32 v201, 0xbfb8aa3b, v201
	v_exp_f32_e32 v201, v201
	v_cndmask_b32_e64 v195, v198, v195, s[8:9]
	v_cndmask_b32_e64 v198, 0, v171, s[6:7]
	v_sub_f32_e32 v195, v195, v198
	v_mul_f32_e32 v198, 0x3f317217, v199
	v_fma_f32 v198, v199, s92, -v198
	v_fmac_f32_e32 v198, 0x3377d1cf, v199
	v_add_f32_e32 v201, 1.0, v201
	v_fmac_f32_e32 v198, 0x3f317217, v199
	v_cmp_lt_f32_e64 s[6:7], |v199|, s93
	v_rcp_f32_e32 v201, v201
	s_nop 0
	v_cndmask_b32_e64 v198, v199, v198, s[6:7]
	v_cndmask_b32_e32 v199, 0, v171, vcc
	v_sub_f32_e32 v198, v198, v199
	v_cvt_pk_f16_f32 v195, v195, v198
	v_fma_f32 v198, v184, v201, v161
	global_store_dwordx4 v[196:197], v[192:195], off
	v_cmp_gt_f32_e32 vcc, s87, v198
	s_nop 0
	v_mul_f32_e32 v193, v85, v191
	v_mul_f32_e32 v193, 0xbfb8aa3b, v193
	v_cndmask_b32_e64 v199, 0, 32, vcc
	v_exp_f32_e32 v193, v193
	v_ldexp_f32 v198, v198, v199
	v_log_f32_e32 v198, v198
	v_cndmask_b32_e32 v194, 0, v171, vcc
	v_add_f32_e32 v193, 1.0, v193
	v_rcp_f32_e32 v193, v193
	v_mul_f32_e32 v192, 0x3f317217, v198
	v_fma_f32 v192, v198, s92, -v192
	v_fmac_f32_e32 v192, 0x3377d1cf, v198
	v_fmac_f32_e32 v192, 0x3f317217, v198
	v_cmp_lt_f32_e64 s[6:7], |v198|, s93
	v_fma_f32 v193, v181, v193, v160
	v_cmp_gt_f32_e32 vcc, s87, v193
	v_cndmask_b32_e64 v192, v198, v192, s[6:7]
	v_sub_f32_e32 v192, v192, v194
	v_cndmask_b32_e64 v194, 0, 32, vcc
	v_ldexp_f32 v193, v193, v194
	v_mul_f32_e32 v194, v86, v191
	v_mul_f32_e32 v194, 0xbfb8aa3b, v194
	v_exp_f32_e32 v194, v194
	v_log_f32_e32 v193, v193
	v_cndmask_b32_e32 v198, 0, v171, vcc
	v_add_f32_e32 v194, 1.0, v194
	v_rcp_f32_e32 v194, v194
	v_mul_f32_e32 v195, 0x3f317217, v193
	v_fma_f32 v195, v193, s92, -v195
	v_fmac_f32_e32 v195, 0x3377d1cf, v193
	v_fmac_f32_e32 v195, 0x3f317217, v193
	v_cmp_lt_f32_e64 s[6:7], |v193|, s93
	v_fma_f32 v194, v185, v194, v159
	s_nop 0
	v_cndmask_b32_e64 v193, v193, v195, s[6:7]
	v_cmp_gt_f32_e64 s[6:7], s87, v194
	v_sub_f32_e32 v198, v193, v198
	v_cvt_pk_f16_f32 v192, v192, v198
	v_cndmask_b32_e64 v195, 0, 32, s[6:7]
	v_ldexp_f32 v194, v194, v195
	v_mul_f32_e32 v195, v87, v191
	v_mul_f32_e32 v195, 0xbfb8aa3b, v195
	v_exp_f32_e32 v195, v195
	v_log_f32_e32 v194, v194
	v_add_f32_e32 v195, 1.0, v195
	v_rcp_f32_e32 v195, v195
	v_mul_f32_e32 v193, 0x3f317217, v194
	v_fma_f32 v193, v194, s92, -v193
	v_fmac_f32_e32 v193, 0x3377d1cf, v194
	v_fma_f32 v195, v186, v195, v158
	v_cmp_gt_f32_e32 vcc, s87, v195
	v_fmac_f32_e32 v193, 0x3f317217, v194
	v_cmp_lt_f32_e64 s[8:9], |v194|, s93
	v_cndmask_b32_e64 v199, 0, 32, vcc
	v_ldexp_f32 v195, v195, v199
	v_mul_f32_e32 v199, v80, v191
	v_mul_f32_e32 v199, 0xbfb8aa3b, v199
	v_log_f32_e32 v195, v195
	v_exp_f32_e32 v199, v199
	v_cndmask_b32_e64 v193, v194, v193, s[8:9]
	v_cndmask_b32_e64 v194, 0, v171, s[6:7]
	v_sub_f32_e32 v193, v193, v194
	v_mul_f32_e32 v194, 0x3f317217, v195
; __device__ __forceinline__ float fsigm(float x) { return __builtin_amdgcn_rcpf(1.f + __expf(-x)); }
; __device__ __forceinline__ float row_rs(const float* ssq, int row) { return ssq ? rsqrtf(ssq[row] * (1.f / 1024.f) + RMS_EPS) : 1.f; }
;     __device__ __forceinline__ void operator()(const f32x4 (&acc)[2][2][4][2], const Unit& u, int wr, int wc, int fr, int fq) const {
;     ...
;                 for (int m = 0; m < 4; ++m) { const int row = row0 + ai * HALF + m * 16; const float rs = row_rs(ssq, row);
; #pragma unroll
;                     for (int bj = 0; bj < 2; ++bj) { f16x4 o[2];
; #pragma unroll
;                         for (int n = 0; n < 2; ++n) { const f32x4 p = acc[ai][bj][m][n] * rs;
; #pragma unroll
;                             for (int j = 0; j < 4; ++j) { const float l = lb[bj][n][j]; const float f = l + (1.f - l) * fsigm(p[j]); o[n][j] = (_Float16)__logf(f); } }
;                         const u32x2 a0 = __builtin_bit_cast(u32x2, o[0]), a1 = __builtin_bit_cast(u32x2, o[1]); u32x4 w; w.x = a0.x; w.y = a0.y; w.z = a1.x; w.w = a1.y;
;                         *(u32x4*)(LF + (size_t)row * 512 + cbase + bj * HALF) = w; } }
	v_add_f32_e32 v199, 1.0, v199
	v_fma_f32 v194, v195, s92, -v194
	v_rcp_f32_e32 v199, v199
	v_fmac_f32_e32 v194, 0x3377d1cf, v195
	v_fmac_f32_e32 v194, 0x3f317217, v195
	v_cmp_lt_f32_e64 s[6:7], |v195|, s93
	v_fma_f32 v199, v187, v199, v157
	s_nop 0
	v_cndmask_b32_e64 v194, v195, v194, s[6:7]
	v_cndmask_b32_e32 v195, 0, v171, vcc
	v_sub_f32_e32 v194, v194, v195
	v_mul_f32_e32 v195, v81, v191
	v_cmp_gt_f32_e32 vcc, s87, v199
	v_mul_f32_e32 v195, 0xbfb8aa3b, v195
	v_exp_f32_e32 v195, v195
	v_cndmask_b32_e64 v200, 0, 32, vcc
	v_ldexp_f32 v199, v199, v200
	v_log_f32_e32 v199, v199
	v_add_f32_e32 v195, 1.0, v195
	v_rcp_f32_e32 v195, v195
	v_cvt_pk_f16_f32 v193, v193, v194
	v_mul_f32_e32 v194, 0x3f317217, v199
	v_fma_f32 v194, v199, s92, -v194
	v_fmac_f32_e32 v194, 0x3377d1cf, v199
	v_fmac_f32_e32 v194, 0x3f317217, v199
	v_cmp_lt_f32_e64 s[6:7], |v199|, s93
	v_fma_f32 v195, v182, v195, v156
	v_cndmask_b32_e32 v198, 0, v171, vcc
	v_cndmask_b32_e64 v194, v199, v194, s[6:7]
	v_cmp_gt_f32_e32 vcc, s87, v195
	v_sub_f32_e32 v194, v194, v198
	s_nop 0
	v_cndmask_b32_e64 v198, 0, 32, vcc
	v_ldexp_f32 v195, v195, v198
	v_mul_f32_e32 v198, v82, v191
	v_mul_f32_e32 v198, 0xbfb8aa3b, v198
	v_exp_f32_e32 v198, v198
	v_log_f32_e32 v195, v195
	v_mul_f32_e32 v191, v83, v191
	v_mul_f32_e32 v191, 0xbfb8aa3b, v191
	v_add_f32_e32 v198, 1.0, v198
	v_rcp_f32_e32 v198, v198
	v_exp_f32_e32 v191, v191
	v_mul_f32_e32 v199, 0x3f317217, v195
	v_fma_f32 v199, v195, s92, -v199
	v_fmac_f32_e32 v199, 0x3377d1cf, v195
	v_fmac_f32_e32 v199, 0x3f317217, v195
	v_cmp_lt_f32_e64 s[6:7], |v195|, s93
	v_fma_f32 v198, v189, v198, v155
	v_add_f32_e32 v191, 1.0, v191
	v_cndmask_b32_e64 v195, v195, v199, s[6:7]
	v_cmp_gt_f32_e64 s[6:7], s87, v198
	v_rcp_f32_e32 v191, v191
	s_nop 0
	v_cndmask_b32_e64 v199, 0, 32, s[6:7]
	v_ldexp_f32 v198, v198, v199
	v_log_f32_e32 v198, v198
	v_fma_f32 v191, v190, v191, v154
	v_cndmask_b32_e32 v199, 0, v171, vcc
	v_cmp_gt_f32_e32 vcc, s87, v191
	v_sub_f32_e32 v199, v195, v199
	v_mul_f32_e32 v195, 0x3f317217, v198
	v_cndmask_b32_e64 v200, 0, 32, vcc
	v_ldexp_f32 v191, v191, v200
	v_fma_f32 v195, v198, s92, -v195
	v_log_f32_e32 v191, v191
	v_fmac_f32_e32 v195, 0x3377d1cf, v198
	v_fmac_f32_e32 v195, 0x3f317217, v198
	v_cmp_lt_f32_e64 s[8:9], |v198|, s93
	v_cvt_pk_f16_f32 v194, v194, v199
	s_nop 0
	v_cndmask_b32_e64 v195, v198, v195, s[8:9]
	v_cndmask_b32_e64 v198, 0, v171, s[6:7]
	v_sub_f32_e32 v195, v195, v198
	v_mul_f32_e32 v198, 0x3f317217, v191
	v_fma_f32 v198, v191, s92, -v198
	v_fmac_f32_e32 v198, 0x3377d1cf, v191
	v_fmac_f32_e32 v198, 0x3f317217, v191
	v_cmp_lt_f32_e64 s[6:7], |v191|, s93
	s_nop 1
	v_cndmask_b32_e64 v191, v191, v198, s[6:7]
	v_cndmask_b32_e32 v198, 0, v171, vcc
	v_sub_f32_e32 v191, v191, v198
	v_cvt_pk_f16_f32 v195, v195, v191
	global_store_dwordx4 v[196:197], v[192:195], off offset:256
	s_nop 1
	v_or_b32_e32 v192, 48, v148
	v_ashrrev_i32_e32 v193, 31, v192
	v_lshl_add_u64 v[194:195], v[192:193], 2, s[30:31]
	v_lshlrev_b64 v[196:197], 10, v[192:193]
	v_lshl_add_u64 v[196:197], s[28:29], 0, v[196:197]
	v_lshl_add_u64 v[196:197], v[196:197], 0, v[136:137]
	v_fmamk_f32 v191, v212, 0x3a800000, v170
	v_mul_f32_e32 v194, 0x4b800000, v191
	v_cmp_gt_f32_e32 vcc, s87, v191
	s_nop 1
	v_cndmask_b32_e32 v191, v191, v194, vcc
	v_rsq_f32_e32 v191, v191
	s_nop 0
	v_mul_f32_e32 v194, 0x45800000, v191
	v_cndmask_b32_e32 v191, v191, v194, vcc
	v_mul_f32_e32 v194, v76, v191
	v_mul_f32_e32 v194, 0xbfb8aa3b, v194
	v_exp_f32_e32 v194, v194
	v_mul_f32_e32 v193, v77, v191
	v_mul_f32_e32 v193, 0xbfb8aa3b, v193
	v_exp_f32_e32 v193, v193
	v_add_f32_e32 v194, 1.0, v194
	v_rcp_f32_e32 v194, v194
	v_add_f32_e32 v193, 1.0, v193
	v_rcp_f32_e32 v193, v193
	v_fma_f32 v194, v176, v194, v175
	v_cmp_gt_f32_e32 vcc, s87, v194
	v_fma_f32 v193, v177, v193, v174
	s_nop 0
	v_cndmask_b32_e64 v195, 0, 32, vcc
	v_ldexp_f32 v194, v194, v195
	v_log_f32_e32 v194, v194
	s_nop 0
	v_mul_f32_e32 v192, 0x3f317217, v194
	v_fma_f32 v192, v194, s92, -v192
	v_fmac_f32_e32 v192, 0x3377d1cf, v194
	v_fmac_f32_e32 v192, 0x3f317217, v194
	v_cmp_lt_f32_e64 s[6:7], |v194|, s93
	s_nop 1
	v_cndmask_b32_e64 v192, v194, v192, s[6:7]
	v_cndmask_b32_e32 v194, 0, v171, vcc
	v_cmp_gt_f32_e32 vcc, s87, v193
	v_sub_f32_e32 v192, v192, v194
	s_nop 0
	v_cndmask_b32_e64 v194, 0, 32, vcc
	v_ldexp_f32 v193, v193, v194
	v_mul_f32_e32 v194, v78, v191
	v_mul_f32_e32 v194, 0xbfb8aa3b, v194
	v_exp_f32_e32 v194, v194
	v_log_f32_e32 v193, v193
	v_cndmask_b32_e32 v198, 0, v171, vcc
	v_add_f32_e32 v194, 1.0, v194
	v_rcp_f32_e32 v194, v194
	v_mul_f32_e32 v195, 0x3f317217, v193
	v_fma_f32 v195, v193, s92, -v195
	v_fmac_f32_e32 v195, 0x3377d1cf, v193
	v_fmac_f32_e32 v195, 0x3f317217, v193
	v_cmp_lt_f32_e64 s[6:7], |v193|, s93
	v_fma_f32 v194, v178, v194, v173
	s_nop 0
	v_cndmask_b32_e64 v193, v193, v195, s[6:7]
	v_cmp_gt_f32_e64 s[6:7], s87, v194
	v_sub_f32_e32 v198, v193, v198
	v_cvt_pk_f16_f32 v192, v192, v198
	v_cndmask_b32_e64 v195, 0, 32, s[6:7]
	v_ldexp_f32 v194, v194, v195
	v_mul_f32_e32 v195, v79, v191
	v_mul_f32_e32 v195, 0xbfb8aa3b, v195
	v_exp_f32_e32 v195, v195
	v_log_f32_e32 v194, v194
	v_add_f32_e32 v195, 1.0, v195
	v_rcp_f32_e32 v195, v195
	v_mul_f32_e32 v193, 0x3f317217, v194
	v_fma_f32 v193, v194, s92, -v193
	v_fmac_f32_e32 v193, 0x3377d1cf, v194
	v_fma_f32 v195, v183, v195, v172
	v_cmp_gt_f32_e32 vcc, s87, v195
	v_fmac_f32_e32 v193, 0x3f317217, v194
	v_cmp_lt_f32_e64 s[8:9], |v194|, s93
	v_cndmask_b32_e64 v199, 0, 32, vcc
	v_ldexp_f32 v195, v195, v199
	v_mul_f32_e32 v199, v72, v191
	v_mul_f32_e32 v199, 0xbfb8aa3b, v199
	v_log_f32_e32 v195, v195
	v_exp_f32_e32 v199, v199
	v_cndmask_b32_e64 v193, v194, v193, s[8:9]
; __device__ __forceinline__ float fsigm(float x) { return __builtin_amdgcn_rcpf(1.f + __expf(-x)); }
; __device__ __forceinline__ float row_rs(const float* ssq, int row) { return ssq ? rsqrtf(ssq[row] * (1.f / 1024.f) + RMS_EPS) : 1.f; }
;     __device__ __forceinline__ void operator()(const f32x4 (&acc)[2][2][4][2], const Unit& u, int wr, int wc, int fr, int fq) const {
;     ...
;                 for (int m = 0; m < 4; ++m) { const int row = row0 + ai * HALF + m * 16; const float rs = row_rs(ssq, row);
; #pragma unroll
;                     for (int bj = 0; bj < 2; ++bj) { f16x4 o[2];
; #pragma unroll
;                         for (int n = 0; n < 2; ++n) { const f32x4 p = acc[ai][bj][m][n] * rs;
; #pragma unroll
;                             for (int j = 0; j < 4; ++j) { const float l = lb[bj][n][j]; const float f = l + (1.f - l) * fsigm(p[j]); o[n][j] = (_Float16)__logf(f); } }
;                         const u32x2 a0 = __builtin_bit_cast(u32x2, o[0]), a1 = __builtin_bit_cast(u32x2, o[1]); u32x4 w; w.x = a0.x; w.y = a0.y; w.z = a1.x; w.w = a1.y;
;                         *(u32x4*)(LF + (size_t)row * 512 + cbase + bj * HALF) = w; } }
	v_cndmask_b32_e64 v194, 0, v171, s[6:7]
	v_sub_f32_e32 v193, v193, v194
	v_mul_f32_e32 v194, 0x3f317217, v195
	v_add_f32_e32 v199, 1.0, v199
	v_fma_f32 v194, v195, s92, -v194
	v_rcp_f32_e32 v199, v199
	v_fmac_f32_e32 v194, 0x3377d1cf, v195
	v_fmac_f32_e32 v194, 0x3f317217, v195
	v_cmp_lt_f32_e64 s[6:7], |v195|, s93
	v_fma_f32 v199, v149, v199, v165
	s_nop 0
	v_cndmask_b32_e64 v194, v195, v194, s[6:7]
	v_cndmask_b32_e32 v195, 0, v171, vcc
	v_sub_f32_e32 v194, v194, v195
	v_mul_f32_e32 v195, v73, v191
	v_cmp_gt_f32_e32 vcc, s87, v199
	v_mul_f32_e32 v195, 0xbfb8aa3b, v195
	v_exp_f32_e32 v195, v195
	v_cndmask_b32_e64 v200, 0, 32, vcc
	v_ldexp_f32 v199, v199, v200
	v_log_f32_e32 v199, v199
	v_add_f32_e32 v195, 1.0, v195
	v_rcp_f32_e32 v195, v195
	v_cvt_pk_f16_f32 v193, v193, v194
	v_mul_f32_e32 v194, 0x3f317217, v199
	v_fma_f32 v194, v199, s92, -v194
	v_fmac_f32_e32 v194, 0x3377d1cf, v199
	v_fmac_f32_e32 v194, 0x3f317217, v199
	v_cmp_lt_f32_e64 s[6:7], |v199|, s93
	v_fma_f32 v195, v179, v195, v164
	v_cndmask_b32_e32 v198, 0, v171, vcc
	v_cndmask_b32_e64 v194, v199, v194, s[6:7]
	v_cmp_gt_f32_e32 vcc, s87, v195
	v_sub_f32_e32 v194, v194, v198
	s_nop 0
	v_cndmask_b32_e64 v198, 0, 32, vcc
	v_ldexp_f32 v195, v195, v198
	v_mul_f32_e32 v198, v74, v191
	v_mul_f32_e32 v198, 0xbfb8aa3b, v198
	v_exp_f32_e32 v198, v198
	v_log_f32_e32 v195, v195
	v_cndmask_b32_e32 v200, 0, v171, vcc
	v_add_f32_e32 v198, 1.0, v198
	v_rcp_f32_e32 v198, v198
	v_mul_f32_e32 v199, 0x3f317217, v195
	v_fma_f32 v199, v195, s92, -v199
	v_fmac_f32_e32 v199, 0x3377d1cf, v195
	v_fmac_f32_e32 v199, 0x3f317217, v195
	v_cmp_lt_f32_e64 s[6:7], |v195|, s93
	v_fma_f32 v198, v180, v198, v163
	s_nop 0
	v_cndmask_b32_e64 v195, v195, v199, s[6:7]
	v_cmp_gt_f32_e64 s[6:7], s87, v198
	v_sub_f32_e32 v200, v195, v200
	v_cvt_pk_f16_f32 v194, v194, v200
	v_cndmask_b32_e64 v199, 0, 32, s[6:7]
	v_ldexp_f32 v198, v198, v199
	v_mul_f32_e32 v199, v75, v191
	v_mul_f32_e32 v199, 0xbfb8aa3b, v199
	v_exp_f32_e32 v199, v199
	v_log_f32_e32 v198, v198
	v_add_f32_e32 v199, 1.0, v199
	v_rcp_f32_e32 v199, v199
	v_mul_f32_e32 v195, 0x3f317217, v198
	v_fma_f32 v195, v198, s92, -v195
	v_fmac_f32_e32 v195, 0x3377d1cf, v198
	v_fma_f32 v199, v188, v199, v162
	v_cmp_gt_f32_e32 vcc, s87, v199
	v_fmac_f32_e32 v195, 0x3f317217, v198
	v_cmp_lt_f32_e64 s[8:9], |v198|, s93
	v_cndmask_b32_e64 v201, 0, 32, vcc
	v_ldexp_f32 v199, v199, v201
	v_log_f32_e32 v199, v199
	v_mul_f32_e32 v201, v68, v191
	v_mul_f32_e32 v201, 0xbfb8aa3b, v201
	v_exp_f32_e32 v201, v201
	v_cndmask_b32_e64 v195, v198, v195, s[8:9]
	v_cndmask_b32_e64 v198, 0, v171, s[6:7]
	v_sub_f32_e32 v195, v195, v198
	v_mul_f32_e32 v198, 0x3f317217, v199
	v_fma_f32 v198, v199, s92, -v198
	v_fmac_f32_e32 v198, 0x3377d1cf, v199
	v_add_f32_e32 v201, 1.0, v201
	v_fmac_f32_e32 v198, 0x3f317217, v199
	v_cmp_lt_f32_e64 s[6:7], |v199|, s93
	v_rcp_f32_e32 v201, v201
	s_nop 0
	v_cndmask_b32_e64 v198, v199, v198, s[6:7]
	v_cndmask_b32_e32 v199, 0, v171, vcc
	v_sub_f32_e32 v198, v198, v199
	v_cvt_pk_f16_f32 v195, v195, v198
	v_fma_f32 v198, v184, v201, v161
	global_store_dwordx4 v[196:197], v[192:195], off
	v_cmp_gt_f32_e32 vcc, s87, v198
	s_nop 0
	v_mul_f32_e32 v192, v69, v191
	v_mul_f32_e32 v192, 0xbfb8aa3b, v192
	v_cndmask_b32_e64 v199, 0, 32, vcc
	v_exp_f32_e32 v192, v192
	v_ldexp_f32 v198, v198, v199
	v_log_f32_e32 v198, v198
	v_cndmask_b32_e32 v193, 0, v171, vcc
	v_add_f32_e32 v192, 1.0, v192
	v_rcp_f32_e32 v192, v192
	v_mul_f32_e32 v136, 0x3f317217, v198
	v_fma_f32 v136, v198, s92, -v136
	v_fmac_f32_e32 v136, 0x3377d1cf, v198
	v_fmac_f32_e32 v136, 0x3f317217, v198
	v_cmp_lt_f32_e64 s[6:7], |v198|, s93
	v_fma_f32 v192, v181, v192, v160
	v_cmp_gt_f32_e32 vcc, s87, v192
	v_cndmask_b32_e64 v136, v198, v136, s[6:7]
	v_sub_f32_e32 v136, v136, v193
	v_cndmask_b32_e64 v193, 0, 32, vcc
	v_ldexp_f32 v192, v192, v193
	v_mul_f32_e32 v193, v70, v191
	v_mul_f32_e32 v193, 0xbfb8aa3b, v193
	v_exp_f32_e32 v193, v193
	v_log_f32_e32 v192, v192
	v_cndmask_b32_e32 v195, 0, v171, vcc
	v_add_f32_e32 v193, 1.0, v193
	v_rcp_f32_e32 v193, v193
	v_mul_f32_e32 v194, 0x3f317217, v192
	v_fma_f32 v194, v192, s92, -v194
	v_fmac_f32_e32 v194, 0x3377d1cf, v192
	v_fmac_f32_e32 v194, 0x3f317217, v192
	v_cmp_lt_f32_e64 s[6:7], |v192|, s93
	v_fma_f32 v193, v185, v193, v159
	s_nop 0
	v_cndmask_b32_e64 v192, v192, v194, s[6:7]
	v_cmp_gt_f32_e64 s[6:7], s87, v193
	v_sub_f32_e32 v192, v192, v195
	v_cvt_pk_f16_f32 v192, v136, v192
	v_cndmask_b32_e64 v194, 0, 32, s[6:7]
	v_ldexp_f32 v193, v193, v194
	v_mul_f32_e32 v194, v71, v191
	v_mul_f32_e32 v194, 0xbfb8aa3b, v194
	v_exp_f32_e32 v194, v194
	v_log_f32_e32 v193, v193
	v_add_f32_e32 v194, 1.0, v194
	v_rcp_f32_e32 v194, v194
	v_mul_f32_e32 v195, 0x3f317217, v193
	v_fma_f32 v195, v193, s92, -v195
	v_fmac_f32_e32 v195, 0x3377d1cf, v193
	v_fma_f32 v194, v186, v194, v158
	v_cmp_gt_f32_e32 vcc, s87, v194
	v_fmac_f32_e32 v195, 0x3f317217, v193
	v_cmp_lt_f32_e64 s[8:9], |v193|, s93
	v_cndmask_b32_e64 v198, 0, 32, vcc
	v_ldexp_f32 v194, v194, v198
	v_mul_f32_e32 v198, v64, v191
	v_log_f32_e32 v194, v194
	v_mul_f32_e32 v198, 0xbfb8aa3b, v198
	v_exp_f32_e32 v198, v198
	v_cndmask_b32_e64 v193, v193, v195, s[8:9]
	v_cndmask_b32_e64 v195, 0, v171, s[6:7]
	v_sub_f32_e32 v193, v193, v195
	v_mul_f32_e32 v195, 0x3f317217, v194
	v_fma_f32 v195, v194, s92, -v195
	v_add_f32_e32 v198, 1.0, v198
	v_fmac_f32_e32 v195, 0x3377d1cf, v194
	v_rcp_f32_e32 v198, v198
	v_fmac_f32_e32 v195, 0x3f317217, v194
	v_cmp_lt_f32_e64 s[6:7], |v194|, s93
	v_fma_f32 v198, v187, v198, v157
	s_nop 0
	v_cndmask_b32_e64 v194, v194, v195, s[6:7]
	v_cndmask_b32_e32 v195, 0, v171, vcc
	v_sub_f32_e32 v194, v194, v195
; __device__ __forceinline__ float fsigm(float x) { return __builtin_amdgcn_rcpf(1.f + __expf(-x)); }
; __device__ __forceinline__ float row_rs(const float* ssq, int row) { return ssq ? rsqrtf(ssq[row] * (1.f / 1024.f) + RMS_EPS) : 1.f; }
;     __device__ __forceinline__ void operator()(const f32x4 (&acc)[2][2][4][2], const Unit& u, int wr, int wc, int fr, int fq) const {
;     ...
;                 for (int m = 0; m < 4; ++m) { const int row = row0 + ai * HALF + m * 16; const float rs = row_rs(ssq, row);
; #pragma unroll
;                     for (int bj = 0; bj < 2; ++bj) { f16x4 o[2];
; #pragma unroll
;                         for (int n = 0; n < 2; ++n) { const f32x4 p = acc[ai][bj][m][n] * rs;
; #pragma unroll
;                             for (int j = 0; j < 4; ++j) { const float l = lb[bj][n][j]; const float f = l + (1.f - l) * fsigm(p[j]); o[n][j] = (_Float16)__logf(f); } }
;                         const u32x2 a0 = __builtin_bit_cast(u32x2, o[0]), a1 = __builtin_bit_cast(u32x2, o[1]); u32x4 w; w.x = a0.x; w.y = a0.y; w.z = a1.x; w.w = a1.y;
;                         *(u32x4*)(LF + (size_t)row * 512 + cbase + bj * HALF) = w; } }
	v_cvt_pk_f16_f32 v193, v193, v194
	v_mul_f32_e32 v194, v65, v191
	v_cmp_gt_f32_e32 vcc, s87, v198
	v_mul_f32_e32 v194, 0xbfb8aa3b, v194
	v_exp_f32_e32 v194, v194
	v_cndmask_b32_e64 v199, 0, 32, vcc
	v_ldexp_f32 v198, v198, v199
	v_log_f32_e32 v198, v198
	v_add_f32_e32 v194, 1.0, v194
	v_rcp_f32_e32 v194, v194
	v_cndmask_b32_e32 v195, 0, v171, vcc
	v_mul_f32_e32 v136, 0x3f317217, v198
	v_fma_f32 v136, v198, s92, -v136
	v_fmac_f32_e32 v136, 0x3377d1cf, v198
	v_fmac_f32_e32 v136, 0x3f317217, v198
	v_cmp_lt_f32_e64 s[6:7], |v198|, s93
	v_fma_f32 v194, v182, v194, v156
	v_cmp_gt_f32_e32 vcc, s87, v194
	v_cndmask_b32_e64 v136, v198, v136, s[6:7]
	v_sub_f32_e32 v136, v136, v195
	v_cndmask_b32_e64 v195, 0, 32, vcc
	v_ldexp_f32 v194, v194, v195
	v_mul_f32_e32 v195, v66, v191
	v_mul_f32_e32 v195, 0xbfb8aa3b, v195
	v_exp_f32_e32 v195, v195
	v_log_f32_e32 v194, v194
	v_mul_f32_e32 v191, v67, v191
	v_mul_f32_e32 v191, 0xbfb8aa3b, v191
	v_add_f32_e32 v195, 1.0, v195
	v_rcp_f32_e32 v195, v195
	v_exp_f32_e32 v191, v191
	v_mul_f32_e32 v198, 0x3f317217, v194
	v_fma_f32 v198, v194, s92, -v198
	v_fmac_f32_e32 v198, 0x3377d1cf, v194
	v_fmac_f32_e32 v198, 0x3f317217, v194
	v_cmp_lt_f32_e64 s[6:7], |v194|, s93
	v_fma_f32 v195, v189, v195, v155
	v_add_f32_e32 v191, 1.0, v191
	v_cndmask_b32_e64 v194, v194, v198, s[6:7]
	v_cmp_gt_f32_e64 s[6:7], s87, v195
	v_rcp_f32_e32 v191, v191
	s_nop 0
	v_cndmask_b32_e64 v198, 0, 32, s[6:7]
	v_ldexp_f32 v195, v195, v198
	v_log_f32_e32 v195, v195
	v_fma_f32 v191, v190, v191, v154
	v_cndmask_b32_e32 v198, 0, v171, vcc
	v_cmp_gt_f32_e32 vcc, s87, v191
	v_sub_f32_e32 v194, v194, v198
	v_mul_f32_e32 v198, 0x3f317217, v195
	v_cndmask_b32_e64 v199, 0, 32, vcc
	v_ldexp_f32 v191, v191, v199
	v_fma_f32 v198, v195, s92, -v198
	v_log_f32_e32 v191, v191
	v_fmac_f32_e32 v198, 0x3377d1cf, v195
	v_fmac_f32_e32 v198, 0x3f317217, v195
	v_cmp_lt_f32_e64 s[8:9], |v195|, s93
	v_cvt_pk_f16_f32 v194, v136, v194
	s_nop 0
	v_cndmask_b32_e64 v195, v195, v198, s[8:9]
	v_cndmask_b32_e64 v198, 0, v171, s[6:7]
	v_sub_f32_e32 v195, v195, v198
	v_mul_f32_e32 v198, 0x3f317217, v191
	v_fma_f32 v198, v191, s92, -v198
	v_fmac_f32_e32 v198, 0x3377d1cf, v191
	v_fmac_f32_e32 v198, 0x3f317217, v191
	v_cmp_lt_f32_e64 s[6:7], |v191|, s93
	s_nop 1
	v_cndmask_b32_e64 v191, v191, v198, s[6:7]
	v_cndmask_b32_e32 v198, 0, v171, vcc
	v_sub_f32_e32 v191, v191, v198
	v_cvt_pk_f16_f32 v195, v195, v191
	global_store_dwordx4 v[196:197], v[192:195], off offset:256
	v_fmamk_f32 v136, v213, 0x3a800000, v170
	v_mul_f32_e32 v191, 0x4b800000, v136
	v_cmp_gt_f32_e32 vcc, s87, v136
	s_nop 1
	v_cndmask_b32_e32 v136, v136, v191, vcc
	v_rsq_f32_e32 v136, v136
	s_nop 0
	v_mul_f32_e32 v191, 0x45800000, v136
	v_cndmask_b32_e32 v136, v136, v191, vcc
	v_mul_f32_e32 v191, v60, v136
	v_mul_f32_e32 v191, 0xbfb8aa3b, v191
	v_exp_f32_e32 v191, v191
	v_mul_f32_e32 v193, v61, v136
	v_mul_f32_e32 v193, 0xbfb8aa3b, v193
	v_exp_f32_e32 v193, v193
	v_add_f32_e32 v191, 1.0, v191
	v_rcp_f32_e32 v191, v191
	v_add_f32_e32 v193, 1.0, v193
	v_rcp_f32_e32 v193, v193
	v_fma_f32 v191, v176, v191, v175
	v_cmp_gt_f32_e32 vcc, s87, v191
	s_nop 1
	v_cndmask_b32_e64 v192, 0, 32, vcc
	v_ldexp_f32 v191, v191, v192
	v_log_f32_e32 v191, v191
	s_nop 0
	v_mul_f32_e32 v192, 0x3f317217, v191
	v_fma_f32 v192, v191, s92, -v192
	v_fmac_f32_e32 v192, 0x3377d1cf, v191
	v_fmac_f32_e32 v192, 0x3f317217, v191
	v_cmp_lt_f32_e64 s[6:7], |v191|, s93
	s_nop 1
	v_cndmask_b32_e64 v191, v191, v192, s[6:7]
	v_cndmask_b32_e32 v192, 0, v171, vcc
	v_sub_f32_e32 v191, v191, v192
	v_fma_f32 v192, v177, v193, v174
	v_cmp_gt_f32_e32 vcc, s87, v192
	s_nop 1
	v_cndmask_b32_e64 v193, 0, 32, vcc
	v_ldexp_f32 v192, v192, v193
	v_mul_f32_e32 v193, v62, v136
	v_mul_f32_e32 v193, 0xbfb8aa3b, v193
	v_exp_f32_e32 v193, v193
	v_log_f32_e32 v192, v192
	v_cndmask_b32_e32 v195, 0, v171, vcc
	v_add_f32_e32 v193, 1.0, v193
	v_rcp_f32_e32 v193, v193
	v_mul_f32_e32 v194, 0x3f317217, v192
	v_fma_f32 v194, v192, s92, -v194
	v_fmac_f32_e32 v194, 0x3377d1cf, v192
	v_fmac_f32_e32 v194, 0x3f317217, v192
	v_cmp_lt_f32_e64 s[6:7], |v192|, s93
	v_fma_f32 v193, v178, v193, v173
	s_nop 0
	v_cndmask_b32_e64 v192, v192, v194, s[6:7]
	v_cmp_gt_f32_e64 s[6:7], s87, v193
	v_sub_f32_e32 v192, v192, v195
	v_cvt_pk_f16_f32 v192, v191, v192
	v_cndmask_b32_e64 v194, 0, 32, s[6:7]
	v_ldexp_f32 v193, v193, v194
	v_mul_f32_e32 v194, v63, v136
	v_mul_f32_e32 v194, 0xbfb8aa3b, v194
	v_exp_f32_e32 v194, v194
	v_log_f32_e32 v193, v193
	v_add_f32_e32 v194, 1.0, v194
	v_rcp_f32_e32 v194, v194
	v_mul_f32_e32 v195, 0x3f317217, v193
	v_fma_f32 v195, v193, s92, -v195
	v_fmac_f32_e32 v195, 0x3377d1cf, v193
	v_fma_f32 v194, v183, v194, v172
	v_cmp_gt_f32_e32 vcc, s87, v194
	v_fmac_f32_e32 v195, 0x3f317217, v193
	v_cmp_lt_f32_e64 s[8:9], |v193|, s93
	v_cndmask_b32_e64 v196, 0, 32, vcc
	v_ldexp_f32 v194, v194, v196
	v_mul_f32_e32 v196, v56, v136
	v_log_f32_e32 v194, v194
	v_mul_f32_e32 v196, 0xbfb8aa3b, v196
	v_exp_f32_e32 v196, v196
	v_cndmask_b32_e64 v193, v193, v195, s[8:9]
	v_cndmask_b32_e64 v195, 0, v171, s[6:7]
	v_sub_f32_e32 v193, v193, v195
	v_mul_f32_e32 v195, 0x3f317217, v194
	v_fma_f32 v195, v194, s92, -v195
	v_add_f32_e32 v196, 1.0, v196
	v_fmac_f32_e32 v195, 0x3377d1cf, v194
	v_rcp_f32_e32 v196, v196
	v_fmac_f32_e32 v195, 0x3f317217, v194
	v_cmp_lt_f32_e64 s[6:7], |v194|, s93
	v_fma_f32 v196, v149, v196, v165
	s_nop 0
	v_cndmask_b32_e64 v194, v194, v195, s[6:7]
	v_cndmask_b32_e32 v195, 0, v171, vcc
	v_sub_f32_e32 v194, v194, v195
	v_cvt_pk_f16_f32 v193, v193, v194
	v_mul_f32_e32 v194, v57, v136
	v_cmp_gt_f32_e32 vcc, s87, v196
	v_mul_f32_e32 v194, 0xbfb8aa3b, v194
	v_exp_f32_e32 v194, v194
; __device__ __forceinline__ float fsigm(float x) { return __builtin_amdgcn_rcpf(1.f + __expf(-x)); }
; __device__ __forceinline__ float row_rs(const float* ssq, int row) { return ssq ? rsqrtf(ssq[row] * (1.f / 1024.f) + RMS_EPS) : 1.f; }
;     __device__ __forceinline__ void operator()(const f32x4 (&acc)[2][2][4][2], const Unit& u, int wr, int wc, int fr, int fq) const {
;     ...
;                 for (int m = 0; m < 4; ++m) { const int row = row0 + ai * HALF + m * 16; const float rs = row_rs(ssq, row);
; #pragma unroll
;                     for (int bj = 0; bj < 2; ++bj) { f16x4 o[2];
; #pragma unroll
;                         for (int n = 0; n < 2; ++n) { const f32x4 p = acc[ai][bj][m][n] * rs;
; #pragma unroll
;                             for (int j = 0; j < 4; ++j) { const float l = lb[bj][n][j]; const float f = l + (1.f - l) * fsigm(p[j]); o[n][j] = (_Float16)__logf(f); } }
;                         const u32x2 a0 = __builtin_bit_cast(u32x2, o[0]), a1 = __builtin_bit_cast(u32x2, o[1]); u32x4 w; w.x = a0.x; w.y = a0.y; w.z = a1.x; w.w = a1.y;
;                         *(u32x4*)(LF + (size_t)row * 512 + cbase + bj * HALF) = w; } }
	v_cndmask_b32_e64 v197, 0, 32, vcc
	v_ldexp_f32 v196, v196, v197
	v_log_f32_e32 v196, v196
	v_add_f32_e32 v194, 1.0, v194
	v_rcp_f32_e32 v194, v194
	v_cndmask_b32_e32 v195, 0, v171, vcc
	v_mul_f32_e32 v191, 0x3f317217, v196
	v_fma_f32 v191, v196, s92, -v191
	v_fmac_f32_e32 v191, 0x3377d1cf, v196
	v_fmac_f32_e32 v191, 0x3f317217, v196
	v_cmp_lt_f32_e64 s[6:7], |v196|, s93
	v_fma_f32 v194, v179, v194, v164
	v_cmp_gt_f32_e32 vcc, s87, v194
	v_cndmask_b32_e64 v191, v196, v191, s[6:7]
	v_sub_f32_e32 v191, v191, v195
	v_cndmask_b32_e64 v195, 0, 32, vcc
	v_ldexp_f32 v194, v194, v195
	v_mul_f32_e32 v195, v58, v136
	v_mul_f32_e32 v195, 0xbfb8aa3b, v195
	v_exp_f32_e32 v195, v195
	v_log_f32_e32 v194, v194
	v_cndmask_b32_e32 v197, 0, v171, vcc
	v_add_f32_e32 v195, 1.0, v195
	v_rcp_f32_e32 v195, v195
	v_mul_f32_e32 v196, 0x3f317217, v194
	v_fma_f32 v196, v194, s92, -v196
	v_fmac_f32_e32 v196, 0x3377d1cf, v194
	v_fmac_f32_e32 v196, 0x3f317217, v194
	v_cmp_lt_f32_e64 s[6:7], |v194|, s93
	v_fma_f32 v195, v180, v195, v163
	s_nop 0
	v_cndmask_b32_e64 v194, v194, v196, s[6:7]
	v_cmp_gt_f32_e64 s[6:7], s87, v195
	v_sub_f32_e32 v194, v194, v197
	v_cvt_pk_f16_f32 v194, v191, v194
	v_cndmask_b32_e64 v196, 0, 32, s[6:7]
	v_ldexp_f32 v195, v195, v196
	v_mul_f32_e32 v196, v59, v136
	v_mul_f32_e32 v196, 0xbfb8aa3b, v196
	v_exp_f32_e32 v196, v196
	v_log_f32_e32 v195, v195
	v_add_f32_e32 v196, 1.0, v196
	v_rcp_f32_e32 v196, v196
	v_mul_f32_e32 v197, 0x3f317217, v195
	v_fma_f32 v197, v195, s92, -v197
	v_fmac_f32_e32 v197, 0x3377d1cf, v195
	v_fma_f32 v196, v188, v196, v162
	v_cmp_gt_f32_e32 vcc, s87, v196
	v_fmac_f32_e32 v197, 0x3f317217, v195
	v_cmp_lt_f32_e64 s[8:9], |v195|, s93
	v_cndmask_b32_e64 v198, 0, 32, vcc
	v_ldexp_f32 v196, v196, v198
	v_log_f32_e32 v196, v196
	v_cndmask_b32_e64 v195, v195, v197, s[8:9]
	v_cndmask_b32_e64 v197, 0, v171, s[6:7]
	v_mul_f32_e32 v198, v52, v136
	v_sub_f32_e32 v195, v195, v197
	v_mul_f32_e32 v197, 0x3f317217, v196
	v_mul_f32_e32 v198, 0xbfb8aa3b, v198
	v_fma_f32 v197, v196, s92, -v197
	v_exp_f32_e32 v198, v198
	v_fmac_f32_e32 v197, 0x3377d1cf, v196
	v_fmac_f32_e32 v197, 0x3f317217, v196
	v_cmp_lt_f32_e64 s[6:7], |v196|, s93
	s_nop 1
	v_cndmask_b32_e64 v196, v196, v197, s[6:7]
	v_cndmask_b32_e32 v197, 0, v171, vcc
	v_sub_f32_e32 v196, v196, v197
	v_add_f32_e32 v197, 1.0, v198
	v_rcp_f32_e32 v198, v197
	v_cvt_pk_f16_f32 v195, v195, v196
	v_lshl_add_u64 v[196:197], v[152:153], 0, s[38:39]
	v_fma_f32 v191, v184, v198, v161
	v_cmp_gt_f32_e32 vcc, s87, v191
	s_nop 1
	v_cndmask_b32_e64 v198, 0, 32, vcc
	v_ldexp_f32 v191, v191, v198
	v_add_co_u32_e64 v198, s[6:7], s88, v152
	v_log_f32_e32 v191, v191
	s_nop 0
	v_addc_co_u32_e64 v199, s[6:7], 0, v153, s[6:7]
	global_store_dwordx4 v[198:199], v[192:195], off
	v_cmp_lt_f32_e64 s[6:7], |v191|, s93
	s_nop 0
	v_mul_f32_e32 v193, v53, v136
	v_mul_f32_e32 v193, 0xbfb8aa3b, v193
	v_exp_f32_e32 v193, v193
	v_mul_f32_e32 v192, 0x3f317217, v191
	v_fma_f32 v192, v191, s92, -v192
	v_fmac_f32_e32 v192, 0x3377d1cf, v191
	v_add_f32_e32 v193, 1.0, v193
	v_rcp_f32_e32 v193, v193
	v_fmac_f32_e32 v192, 0x3f317217, v191
	v_cndmask_b32_e64 v191, v191, v192, s[6:7]
	v_cndmask_b32_e32 v192, 0, v171, vcc
	v_sub_f32_e32 v191, v191, v192
	v_fma_f32 v192, v181, v193, v160
	v_cmp_gt_f32_e32 vcc, s87, v192
	s_nop 1
	v_cndmask_b32_e64 v193, 0, 32, vcc
	v_ldexp_f32 v192, v192, v193
	v_mul_f32_e32 v193, v54, v136
	v_mul_f32_e32 v193, 0xbfb8aa3b, v193
	v_exp_f32_e32 v193, v193
	v_log_f32_e32 v192, v192
	v_cndmask_b32_e32 v195, 0, v171, vcc
	v_add_f32_e32 v193, 1.0, v193
	v_rcp_f32_e32 v193, v193
	v_mul_f32_e32 v194, 0x3f317217, v192
	v_fma_f32 v194, v192, s92, -v194
	v_fmac_f32_e32 v194, 0x3377d1cf, v192
	v_fmac_f32_e32 v194, 0x3f317217, v192
	v_cmp_lt_f32_e64 s[6:7], |v192|, s93
	v_fma_f32 v193, v185, v193, v159
	s_nop 0
	v_cndmask_b32_e64 v192, v192, v194, s[6:7]
	v_cmp_gt_f32_e64 s[6:7], s87, v193
	v_sub_f32_e32 v192, v192, v195
	v_cvt_pk_f16_f32 v192, v191, v192
	v_cndmask_b32_e64 v194, 0, 32, s[6:7]
	v_ldexp_f32 v193, v193, v194
	v_mul_f32_e32 v194, v55, v136
	v_mul_f32_e32 v194, 0xbfb8aa3b, v194
	v_exp_f32_e32 v194, v194
	v_log_f32_e32 v193, v193
	v_add_f32_e32 v194, 1.0, v194
	v_rcp_f32_e32 v194, v194
	v_mul_f32_e32 v195, 0x3f317217, v193
	v_fma_f32 v195, v193, s92, -v195
	v_fmac_f32_e32 v195, 0x3377d1cf, v193
	v_fma_f32 v194, v186, v194, v158
	v_cmp_gt_f32_e32 vcc, s87, v194
	v_fmac_f32_e32 v195, 0x3f317217, v193
	v_cmp_lt_f32_e64 s[8:9], |v193|, s93
	v_cndmask_b32_e64 v198, 0, 32, vcc
	v_ldexp_f32 v194, v194, v198
	v_mul_f32_e32 v198, v48, v136
	v_log_f32_e32 v194, v194
	v_mul_f32_e32 v198, 0xbfb8aa3b, v198
	v_exp_f32_e32 v198, v198
	v_cndmask_b32_e64 v193, v193, v195, s[8:9]
	v_cndmask_b32_e64 v195, 0, v171, s[6:7]
	v_sub_f32_e32 v193, v193, v195
	v_mul_f32_e32 v195, 0x3f317217, v194
	v_fma_f32 v195, v194, s92, -v195
	v_add_f32_e32 v198, 1.0, v198
	v_fmac_f32_e32 v195, 0x3377d1cf, v194
	v_rcp_f32_e32 v198, v198
	v_fmac_f32_e32 v195, 0x3f317217, v194
	v_cmp_lt_f32_e64 s[6:7], |v194|, s93
	v_fma_f32 v198, v187, v198, v157
	s_nop 0
	v_cndmask_b32_e64 v194, v194, v195, s[6:7]
	v_cndmask_b32_e32 v195, 0, v171, vcc
	v_sub_f32_e32 v194, v194, v195
	v_cvt_pk_f16_f32 v193, v193, v194
	v_mul_f32_e32 v194, v49, v136
	v_cmp_gt_f32_e32 vcc, s87, v198
	v_mul_f32_e32 v194, 0xbfb8aa3b, v194
	v_exp_f32_e32 v194, v194
	v_cndmask_b32_e64 v199, 0, 32, vcc
	v_ldexp_f32 v198, v198, v199
	v_log_f32_e32 v198, v198
	v_add_f32_e32 v194, 1.0, v194
	v_rcp_f32_e32 v194, v194
	v_cndmask_b32_e32 v195, 0, v171, vcc
	v_mul_f32_e32 v191, 0x3f317217, v198
	v_fma_f32 v191, v198, s92, -v191
	v_fmac_f32_e32 v191, 0x3377d1cf, v198
; __device__ __forceinline__ float fsigm(float x) { return __builtin_amdgcn_rcpf(1.f + __expf(-x)); }
; __device__ __forceinline__ float row_rs(const float* ssq, int row) { return ssq ? rsqrtf(ssq[row] * (1.f / 1024.f) + RMS_EPS) : 1.f; }
;     __device__ __forceinline__ void operator()(const f32x4 (&acc)[2][2][4][2], const Unit& u, int wr, int wc, int fr, int fq) const {
;     ...
;                 for (int m = 0; m < 4; ++m) { const int row = row0 + ai * HALF + m * 16; const float rs = row_rs(ssq, row);
; #pragma unroll
;                     for (int bj = 0; bj < 2; ++bj) { f16x4 o[2];
; #pragma unroll
;                         for (int n = 0; n < 2; ++n) { const f32x4 p = acc[ai][bj][m][n] * rs;
; #pragma unroll
;                             for (int j = 0; j < 4; ++j) { const float l = lb[bj][n][j]; const float f = l + (1.f - l) * fsigm(p[j]); o[n][j] = (_Float16)__logf(f); } }
;                         const u32x2 a0 = __builtin_bit_cast(u32x2, o[0]), a1 = __builtin_bit_cast(u32x2, o[1]); u32x4 w; w.x = a0.x; w.y = a0.y; w.z = a1.x; w.w = a1.y;
;                         *(u32x4*)(LF + (size_t)row * 512 + cbase + bj * HALF) = w; } }
	v_fmac_f32_e32 v191, 0x3f317217, v198
	v_cmp_lt_f32_e64 s[6:7], |v198|, s93
	v_fma_f32 v194, v182, v194, v156
	v_cmp_gt_f32_e32 vcc, s87, v194
	v_cndmask_b32_e64 v191, v198, v191, s[6:7]
	v_sub_f32_e32 v191, v191, v195
	v_cndmask_b32_e64 v195, 0, 32, vcc
	v_ldexp_f32 v194, v194, v195
	v_mul_f32_e32 v195, v50, v136
	v_mul_f32_e32 v195, 0xbfb8aa3b, v195
	v_exp_f32_e32 v195, v195
	v_log_f32_e32 v194, v194
	v_mul_f32_e32 v136, v51, v136
	v_mul_f32_e32 v136, 0xbfb8aa3b, v136
	v_add_f32_e32 v195, 1.0, v195
	v_rcp_f32_e32 v195, v195
	v_exp_f32_e32 v136, v136
	v_mul_f32_e32 v198, 0x3f317217, v194
	v_fma_f32 v198, v194, s92, -v198
	v_fmac_f32_e32 v198, 0x3377d1cf, v194
	v_fmac_f32_e32 v198, 0x3f317217, v194
	v_cmp_lt_f32_e64 s[6:7], |v194|, s93
	v_fma_f32 v195, v189, v195, v155
	v_add_f32_e32 v136, 1.0, v136
	v_cndmask_b32_e64 v194, v194, v198, s[6:7]
	v_cmp_gt_f32_e64 s[6:7], s87, v195
	v_rcp_f32_e32 v136, v136
	s_nop 0
	v_cndmask_b32_e64 v198, 0, 32, s[6:7]
	v_ldexp_f32 v195, v195, v198
	v_log_f32_e32 v195, v195
	v_fma_f32 v136, v190, v136, v154
	v_cndmask_b32_e32 v198, 0, v171, vcc
	v_cmp_gt_f32_e32 vcc, s87, v136
	v_sub_f32_e32 v194, v194, v198
	v_mul_f32_e32 v198, 0x3f317217, v195
	v_cndmask_b32_e64 v199, 0, 32, vcc
	v_ldexp_f32 v136, v136, v199
	v_fma_f32 v198, v195, s92, -v198
	v_log_f32_e32 v136, v136
	v_fmac_f32_e32 v198, 0x3377d1cf, v195
	v_fmac_f32_e32 v198, 0x3f317217, v195
	v_cmp_lt_f32_e64 s[8:9], |v195|, s93
	v_cvt_pk_f16_f32 v194, v191, v194
	s_nop 0
	v_cndmask_b32_e64 v195, v195, v198, s[8:9]
	v_cndmask_b32_e64 v198, 0, v171, s[6:7]
	v_sub_f32_e32 v195, v195, v198
	v_mul_f32_e32 v198, 0x3f317217, v136
	v_fma_f32 v198, v136, s92, -v198
	v_fmac_f32_e32 v198, 0x3377d1cf, v136
	v_fmac_f32_e32 v198, 0x3f317217, v136
	v_cmp_lt_f32_e64 s[6:7], |v136|, s93
	s_nop 1
	v_cndmask_b32_e64 v136, v136, v198, s[6:7]
	v_cndmask_b32_e32 v198, 0, v171, vcc
	v_sub_f32_e32 v136, v136, v198
	v_cvt_pk_f16_f32 v195, v195, v136
	global_store_dwordx4 v[196:197], v[192:195], off offset:256
	v_fmamk_f32 v136, v214, 0x3a800000, v170
	v_mul_f32_e32 v191, 0x4b800000, v136
	v_cmp_gt_f32_e32 vcc, s87, v136
	s_nop 1
	v_cndmask_b32_e32 v136, v136, v191, vcc
	v_rsq_f32_e32 v136, v136
	s_nop 0
	v_mul_f32_e32 v191, 0x45800000, v136
	v_cndmask_b32_e32 v136, v136, v191, vcc
	v_mul_f32_e32 v191, v44, v136
	v_mul_f32_e32 v191, 0xbfb8aa3b, v191
	v_exp_f32_e32 v191, v191
	v_mul_f32_e32 v193, v45, v136
	v_mul_f32_e32 v193, 0xbfb8aa3b, v193
	v_exp_f32_e32 v193, v193
	v_add_f32_e32 v191, 1.0, v191
	v_rcp_f32_e32 v191, v191
	v_add_f32_e32 v193, 1.0, v193
	v_rcp_f32_e32 v193, v193
	v_fma_f32 v191, v176, v191, v175
	v_cmp_gt_f32_e32 vcc, s87, v191
	s_nop 1
	v_cndmask_b32_e64 v192, 0, 32, vcc
	v_ldexp_f32 v191, v191, v192
	v_log_f32_e32 v191, v191
	s_nop 0
	v_mul_f32_e32 v192, 0x3f317217, v191
	v_fma_f32 v192, v191, s92, -v192
	v_fmac_f32_e32 v192, 0x3377d1cf, v191
	v_fmac_f32_e32 v192, 0x3f317217, v191
	v_cmp_lt_f32_e64 s[6:7], |v191|, s93
	s_nop 1
	v_cndmask_b32_e64 v191, v191, v192, s[6:7]
	v_cndmask_b32_e32 v192, 0, v171, vcc
	v_sub_f32_e32 v191, v191, v192
	v_fma_f32 v192, v177, v193, v174
	v_cmp_gt_f32_e32 vcc, s87, v192
	s_nop 1
	v_cndmask_b32_e64 v193, 0, 32, vcc
	v_ldexp_f32 v192, v192, v193
	v_mul_f32_e32 v193, v46, v136
	v_mul_f32_e32 v193, 0xbfb8aa3b, v193
	v_exp_f32_e32 v193, v193
	v_log_f32_e32 v192, v192
	v_cndmask_b32_e32 v195, 0, v171, vcc
	v_add_f32_e32 v193, 1.0, v193
	v_rcp_f32_e32 v193, v193
	v_mul_f32_e32 v194, 0x3f317217, v192
	v_fma_f32 v194, v192, s92, -v194
	v_fmac_f32_e32 v194, 0x3377d1cf, v192
	v_fmac_f32_e32 v194, 0x3f317217, v192
	v_cmp_lt_f32_e64 s[6:7], |v192|, s93
	v_fma_f32 v193, v178, v193, v173
	s_nop 0
	v_cndmask_b32_e64 v192, v192, v194, s[6:7]
	v_cmp_gt_f32_e64 s[6:7], s87, v193
	v_sub_f32_e32 v192, v192, v195
	v_cvt_pk_f16_f32 v192, v191, v192
	v_cndmask_b32_e64 v194, 0, 32, s[6:7]
	v_ldexp_f32 v193, v193, v194
	v_mul_f32_e32 v194, v47, v136
	v_mul_f32_e32 v194, 0xbfb8aa3b, v194
	v_exp_f32_e32 v194, v194
	v_log_f32_e32 v193, v193
	v_add_f32_e32 v194, 1.0, v194
	v_rcp_f32_e32 v194, v194
	v_mul_f32_e32 v195, 0x3f317217, v193
	v_fma_f32 v195, v193, s92, -v195
	v_fmac_f32_e32 v195, 0x3377d1cf, v193
	v_fma_f32 v194, v183, v194, v172
	v_cmp_gt_f32_e32 vcc, s87, v194
	v_fmac_f32_e32 v195, 0x3f317217, v193
	v_cmp_lt_f32_e64 s[8:9], |v193|, s93
	v_cndmask_b32_e64 v196, 0, 32, vcc
	v_ldexp_f32 v194, v194, v196
	v_mul_f32_e32 v196, v40, v136
	v_log_f32_e32 v194, v194
	v_mul_f32_e32 v196, 0xbfb8aa3b, v196
	v_exp_f32_e32 v196, v196
	v_cndmask_b32_e64 v193, v193, v195, s[8:9]
	v_cndmask_b32_e64 v195, 0, v171, s[6:7]
	v_sub_f32_e32 v193, v193, v195
	v_mul_f32_e32 v195, 0x3f317217, v194
	v_fma_f32 v195, v194, s92, -v195
	v_add_f32_e32 v196, 1.0, v196
	v_fmac_f32_e32 v195, 0x3377d1cf, v194
	v_rcp_f32_e32 v196, v196
	v_fmac_f32_e32 v195, 0x3f317217, v194
	v_cmp_lt_f32_e64 s[6:7], |v194|, s93
	v_fma_f32 v196, v149, v196, v165
	s_nop 0
	v_cndmask_b32_e64 v194, v194, v195, s[6:7]
	v_cndmask_b32_e32 v195, 0, v171, vcc
	v_sub_f32_e32 v194, v194, v195
	v_cvt_pk_f16_f32 v193, v193, v194
	v_mul_f32_e32 v194, v41, v136
	v_cmp_gt_f32_e32 vcc, s87, v196
	v_mul_f32_e32 v194, 0xbfb8aa3b, v194
	v_exp_f32_e32 v194, v194
	v_cndmask_b32_e64 v197, 0, 32, vcc
	v_ldexp_f32 v196, v196, v197
	v_log_f32_e32 v196, v196
	v_add_f32_e32 v194, 1.0, v194
	v_rcp_f32_e32 v194, v194
	v_cndmask_b32_e32 v195, 0, v171, vcc
	v_mul_f32_e32 v191, 0x3f317217, v196
	v_fma_f32 v191, v196, s92, -v191
	v_fmac_f32_e32 v191, 0x3377d1cf, v196
	v_fmac_f32_e32 v191, 0x3f317217, v196
	v_cmp_lt_f32_e64 s[6:7], |v196|, s93
	v_fma_f32 v194, v179, v194, v164
	v_cmp_gt_f32_e32 vcc, s87, v194
; __device__ __forceinline__ float fsigm(float x) { return __builtin_amdgcn_rcpf(1.f + __expf(-x)); }
; __device__ __forceinline__ float row_rs(const float* ssq, int row) { return ssq ? rsqrtf(ssq[row] * (1.f / 1024.f) + RMS_EPS) : 1.f; }
;     __device__ __forceinline__ void operator()(const f32x4 (&acc)[2][2][4][2], const Unit& u, int wr, int wc, int fr, int fq) const {
;     ...
;                 for (int m = 0; m < 4; ++m) { const int row = row0 + ai * HALF + m * 16; const float rs = row_rs(ssq, row);
; #pragma unroll
;                     for (int bj = 0; bj < 2; ++bj) { f16x4 o[2];
; #pragma unroll
;                         for (int n = 0; n < 2; ++n) { const f32x4 p = acc[ai][bj][m][n] * rs;
; #pragma unroll
;                             for (int j = 0; j < 4; ++j) { const float l = lb[bj][n][j]; const float f = l + (1.f - l) * fsigm(p[j]); o[n][j] = (_Float16)__logf(f); } }
;                         const u32x2 a0 = __builtin_bit_cast(u32x2, o[0]), a1 = __builtin_bit_cast(u32x2, o[1]); u32x4 w; w.x = a0.x; w.y = a0.y; w.z = a1.x; w.w = a1.y;
;                         *(u32x4*)(LF + (size_t)row * 512 + cbase + bj * HALF) = w; } }
	v_cndmask_b32_e64 v191, v196, v191, s[6:7]
	v_sub_f32_e32 v191, v191, v195
	v_cndmask_b32_e64 v195, 0, 32, vcc
	v_ldexp_f32 v194, v194, v195
	v_mul_f32_e32 v195, v42, v136
	v_mul_f32_e32 v195, 0xbfb8aa3b, v195
	v_exp_f32_e32 v195, v195
	v_log_f32_e32 v194, v194
	v_cndmask_b32_e32 v197, 0, v171, vcc
	v_add_f32_e32 v195, 1.0, v195
	v_rcp_f32_e32 v195, v195
	v_mul_f32_e32 v196, 0x3f317217, v194
	v_fma_f32 v196, v194, s92, -v196
	v_fmac_f32_e32 v196, 0x3377d1cf, v194
	v_fmac_f32_e32 v196, 0x3f317217, v194
	v_cmp_lt_f32_e64 s[6:7], |v194|, s93
	v_fma_f32 v195, v180, v195, v163
	s_nop 0
	v_cndmask_b32_e64 v194, v194, v196, s[6:7]
	v_cmp_gt_f32_e64 s[6:7], s87, v195
	v_sub_f32_e32 v194, v194, v197
	v_cvt_pk_f16_f32 v194, v191, v194
	v_cndmask_b32_e64 v196, 0, 32, s[6:7]
	v_ldexp_f32 v195, v195, v196
	v_mul_f32_e32 v196, v43, v136
	v_mul_f32_e32 v196, 0xbfb8aa3b, v196
	v_exp_f32_e32 v196, v196
	v_log_f32_e32 v195, v195
	v_add_f32_e32 v196, 1.0, v196
	v_rcp_f32_e32 v196, v196
	v_mul_f32_e32 v197, 0x3f317217, v195
	v_fma_f32 v197, v195, s92, -v197
	v_fmac_f32_e32 v197, 0x3377d1cf, v195
	v_fma_f32 v196, v188, v196, v162
	v_cmp_gt_f32_e32 vcc, s87, v196
	v_fmac_f32_e32 v197, 0x3f317217, v195
	v_cmp_lt_f32_e64 s[8:9], |v195|, s93
	v_cndmask_b32_e64 v198, 0, 32, vcc
	v_ldexp_f32 v196, v196, v198
	v_log_f32_e32 v196, v196
	v_cndmask_b32_e64 v195, v195, v197, s[8:9]
	v_cndmask_b32_e64 v197, 0, v171, s[6:7]
	v_mul_f32_e32 v198, v36, v136
	v_sub_f32_e32 v195, v195, v197
	v_mul_f32_e32 v197, 0x3f317217, v196
	v_mul_f32_e32 v198, 0xbfb8aa3b, v198
	v_fma_f32 v197, v196, s92, -v197
	v_exp_f32_e32 v198, v198
	v_fmac_f32_e32 v197, 0x3377d1cf, v196
	v_fmac_f32_e32 v197, 0x3f317217, v196
	v_cmp_lt_f32_e64 s[6:7], |v196|, s93
	s_nop 1
	v_cndmask_b32_e64 v196, v196, v197, s[6:7]
	v_cndmask_b32_e32 v197, 0, v171, vcc
	v_sub_f32_e32 v196, v196, v197
	v_add_f32_e32 v197, 1.0, v198
	v_rcp_f32_e32 v198, v197
	v_cvt_pk_f16_f32 v195, v195, v196
	v_lshl_add_u64 v[196:197], v[152:153], 0, s[40:41]
	v_fma_f32 v191, v184, v198, v161
	v_cmp_gt_f32_e32 vcc, s87, v191
	s_nop 1
	v_cndmask_b32_e64 v198, 0, 32, vcc
	v_ldexp_f32 v191, v191, v198
	v_add_co_u32_e64 v198, s[6:7], s89, v152
	v_log_f32_e32 v191, v191
	s_nop 0
	v_addc_co_u32_e64 v199, s[6:7], 0, v153, s[6:7]
	global_store_dwordx4 v[198:199], v[192:195], off
	v_cmp_lt_f32_e64 s[6:7], |v191|, s93
	s_nop 0
	v_mul_f32_e32 v193, v37, v136
	v_mul_f32_e32 v193, 0xbfb8aa3b, v193
	v_exp_f32_e32 v193, v193
	v_mul_f32_e32 v192, 0x3f317217, v191
	v_fma_f32 v192, v191, s92, -v192
	v_fmac_f32_e32 v192, 0x3377d1cf, v191
	v_add_f32_e32 v193, 1.0, v193
	v_rcp_f32_e32 v193, v193
	v_fmac_f32_e32 v192, 0x3f317217, v191
	v_cndmask_b32_e64 v191, v191, v192, s[6:7]
	v_cndmask_b32_e32 v192, 0, v171, vcc
	v_sub_f32_e32 v191, v191, v192
	v_fma_f32 v192, v181, v193, v160
	v_cmp_gt_f32_e32 vcc, s87, v192
	s_nop 1
	v_cndmask_b32_e64 v193, 0, 32, vcc
	v_ldexp_f32 v192, v192, v193
	v_mul_f32_e32 v193, v38, v136
	v_mul_f32_e32 v193, 0xbfb8aa3b, v193
	v_exp_f32_e32 v193, v193
	v_log_f32_e32 v192, v192
	v_cndmask_b32_e32 v195, 0, v171, vcc
	v_add_f32_e32 v193, 1.0, v193
	v_rcp_f32_e32 v193, v193
	v_mul_f32_e32 v194, 0x3f317217, v192
	v_fma_f32 v194, v192, s92, -v194
	v_fmac_f32_e32 v194, 0x3377d1cf, v192
	v_fmac_f32_e32 v194, 0x3f317217, v192
	v_cmp_lt_f32_e64 s[6:7], |v192|, s93
	v_fma_f32 v193, v185, v193, v159
	s_nop 0
	v_cndmask_b32_e64 v192, v192, v194, s[6:7]
	v_cmp_gt_f32_e64 s[6:7], s87, v193
	v_sub_f32_e32 v192, v192, v195
	v_cvt_pk_f16_f32 v192, v191, v192
	v_cndmask_b32_e64 v194, 0, 32, s[6:7]
	v_ldexp_f32 v193, v193, v194
	v_mul_f32_e32 v194, v39, v136
	v_mul_f32_e32 v194, 0xbfb8aa3b, v194
	v_exp_f32_e32 v194, v194
	v_log_f32_e32 v193, v193
	v_add_f32_e32 v194, 1.0, v194
	v_rcp_f32_e32 v194, v194
	v_mul_f32_e32 v195, 0x3f317217, v193
	v_fma_f32 v195, v193, s92, -v195
	v_fmac_f32_e32 v195, 0x3377d1cf, v193
	v_fma_f32 v194, v186, v194, v158
	v_cmp_gt_f32_e32 vcc, s87, v194
	v_fmac_f32_e32 v195, 0x3f317217, v193
	v_cmp_lt_f32_e64 s[8:9], |v193|, s93
	v_cndmask_b32_e64 v198, 0, 32, vcc
	v_ldexp_f32 v194, v194, v198
	v_mul_f32_e32 v198, v32, v136
	v_log_f32_e32 v194, v194
	v_mul_f32_e32 v198, 0xbfb8aa3b, v198
	v_exp_f32_e32 v198, v198
	v_cndmask_b32_e64 v193, v193, v195, s[8:9]
	v_cndmask_b32_e64 v195, 0, v171, s[6:7]
	v_sub_f32_e32 v193, v193, v195
	v_mul_f32_e32 v195, 0x3f317217, v194
	v_fma_f32 v195, v194, s92, -v195
	v_add_f32_e32 v198, 1.0, v198
	v_fmac_f32_e32 v195, 0x3377d1cf, v194
	v_rcp_f32_e32 v198, v198
	v_fmac_f32_e32 v195, 0x3f317217, v194
	v_cmp_lt_f32_e64 s[6:7], |v194|, s93
	v_fma_f32 v198, v187, v198, v157
	s_nop 0
	v_cndmask_b32_e64 v194, v194, v195, s[6:7]
	v_cndmask_b32_e32 v195, 0, v171, vcc
	v_sub_f32_e32 v194, v194, v195
	v_cvt_pk_f16_f32 v193, v193, v194
	v_mul_f32_e32 v194, v33, v136
	v_cmp_gt_f32_e32 vcc, s87, v198
	v_mul_f32_e32 v194, 0xbfb8aa3b, v194
	v_exp_f32_e32 v194, v194
	v_cndmask_b32_e64 v199, 0, 32, vcc
	v_ldexp_f32 v198, v198, v199
	v_log_f32_e32 v198, v198
	v_add_f32_e32 v194, 1.0, v194
	v_rcp_f32_e32 v194, v194
	v_cndmask_b32_e32 v195, 0, v171, vcc
	v_mul_f32_e32 v191, 0x3f317217, v198
	v_fma_f32 v191, v198, s92, -v191
	v_fmac_f32_e32 v191, 0x3377d1cf, v198
	v_fmac_f32_e32 v191, 0x3f317217, v198
	v_cmp_lt_f32_e64 s[6:7], |v198|, s93
	v_fma_f32 v194, v182, v194, v156
	v_cmp_gt_f32_e32 vcc, s87, v194
	v_cndmask_b32_e64 v191, v198, v191, s[6:7]
	v_sub_f32_e32 v191, v191, v195
	v_cndmask_b32_e64 v195, 0, 32, vcc
	v_ldexp_f32 v194, v194, v195
	v_mul_f32_e32 v195, v34, v136
	v_mul_f32_e32 v195, 0xbfb8aa3b, v195
	v_exp_f32_e32 v195, v195
	v_log_f32_e32 v194, v194
	v_mul_f32_e32 v136, v35, v136
; __device__ __forceinline__ float fsigm(float x) { return __builtin_amdgcn_rcpf(1.f + __expf(-x)); }
; __device__ __forceinline__ float row_rs(const float* ssq, int row) { return ssq ? rsqrtf(ssq[row] * (1.f / 1024.f) + RMS_EPS) : 1.f; }
;     __device__ __forceinline__ void operator()(const f32x4 (&acc)[2][2][4][2], const Unit& u, int wr, int wc, int fr, int fq) const {
;     ...
;                 for (int m = 0; m < 4; ++m) { const int row = row0 + ai * HALF + m * 16; const float rs = row_rs(ssq, row);
; #pragma unroll
;                     for (int bj = 0; bj < 2; ++bj) { f16x4 o[2];
; #pragma unroll
;                         for (int n = 0; n < 2; ++n) { const f32x4 p = acc[ai][bj][m][n] * rs;
; #pragma unroll
;                             for (int j = 0; j < 4; ++j) { const float l = lb[bj][n][j]; const float f = l + (1.f - l) * fsigm(p[j]); o[n][j] = (_Float16)__logf(f); } }
;                         const u32x2 a0 = __builtin_bit_cast(u32x2, o[0]), a1 = __builtin_bit_cast(u32x2, o[1]); u32x4 w; w.x = a0.x; w.y = a0.y; w.z = a1.x; w.w = a1.y;
;                         *(u32x4*)(LF + (size_t)row * 512 + cbase + bj * HALF) = w; } }
	v_mul_f32_e32 v136, 0xbfb8aa3b, v136
	v_add_f32_e32 v195, 1.0, v195
	v_rcp_f32_e32 v195, v195
	v_exp_f32_e32 v136, v136
	v_mul_f32_e32 v198, 0x3f317217, v194
	v_fma_f32 v198, v194, s92, -v198
	v_fmac_f32_e32 v198, 0x3377d1cf, v194
	v_fmac_f32_e32 v198, 0x3f317217, v194
	v_cmp_lt_f32_e64 s[6:7], |v194|, s93
	v_fma_f32 v195, v189, v195, v155
	v_add_f32_e32 v136, 1.0, v136
	v_cndmask_b32_e64 v194, v194, v198, s[6:7]
	v_cmp_gt_f32_e64 s[6:7], s87, v195
	v_rcp_f32_e32 v136, v136
	s_nop 0
	v_cndmask_b32_e64 v198, 0, 32, s[6:7]
	v_ldexp_f32 v195, v195, v198
	v_log_f32_e32 v195, v195
	v_fma_f32 v136, v190, v136, v154
	v_cndmask_b32_e32 v198, 0, v171, vcc
	v_cmp_gt_f32_e32 vcc, s87, v136
	v_sub_f32_e32 v194, v194, v198
	v_mul_f32_e32 v198, 0x3f317217, v195
	v_cndmask_b32_e64 v199, 0, 32, vcc
	v_ldexp_f32 v136, v136, v199
	v_fma_f32 v198, v195, s92, -v198
	v_log_f32_e32 v136, v136
	v_fmac_f32_e32 v198, 0x3377d1cf, v195
	v_fmac_f32_e32 v198, 0x3f317217, v195
	v_cmp_lt_f32_e64 s[8:9], |v195|, s93
	v_cvt_pk_f16_f32 v194, v191, v194
	s_nop 0
	v_cndmask_b32_e64 v195, v195, v198, s[8:9]
	v_cndmask_b32_e64 v198, 0, v171, s[6:7]
	v_sub_f32_e32 v195, v195, v198
	v_mul_f32_e32 v198, 0x3f317217, v136
	v_fma_f32 v198, v136, s92, -v198
	v_fmac_f32_e32 v198, 0x3377d1cf, v136
	v_fmac_f32_e32 v198, 0x3f317217, v136
	v_cmp_lt_f32_e64 s[6:7], |v136|, s93
	s_nop 1
	v_cndmask_b32_e64 v136, v136, v198, s[6:7]
	v_cndmask_b32_e32 v198, 0, v171, vcc
	v_sub_f32_e32 v136, v136, v198
	v_cvt_pk_f16_f32 v195, v195, v136
	global_store_dwordx4 v[196:197], v[192:195], off offset:256
	v_fmamk_f32 v136, v215, 0x3a800000, v170
	v_mul_f32_e32 v191, 0x4b800000, v136
	v_cmp_gt_f32_e32 vcc, s87, v136
	s_nop 1
	v_cndmask_b32_e32 v136, v136, v191, vcc
	v_rsq_f32_e32 v136, v136
	s_nop 0
	v_mul_f32_e32 v191, 0x45800000, v136
	v_cndmask_b32_e32 v136, v136, v191, vcc
	v_mul_f32_e32 v191, v28, v136
	v_mul_f32_e32 v191, 0xbfb8aa3b, v191
	v_exp_f32_e32 v191, v191
	v_mul_f32_e32 v193, v29, v136
	v_mul_f32_e32 v193, 0xbfb8aa3b, v193
	v_exp_f32_e32 v193, v193
	v_add_f32_e32 v191, 1.0, v191
	v_rcp_f32_e32 v191, v191
	v_add_f32_e32 v193, 1.0, v193
	v_rcp_f32_e32 v193, v193
	v_fma_f32 v191, v176, v191, v175
	v_cmp_gt_f32_e32 vcc, s87, v191
	s_nop 1
	v_cndmask_b32_e64 v192, 0, 32, vcc
	v_ldexp_f32 v191, v191, v192
	v_log_f32_e32 v191, v191
	s_nop 0
	v_mul_f32_e32 v192, 0x3f317217, v191
	v_fma_f32 v192, v191, s92, -v192
	v_fmac_f32_e32 v192, 0x3377d1cf, v191
	v_fmac_f32_e32 v192, 0x3f317217, v191
	v_cmp_lt_f32_e64 s[6:7], |v191|, s93
	s_nop 1
	v_cndmask_b32_e64 v191, v191, v192, s[6:7]
	v_cndmask_b32_e32 v192, 0, v171, vcc
	v_sub_f32_e32 v191, v191, v192
	v_fma_f32 v192, v177, v193, v174
	v_cmp_gt_f32_e32 vcc, s87, v192
	s_nop 1
	v_cndmask_b32_e64 v193, 0, 32, vcc
	v_ldexp_f32 v192, v192, v193
	v_mul_f32_e32 v193, v30, v136
	v_mul_f32_e32 v193, 0xbfb8aa3b, v193
	v_exp_f32_e32 v193, v193
	v_log_f32_e32 v192, v192
	v_cndmask_b32_e32 v195, 0, v171, vcc
	v_add_f32_e32 v193, 1.0, v193
	v_rcp_f32_e32 v193, v193
	v_mul_f32_e32 v194, 0x3f317217, v192
	v_fma_f32 v194, v192, s92, -v194
	v_fmac_f32_e32 v194, 0x3377d1cf, v192
	v_fmac_f32_e32 v194, 0x3f317217, v192
	v_cmp_lt_f32_e64 s[6:7], |v192|, s93
	v_fma_f32 v193, v178, v193, v173
	s_nop 0
	v_cndmask_b32_e64 v192, v192, v194, s[6:7]
	v_cmp_gt_f32_e64 s[6:7], s87, v193
	v_sub_f32_e32 v192, v192, v195
	v_cvt_pk_f16_f32 v192, v191, v192
	v_cndmask_b32_e64 v194, 0, 32, s[6:7]
	v_ldexp_f32 v193, v193, v194
	v_mul_f32_e32 v194, v31, v136
	v_mul_f32_e32 v194, 0xbfb8aa3b, v194
	v_exp_f32_e32 v194, v194
	v_log_f32_e32 v193, v193
	v_add_f32_e32 v194, 1.0, v194
	v_rcp_f32_e32 v194, v194
	v_mul_f32_e32 v195, 0x3f317217, v193
	v_fma_f32 v195, v193, s92, -v195
	v_fmac_f32_e32 v195, 0x3377d1cf, v193
	v_fma_f32 v194, v183, v194, v172
	v_cmp_gt_f32_e32 vcc, s87, v194
	v_fmac_f32_e32 v195, 0x3f317217, v193
	v_cmp_lt_f32_e64 s[8:9], |v193|, s93
	v_cndmask_b32_e64 v196, 0, 32, vcc
	v_ldexp_f32 v194, v194, v196
	v_mul_f32_e32 v196, v24, v136
	v_log_f32_e32 v194, v194
	v_mul_f32_e32 v196, 0xbfb8aa3b, v196
	v_exp_f32_e32 v196, v196
	v_cndmask_b32_e64 v193, v193, v195, s[8:9]
	v_cndmask_b32_e64 v195, 0, v171, s[6:7]
	v_sub_f32_e32 v193, v193, v195
	v_mul_f32_e32 v195, 0x3f317217, v194
	v_fma_f32 v195, v194, s92, -v195
	v_add_f32_e32 v196, 1.0, v196
	v_fmac_f32_e32 v195, 0x3377d1cf, v194
	v_rcp_f32_e32 v196, v196
	v_fmac_f32_e32 v195, 0x3f317217, v194
	v_cmp_lt_f32_e64 s[6:7], |v194|, s93
	v_fma_f32 v196, v149, v196, v165
	s_nop 0
	v_cndmask_b32_e64 v194, v194, v195, s[6:7]
	v_cndmask_b32_e32 v195, 0, v171, vcc
	v_sub_f32_e32 v194, v194, v195
	v_cvt_pk_f16_f32 v193, v193, v194
	v_mul_f32_e32 v194, v25, v136
	v_cmp_gt_f32_e32 vcc, s87, v196
	v_mul_f32_e32 v194, 0xbfb8aa3b, v194
	v_exp_f32_e32 v194, v194
	v_cndmask_b32_e64 v197, 0, 32, vcc
	v_ldexp_f32 v196, v196, v197
	v_log_f32_e32 v196, v196
	v_add_f32_e32 v194, 1.0, v194
	v_rcp_f32_e32 v194, v194
	v_cndmask_b32_e32 v195, 0, v171, vcc
	v_mul_f32_e32 v191, 0x3f317217, v196
	v_fma_f32 v191, v196, s92, -v191
	v_fmac_f32_e32 v191, 0x3377d1cf, v196
	v_fmac_f32_e32 v191, 0x3f317217, v196
	v_cmp_lt_f32_e64 s[6:7], |v196|, s93
	v_fma_f32 v194, v179, v194, v164
	v_cmp_gt_f32_e32 vcc, s87, v194
	v_cndmask_b32_e64 v191, v196, v191, s[6:7]
	v_sub_f32_e32 v191, v191, v195
	v_cndmask_b32_e64 v195, 0, 32, vcc
	v_ldexp_f32 v194, v194, v195
	v_mul_f32_e32 v195, v26, v136
	v_mul_f32_e32 v195, 0xbfb8aa3b, v195
	v_exp_f32_e32 v195, v195
	v_log_f32_e32 v194, v194
	v_cndmask_b32_e32 v197, 0, v171, vcc
	v_add_f32_e32 v195, 1.0, v195
	v_rcp_f32_e32 v195, v195
	v_mul_f32_e32 v196, 0x3f317217, v194
	v_fma_f32 v196, v194, s92, -v196
	v_fmac_f32_e32 v196, 0x3377d1cf, v194
; __device__ __forceinline__ float fsigm(float x) { return __builtin_amdgcn_rcpf(1.f + __expf(-x)); }
; __device__ __forceinline__ float row_rs(const float* ssq, int row) { return ssq ? rsqrtf(ssq[row] * (1.f / 1024.f) + RMS_EPS) : 1.f; }
;     __device__ __forceinline__ void operator()(const f32x4 (&acc)[2][2][4][2], const Unit& u, int wr, int wc, int fr, int fq) const {
;     ...
;                 for (int m = 0; m < 4; ++m) { const int row = row0 + ai * HALF + m * 16; const float rs = row_rs(ssq, row);
; #pragma unroll
;                     for (int bj = 0; bj < 2; ++bj) { f16x4 o[2];
; #pragma unroll
;                         for (int n = 0; n < 2; ++n) { const f32x4 p = acc[ai][bj][m][n] * rs;
; #pragma unroll
;                             for (int j = 0; j < 4; ++j) { const float l = lb[bj][n][j]; const float f = l + (1.f - l) * fsigm(p[j]); o[n][j] = (_Float16)__logf(f); } }
;                         const u32x2 a0 = __builtin_bit_cast(u32x2, o[0]), a1 = __builtin_bit_cast(u32x2, o[1]); u32x4 w; w.x = a0.x; w.y = a0.y; w.z = a1.x; w.w = a1.y;
;                         *(u32x4*)(LF + (size_t)row * 512 + cbase + bj * HALF) = w; } }
	v_fmac_f32_e32 v196, 0x3f317217, v194
	v_cmp_lt_f32_e64 s[6:7], |v194|, s93
	v_fma_f32 v195, v180, v195, v163
	s_nop 0
	v_cndmask_b32_e64 v194, v194, v196, s[6:7]
	v_cmp_gt_f32_e64 s[6:7], s87, v195
	v_sub_f32_e32 v194, v194, v197
	v_cvt_pk_f16_f32 v194, v191, v194
	v_cndmask_b32_e64 v196, 0, 32, s[6:7]
	v_ldexp_f32 v195, v195, v196
	v_mul_f32_e32 v196, v27, v136
	v_mul_f32_e32 v196, 0xbfb8aa3b, v196
	v_exp_f32_e32 v196, v196
	v_log_f32_e32 v195, v195
	v_add_f32_e32 v196, 1.0, v196
	v_rcp_f32_e32 v196, v196
	v_mul_f32_e32 v197, 0x3f317217, v195
	v_fma_f32 v197, v195, s92, -v197
	v_fmac_f32_e32 v197, 0x3377d1cf, v195
	v_fma_f32 v196, v188, v196, v162
	v_cmp_gt_f32_e32 vcc, s87, v196
	v_fmac_f32_e32 v197, 0x3f317217, v195
	v_cmp_lt_f32_e64 s[8:9], |v195|, s93
	v_cndmask_b32_e64 v198, 0, 32, vcc
	v_ldexp_f32 v196, v196, v198
	v_log_f32_e32 v196, v196
	v_cndmask_b32_e64 v195, v195, v197, s[8:9]
	v_cndmask_b32_e64 v197, 0, v171, s[6:7]
	v_mul_f32_e32 v198, v20, v136
	v_sub_f32_e32 v195, v195, v197
	v_mul_f32_e32 v197, 0x3f317217, v196
	v_mul_f32_e32 v198, 0xbfb8aa3b, v198
	v_fma_f32 v197, v196, s92, -v197
	v_exp_f32_e32 v198, v198
	v_fmac_f32_e32 v197, 0x3377d1cf, v196
	v_fmac_f32_e32 v197, 0x3f317217, v196
	v_cmp_lt_f32_e64 s[6:7], |v196|, s93
	s_nop 1
	v_cndmask_b32_e64 v196, v196, v197, s[6:7]
	v_cndmask_b32_e32 v197, 0, v171, vcc
	v_sub_f32_e32 v196, v196, v197
	v_add_f32_e32 v197, 1.0, v198
	v_rcp_f32_e32 v198, v197
	v_cvt_pk_f16_f32 v195, v195, v196
	v_lshl_add_u64 v[196:197], v[152:153], 0, s[42:43]
	v_fma_f32 v191, v184, v198, v161
	v_cmp_gt_f32_e32 vcc, s87, v191
	s_nop 1
	v_cndmask_b32_e64 v198, 0, 32, vcc
	v_ldexp_f32 v191, v191, v198
	v_add_co_u32_e64 v198, s[6:7], s90, v152
	v_log_f32_e32 v191, v191
	s_nop 0
	v_addc_co_u32_e64 v199, s[6:7], 0, v153, s[6:7]
	global_store_dwordx4 v[198:199], v[192:195], off
	v_cmp_lt_f32_e64 s[6:7], |v191|, s93
	s_nop 0
	v_mul_f32_e32 v193, v21, v136
	v_mul_f32_e32 v193, 0xbfb8aa3b, v193
	v_exp_f32_e32 v193, v193
	v_mul_f32_e32 v192, 0x3f317217, v191
	v_fma_f32 v192, v191, s92, -v192
	v_fmac_f32_e32 v192, 0x3377d1cf, v191
	v_add_f32_e32 v193, 1.0, v193
	v_rcp_f32_e32 v193, v193
	v_fmac_f32_e32 v192, 0x3f317217, v191
	v_cndmask_b32_e64 v191, v191, v192, s[6:7]
	v_cndmask_b32_e32 v192, 0, v171, vcc
	v_sub_f32_e32 v191, v191, v192
	v_fma_f32 v192, v181, v193, v160
	v_cmp_gt_f32_e32 vcc, s87, v192
	s_nop 1
	v_cndmask_b32_e64 v193, 0, 32, vcc
	v_ldexp_f32 v192, v192, v193
	v_mul_f32_e32 v193, v22, v136
	v_mul_f32_e32 v193, 0xbfb8aa3b, v193
	v_exp_f32_e32 v193, v193
	v_log_f32_e32 v192, v192
	v_cndmask_b32_e32 v195, 0, v171, vcc
	v_add_f32_e32 v193, 1.0, v193
	v_rcp_f32_e32 v193, v193
	v_mul_f32_e32 v194, 0x3f317217, v192
	v_fma_f32 v194, v192, s92, -v194
	v_fmac_f32_e32 v194, 0x3377d1cf, v192
	v_fmac_f32_e32 v194, 0x3f317217, v192
	v_cmp_lt_f32_e64 s[6:7], |v192|, s93
	v_fma_f32 v193, v185, v193, v159
	s_nop 0
	v_cndmask_b32_e64 v192, v192, v194, s[6:7]
	v_cmp_gt_f32_e64 s[6:7], s87, v193
	v_sub_f32_e32 v192, v192, v195
	v_cvt_pk_f16_f32 v192, v191, v192
	v_cndmask_b32_e64 v194, 0, 32, s[6:7]
	v_ldexp_f32 v193, v193, v194
	v_mul_f32_e32 v194, v23, v136
	v_mul_f32_e32 v194, 0xbfb8aa3b, v194
	v_exp_f32_e32 v194, v194
	v_log_f32_e32 v193, v193
	v_add_f32_e32 v194, 1.0, v194
	v_rcp_f32_e32 v194, v194
	v_mul_f32_e32 v195, 0x3f317217, v193
	v_fma_f32 v195, v193, s92, -v195
	v_fmac_f32_e32 v195, 0x3377d1cf, v193
	v_fma_f32 v194, v186, v194, v158
	v_cmp_gt_f32_e32 vcc, s87, v194
	v_fmac_f32_e32 v195, 0x3f317217, v193
	v_cmp_lt_f32_e64 s[8:9], |v193|, s93
	v_cndmask_b32_e64 v198, 0, 32, vcc
	v_ldexp_f32 v194, v194, v198
	v_mul_f32_e32 v198, v16, v136
	v_log_f32_e32 v194, v194
	v_mul_f32_e32 v198, 0xbfb8aa3b, v198
	v_exp_f32_e32 v198, v198
	v_cndmask_b32_e64 v193, v193, v195, s[8:9]
	v_cndmask_b32_e64 v195, 0, v171, s[6:7]
	v_sub_f32_e32 v193, v193, v195
	v_mul_f32_e32 v195, 0x3f317217, v194
	v_fma_f32 v195, v194, s92, -v195
	v_add_f32_e32 v198, 1.0, v198
	v_fmac_f32_e32 v195, 0x3377d1cf, v194
	v_rcp_f32_e32 v198, v198
	v_fmac_f32_e32 v195, 0x3f317217, v194
	v_cmp_lt_f32_e64 s[6:7], |v194|, s93
	v_fma_f32 v198, v187, v198, v157
	s_nop 0
	v_cndmask_b32_e64 v194, v194, v195, s[6:7]
	v_cndmask_b32_e32 v195, 0, v171, vcc
	v_sub_f32_e32 v194, v194, v195
	v_cvt_pk_f16_f32 v193, v193, v194
	v_mul_f32_e32 v194, v17, v136
	v_cmp_gt_f32_e32 vcc, s87, v198
	v_mul_f32_e32 v194, 0xbfb8aa3b, v194
	v_exp_f32_e32 v194, v194
	v_cndmask_b32_e64 v199, 0, 32, vcc
	v_ldexp_f32 v198, v198, v199
	v_log_f32_e32 v198, v198
	v_add_f32_e32 v194, 1.0, v194
	v_rcp_f32_e32 v194, v194
	v_cndmask_b32_e32 v195, 0, v171, vcc
	v_mul_f32_e32 v191, 0x3f317217, v198
	v_fma_f32 v191, v198, s92, -v191
	v_fmac_f32_e32 v191, 0x3377d1cf, v198
	v_fmac_f32_e32 v191, 0x3f317217, v198
	v_cmp_lt_f32_e64 s[6:7], |v198|, s93
	v_fma_f32 v194, v182, v194, v156
	v_cmp_gt_f32_e32 vcc, s87, v194
	v_cndmask_b32_e64 v191, v198, v191, s[6:7]
	v_sub_f32_e32 v191, v191, v195
	v_cndmask_b32_e64 v195, 0, 32, vcc
	v_ldexp_f32 v194, v194, v195
	v_mul_f32_e32 v195, v18, v136
	v_mul_f32_e32 v195, 0xbfb8aa3b, v195
	v_exp_f32_e32 v195, v195
	v_log_f32_e32 v194, v194
	v_mul_f32_e32 v136, v19, v136
	v_mul_f32_e32 v136, 0xbfb8aa3b, v136
	v_add_f32_e32 v195, 1.0, v195
	v_rcp_f32_e32 v195, v195
	v_exp_f32_e32 v136, v136
	v_mul_f32_e32 v198, 0x3f317217, v194
	v_fma_f32 v198, v194, s92, -v198
	v_fmac_f32_e32 v198, 0x3377d1cf, v194
	v_fmac_f32_e32 v198, 0x3f317217, v194
	v_cmp_lt_f32_e64 s[6:7], |v194|, s93
	v_fma_f32 v195, v189, v195, v155
	v_add_f32_e32 v136, 1.0, v136
	v_cndmask_b32_e64 v194, v194, v198, s[6:7]
	v_cmp_gt_f32_e64 s[6:7], s87, v195
	v_rcp_f32_e32 v136, v136
	s_nop 0
; __device__ __forceinline__ float fsigm(float x) { return __builtin_amdgcn_rcpf(1.f + __expf(-x)); }
; __device__ __forceinline__ float row_rs(const float* ssq, int row) { return ssq ? rsqrtf(ssq[row] * (1.f / 1024.f) + RMS_EPS) : 1.f; }
;     __device__ __forceinline__ void operator()(const f32x4 (&acc)[2][2][4][2], const Unit& u, int wr, int wc, int fr, int fq) const {
;     ...
;                 for (int m = 0; m < 4; ++m) { const int row = row0 + ai * HALF + m * 16; const float rs = row_rs(ssq, row);
; #pragma unroll
;                     for (int bj = 0; bj < 2; ++bj) { f16x4 o[2];
; #pragma unroll
;                         for (int n = 0; n < 2; ++n) { const f32x4 p = acc[ai][bj][m][n] * rs;
; #pragma unroll
;                             for (int j = 0; j < 4; ++j) { const float l = lb[bj][n][j]; const float f = l + (1.f - l) * fsigm(p[j]); o[n][j] = (_Float16)__logf(f); } }
;                         const u32x2 a0 = __builtin_bit_cast(u32x2, o[0]), a1 = __builtin_bit_cast(u32x2, o[1]); u32x4 w; w.x = a0.x; w.y = a0.y; w.z = a1.x; w.w = a1.y;
;                         *(u32x4*)(LF + (size_t)row * 512 + cbase + bj * HALF) = w; } }
	v_cndmask_b32_e64 v198, 0, 32, s[6:7]
	v_ldexp_f32 v195, v195, v198
	v_log_f32_e32 v195, v195
	v_fma_f32 v136, v190, v136, v154
	v_cndmask_b32_e32 v198, 0, v171, vcc
	v_cmp_gt_f32_e32 vcc, s87, v136
	v_sub_f32_e32 v194, v194, v198
	v_mul_f32_e32 v198, 0x3f317217, v195
	v_cndmask_b32_e64 v199, 0, 32, vcc
	v_ldexp_f32 v136, v136, v199
	v_fma_f32 v198, v195, s92, -v198
	v_log_f32_e32 v136, v136
	v_fmac_f32_e32 v198, 0x3377d1cf, v195
	v_fmac_f32_e32 v198, 0x3f317217, v195
	v_cmp_lt_f32_e64 s[8:9], |v195|, s93
	v_cvt_pk_f16_f32 v194, v191, v194
	s_nop 0
	v_cndmask_b32_e64 v195, v195, v198, s[8:9]
	v_cndmask_b32_e64 v198, 0, v171, s[6:7]
	v_sub_f32_e32 v195, v195, v198
	v_mul_f32_e32 v198, 0x3f317217, v136
	v_fma_f32 v198, v136, s92, -v198
	v_fmac_f32_e32 v198, 0x3377d1cf, v136
	v_fmac_f32_e32 v198, 0x3f317217, v136
	v_cmp_lt_f32_e64 s[6:7], |v136|, s93
	s_nop 1
	v_cndmask_b32_e64 v136, v136, v198, s[6:7]
	v_cndmask_b32_e32 v198, 0, v171, vcc
	v_sub_f32_e32 v136, v136, v198
	v_cvt_pk_f16_f32 v195, v195, v136
	global_store_dwordx4 v[196:197], v[192:195], off offset:256
	v_fmamk_f32 v136, v216, 0x3a800000, v170
	v_mul_f32_e32 v150, 0x4b800000, v136
	v_cmp_gt_f32_e32 vcc, s87, v136
	s_nop 1
	v_cndmask_b32_e32 v136, v136, v150, vcc
	v_rsq_f32_e32 v136, v136
	s_nop 0
	v_mul_f32_e32 v150, 0x45800000, v136
	v_cndmask_b32_e32 v136, v136, v150, vcc
	v_mul_f32_e32 v150, v12, v136
	v_mul_f32_e32 v150, 0xbfb8aa3b, v150
	v_exp_f32_e32 v150, v150
	s_nop 0
	v_add_f32_e32 v150, 1.0, v150
	v_rcp_f32_e32 v150, v150
	s_nop 0
	v_fmac_f32_e32 v175, v176, v150
	v_cmp_gt_f32_e32 vcc, s87, v175
	s_nop 1
	v_cndmask_b32_e64 v150, 0, 32, vcc
	v_ldexp_f32 v150, v175, v150
	v_mul_f32_e32 v175, v13, v136
	v_mul_f32_e32 v175, 0xbfb8aa3b, v175
	v_exp_f32_e32 v175, v175
	v_log_f32_e32 v150, v150
	v_add_f32_e32 v175, 1.0, v175
	v_rcp_f32_e32 v175, v175
	v_mul_f32_e32 v151, 0x3f317217, v150
	v_fma_f32 v151, v150, s92, -v151
	v_fmac_f32_e32 v151, 0x3377d1cf, v150
	v_fmac_f32_e32 v151, 0x3f317217, v150
	v_cmp_lt_f32_e64 s[6:7], |v150|, s93
	v_fmac_f32_e32 v174, v177, v175
	s_nop 0
	v_cndmask_b32_e64 v150, v150, v151, s[6:7]
	v_cndmask_b32_e32 v151, 0, v171, vcc
	v_cmp_gt_f32_e32 vcc, s87, v174
	v_sub_f32_e32 v150, v150, v151
	s_nop 0
	v_cndmask_b32_e64 v151, 0, 32, vcc
	v_ldexp_f32 v151, v174, v151
	v_mul_f32_e32 v174, v14, v136
	v_mul_f32_e32 v174, 0xbfb8aa3b, v174
	v_exp_f32_e32 v174, v174
	v_log_f32_e32 v151, v151
	v_add_f32_e32 v174, 1.0, v174
	v_rcp_f32_e32 v174, v174
	v_mul_f32_e32 v175, 0x3f317217, v151
	v_fma_f32 v175, v151, s92, -v175
	v_fmac_f32_e32 v175, 0x3377d1cf, v151
	v_fmac_f32_e32 v175, 0x3f317217, v151
	v_cmp_lt_f32_e64 s[6:7], |v151|, s93
	v_fmac_f32_e32 v173, v178, v174
	s_nop 0
	v_cndmask_b32_e64 v151, v151, v175, s[6:7]
	v_cmp_gt_f32_e64 s[6:7], s87, v173
	v_cndmask_b32_e32 v175, 0, v171, vcc
	v_sub_f32_e32 v151, v151, v175
	v_cndmask_b32_e64 v174, 0, 32, s[6:7]
	v_ldexp_f32 v173, v173, v174
	v_mul_f32_e32 v174, v15, v136
	v_mul_f32_e32 v174, 0xbfb8aa3b, v174
	v_exp_f32_e32 v174, v174
	v_log_f32_e32 v173, v173
	v_add_f32_e32 v174, 1.0, v174
	v_mul_f32_e32 v175, 0x3f317217, v173
	v_rcp_f32_e32 v174, v174
	v_fma_f32 v175, v173, s92, -v175
	v_fmac_f32_e32 v175, 0x3377d1cf, v173
	v_fmac_f32_e32 v175, 0x3f317217, v173
	v_cmp_lt_f32_e64 s[8:9], |v173|, s93
	v_fmac_f32_e32 v172, v183, v174
	v_cmp_gt_f32_e32 vcc, s87, v172
	v_cndmask_b32_e64 v173, v173, v175, s[8:9]
	v_mul_f32_e32 v175, v8, v136
	v_mul_f32_e32 v175, 0xbfb8aa3b, v175
	v_cndmask_b32_e64 v174, 0, 32, vcc
	v_exp_f32_e32 v175, v175
	v_ldexp_f32 v172, v172, v174
	v_log_f32_e32 v172, v172
	v_cndmask_b32_e64 v174, 0, v171, s[6:7]
	v_add_f32_e32 v175, 1.0, v175
	v_rcp_f32_e32 v175, v175
	v_sub_f32_e32 v173, v173, v174
	v_mul_f32_e32 v174, 0x3f317217, v172
	v_fma_f32 v174, v172, s92, -v174
	v_fmac_f32_e32 v174, 0x3377d1cf, v172
	v_fmac_f32_e32 v174, 0x3f317217, v172
	v_cmp_lt_f32_e64 s[6:7], |v172|, s93
	v_fmac_f32_e32 v165, v149, v175
	s_nop 0
	v_cndmask_b32_e64 v172, v172, v174, s[6:7]
	v_cndmask_b32_e32 v174, 0, v171, vcc
	v_cmp_gt_f32_e32 vcc, s87, v165
	s_nop 1
	v_cndmask_b32_e64 v149, 0, 32, vcc
	v_ldexp_f32 v149, v165, v149
	v_sub_f32_e32 v165, v172, v174
	v_cvt_pk_f16_f32 v172, v150, v151
	v_mul_f32_e32 v151, v9, v136
	v_mul_f32_e32 v151, 0xbfb8aa3b, v151
	v_exp_f32_e32 v151, v151
	v_log_f32_e32 v149, v149
	v_cvt_pk_f16_f32 v173, v173, v165
	v_add_f32_e32 v151, 1.0, v151
	v_rcp_f32_e32 v151, v151
	v_mul_f32_e32 v150, 0x3f317217, v149
	v_fma_f32 v150, v149, s92, -v150
	v_fmac_f32_e32 v150, 0x3377d1cf, v149
	v_fmac_f32_e32 v150, 0x3f317217, v149
	v_cmp_lt_f32_e64 s[6:7], |v149|, s93
	v_fmac_f32_e32 v164, v179, v151
	v_mul_f32_e32 v151, v10, v136
	v_cndmask_b32_e64 v149, v149, v150, s[6:7]
	v_cndmask_b32_e32 v150, 0, v171, vcc
	v_cmp_gt_f32_e32 vcc, s87, v164
	v_mul_f32_e32 v151, 0xbfb8aa3b, v151
	v_sub_f32_e32 v149, v149, v150
	v_cndmask_b32_e64 v150, 0, 32, vcc
	v_exp_f32_e32 v151, v151
	v_ldexp_f32 v150, v164, v150
	v_log_f32_e32 v150, v150
	v_add_f32_e32 v151, 1.0, v151
	v_rcp_f32_e32 v151, v151
	v_mul_f32_e32 v164, 0x3f317217, v150
	v_fma_f32 v164, v150, s92, -v164
	v_fmac_f32_e32 v164, 0x3377d1cf, v150
	v_fmac_f32_e32 v164, 0x3f317217, v150
	v_cmp_lt_f32_e64 s[6:7], |v150|, s93
	v_fmac_f32_e32 v163, v180, v151
	s_nop 0
	v_cndmask_b32_e64 v150, v150, v164, s[6:7]
	v_cmp_gt_f32_e64 s[6:7], s87, v163
	v_cndmask_b32_e32 v164, 0, v171, vcc
	v_sub_f32_e32 v150, v150, v164
	v_cndmask_b32_e64 v151, 0, 32, s[6:7]
	v_ldexp_f32 v151, v163, v151
	v_mul_f32_e32 v163, v11, v136
	v_mul_f32_e32 v163, 0xbfb8aa3b, v163
	v_exp_f32_e32 v163, v163
	v_log_f32_e32 v151, v151
	v_cvt_pk_f16_f32 v174, v149, v150
; __device__ __forceinline__ float fsigm(float x) { return __builtin_amdgcn_rcpf(1.f + __expf(-x)); }
; __device__ __forceinline__ float row_rs(const float* ssq, int row) { return ssq ? rsqrtf(ssq[row] * (1.f / 1024.f) + RMS_EPS) : 1.f; }
;     __device__ __forceinline__ void operator()(const f32x4 (&acc)[2][2][4][2], const Unit& u, int wr, int wc, int fr, int fq) const {
;     ...
;                 for (int m = 0; m < 4; ++m) { const int row = row0 + ai * HALF + m * 16; const float rs = row_rs(ssq, row);
; #pragma unroll
;                     for (int bj = 0; bj < 2; ++bj) { f16x4 o[2];
; #pragma unroll
;                         for (int n = 0; n < 2; ++n) { const f32x4 p = acc[ai][bj][m][n] * rs;
; #pragma unroll
;                             for (int j = 0; j < 4; ++j) { const float l = lb[bj][n][j]; const float f = l + (1.f - l) * fsigm(p[j]); o[n][j] = (_Float16)__logf(f); } }
;                         const u32x2 a0 = __builtin_bit_cast(u32x2, o[0]), a1 = __builtin_bit_cast(u32x2, o[1]); u32x4 w; w.x = a0.x; w.y = a0.y; w.z = a1.x; w.w = a1.y;
;                         *(u32x4*)(LF + (size_t)row * 512 + cbase + bj * HALF) = w; } }
	v_add_f32_e32 v163, 1.0, v163
	v_rcp_f32_e32 v163, v163
	v_mul_f32_e32 v164, 0x3f317217, v151
	v_fma_f32 v164, v151, s92, -v164
	v_fmac_f32_e32 v164, 0x3377d1cf, v151
	v_fmac_f32_e32 v162, v188, v163
	v_cmp_gt_f32_e32 vcc, s87, v162
	v_fmac_f32_e32 v164, 0x3f317217, v151
	v_cmp_lt_f32_e64 s[8:9], |v151|, s93
	v_cndmask_b32_e64 v163, 0, 32, vcc
	v_ldexp_f32 v162, v162, v163
	v_log_f32_e32 v162, v162
	v_cndmask_b32_e64 v151, v151, v164, s[8:9]
	v_cndmask_b32_e64 v163, 0, v171, s[6:7]
	v_mul_f32_e32 v164, v4, v136
	v_sub_f32_e32 v151, v151, v163
	v_mul_f32_e32 v163, 0x3f317217, v162
	v_mul_f32_e32 v164, 0xbfb8aa3b, v164
	v_fma_f32 v163, v162, s92, -v163
	v_exp_f32_e32 v164, v164
	v_fmac_f32_e32 v163, 0x3377d1cf, v162
	v_fmac_f32_e32 v163, 0x3f317217, v162
	v_cmp_lt_f32_e64 s[6:7], |v162|, s93
	s_nop 1
	v_cndmask_b32_e64 v162, v162, v163, s[6:7]
	v_cndmask_b32_e32 v163, 0, v171, vcc
	v_sub_f32_e32 v162, v162, v163
	v_add_f32_e32 v163, 1.0, v164
	v_rcp_f32_e32 v164, v163
	v_add_co_u32_e64 v150, s[6:7], s91, v152
	v_cvt_pk_f16_f32 v175, v151, v162
	s_nop 0
	v_addc_co_u32_e64 v151, s[6:7], 0, v153, s[6:7]
	v_fmac_f32_e32 v161, v184, v164
	global_store_dwordx4 v[150:151], v[172:175], off
	v_mul_f32_e32 v151, v5, v136
	v_cmp_gt_f32_e32 vcc, s87, v161
	v_mul_f32_e32 v151, 0xbfb8aa3b, v151
	v_exp_f32_e32 v151, v151
	v_cndmask_b32_e64 v149, 0, 32, vcc
	v_ldexp_f32 v149, v161, v149
	v_log_f32_e32 v149, v149
	v_add_f32_e32 v151, 1.0, v151
	v_rcp_f32_e32 v151, v151
	v_lshl_add_u64 v[162:163], v[152:153], 0, s[62:63]
	v_mul_f32_e32 v150, 0x3f317217, v149
	v_fma_f32 v150, v149, s92, -v150
	v_fmac_f32_e32 v150, 0x3377d1cf, v149
	v_fmac_f32_e32 v150, 0x3f317217, v149
	v_cmp_lt_f32_e64 s[6:7], |v149|, s93
	v_fmac_f32_e32 v160, v181, v151
	v_mul_f32_e32 v151, v6, v136
	v_cndmask_b32_e64 v149, v149, v150, s[6:7]
	v_cndmask_b32_e32 v150, 0, v171, vcc
	v_cmp_gt_f32_e32 vcc, s87, v160
	v_sub_f32_e32 v149, v149, v150
	v_mul_f32_e32 v151, 0xbfb8aa3b, v151
	v_cndmask_b32_e64 v150, 0, 32, vcc
	v_ldexp_f32 v150, v160, v150
	v_log_f32_e32 v150, v150
	v_exp_f32_e32 v151, v151
	v_cndmask_b32_e32 v153, 0, v171, vcc
	v_mul_f32_e32 v152, 0x3f317217, v150
	v_fma_f32 v152, v150, s92, -v152
	v_fmac_f32_e32 v152, 0x3377d1cf, v150
	v_fmac_f32_e32 v152, 0x3f317217, v150
	v_cmp_lt_f32_e64 s[6:7], |v150|, s93
	v_add_f32_e32 v151, 1.0, v151
	v_rcp_f32_e32 v151, v151
	v_cndmask_b32_e64 v150, v150, v152, s[6:7]
	v_mul_f32_e32 v152, v7, v136
	v_mul_f32_e32 v152, 0xbfb8aa3b, v152
	v_exp_f32_e32 v152, v152
	v_fmac_f32_e32 v159, v185, v151
	v_cmp_gt_f32_e64 s[6:7], s87, v159
	v_sub_f32_e32 v150, v150, v153
	v_add_f32_e32 v152, 1.0, v152
	v_rcp_f32_e32 v152, v152
	v_cndmask_b32_e64 v151, 0, 32, s[6:7]
	v_ldexp_f32 v151, v159, v151
	v_log_f32_e32 v151, v151
	v_fmac_f32_e32 v158, v186, v152
	v_cmp_gt_f32_e32 vcc, s87, v158
	v_cvt_pk_f16_f32 v150, v149, v150
	v_mul_f32_e32 v153, 0x3f317217, v151
	v_cndmask_b32_e64 v152, 0, 32, vcc
	v_ldexp_f32 v152, v158, v152
	v_mul_f32_e32 v158, v0, v136
	v_mul_f32_e32 v158, 0xbfb8aa3b, v158
	v_exp_f32_e32 v158, v158
	v_fma_f32 v153, v151, s92, -v153
	v_log_f32_e32 v152, v152
	v_fmac_f32_e32 v153, 0x3377d1cf, v151
	v_fmac_f32_e32 v153, 0x3f317217, v151
	v_cmp_lt_f32_e64 s[8:9], |v151|, s93
	v_add_f32_e32 v158, 1.0, v158
	v_rcp_f32_e32 v158, v158
	v_cndmask_b32_e64 v151, v151, v153, s[8:9]
	v_cndmask_b32_e64 v153, 0, v171, s[6:7]
	v_sub_f32_e32 v151, v151, v153
	v_mul_f32_e32 v153, 0x3f317217, v152
	v_fma_f32 v153, v152, s92, -v153
	v_fmac_f32_e32 v153, 0x3377d1cf, v152
	v_fmac_f32_e32 v153, 0x3f317217, v152
	v_cmp_lt_f32_e64 s[6:7], |v152|, s93
	v_fmac_f32_e32 v157, v187, v158
	s_nop 0
	v_cndmask_b32_e64 v152, v152, v153, s[6:7]
	v_cndmask_b32_e32 v153, 0, v171, vcc
	v_cmp_gt_f32_e32 vcc, s87, v157
	v_sub_f32_e32 v152, v152, v153
	v_cvt_pk_f16_f32 v151, v151, v152
	v_cndmask_b32_e64 v158, 0, 32, vcc
	v_mul_f32_e32 v152, v1, v136
	v_ldexp_f32 v157, v157, v158
	v_mul_f32_e32 v152, 0xbfb8aa3b, v152
	v_log_f32_e32 v157, v157
	v_exp_f32_e32 v152, v152
	v_cndmask_b32_e32 v153, 0, v171, vcc
	v_mul_f32_e32 v149, 0x3f317217, v157
	v_add_f32_e32 v152, 1.0, v152
	v_fma_f32 v149, v157, s92, -v149
	v_rcp_f32_e32 v152, v152
	v_fmac_f32_e32 v149, 0x3377d1cf, v157
	v_fmac_f32_e32 v149, 0x3f317217, v157
	v_cmp_lt_f32_e64 s[6:7], |v157|, s93
	v_fmac_f32_e32 v156, v182, v152
	v_cmp_gt_f32_e32 vcc, s87, v156
	v_cndmask_b32_e64 v149, v157, v149, s[6:7]
	v_sub_f32_e32 v149, v149, v153
	v_mul_f32_e32 v153, v2, v136
	v_mul_f32_e32 v153, 0xbfb8aa3b, v153
	v_cndmask_b32_e64 v152, 0, 32, vcc
	v_exp_f32_e32 v153, v153
	v_ldexp_f32 v152, v156, v152
	v_log_f32_e32 v152, v152
	v_mul_f32_e32 v136, v3, v136
	v_add_f32_e32 v153, 1.0, v153
	v_mul_f32_e32 v136, 0xbfb8aa3b, v136
	v_rcp_f32_e32 v153, v153
	v_exp_f32_e32 v136, v136
	v_mul_f32_e32 v156, 0x3f317217, v152
	v_fma_f32 v156, v152, s92, -v156
	v_fmac_f32_e32 v156, 0x3377d1cf, v152
	v_fmac_f32_e32 v156, 0x3f317217, v152
	v_cmp_lt_f32_e64 s[6:7], |v152|, s93
	v_fmac_f32_e32 v155, v189, v153
	v_add_f32_e32 v136, 1.0, v136
	v_cndmask_b32_e64 v152, v152, v156, s[6:7]
	v_cmp_gt_f32_e64 s[6:7], s87, v155
	v_rcp_f32_e32 v136, v136
	s_nop 0
	v_cndmask_b32_e64 v153, 0, 32, s[6:7]
	v_ldexp_f32 v153, v155, v153
	v_log_f32_e32 v153, v153
	v_fmac_f32_e32 v154, v190, v136
	v_cndmask_b32_e32 v155, 0, v171, vcc
	v_cmp_gt_f32_e32 vcc, s87, v154
	v_sub_f32_e32 v152, v152, v155
	v_mul_f32_e32 v155, 0x3f317217, v153
	v_cndmask_b32_e64 v136, 0, 32, vcc
	v_ldexp_f32 v136, v154, v136
	v_fma_f32 v155, v153, s92, -v155
	v_log_f32_e32 v136, v136
	v_fmac_f32_e32 v155, 0x3377d1cf, v153
	v_fmac_f32_e32 v155, 0x3f317217, v153
	v_cmp_lt_f32_e64 s[8:9], |v153|, s93
	v_cndmask_b32_e64 v154, 0, v171, s[6:7]
	v_cmp_lt_f32_e64 s[6:7], |v136|, s93
	v_cndmask_b32_e64 v153, v153, v155, s[8:9]
	v_sub_f32_e32 v153, v153, v154
	v_mul_f32_e32 v154, 0x3f317217, v136
	v_fma_f32 v154, v136, s92, -v154
	v_fmac_f32_e32 v154, 0x3377d1cf, v136
	v_fmac_f32_e32 v154, 0x3f317217, v136
	v_cndmask_b32_e64 v136, v136, v154, s[6:7]
	v_cndmask_b32_e32 v154, 0, v171, vcc
	v_sub_f32_e32 v136, v136, v154
	v_cvt_pk_f16_f32 v153, v153, v136
	v_cvt_pk_f16_f32 v152, v149, v152
	global_store_dwordx4 v[162:163], v[150:153], off offset:256

; __device__ __forceinline__ unsigned cvt_pk_bf16(float lo, float hi) { cvf32x2_t v = {lo, hi}; cvbf16x2_t b = __builtin_convertvector(v, cvbf16x2_t); return __builtin_bit_cast(unsigned, b); }
; __device__ __forceinline__ float row_rs(const float* ssq, int row) { return ssq ? rsqrtf(ssq[row] * (1.f / 1024.f) + RMS_EPS) : 1.f; }
;     __device__ __forceinline__ void operator()(const f32x4 (&acc)[2][2][4][2], const Unit& u, int wr, int wc, int fr, int fq) const {
;     ...
;                 for (int m = 0; m < 4; ++m) { const int row = row0 + ai * HALF + m * 16; const float rs = row_rs(ssq, row); const float rs2 = rs * rs;
;                     const f32x4 v0 = acc[ai][0][m][0] * acc[ai][1][m][0] * rs2, v1 = acc[ai][0][m][1] * acc[ai][1][m][1] * rs2; u32x4 w;
;                     w.x = cvt_pk_bf16(v0[0], v0[1]); w.y = cvt_pk_bf16(v0[2], v0[3]); w.z = cvt_pk_bf16(v1[0], v1[1]); w.w = cvt_pk_bf16(v1[2], v1[3]);
;                     *(u32x4*)(CU + (size_t)row * 512 + (pn - 10) * HALF + cw) = w; }
.LBB0_514:
	v_ashrrev_i32_e32 v149, 31, v148
	v_lshl_add_u64 v[150:151], v[148:149], 2, s[30:31]
	global_load_dword v152, v[150:151], off
	global_load_dword v210, v[150:151], off offset:64
	global_load_dword v211, v[150:151], off offset:128
	global_load_dword v212, v[150:151], off offset:192
	global_load_dword v213, v[150:151], off offset:512
	global_load_dword v214, v[150:151], off offset:576
	global_load_dword v215, v[150:151], off offset:640
	global_load_dword v216, v[150:151], off offset:704
	v_pk_mul_f32 v[116:117], v[124:125], v[116:117]
	v_pk_mul_f32 v[118:119], v[126:127], v[118:119]
	s_lshl_b32 s6, s14, 7
	v_pk_mul_f32 v[120:121], v[120:121], v[112:113]
	s_add_i32 s14, s6, 0xfffffb00
	v_lshlrev_b64 v[112:113], 10, v[148:149]
	v_pk_mul_f32 v[114:115], v[122:123], v[114:115]
	v_lshl_add_u64 v[112:113], s[26:27], 0, v[112:113]
	s_lshl_b64 s[6:7], s[14:15], 1
	v_lshlrev_b32_e32 v136, 1, v138
	v_or_b32_e32 v122, 16, v148
	v_lshl_add_u64 v[112:113], v[112:113], 0, s[6:7]
	v_ashrrev_i32_e32 v123, 31, v122
	v_lshl_add_u64 v[112:113], v[112:113], 0, v[136:137]
	v_pk_mul_f32 v[102:103], v[110:111], v[102:103]
	v_pk_mul_f32 v[98:99], v[106:107], v[98:99]
	v_lshlrev_b64 v[106:107], 10, v[122:123]
	v_pk_mul_f32 v[100:101], v[108:109], v[100:101]
	v_pk_mul_f32 v[96:97], v[104:105], v[96:97]
	v_lshl_add_u64 v[106:107], s[26:27], 0, v[106:107]
	v_or_b32_e32 v104, 32, v148
	v_lshl_add_u64 v[106:107], v[106:107], 0, s[6:7]
	v_ashrrev_i32_e32 v105, 31, v104
	v_lshl_add_u64 v[106:107], v[106:107], 0, v[136:137]
	v_lshl_add_u64 v[108:109], v[104:105], 2, s[30:31]
	v_pk_mul_f32 v[86:87], v[94:95], v[86:87]
	v_pk_mul_f32 v[82:83], v[90:91], v[82:83]
	v_lshlrev_b64 v[90:91], 10, v[104:105]
	v_pk_mul_f32 v[84:85], v[92:93], v[84:85]
	v_pk_mul_f32 v[80:81], v[88:89], v[80:81]
	v_lshl_add_u64 v[90:91], s[26:27], 0, v[90:91]
	v_or_b32_e32 v88, 48, v148
	v_lshl_add_u64 v[90:91], v[90:91], 0, s[6:7]
	v_ashrrev_i32_e32 v89, 31, v88
	v_lshl_add_u64 v[90:91], v[90:91], 0, v[136:137]
	v_lshl_add_u64 v[92:93], v[88:89], 2, s[30:31]
	v_pk_mul_f32 v[66:67], v[74:75], v[66:67]
	v_pk_mul_f32 v[64:65], v[72:73], v[64:65]
	v_lshlrev_b64 v[72:73], 10, v[88:89]
	v_pk_mul_f32 v[70:71], v[78:79], v[70:71]
	v_pk_mul_f32 v[68:69], v[76:77], v[68:69]
	v_lshl_add_u64 v[72:73], s[26:27], 0, v[72:73]
	v_lshl_add_u64 v[72:73], v[72:73], 0, s[6:7]
	v_lshl_add_u64 v[72:73], v[72:73], 0, v[136:137]
	v_pk_mul_f32 v[48:49], v[56:57], v[48:49]
	v_pk_mul_f32 v[50:51], v[58:59], v[50:51]
	v_pk_mul_f32 v[54:55], v[62:63], v[54:55]
	v_pk_mul_f32 v[52:53], v[60:61], v[52:53]
	v_pk_mul_f32 v[32:33], v[40:41], v[32:33]
	v_pk_mul_f32 v[34:35], v[42:43], v[34:35]
	v_pk_mul_f32 v[38:39], v[46:47], v[38:39]
	v_pk_mul_f32 v[36:37], v[44:45], v[36:37]
	v_pk_mul_f32 v[16:17], v[24:25], v[16:17]
	v_pk_mul_f32 v[18:19], v[26:27], v[18:19]
	v_pk_mul_f32 v[22:23], v[30:31], v[22:23]
	v_pk_mul_f32 v[20:21], v[28:29], v[20:21]
	v_pk_mul_f32 v[2:3], v[10:11], v[2:3]
	v_pk_mul_f32 v[0:1], v[8:9], v[0:1]
	v_pk_mul_f32 v[6:7], v[14:15], v[6:7]
	v_pk_mul_f32 v[4:5], v[12:13], v[4:5]
	s_waitcnt vmcnt(0)
; __device__ __forceinline__ unsigned cvt_pk_bf16(float lo, float hi) { cvf32x2_t v = {lo, hi}; cvbf16x2_t b = __builtin_convertvector(v, cvbf16x2_t); return __builtin_bit_cast(unsigned, b); }
; __device__ __forceinline__ float row_rs(const float* ssq, int row) { return ssq ? rsqrtf(ssq[row] * (1.f / 1024.f) + RMS_EPS) : 1.f; }
;     __device__ __forceinline__ void operator()(const f32x4 (&acc)[2][2][4][2], const Unit& u, int wr, int wc, int fr, int fq) const {
;     ...
;                 for (int m = 0; m < 4; ++m) { const int row = row0 + ai * HALF + m * 16; const float rs = row_rs(ssq, row); const float rs2 = rs * rs;
;                     const f32x4 v0 = acc[ai][0][m][0] * acc[ai][1][m][0] * rs2, v1 = acc[ai][0][m][1] * acc[ai][1][m][1] * rs2; u32x4 w;
;                     w.x = cvt_pk_bf16(v0[0], v0[1]); w.y = cvt_pk_bf16(v0[2], v0[3]); w.z = cvt_pk_bf16(v1[0], v1[1]); w.w = cvt_pk_bf16(v1[2], v1[3]);
;                     *(u32x4*)(CU + (size_t)row * 512 + (pn - 10) * HALF + cw) = w; }
	v_fmamk_f32 v124, v152, 0x3a800000, v170
	v_mul_f32_e32 v125, 0x4b800000, v124
	v_cmp_gt_f32_e32 vcc, s87, v124
	s_nop 1
	v_cndmask_b32_e32 v124, v124, v125, vcc
	v_rsq_f32_e32 v126, v124
	v_lshl_add_u64 v[124:125], v[122:123], 2, s[30:31]
	v_mul_f32_e32 v127, 0x45800000, v126
	v_cndmask_b32_e32 v126, v126, v127, vcc
	v_mul_f32_e32 v126, v126, v126
	v_pk_mul_f32 v[118:119], v[118:119], v[126:127] op_sel_hi:[1,0]
	v_pk_mul_f32 v[116:117], v[116:117], v[126:127] op_sel_hi:[1,0]
	v_pk_mul_f32 v[152:153], v[114:115], v[126:127] op_sel_hi:[1,0]
	v_pk_mul_f32 v[120:121], v[120:121], v[126:127] op_sel_hi:[1,0]
	v_cvt_pk_bf16_f32 v114, v116, v117
	v_cvt_pk_bf16_f32 v115, v118, v119
	v_cvt_pk_bf16_f32 v116, v120, v121
	v_cvt_pk_bf16_f32 v117, v152, v153
	global_store_dwordx4 v[112:113], v[114:117], off
	v_fmamk_f32 v110, v210, 0x3a800000, v170
	v_mul_f32_e32 v111, 0x4b800000, v110
	v_cmp_gt_f32_e32 vcc, s87, v110
	s_nop 1
	v_cndmask_b32_e32 v110, v110, v111, vcc
	v_rsq_f32_e32 v110, v110
	s_nop 0
	v_mul_f32_e32 v111, 0x45800000, v110
	v_cndmask_b32_e32 v110, v110, v111, vcc
	v_mul_f32_e32 v110, v110, v110
	v_pk_mul_f32 v[102:103], v[102:103], v[110:111] op_sel_hi:[1,0]
	v_pk_mul_f32 v[100:101], v[100:101], v[110:111] op_sel_hi:[1,0]
	v_pk_mul_f32 v[114:115], v[98:99], v[110:111] op_sel_hi:[1,0]
	v_pk_mul_f32 v[98:99], v[96:97], v[110:111] op_sel_hi:[1,0]
	v_cvt_pk_bf16_f32 v96, v100, v101
	v_cvt_pk_bf16_f32 v97, v102, v103
	v_cvt_pk_bf16_f32 v98, v98, v99
	v_cvt_pk_bf16_f32 v99, v114, v115
	global_store_dwordx4 v[106:107], v[96:99], off
	v_fmamk_f32 v94, v211, 0x3a800000, v170
	v_mul_f32_e32 v95, 0x4b800000, v94
	v_cmp_gt_f32_e32 vcc, s87, v94
	s_nop 1
	v_cndmask_b32_e32 v94, v94, v95, vcc
	v_rsq_f32_e32 v94, v94
	s_nop 0
	v_mul_f32_e32 v95, 0x45800000, v94
	v_cndmask_b32_e32 v94, v94, v95, vcc
	v_mul_f32_e32 v94, v94, v94
	v_pk_mul_f32 v[86:87], v[86:87], v[94:95] op_sel_hi:[1,0]
	v_pk_mul_f32 v[84:85], v[84:85], v[94:95] op_sel_hi:[1,0]
	v_pk_mul_f32 v[96:97], v[82:83], v[94:95] op_sel_hi:[1,0]
	v_pk_mul_f32 v[82:83], v[80:81], v[94:95] op_sel_hi:[1,0]
	v_cvt_pk_bf16_f32 v80, v84, v85
	v_cvt_pk_bf16_f32 v81, v86, v87
	v_cvt_pk_bf16_f32 v82, v82, v83
	v_cvt_pk_bf16_f32 v83, v96, v97
	global_store_dwordx4 v[90:91], v[80:83], off
	v_fmamk_f32 v74, v212, 0x3a800000, v170
	v_mul_f32_e32 v75, 0x4b800000, v74
	v_cmp_gt_f32_e32 vcc, s87, v74
	s_nop 1
	v_cndmask_b32_e32 v74, v74, v75, vcc
	v_rsq_f32_e32 v74, v74
	s_nop 0
	v_mul_f32_e32 v75, 0x45800000, v74
	v_cndmask_b32_e32 v74, v74, v75, vcc
	v_mul_f32_e32 v74, v74, v74
	v_pk_mul_f32 v[70:71], v[70:71], v[74:75] op_sel_hi:[1,0]
	v_pk_mul_f32 v[68:69], v[68:69], v[74:75] op_sel_hi:[1,0]
	v_pk_mul_f32 v[76:77], v[66:67], v[74:75] op_sel_hi:[1,0]
	v_pk_mul_f32 v[66:67], v[64:65], v[74:75] op_sel_hi:[1,0]
	v_cvt_pk_bf16_f32 v64, v68, v69
	v_cvt_pk_bf16_f32 v65, v70, v71
	v_cvt_pk_bf16_f32 v66, v66, v67
	v_cvt_pk_bf16_f32 v67, v76, v77
	global_store_dwordx4 v[72:73], v[64:67], off
	v_fmamk_f32 v56, v213, 0x3a800000, v170
	v_mul_f32_e32 v57, 0x4b800000, v56
	v_cmp_gt_f32_e32 vcc, s87, v56
	s_nop 1
	v_cndmask_b32_e32 v56, v56, v57, vcc
	v_rsq_f32_e32 v58, v56
	v_add_co_u32_e64 v56, s[6:7], s88, v112
	v_mul_f32_e32 v59, 0x45800000, v58
	v_cndmask_b32_e32 v58, v58, v59, vcc
	v_mul_f32_e32 v58, v58, v58
	v_pk_mul_f32 v[54:55], v[54:55], v[58:59] op_sel_hi:[1,0]
	v_pk_mul_f32 v[52:53], v[52:53], v[58:59] op_sel_hi:[1,0]
	v_pk_mul_f32 v[60:61], v[50:51], v[58:59] op_sel_hi:[1,0]
	v_pk_mul_f32 v[50:51], v[48:49], v[58:59] op_sel_hi:[1,0]
	v_addc_co_u32_e64 v57, s[6:7], 0, v113, s[6:7]
	v_cvt_pk_bf16_f32 v48, v52, v53
	v_cvt_pk_bf16_f32 v49, v54, v55
	v_cvt_pk_bf16_f32 v50, v50, v51
	v_cvt_pk_bf16_f32 v51, v60, v61
	global_store_dwordx4 v[56:57], v[48:51], off
	v_fmamk_f32 v40, v214, 0x3a800000, v170
	v_mul_f32_e32 v41, 0x4b800000, v40
	v_cmp_gt_f32_e32 vcc, s87, v40
	s_nop 1
	v_cndmask_b32_e32 v40, v40, v41, vcc
	v_rsq_f32_e32 v42, v40
	v_add_co_u32_e64 v40, s[6:7], s89, v112
	v_mul_f32_e32 v43, 0x45800000, v42
	v_cndmask_b32_e32 v42, v42, v43, vcc
	v_mul_f32_e32 v42, v42, v42
	v_pk_mul_f32 v[38:39], v[38:39], v[42:43] op_sel_hi:[1,0]
	v_pk_mul_f32 v[36:37], v[36:37], v[42:43] op_sel_hi:[1,0]
	v_pk_mul_f32 v[44:45], v[34:35], v[42:43] op_sel_hi:[1,0]
	v_pk_mul_f32 v[34:35], v[32:33], v[42:43] op_sel_hi:[1,0]
	v_addc_co_u32_e64 v41, s[6:7], 0, v113, s[6:7]
	v_cvt_pk_bf16_f32 v32, v36, v37
	v_cvt_pk_bf16_f32 v33, v38, v39
	v_cvt_pk_bf16_f32 v34, v34, v35
	v_cvt_pk_bf16_f32 v35, v44, v45
	global_store_dwordx4 v[40:41], v[32:35], off
	v_fmamk_f32 v24, v215, 0x3a800000, v170
	v_mul_f32_e32 v25, 0x4b800000, v24
	v_cmp_gt_f32_e32 vcc, s87, v24
	s_nop 1
	v_cndmask_b32_e32 v24, v24, v25, vcc
	v_rsq_f32_e32 v26, v24
	v_add_co_u32_e64 v24, s[6:7], s90, v112
	v_mul_f32_e32 v27, 0x45800000, v26
	v_cndmask_b32_e32 v26, v26, v27, vcc
	v_mul_f32_e32 v26, v26, v26
	v_pk_mul_f32 v[22:23], v[22:23], v[26:27] op_sel_hi:[1,0]
	v_pk_mul_f32 v[20:21], v[20:21], v[26:27] op_sel_hi:[1,0]
	v_pk_mul_f32 v[28:29], v[18:19], v[26:27] op_sel_hi:[1,0]
	v_pk_mul_f32 v[18:19], v[16:17], v[26:27] op_sel_hi:[1,0]
	v_addc_co_u32_e64 v25, s[6:7], 0, v113, s[6:7]
	v_cvt_pk_bf16_f32 v16, v20, v21
	v_cvt_pk_bf16_f32 v17, v22, v23
	v_cvt_pk_bf16_f32 v18, v18, v19
	v_cvt_pk_bf16_f32 v19, v28, v29
	global_store_dwordx4 v[24:25], v[16:19], off
	v_add_co_u32_e32 v8, vcc, 0x2c000, v112
	v_fmamk_f32 v10, v216, 0x3a800000, v170
	v_mul_f32_e32 v11, 0x4b800000, v10
	v_cmp_gt_f32_e64 s[6:7], s87, v10
	s_nop 1
	v_cndmask_b32_e64 v10, v10, v11, s[6:7]
	v_rsq_f32_e32 v10, v10
	s_nop 0
	v_mul_f32_e32 v9, 0x45800000, v10
	v_cndmask_b32_e64 v9, v10, v9, s[6:7]
	v_mul_f32_e32 v10, v9, v9
	v_pk_mul_f32 v[6:7], v[6:7], v[10:11] op_sel_hi:[1,0]
	v_pk_mul_f32 v[4:5], v[4:5], v[10:11] op_sel_hi:[1,0]
	v_pk_mul_f32 v[12:13], v[2:3], v[10:11] op_sel_hi:[1,0]
	v_pk_mul_f32 v[2:3], v[0:1], v[10:11] op_sel_hi:[1,0]
	v_cvt_pk_bf16_f32 v0, v4, v5
	v_cvt_pk_bf16_f32 v1, v6, v7
	v_cvt_pk_bf16_f32 v2, v2, v3
	v_cvt_pk_bf16_f32 v3, v12, v13
	v_addc_co_u32_e32 v9, vcc, 0, v113, vcc
	global_store_dwordx4 v[8:9], v[0:3], off
	s_andn2_b64 vcc, exec, s[4:5]
	s_mov_b64 s[4:5], -1
	s_cbranch_vccnz .LBB0_454

; __device__ __forceinline__ unsigned cvt_pk_bf16(float lo, float hi) { cvf32x2_t v = {lo, hi}; cvbf16x2_t b = __builtin_convertvector(v, cvbf16x2_t); return __builtin_bit_cast(unsigned, b); }
; __device__ __forceinline__ float fsilu(float x) { return x * fsigm(x); }
; __device__ __forceinline__ float row_rs(const float* ssq, int row) { return ssq ? rsqrtf(ssq[row] * (1.f / 1024.f) + RMS_EPS) : 1.f; }
;     __device__ __forceinline__ void operator()(const f32x4 (&acc)[2][2][4][2], const Unit& u, int wr, int wc, int fr, int fq) const {
;     ...
;             for (int m = 0; m < 4; ++m) { const int row = row0 + ai * HALF + m * 16; const float rs = row_rs(ssq, row);
; #pragma unroll
;                 for (int bj = 0; bj < 2; ++bj) { f32x4 p0 = acc[ai][bj][m][0] * rs, p1 = acc[ai][bj][m][1] * rs;
;                     if (act) { p0[0] = fsilu(p0[0]); p0[1] = fsilu(p0[1]); p0[2] = fsilu(p0[2]); p0[3] = fsilu(p0[3]); p1[0] = fsilu(p1[0]); p1[1] = fsilu(p1[1]); p1[2] = fsilu(p1[2]); p1[3] = fsilu(p1[3]); }
;                     u32x4 w; w.x = cvt_pk_bf16(p0[0], p0[1]); w.y = cvt_pk_bf16(p0[2], p0[3]); w.z = cvt_pk_bf16(p1[0], p1[1]); w.w = cvt_pk_bf16(p1[2], p1[3]);
;                     *(u32x4*)(dst + (size_t)row * 512 + cbase + bj * HALF) = w; } }
.LBB0_612:
	v_ashrrev_i32_e32 v149, 31, v148
	v_lshl_add_u64 v[150:151], v[148:149], 2, s[30:31]
	global_load_dword v136, v[150:151], off
	global_load_dword v210, v[150:151], off offset:64
	global_load_dword v211, v[150:151], off offset:128
	global_load_dword v212, v[150:151], off offset:192
	global_load_dword v213, v[150:151], off offset:512
	global_load_dword v214, v[150:151], off offset:576
	global_load_dword v215, v[150:151], off offset:640
	global_load_dword v216, v[150:151], off offset:704
	s_cmp_eq_u32 s65, 3
	s_cselect_b64 s[52:53], -1, 0
	s_or_b64 s[52:53], s[6:7], s[52:53]
	s_andn2_b64 vcc, exec, s[52:53]
	s_waitcnt vmcnt(0)
	v_fmamk_f32 v136, v136, 0x3a800000, v170
	v_mul_f32_e32 v152, 0x4b800000, v136
	v_cmp_gt_f32_e64 s[8:9], s90, v136
	s_nop 1
	v_cndmask_b32_e64 v136, v136, v152, s[8:9]
	v_rsq_f32_e32 v136, v136
	v_cndmask_b32_e64 v152, 0, 1, s[52:53]
	v_cmp_ne_u32_e64 s[6:7], 1, v152
	v_mul_f32_e32 v152, 0x45800000, v136
	v_cndmask_b32_e64 v154, v136, v152, s[8:9]
	v_pk_mul_f32 v[160:161], v[126:127], v[154:155] op_sel_hi:[1,0]
	v_pk_mul_f32 v[164:165], v[124:125], v[154:155] op_sel_hi:[1,0]
	v_pk_mul_f32 v[158:159], v[122:123], v[154:155] op_sel_hi:[1,0]
	v_pk_mul_f32 v[162:163], v[120:121], v[154:155] op_sel_hi:[1,0]
	s_cbranch_vccnz .LBB0_614
	v_mul_f32_e32 v136, 0xbfb8aa3b, v164
	v_exp_f32_e32 v136, v136
	v_mul_f32_e32 v152, 0xbfb8aa3b, v165
	v_mul_f32_e32 v153, 0xbfb8aa3b, v160
	v_exp_f32_e32 v155, v152
	v_exp_f32_e32 v156, v153
	v_add_f32_e32 v136, 1.0, v136
	v_rcp_f32_e32 v152, v136
	v_add_f32_e32 v136, 1.0, v155
	v_mul_f32_e32 v155, 0xbfb8aa3b, v161
	v_rcp_f32_e32 v153, v136
	v_add_f32_e32 v136, 1.0, v156
	v_exp_f32_e32 v155, v155
	v_mul_f32_e32 v156, 0xbfb8aa3b, v162
	v_exp_f32_e32 v172, v156
	v_rcp_f32_e32 v156, v136
	v_add_f32_e32 v136, 1.0, v155
	v_rcp_f32_e32 v157, v136
	v_add_f32_e32 v136, 1.0, v172
	v_mul_f32_e32 v155, 0xbfb8aa3b, v158
	v_rcp_f32_e32 v172, v136
	v_mul_f32_e32 v136, 0xbfb8aa3b, v163
	v_exp_f32_e32 v155, v155
	v_mul_f32_e32 v173, 0xbfb8aa3b, v159
	v_exp_f32_e32 v136, v136
	v_exp_f32_e32 v173, v173
	v_add_f32_e32 v155, 1.0, v155
	v_rcp_f32_e32 v174, v155
	v_add_f32_e32 v136, 1.0, v136
	v_add_f32_e32 v155, 1.0, v173
	v_rcp_f32_e32 v175, v155
	v_rcp_f32_e32 v173, v136
	v_pk_mul_f32 v[160:161], v[160:161], v[156:157]
	v_pk_mul_f32 v[164:165], v[164:165], v[152:153]
	v_pk_mul_f32 v[158:159], v[158:159], v[174:175]
	v_pk_mul_f32 v[162:163], v[162:163], v[172:173]

; __device__ __forceinline__ unsigned cvt_pk_bf16(float lo, float hi) { cvf32x2_t v = {lo, hi}; cvbf16x2_t b = __builtin_convertvector(v, cvbf16x2_t); return __builtin_bit_cast(unsigned, b); }
; __device__ __forceinline__ float fsilu(float x) { return x * fsigm(x); }
; __device__ __forceinline__ float row_rs(const float* ssq, int row) { return ssq ? rsqrtf(ssq[row] * (1.f / 1024.f) + RMS_EPS) : 1.f; }
;     __device__ __forceinline__ void operator()(const f32x4 (&acc)[2][2][4][2], const Unit& u, int wr, int wc, int fr, int fq) const {
;     ...
;             for (int m = 0; m < 4; ++m) { const int row = row0 + ai * HALF + m * 16; const float rs = row_rs(ssq, row);
; #pragma unroll
;                 for (int bj = 0; bj < 2; ++bj) { f32x4 p0 = acc[ai][bj][m][0] * rs, p1 = acc[ai][bj][m][1] * rs;
;                     if (act) { p0[0] = fsilu(p0[0]); p0[1] = fsilu(p0[1]); p0[2] = fsilu(p0[2]); p0[3] = fsilu(p0[3]); p1[0] = fsilu(p1[0]); p1[1] = fsilu(p1[1]); p1[2] = fsilu(p1[2]); p1[3] = fsilu(p1[3]); }
;                     u32x4 w; w.x = cvt_pk_bf16(p0[0], p0[1]); w.y = cvt_pk_bf16(p0[2], p0[3]); w.z = cvt_pk_bf16(p1[0], p1[1]); w.w = cvt_pk_bf16(p1[2], p1[3]);
;                     *(u32x4*)(dst + (size_t)row * 512 + cbase + bj * HALF) = w; } }
.LBB0_616:
	s_nop 0
	v_cvt_pk_bf16_f32 v174, v154, v155
	v_or_b32_e32 v154, 16, v148
	v_cvt_pk_bf16_f32 v172, v160, v161
	v_cvt_pk_bf16_f32 v173, v158, v159
	v_cvt_pk_bf16_f32 v175, v162, v163
	v_ashrrev_i32_e32 v155, 31, v154
	global_store_dwordx4 v[156:157], v[172:175], off offset:256
	v_lshl_add_u64 v[156:157], v[154:155], 2, s[30:31]
	s_and_b64 vcc, exec, s[6:7]
	v_fmamk_f32 v136, v210, 0x3a800000, v170
	v_mul_f32_e32 v156, 0x4b800000, v136
	v_cmp_gt_f32_e64 s[8:9], s90, v136
	s_nop 1
	v_cndmask_b32_e64 v136, v136, v156, s[8:9]
	v_rsq_f32_e32 v136, v136
	s_nop 0
	v_mul_f32_e32 v156, 0x45800000, v136
	v_cndmask_b32_e64 v156, v136, v156, s[8:9]
	v_pk_mul_f32 v[160:161], v[110:111], v[156:157] op_sel_hi:[1,0]
	v_pk_mul_f32 v[164:165], v[108:109], v[156:157] op_sel_hi:[1,0]
	v_pk_mul_f32 v[158:159], v[106:107], v[156:157] op_sel_hi:[1,0]
	v_pk_mul_f32 v[162:163], v[104:105], v[156:157] op_sel_hi:[1,0]
	s_cbranch_vccnz .LBB0_618
	v_mul_f32_e32 v136, 0xbfb8aa3b, v164
	v_exp_f32_e32 v136, v136
	v_mul_f32_e32 v157, 0xbfb8aa3b, v165
	v_mul_f32_e32 v172, 0xbfb8aa3b, v160
	v_exp_f32_e32 v157, v157
	v_exp_f32_e32 v174, v172
	v_add_f32_e32 v136, 1.0, v136
	v_rcp_f32_e32 v172, v136
	v_add_f32_e32 v136, 1.0, v157
	v_mul_f32_e32 v157, 0xbfb8aa3b, v161
	v_rcp_f32_e32 v173, v136
	v_add_f32_e32 v136, 1.0, v174
	v_exp_f32_e32 v157, v157
	v_mul_f32_e32 v174, 0xbfb8aa3b, v162
	v_exp_f32_e32 v176, v174
	v_rcp_f32_e32 v174, v136
	v_add_f32_e32 v136, 1.0, v157
	v_rcp_f32_e32 v175, v136
	v_add_f32_e32 v136, 1.0, v176
	v_mul_f32_e32 v157, 0xbfb8aa3b, v158
	v_rcp_f32_e32 v176, v136
	v_mul_f32_e32 v136, 0xbfb8aa3b, v163
	v_exp_f32_e32 v157, v157
	v_mul_f32_e32 v177, 0xbfb8aa3b, v159
	v_exp_f32_e32 v136, v136
	v_exp_f32_e32 v177, v177
	v_add_f32_e32 v157, 1.0, v157
	v_rcp_f32_e32 v178, v157
	v_add_f32_e32 v136, 1.0, v136
	v_add_f32_e32 v157, 1.0, v177
	v_rcp_f32_e32 v179, v157
	v_rcp_f32_e32 v177, v136
	v_pk_mul_f32 v[160:161], v[160:161], v[174:175]
	v_pk_mul_f32 v[164:165], v[164:165], v[172:173]
	v_pk_mul_f32 v[158:159], v[158:159], v[178:179]
	v_pk_mul_f32 v[162:163], v[162:163], v[176:177]

; __device__ __forceinline__ unsigned cvt_pk_bf16(float lo, float hi) { cvf32x2_t v = {lo, hi}; cvbf16x2_t b = __builtin_convertvector(v, cvbf16x2_t); return __builtin_bit_cast(unsigned, b); }
; __device__ __forceinline__ float fsilu(float x) { return x * fsigm(x); }
; __device__ __forceinline__ float row_rs(const float* ssq, int row) { return ssq ? rsqrtf(ssq[row] * (1.f / 1024.f) + RMS_EPS) : 1.f; }
;     __device__ __forceinline__ void operator()(const f32x4 (&acc)[2][2][4][2], const Unit& u, int wr, int wc, int fr, int fq) const {
;     ...
;             for (int m = 0; m < 4; ++m) { const int row = row0 + ai * HALF + m * 16; const float rs = row_rs(ssq, row);
; #pragma unroll
;                 for (int bj = 0; bj < 2; ++bj) { f32x4 p0 = acc[ai][bj][m][0] * rs, p1 = acc[ai][bj][m][1] * rs;
;                     if (act) { p0[0] = fsilu(p0[0]); p0[1] = fsilu(p0[1]); p0[2] = fsilu(p0[2]); p0[3] = fsilu(p0[3]); p1[0] = fsilu(p1[0]); p1[1] = fsilu(p1[1]); p1[2] = fsilu(p1[2]); p1[3] = fsilu(p1[3]); }
;                     u32x4 w; w.x = cvt_pk_bf16(p0[0], p0[1]); w.y = cvt_pk_bf16(p0[2], p0[3]); w.z = cvt_pk_bf16(p1[0], p1[1]); w.w = cvt_pk_bf16(p1[2], p1[3]);
;                     *(u32x4*)(dst + (size_t)row * 512 + cbase + bj * HALF) = w; } }
.LBB0_620:
	s_nop 0
	v_cvt_pk_bf16_f32 v172, v160, v161
	v_cvt_pk_bf16_f32 v173, v158, v159
	v_cvt_pk_bf16_f32 v174, v156, v157
	v_cvt_pk_bf16_f32 v175, v162, v163
	global_store_dwordx4 v[154:155], v[172:175], off offset:256
	v_or_b32_e32 v154, 32, v148
	v_ashrrev_i32_e32 v155, 31, v154
	v_lshl_add_u64 v[156:157], v[154:155], 2, s[30:31]
	s_and_b64 vcc, exec, s[6:7]
	v_fmamk_f32 v136, v211, 0x3a800000, v170
	v_mul_f32_e32 v156, 0x4b800000, v136
	v_cmp_gt_f32_e64 s[8:9], s90, v136
	s_nop 1
	v_cndmask_b32_e64 v136, v136, v156, s[8:9]
	v_rsq_f32_e32 v136, v136
	s_nop 0
	v_mul_f32_e32 v156, 0x45800000, v136
	v_cndmask_b32_e64 v156, v136, v156, s[8:9]
	v_pk_mul_f32 v[160:161], v[94:95], v[156:157] op_sel_hi:[1,0]
	v_pk_mul_f32 v[164:165], v[92:93], v[156:157] op_sel_hi:[1,0]
	v_pk_mul_f32 v[158:159], v[90:91], v[156:157] op_sel_hi:[1,0]
	v_pk_mul_f32 v[162:163], v[88:89], v[156:157] op_sel_hi:[1,0]
	s_cbranch_vccnz .LBB0_622
	v_mul_f32_e32 v136, 0xbfb8aa3b, v164
	v_exp_f32_e32 v136, v136
	v_mul_f32_e32 v157, 0xbfb8aa3b, v165
	v_mul_f32_e32 v172, 0xbfb8aa3b, v160
	v_exp_f32_e32 v157, v157
	v_exp_f32_e32 v174, v172
	v_add_f32_e32 v136, 1.0, v136
	v_rcp_f32_e32 v172, v136
	v_add_f32_e32 v136, 1.0, v157
	v_mul_f32_e32 v157, 0xbfb8aa3b, v161
	v_rcp_f32_e32 v173, v136
	v_add_f32_e32 v136, 1.0, v174
	v_exp_f32_e32 v157, v157
	v_mul_f32_e32 v174, 0xbfb8aa3b, v162
	v_exp_f32_e32 v176, v174
	v_rcp_f32_e32 v174, v136
	v_add_f32_e32 v136, 1.0, v157
	v_rcp_f32_e32 v175, v136
	v_add_f32_e32 v136, 1.0, v176
	v_mul_f32_e32 v157, 0xbfb8aa3b, v158
	v_rcp_f32_e32 v176, v136
	v_mul_f32_e32 v136, 0xbfb8aa3b, v163
	v_exp_f32_e32 v157, v157
	v_mul_f32_e32 v177, 0xbfb8aa3b, v159
	v_exp_f32_e32 v136, v136
	v_exp_f32_e32 v177, v177
	v_add_f32_e32 v157, 1.0, v157
	v_rcp_f32_e32 v178, v157
	v_add_f32_e32 v136, 1.0, v136
	v_add_f32_e32 v157, 1.0, v177
	v_rcp_f32_e32 v179, v157
	v_rcp_f32_e32 v177, v136
	v_pk_mul_f32 v[160:161], v[160:161], v[174:175]
	v_pk_mul_f32 v[164:165], v[164:165], v[172:173]
	v_pk_mul_f32 v[158:159], v[158:159], v[178:179]
	v_pk_mul_f32 v[162:163], v[162:163], v[176:177]

; __device__ __forceinline__ unsigned cvt_pk_bf16(float lo, float hi) { cvf32x2_t v = {lo, hi}; cvbf16x2_t b = __builtin_convertvector(v, cvbf16x2_t); return __builtin_bit_cast(unsigned, b); }
; __device__ __forceinline__ float fsilu(float x) { return x * fsigm(x); }
; __device__ __forceinline__ float row_rs(const float* ssq, int row) { return ssq ? rsqrtf(ssq[row] * (1.f / 1024.f) + RMS_EPS) : 1.f; }
;     __device__ __forceinline__ void operator()(const f32x4 (&acc)[2][2][4][2], const Unit& u, int wr, int wc, int fr, int fq) const {
;     ...
;             for (int m = 0; m < 4; ++m) { const int row = row0 + ai * HALF + m * 16; const float rs = row_rs(ssq, row);
; #pragma unroll
;                 for (int bj = 0; bj < 2; ++bj) { f32x4 p0 = acc[ai][bj][m][0] * rs, p1 = acc[ai][bj][m][1] * rs;
;                     if (act) { p0[0] = fsilu(p0[0]); p0[1] = fsilu(p0[1]); p0[2] = fsilu(p0[2]); p0[3] = fsilu(p0[3]); p1[0] = fsilu(p1[0]); p1[1] = fsilu(p1[1]); p1[2] = fsilu(p1[2]); p1[3] = fsilu(p1[3]); }
;                     u32x4 w; w.x = cvt_pk_bf16(p0[0], p0[1]); w.y = cvt_pk_bf16(p0[2], p0[3]); w.z = cvt_pk_bf16(p1[0], p1[1]); w.w = cvt_pk_bf16(p1[2], p1[3]);
;                     *(u32x4*)(dst + (size_t)row * 512 + cbase + bj * HALF) = w; } }
.LBB0_624:
	s_nop 0
	v_cvt_pk_bf16_f32 v172, v160, v161
	v_cvt_pk_bf16_f32 v173, v158, v159
	v_cvt_pk_bf16_f32 v174, v156, v157
	v_cvt_pk_bf16_f32 v175, v162, v163
	global_store_dwordx4 v[154:155], v[172:175], off offset:256
	v_or_b32_e32 v154, 48, v148
	v_ashrrev_i32_e32 v155, 31, v154
	v_lshl_add_u64 v[156:157], v[154:155], 2, s[30:31]
	s_and_b64 vcc, exec, s[6:7]
	v_fmamk_f32 v136, v212, 0x3a800000, v170
	v_mul_f32_e32 v156, 0x4b800000, v136
	v_cmp_gt_f32_e64 s[8:9], s90, v136
	s_nop 1
	v_cndmask_b32_e64 v136, v136, v156, s[8:9]
	v_rsq_f32_e32 v136, v136
	s_nop 0
	v_mul_f32_e32 v156, 0x45800000, v136
	v_cndmask_b32_e64 v156, v136, v156, s[8:9]
	v_pk_mul_f32 v[160:161], v[78:79], v[156:157] op_sel_hi:[1,0]
	v_pk_mul_f32 v[164:165], v[76:77], v[156:157] op_sel_hi:[1,0]
	v_pk_mul_f32 v[158:159], v[74:75], v[156:157] op_sel_hi:[1,0]
	v_pk_mul_f32 v[162:163], v[72:73], v[156:157] op_sel_hi:[1,0]
	s_cbranch_vccnz .LBB0_626
	v_mul_f32_e32 v136, 0xbfb8aa3b, v164
	v_exp_f32_e32 v136, v136
	v_mul_f32_e32 v157, 0xbfb8aa3b, v165
	v_mul_f32_e32 v172, 0xbfb8aa3b, v160
	v_exp_f32_e32 v157, v157
	v_exp_f32_e32 v174, v172
	v_add_f32_e32 v136, 1.0, v136
	v_rcp_f32_e32 v172, v136
	v_add_f32_e32 v136, 1.0, v157
	v_mul_f32_e32 v157, 0xbfb8aa3b, v161
	v_rcp_f32_e32 v173, v136
	v_add_f32_e32 v136, 1.0, v174
	v_exp_f32_e32 v157, v157
	v_mul_f32_e32 v174, 0xbfb8aa3b, v162
	v_exp_f32_e32 v176, v174
	v_rcp_f32_e32 v174, v136
	v_add_f32_e32 v136, 1.0, v157
	v_rcp_f32_e32 v175, v136
	v_add_f32_e32 v136, 1.0, v176
	v_mul_f32_e32 v157, 0xbfb8aa3b, v158
	v_rcp_f32_e32 v176, v136
	v_mul_f32_e32 v136, 0xbfb8aa3b, v163
	v_exp_f32_e32 v157, v157
	v_mul_f32_e32 v177, 0xbfb8aa3b, v159
	v_exp_f32_e32 v136, v136
	v_exp_f32_e32 v177, v177
	v_add_f32_e32 v157, 1.0, v157
	v_rcp_f32_e32 v178, v157
	v_add_f32_e32 v136, 1.0, v136
	v_add_f32_e32 v157, 1.0, v177
	v_rcp_f32_e32 v179, v157
	v_rcp_f32_e32 v177, v136
	v_pk_mul_f32 v[160:161], v[160:161], v[174:175]
	v_pk_mul_f32 v[164:165], v[164:165], v[172:173]
	v_pk_mul_f32 v[158:159], v[158:159], v[178:179]
	v_pk_mul_f32 v[162:163], v[162:163], v[176:177]

; __device__ __forceinline__ unsigned cvt_pk_bf16(float lo, float hi) { cvf32x2_t v = {lo, hi}; cvbf16x2_t b = __builtin_convertvector(v, cvbf16x2_t); return __builtin_bit_cast(unsigned, b); }
; __device__ __forceinline__ float fsilu(float x) { return x * fsigm(x); }
; __device__ __forceinline__ float row_rs(const float* ssq, int row) { return ssq ? rsqrtf(ssq[row] * (1.f / 1024.f) + RMS_EPS) : 1.f; }
;     __device__ __forceinline__ void operator()(const f32x4 (&acc)[2][2][4][2], const Unit& u, int wr, int wc, int fr, int fq) const {
;     ...
;             for (int m = 0; m < 4; ++m) { const int row = row0 + ai * HALF + m * 16; const float rs = row_rs(ssq, row);
; #pragma unroll
;                 for (int bj = 0; bj < 2; ++bj) { f32x4 p0 = acc[ai][bj][m][0] * rs, p1 = acc[ai][bj][m][1] * rs;
;                     if (act) { p0[0] = fsilu(p0[0]); p0[1] = fsilu(p0[1]); p0[2] = fsilu(p0[2]); p0[3] = fsilu(p0[3]); p1[0] = fsilu(p1[0]); p1[1] = fsilu(p1[1]); p1[2] = fsilu(p1[2]); p1[3] = fsilu(p1[3]); }
;                     u32x4 w; w.x = cvt_pk_bf16(p0[0], p0[1]); w.y = cvt_pk_bf16(p0[2], p0[3]); w.z = cvt_pk_bf16(p1[0], p1[1]); w.w = cvt_pk_bf16(p1[2], p1[3]);
;                     *(u32x4*)(dst + (size_t)row * 512 + cbase + bj * HALF) = w; } }
.LBB0_628:
	s_nop 0
	v_cvt_pk_bf16_f32 v172, v160, v161
	v_cvt_pk_bf16_f32 v173, v158, v159
	v_cvt_pk_bf16_f32 v174, v156, v157
	v_cvt_pk_bf16_f32 v175, v162, v163
	global_store_dwordx4 v[154:155], v[172:175], off offset:256
	s_and_b64 vcc, exec, s[6:7]
	v_fmamk_f32 v136, v213, 0x3a800000, v170
	v_mul_f32_e32 v154, 0x4b800000, v136
	v_cmp_gt_f32_e64 s[8:9], s90, v136
	s_nop 1
	v_cndmask_b32_e64 v136, v136, v154, s[8:9]
	v_rsq_f32_e32 v136, v136
	s_nop 0
	v_mul_f32_e32 v154, 0x45800000, v136
	v_cndmask_b32_e64 v154, v136, v154, s[8:9]
	v_pk_mul_f32 v[160:161], v[62:63], v[154:155] op_sel_hi:[1,0]
	v_pk_mul_f32 v[164:165], v[60:61], v[154:155] op_sel_hi:[1,0]
	v_pk_mul_f32 v[158:159], v[58:59], v[154:155] op_sel_hi:[1,0]
	v_pk_mul_f32 v[162:163], v[56:57], v[154:155] op_sel_hi:[1,0]
	s_cbranch_vccnz .LBB0_630
	v_mul_f32_e32 v136, 0xbfb8aa3b, v164
	v_exp_f32_e32 v136, v136
	v_mul_f32_e32 v155, 0xbfb8aa3b, v165
	v_mul_f32_e32 v156, 0xbfb8aa3b, v160
	v_exp_f32_e32 v155, v155
	v_exp_f32_e32 v172, v156
	v_add_f32_e32 v136, 1.0, v136
	v_rcp_f32_e32 v156, v136
	v_add_f32_e32 v136, 1.0, v155
	v_mul_f32_e32 v155, 0xbfb8aa3b, v161
	v_rcp_f32_e32 v157, v136
	v_add_f32_e32 v136, 1.0, v172
	v_exp_f32_e32 v155, v155
	v_mul_f32_e32 v172, 0xbfb8aa3b, v162
	v_exp_f32_e32 v174, v172
	v_rcp_f32_e32 v172, v136
	v_add_f32_e32 v136, 1.0, v155
	v_rcp_f32_e32 v173, v136
	v_add_f32_e32 v136, 1.0, v174
	v_mul_f32_e32 v155, 0xbfb8aa3b, v158
	v_rcp_f32_e32 v174, v136
	v_mul_f32_e32 v136, 0xbfb8aa3b, v163
	v_exp_f32_e32 v155, v155
	v_mul_f32_e32 v175, 0xbfb8aa3b, v159
	v_exp_f32_e32 v136, v136
	v_exp_f32_e32 v175, v175
	v_add_f32_e32 v155, 1.0, v155
	v_rcp_f32_e32 v176, v155
	v_add_f32_e32 v136, 1.0, v136
	v_add_f32_e32 v155, 1.0, v175
	v_rcp_f32_e32 v177, v155
	v_rcp_f32_e32 v175, v136
	v_pk_mul_f32 v[160:161], v[160:161], v[172:173]
	v_pk_mul_f32 v[164:165], v[164:165], v[156:157]
	v_pk_mul_f32 v[158:159], v[158:159], v[176:177]
	v_pk_mul_f32 v[162:163], v[162:163], v[174:175]

; __device__ __forceinline__ unsigned cvt_pk_bf16(float lo, float hi) { cvf32x2_t v = {lo, hi}; cvbf16x2_t b = __builtin_convertvector(v, cvbf16x2_t); return __builtin_bit_cast(unsigned, b); }
; __device__ __forceinline__ float fsilu(float x) { return x * fsigm(x); }
; __device__ __forceinline__ float row_rs(const float* ssq, int row) { return ssq ? rsqrtf(ssq[row] * (1.f / 1024.f) + RMS_EPS) : 1.f; }
;     __device__ __forceinline__ void operator()(const f32x4 (&acc)[2][2][4][2], const Unit& u, int wr, int wc, int fr, int fq) const {
;     ...
;             for (int m = 0; m < 4; ++m) { const int row = row0 + ai * HALF + m * 16; const float rs = row_rs(ssq, row);
; #pragma unroll
;                 for (int bj = 0; bj < 2; ++bj) { f32x4 p0 = acc[ai][bj][m][0] * rs, p1 = acc[ai][bj][m][1] * rs;
;                     if (act) { p0[0] = fsilu(p0[0]); p0[1] = fsilu(p0[1]); p0[2] = fsilu(p0[2]); p0[3] = fsilu(p0[3]); p1[0] = fsilu(p1[0]); p1[1] = fsilu(p1[1]); p1[2] = fsilu(p1[2]); p1[3] = fsilu(p1[3]); }
;                     u32x4 w; w.x = cvt_pk_bf16(p0[0], p0[1]); w.y = cvt_pk_bf16(p0[2], p0[3]); w.z = cvt_pk_bf16(p1[0], p1[1]); w.w = cvt_pk_bf16(p1[2], p1[3]);
;                     *(u32x4*)(dst + (size_t)row * 512 + cbase + bj * HALF) = w; } }
.LBB0_632:
	v_lshl_add_u64 v[164:165], v[156:157], 0, s[38:39]
	v_cvt_pk_bf16_f32 v156, v160, v161
	v_cvt_pk_bf16_f32 v157, v158, v159
	v_cvt_pk_bf16_f32 v158, v154, v155
	v_cvt_pk_bf16_f32 v159, v162, v163
	global_store_dwordx4 v[164:165], v[156:159], off offset:256
	s_and_b64 vcc, exec, s[6:7]
	v_fmamk_f32 v136, v214, 0x3a800000, v170
	v_mul_f32_e32 v154, 0x4b800000, v136
	v_cmp_gt_f32_e64 s[8:9], s90, v136
	s_nop 1
	v_cndmask_b32_e64 v136, v136, v154, s[8:9]
	v_rsq_f32_e32 v136, v136
	s_nop 0
	v_mul_f32_e32 v154, 0x45800000, v136
	v_cndmask_b32_e64 v154, v136, v154, s[8:9]
	v_pk_mul_f32 v[160:161], v[46:47], v[154:155] op_sel_hi:[1,0]
	v_pk_mul_f32 v[164:165], v[44:45], v[154:155] op_sel_hi:[1,0]
	v_pk_mul_f32 v[158:159], v[42:43], v[154:155] op_sel_hi:[1,0]
	v_pk_mul_f32 v[162:163], v[40:41], v[154:155] op_sel_hi:[1,0]
	s_cbranch_vccnz .LBB0_634
	v_mul_f32_e32 v136, 0xbfb8aa3b, v164
	v_exp_f32_e32 v136, v136
	v_mul_f32_e32 v155, 0xbfb8aa3b, v165
	v_mul_f32_e32 v156, 0xbfb8aa3b, v160
	v_exp_f32_e32 v155, v155
	v_exp_f32_e32 v172, v156
	v_add_f32_e32 v136, 1.0, v136
	v_rcp_f32_e32 v156, v136
	v_add_f32_e32 v136, 1.0, v155
	v_mul_f32_e32 v155, 0xbfb8aa3b, v161
	v_rcp_f32_e32 v157, v136
	v_add_f32_e32 v136, 1.0, v172
	v_exp_f32_e32 v155, v155
	v_mul_f32_e32 v172, 0xbfb8aa3b, v162
	v_exp_f32_e32 v174, v172
	v_rcp_f32_e32 v172, v136
	v_add_f32_e32 v136, 1.0, v155
	v_rcp_f32_e32 v173, v136
	v_add_f32_e32 v136, 1.0, v174
	v_mul_f32_e32 v155, 0xbfb8aa3b, v158
	v_rcp_f32_e32 v174, v136
	v_mul_f32_e32 v136, 0xbfb8aa3b, v163
	v_exp_f32_e32 v155, v155
	v_mul_f32_e32 v175, 0xbfb8aa3b, v159
	v_exp_f32_e32 v136, v136
	v_exp_f32_e32 v175, v175
	v_add_f32_e32 v155, 1.0, v155
	v_rcp_f32_e32 v176, v155
	v_add_f32_e32 v136, 1.0, v136
	v_add_f32_e32 v155, 1.0, v175
	v_rcp_f32_e32 v177, v155
	v_rcp_f32_e32 v175, v136
	v_pk_mul_f32 v[160:161], v[160:161], v[172:173]
	v_pk_mul_f32 v[164:165], v[164:165], v[156:157]
	v_pk_mul_f32 v[158:159], v[158:159], v[176:177]
	v_pk_mul_f32 v[162:163], v[162:163], v[174:175]

; __device__ __forceinline__ unsigned cvt_pk_bf16(float lo, float hi) { cvf32x2_t v = {lo, hi}; cvbf16x2_t b = __builtin_convertvector(v, cvbf16x2_t); return __builtin_bit_cast(unsigned, b); }
; __device__ __forceinline__ float fsilu(float x) { return x * fsigm(x); }
; __device__ __forceinline__ float row_rs(const float* ssq, int row) { return ssq ? rsqrtf(ssq[row] * (1.f / 1024.f) + RMS_EPS) : 1.f; }
;     __device__ __forceinline__ void operator()(const f32x4 (&acc)[2][2][4][2], const Unit& u, int wr, int wc, int fr, int fq) const {
;     ...
;             for (int m = 0; m < 4; ++m) { const int row = row0 + ai * HALF + m * 16; const float rs = row_rs(ssq, row);
; #pragma unroll
;                 for (int bj = 0; bj < 2; ++bj) { f32x4 p0 = acc[ai][bj][m][0] * rs, p1 = acc[ai][bj][m][1] * rs;
;                     if (act) { p0[0] = fsilu(p0[0]); p0[1] = fsilu(p0[1]); p0[2] = fsilu(p0[2]); p0[3] = fsilu(p0[3]); p1[0] = fsilu(p1[0]); p1[1] = fsilu(p1[1]); p1[2] = fsilu(p1[2]); p1[3] = fsilu(p1[3]); }
;                     u32x4 w; w.x = cvt_pk_bf16(p0[0], p0[1]); w.y = cvt_pk_bf16(p0[2], p0[3]); w.z = cvt_pk_bf16(p1[0], p1[1]); w.w = cvt_pk_bf16(p1[2], p1[3]);
;                     *(u32x4*)(dst + (size_t)row * 512 + cbase + bj * HALF) = w; } }
.LBB0_636:
	v_lshl_add_u64 v[164:165], v[156:157], 0, s[40:41]
	v_cvt_pk_bf16_f32 v156, v160, v161
	v_cvt_pk_bf16_f32 v157, v158, v159
	v_cvt_pk_bf16_f32 v158, v154, v155
	v_cvt_pk_bf16_f32 v159, v162, v163
	global_store_dwordx4 v[164:165], v[156:159], off offset:256
	s_and_b64 vcc, exec, s[6:7]
	v_fmamk_f32 v136, v215, 0x3a800000, v170
	v_mul_f32_e32 v154, 0x4b800000, v136
	v_cmp_gt_f32_e64 s[8:9], s90, v136
	s_nop 1
	v_cndmask_b32_e64 v136, v136, v154, s[8:9]
	v_rsq_f32_e32 v136, v136
	s_nop 0
	v_mul_f32_e32 v154, 0x45800000, v136
	v_cndmask_b32_e64 v154, v136, v154, s[8:9]
	v_pk_mul_f32 v[160:161], v[30:31], v[154:155] op_sel_hi:[1,0]
	v_pk_mul_f32 v[164:165], v[28:29], v[154:155] op_sel_hi:[1,0]
	v_pk_mul_f32 v[158:159], v[26:27], v[154:155] op_sel_hi:[1,0]
	v_pk_mul_f32 v[162:163], v[24:25], v[154:155] op_sel_hi:[1,0]
	s_cbranch_vccnz .LBB0_638
	v_mul_f32_e32 v136, 0xbfb8aa3b, v164
	v_exp_f32_e32 v136, v136
	v_mul_f32_e32 v155, 0xbfb8aa3b, v165
	v_mul_f32_e32 v156, 0xbfb8aa3b, v160
	v_exp_f32_e32 v155, v155
	v_exp_f32_e32 v172, v156
	v_add_f32_e32 v136, 1.0, v136
	v_rcp_f32_e32 v156, v136
	v_add_f32_e32 v136, 1.0, v155
	v_mul_f32_e32 v155, 0xbfb8aa3b, v161
	v_rcp_f32_e32 v157, v136
	v_add_f32_e32 v136, 1.0, v172
	v_exp_f32_e32 v155, v155
	v_mul_f32_e32 v172, 0xbfb8aa3b, v162
	v_exp_f32_e32 v174, v172
	v_rcp_f32_e32 v172, v136
	v_add_f32_e32 v136, 1.0, v155
	v_rcp_f32_e32 v173, v136
	v_add_f32_e32 v136, 1.0, v174
	v_mul_f32_e32 v155, 0xbfb8aa3b, v158
	v_rcp_f32_e32 v174, v136
	v_mul_f32_e32 v136, 0xbfb8aa3b, v163
	v_exp_f32_e32 v155, v155
	v_mul_f32_e32 v175, 0xbfb8aa3b, v159
	v_exp_f32_e32 v136, v136
	v_exp_f32_e32 v175, v175
	v_add_f32_e32 v155, 1.0, v155
	v_rcp_f32_e32 v176, v155
	v_add_f32_e32 v136, 1.0, v136
	v_add_f32_e32 v155, 1.0, v175
	v_rcp_f32_e32 v177, v155
	v_rcp_f32_e32 v175, v136
	v_pk_mul_f32 v[160:161], v[160:161], v[172:173]
	v_pk_mul_f32 v[164:165], v[164:165], v[156:157]
	v_pk_mul_f32 v[158:159], v[158:159], v[176:177]
	v_pk_mul_f32 v[162:163], v[162:163], v[174:175]

; __device__ __forceinline__ unsigned cvt_pk_bf16(float lo, float hi) { cvf32x2_t v = {lo, hi}; cvbf16x2_t b = __builtin_convertvector(v, cvbf16x2_t); return __builtin_bit_cast(unsigned, b); }
; __device__ __forceinline__ float fsilu(float x) { return x * fsigm(x); }
; __device__ __forceinline__ float row_rs(const float* ssq, int row) { return ssq ? rsqrtf(ssq[row] * (1.f / 1024.f) + RMS_EPS) : 1.f; }
;     __device__ __forceinline__ void operator()(const f32x4 (&acc)[2][2][4][2], const Unit& u, int wr, int wc, int fr, int fq) const {
;     ...
;             for (int m = 0; m < 4; ++m) { const int row = row0 + ai * HALF + m * 16; const float rs = row_rs(ssq, row);
; #pragma unroll
;                 for (int bj = 0; bj < 2; ++bj) { f32x4 p0 = acc[ai][bj][m][0] * rs, p1 = acc[ai][bj][m][1] * rs;
;                     if (act) { p0[0] = fsilu(p0[0]); p0[1] = fsilu(p0[1]); p0[2] = fsilu(p0[2]); p0[3] = fsilu(p0[3]); p1[0] = fsilu(p1[0]); p1[1] = fsilu(p1[1]); p1[2] = fsilu(p1[2]); p1[3] = fsilu(p1[3]); }
;                     u32x4 w; w.x = cvt_pk_bf16(p0[0], p0[1]); w.y = cvt_pk_bf16(p0[2], p0[3]); w.z = cvt_pk_bf16(p1[0], p1[1]); w.w = cvt_pk_bf16(p1[2], p1[3]);
;                     *(u32x4*)(dst + (size_t)row * 512 + cbase + bj * HALF) = w; } }
.LBB0_640:
	v_lshl_add_u64 v[164:165], v[156:157], 0, s[42:43]
	v_cvt_pk_bf16_f32 v156, v160, v161
	v_cvt_pk_bf16_f32 v157, v158, v159
	v_cvt_pk_bf16_f32 v158, v154, v155
	v_cvt_pk_bf16_f32 v159, v162, v163
	global_store_dwordx4 v[164:165], v[156:159], off offset:256
	s_and_b64 vcc, exec, s[6:7]
	v_fmamk_f32 v136, v216, 0x3a800000, v170
	v_mul_f32_e32 v150, 0x4b800000, v136
	v_cmp_gt_f32_e64 s[8:9], s90, v136
	s_nop 1
	v_cndmask_b32_e64 v136, v136, v150, s[8:9]
	v_rsq_f32_e32 v136, v136
	s_nop 0
	v_mul_f32_e32 v150, 0x45800000, v136
	v_cndmask_b32_e64 v150, v136, v150, s[8:9]
	v_pk_mul_f32 v[156:157], v[14:15], v[150:151] op_sel_hi:[1,0]
	v_pk_mul_f32 v[160:161], v[12:13], v[150:151] op_sel_hi:[1,0]
	v_pk_mul_f32 v[154:155], v[10:11], v[150:151] op_sel_hi:[1,0]
	v_pk_mul_f32 v[158:159], v[8:9], v[150:151] op_sel_hi:[1,0]
	s_cbranch_vccnz .LBB0_642
	v_mul_f32_e32 v136, 0xbfb8aa3b, v160
	v_exp_f32_e32 v136, v136
	v_mul_f32_e32 v151, 0xbfb8aa3b, v161
	v_mul_f32_e32 v162, 0xbfb8aa3b, v156
	v_exp_f32_e32 v151, v151
	v_exp_f32_e32 v164, v162
	v_add_f32_e32 v136, 1.0, v136
	v_rcp_f32_e32 v162, v136
	v_add_f32_e32 v136, 1.0, v151
	v_mul_f32_e32 v151, 0xbfb8aa3b, v157
	v_rcp_f32_e32 v163, v136
	v_add_f32_e32 v136, 1.0, v164
	v_exp_f32_e32 v151, v151
	v_mul_f32_e32 v164, 0xbfb8aa3b, v158
	v_exp_f32_e32 v172, v164
	v_rcp_f32_e32 v164, v136
	v_add_f32_e32 v136, 1.0, v151
	v_rcp_f32_e32 v165, v136
	v_add_f32_e32 v136, 1.0, v172
	v_mul_f32_e32 v151, 0xbfb8aa3b, v154
	v_rcp_f32_e32 v172, v136
	v_mul_f32_e32 v136, 0xbfb8aa3b, v159
	v_exp_f32_e32 v151, v151
	v_mul_f32_e32 v173, 0xbfb8aa3b, v155
	v_exp_f32_e32 v136, v136
	v_exp_f32_e32 v173, v173
	v_add_f32_e32 v151, 1.0, v151
	v_rcp_f32_e32 v174, v151
	v_add_f32_e32 v136, 1.0, v136
	v_add_f32_e32 v151, 1.0, v173
	v_rcp_f32_e32 v175, v151
	v_rcp_f32_e32 v173, v136
	v_pk_mul_f32 v[156:157], v[156:157], v[164:165]
	v_pk_mul_f32 v[160:161], v[160:161], v[162:163]
	v_pk_mul_f32 v[154:155], v[154:155], v[174:175]
	v_pk_mul_f32 v[158:159], v[158:159], v[172:173]

; __device__ __forceinline__ float fsigm(float x) { return __builtin_amdgcn_rcpf(1.f + __expf(-x)); }
; __device__ __forceinline__ float row_rs(const float* ssq, int row) { return ssq ? rsqrtf(ssq[row] * (1.f / 1024.f) + RMS_EPS) : 1.f; }
;     __device__ __forceinline__ void operator()(const f32x4 (&acc)[2][2][4][2], const Unit& u, int wr, int wc, int fr, int fq) const {
;     ...
;         if (grp == 1) {
;             float lb[2][2][4];
; #pragma unroll
;             for (int bj = 0; bj < 2; ++bj)
; #pragma unroll
;                 for (int n = 0; n < 2; ++n) { const int c = cbase + bj * HALF + n * 4; const f32x4 l0 = *(const f32x4*)(lbl + c), l1 = *(const f32x4*)(lbl + 512 + c);
; #pragma unroll
;                     for (int j = 0; j < 4; ++j) lb[bj][n][j] = fsigm(l0[j] - l1[j]); }
; #pragma unroll
;             for (int ai = 0; ai < 2; ++ai)
; #pragma unroll
;                 for (int m = 0; m < 4; ++m) { const int row = row0 + ai * HALF + m * 16; const float rs = row_rs(ssq, row);
.LBB0_645:
	s_and_b64 vcc, exec, s[6:7]
	s_cbranch_vccz .LBB0_647
	v_ashrrev_i32_e32 v149, 31, v148
	v_lshlrev_b32_e32 v136, 2, v181
	v_lshl_add_u64 v[150:151], v[148:149], 2, s[30:31]
	global_load_dwordx4 v[152:155], v136, s[16:17] offset:2048
	global_load_dwordx4 v[156:159], v136, s[16:17]
	global_load_dwordx4 v[160:163], v136, s[16:17] offset:16
	global_load_dwordx4 v[172:175], v136, s[16:17] offset:2064
	global_load_dwordx4 v[176:179], v136, s[16:17] offset:2560
	global_load_dwordx4 v[182:185], v136, s[16:17] offset:512
	global_load_dwordx4 v[186:189], v136, s[16:17] offset:528
	global_load_dwordx4 v[190:193], v136, s[16:17] offset:2576
	s_waitcnt vmcnt(0)
	v_sub_f32_e32 v152, v156, v152
	global_load_dword v136, v[150:151], off
	global_load_dword v210, v[150:151], off offset:64
	global_load_dword v211, v[150:151], off offset:128
	global_load_dword v212, v[150:151], off offset:192
	global_load_dword v213, v[150:151], off offset:512
	global_load_dword v214, v[150:151], off offset:576
	global_load_dword v215, v[150:151], off offset:640
	global_load_dword v216, v[150:151], off offset:704
	v_sub_f32_e32 v153, v157, v153
	v_sub_f32_e32 v156, v160, v172
	v_sub_f32_e32 v160, v182, v176
	v_mul_f32_e32 v153, 0xbfb8aa3b, v153
	v_sub_f32_e32 v172, v188, v192
	v_mul_f32_e32 v176, 0xbfb8aa3b, v172
	v_exp_f32_e32 v153, v153
	v_sub_f32_e32 v154, v158, v154
	v_sub_f32_e32 v158, v162, v174
	v_mul_f32_e32 v152, 0xbfb8aa3b, v152
	v_add_f32_e32 v153, 1.0, v153
	v_rcp_f32_e32 v174, v153
	v_exp_f32_e32 v152, v152
	v_sub_f32_e32 v157, v161, v173
	v_sub_f32_e32 v161, v183, v177
	v_sub_f32_e32 v155, v159, v155
	v_mul_f32_e32 v160, 0xbfb8aa3b, v160
	v_mul_f32_e32 v161, 0xbfb8aa3b, v161
	v_add_f32_e32 v152, 1.0, v152
	v_sub_f32_e32 v159, v163, v175
	v_mul_f32_e32 v155, 0xbfb8aa3b, v155
	v_exp_f32_e32 v160, v160
	v_exp_f32_e32 v161, v161
	v_rcp_f32_e32 v175, v152
	v_exp_f32_e32 v155, v155
	v_exp_f32_e32 v152, v176
	v_add_f32_e32 v160, 1.0, v160
	v_add_f32_e32 v177, 1.0, v161
	v_sub_f32_e32 v176, 1.0, v175
	v_sub_f32_e32 v162, v184, v178
	v_add_f32_e32 v155, 1.0, v155
	v_rcp_f32_e32 v161, v160
	v_rcp_f32_e32 v160, v177
	v_add_f32_e32 v152, 1.0, v152
	v_mul_f32_e32 v159, 0xbfb8aa3b, v159
	v_mul_f32_e32 v162, 0xbfb8aa3b, v162
	v_mul_f32_e32 v154, 0xbfb8aa3b, v154
	v_exp_f32_e32 v159, v159
	v_exp_f32_e32 v162, v162
	v_exp_f32_e32 v154, v154
	v_sub_f32_e32 v163, v185, v179
	v_add_f32_e32 v159, 1.0, v159
	v_add_f32_e32 v178, 1.0, v162
	v_mul_f32_e32 v158, 0xbfb8aa3b, v158
	v_mul_f32_e32 v163, 0xbfb8aa3b, v163
	v_add_f32_e32 v154, 1.0, v154
	v_rcp_f32_e32 v162, v159
	v_rcp_f32_e32 v159, v178
	v_exp_f32_e32 v158, v158
	v_exp_f32_e32 v163, v163
	v_rcp_f32_e32 v173, v154
	v_sub_f32_e32 v164, v186, v190
	v_add_f32_e32 v158, 1.0, v158
	v_add_f32_e32 v179, 1.0, v163
	v_rcp_f32_e32 v163, v158
	v_rcp_f32_e32 v158, v179
	v_mul_f32_e32 v157, 0xbfb8aa3b, v157
	v_mul_f32_e32 v164, 0xbfb8aa3b, v164
	v_exp_f32_e32 v157, v157
	v_exp_f32_e32 v164, v164
	v_sub_f32_e32 v165, v187, v191
	v_mul_f32_e32 v156, 0xbfb8aa3b, v156
	v_add_f32_e32 v157, 1.0, v157
	v_add_f32_e32 v180, 1.0, v164
	v_mul_f32_e32 v165, 0xbfb8aa3b, v165
	v_rcp_f32_e32 v164, v157
	v_rcp_f32_e32 v157, v180
	v_exp_f32_e32 v156, v156
	v_exp_f32_e32 v165, v165
	v_add_f32_e32 v156, 1.0, v156
	v_add_f32_e32 v182, 1.0, v165
	v_rcp_f32_e32 v165, v156
	v_rcp_f32_e32 v156, v182
	s_waitcnt vmcnt(0)
	v_fmamk_f32 v136, v136, 0x3a800000, v170
	v_mul_f32_e32 v172, 0x4b800000, v136
	v_cmp_gt_f32_e32 vcc, s90, v136
	s_nop 1
	v_cndmask_b32_e32 v136, v136, v172, vcc
	v_rsq_f32_e32 v136, v136
	v_rcp_f32_e32 v172, v155
	v_rcp_f32_e32 v155, v152
	v_sub_f32_e32 v152, v189, v193
	v_mul_f32_e32 v153, 0x45800000, v136
	v_cndmask_b32_e32 v194, v136, v153, vcc
	v_mul_f32_e32 v136, v124, v194
	v_mul_f32_e32 v136, 0xbfb8aa3b, v136
	v_exp_f32_e32 v136, v136
	v_mul_f32_e32 v177, v125, v194
	v_mul_f32_e32 v177, 0xbfb8aa3b, v177
	v_mul_f32_e32 v152, 0xbfb8aa3b, v152
	v_add_f32_e32 v136, 1.0, v136
	v_rcp_f32_e32 v136, v136
	v_exp_f32_e32 v177, v177
	v_exp_f32_e32 v152, v152
	v_sub_f32_e32 v183, 1.0, v172
	v_fma_f32 v136, v176, v136, v175
	v_cmp_gt_f32_e32 vcc, s90, v136
	v_add_f32_e32 v177, 1.0, v177
	v_add_f32_e32 v152, 1.0, v152
	v_cndmask_b32_e64 v153, 0, 32, vcc
	v_ldexp_f32 v136, v136, v153
	v_log_f32_e32 v136, v136
	v_rcp_f32_e32 v178, v177
	v_rcp_f32_e32 v154, v152
	v_lshlrev_b64 v[152:153], 10, v[148:149]
	v_mul_f32_e32 v149, 0x3f317217, v136
	v_fma_f32 v149, v136, s95, -v149
	v_fmac_f32_e32 v149, 0x3377d1cf, v136
	v_sub_f32_e32 v177, 1.0, v174
	v_fmac_f32_e32 v149, 0x3f317217, v136
	v_cmp_lt_f32_e64 s[6:7], |v136|, s96
	v_fma_f32 v178, v177, v178, v174
	v_lshl_add_u64 v[152:153], s[10:11], 0, v[152:153]
	v_cndmask_b32_e64 v136, v136, v149, s[6:7]
	v_cndmask_b32_e32 v149, 0, v171, vcc
	v_cmp_gt_f32_e32 vcc, s90, v178
	v_sub_f32_e32 v136, v136, v149
	s_nop 0
	v_cndmask_b32_e64 v179, 0, 32, vcc
	v_ldexp_f32 v178, v178, v179
	v_log_f32_e32 v179, v178
	v_mul_f32_e32 v178, v126, v194
	v_mul_f32_e32 v178, 0xbfb8aa3b, v178
	v_exp_f32_e32 v178, v178
	v_mul_f32_e32 v149, 0x3f317217, v179
	v_fma_f32 v149, v179, s95, -v149
	v_fmac_f32_e32 v149, 0x3377d1cf, v179
	v_add_f32_e32 v178, 1.0, v178
	v_rcp_f32_e32 v180, v178
	v_sub_f32_e32 v178, 1.0, v173
	v_fmac_f32_e32 v149, 0x3f317217, v179
	v_cmp_lt_f32_e64 s[8:9], |v179|, s96
	v_fma_f32 v180, v178, v180, v173
	v_cmp_gt_f32_e64 s[6:7], s90, v180
	v_cndmask_b32_e64 v149, v179, v149, s[8:9]
	v_cndmask_b32_e32 v179, 0, v171, vcc
	v_cndmask_b32_e64 v182, 0, 32, s[6:7]
	v_ldexp_f32 v180, v180, v182
	v_sub_f32_e32 v182, v149, v179
	v_mul_f32_e32 v179, v127, v194
	v_mul_f32_e32 v179, 0xbfb8aa3b, v179
	v_exp_f32_e32 v179, v179
; __device__ __forceinline__ float fsigm(float x) { return __builtin_amdgcn_rcpf(1.f + __expf(-x)); }
; __device__ __forceinline__ float row_rs(const float* ssq, int row) { return ssq ? rsqrtf(ssq[row] * (1.f / 1024.f) + RMS_EPS) : 1.f; }
;     __device__ __forceinline__ void operator()(const f32x4 (&acc)[2][2][4][2], const Unit& u, int wr, int wc, int fr, int fq) const {
;     ...
;                 for (int m = 0; m < 4; ++m) { const int row = row0 + ai * HALF + m * 16; const float rs = row_rs(ssq, row);
; #pragma unroll
;                     for (int bj = 0; bj < 2; ++bj) { f16x4 o[2];
; #pragma unroll
;                         for (int n = 0; n < 2; ++n) { const f32x4 p = acc[ai][bj][m][n] * rs;
; #pragma unroll
;                             for (int j = 0; j < 4; ++j) { const float l = lb[bj][n][j]; const float f = l + (1.f - l) * fsigm(p[j]); o[n][j] = (_Float16)__logf(f); } }
;                         const u32x2 a0 = __builtin_bit_cast(u32x2, o[0]), a1 = __builtin_bit_cast(u32x2, o[1]); u32x4 w; w.x = a0.x; w.y = a0.y; w.z = a1.x; w.w = a1.y;
;                         *(u32x4*)(LF + (size_t)row * 512 + cbase + bj * HALF) = w; } }
	v_log_f32_e32 v180, v180
	v_add_f32_e32 v179, 1.0, v179
	v_rcp_f32_e32 v179, v179
	v_mul_f32_e32 v149, 0x3f317217, v180
	v_fma_f32 v149, v180, s95, -v149
	v_fmac_f32_e32 v149, 0x3377d1cf, v180
	v_fmac_f32_e32 v149, 0x3f317217, v180
	v_cmp_lt_f32_e64 vcc, |v180|, s96
	v_fma_f32 v179, v183, v179, v172
	s_nop 0
	v_cndmask_b32_e32 v149, v180, v149, vcc
	v_cmp_gt_f32_e32 vcc, s90, v179
	v_cndmask_b32_e64 v180, 0, v171, s[6:7]
	v_sub_f32_e32 v185, v149, v180
	v_cndmask_b32_e64 v184, 0, 32, vcc
	v_ldexp_f32 v179, v179, v184
	v_mul_f32_e32 v184, v120, v194
	v_log_f32_e32 v179, v179
	v_mul_f32_e32 v184, 0xbfb8aa3b, v184
	v_exp_f32_e32 v184, v184
	v_mul_f32_e32 v149, 0x3f317217, v179
	v_fma_f32 v180, v179, s95, -v149
	v_add_f32_e32 v149, 1.0, v184
	v_rcp_f32_e32 v184, v149
	v_sub_f32_e32 v149, 1.0, v165
	v_fmac_f32_e32 v180, 0x3377d1cf, v179
	v_fmac_f32_e32 v180, 0x3f317217, v179
	v_fma_f32 v184, v149, v184, v165
	v_cmp_gt_f32_e64 s[6:7], s90, v184
	v_cmp_lt_f32_e64 s[8:9], |v179|, s96
	s_nop 0
	v_cndmask_b32_e64 v186, 0, 32, s[6:7]
	v_cndmask_b32_e64 v179, v179, v180, s[8:9]
	v_cndmask_b32_e32 v180, 0, v171, vcc
	v_ldexp_f32 v184, v184, v186
	v_sub_f32_e32 v186, v179, v180
	v_mul_f32_e32 v180, v121, v194
	v_mul_f32_e32 v180, 0xbfb8aa3b, v180
	v_log_f32_e32 v184, v184
	v_exp_f32_e32 v180, v180
	v_cndmask_b32_e64 v187, 0, v171, s[6:7]
	v_mul_f32_e32 v179, 0x3f317217, v184
	v_add_f32_e32 v180, 1.0, v180
	v_fma_f32 v179, v184, s95, -v179
	v_rcp_f32_e32 v180, v180
	v_fmac_f32_e32 v179, 0x3377d1cf, v184
	v_fmac_f32_e32 v179, 0x3f317217, v184
	v_cmp_lt_f32_e64 vcc, |v184|, s96
	s_nop 1
	v_cndmask_b32_e32 v184, v184, v179, vcc
	v_sub_f32_e32 v179, 1.0, v164
	v_fma_f32 v180, v179, v180, v164
	v_cmp_gt_f32_e32 vcc, s90, v180
	v_sub_f32_e32 v184, v184, v187
	s_nop 0
	v_cndmask_b32_e64 v188, 0, 32, vcc
	v_ldexp_f32 v180, v180, v188
	v_log_f32_e32 v188, v180
	v_mul_f32_e32 v180, v122, v194
	v_mul_f32_e32 v180, 0xbfb8aa3b, v180
	v_exp_f32_e32 v180, v180
	v_mul_f32_e32 v187, 0x3f317217, v188
	v_fma_f32 v187, v188, s95, -v187
	v_fmac_f32_e32 v187, 0x3377d1cf, v188
	v_add_f32_e32 v180, 1.0, v180
	v_rcp_f32_e32 v189, v180
	v_sub_f32_e32 v180, 1.0, v163
	v_fmac_f32_e32 v187, 0x3f317217, v188
	v_cmp_lt_f32_e64 s[8:9], |v188|, s96
	v_fma_f32 v189, v180, v189, v163
	v_cmp_gt_f32_e64 s[6:7], s90, v189
	v_cndmask_b32_e64 v187, v188, v187, s[8:9]
	v_cndmask_b32_e32 v188, 0, v171, vcc
	v_cndmask_b32_e64 v190, 0, 32, s[6:7]
	v_ldexp_f32 v189, v189, v190
	v_mul_f32_e32 v190, v123, v194
	v_mul_f32_e32 v190, 0xbfb8aa3b, v190
	v_log_f32_e32 v189, v189
	v_exp_f32_e32 v190, v190
	v_sub_f32_e32 v187, v187, v188
	v_cndmask_b32_e64 v191, 0, v171, s[6:7]
	v_mul_f32_e32 v188, 0x3f317217, v189
	v_add_f32_e32 v190, 1.0, v190
	v_fma_f32 v188, v189, s95, -v188
	v_rcp_f32_e32 v190, v190
	v_fmac_f32_e32 v188, 0x3377d1cf, v189
	v_fmac_f32_e32 v188, 0x3f317217, v189
	v_cmp_lt_f32_e64 vcc, |v189|, s96
	s_nop 1
	v_cndmask_b32_e32 v189, v189, v188, vcc
	v_sub_f32_e32 v188, 1.0, v162
	v_fma_f32 v190, v188, v190, v162
	v_cmp_gt_f32_e32 vcc, s90, v190
	v_sub_f32_e32 v189, v189, v191
	v_cvt_pk_f16_f32 v191, v185, v186
	v_cndmask_b32_e64 v192, 0, 32, vcc
	v_ldexp_f32 v190, v190, v192
	v_log_f32_e32 v192, v190
	v_cvt_pk_f16_f32 v190, v136, v182
	v_cndmask_b32_e32 v182, 0, v171, vcc
	v_mul_f32_e32 v136, 0x3f317217, v192
	v_fma_f32 v136, v192, s95, -v136
	v_fmac_f32_e32 v136, 0x3377d1cf, v192
	v_fmac_f32_e32 v136, 0x3f317217, v192
	v_cmp_lt_f32_e64 s[6:7], |v192|, s96
	s_nop 1
	v_cndmask_b32_e64 v136, v192, v136, s[6:7]
	v_sub_f32_e32 v136, v136, v182
	v_mul_f32_e32 v182, v116, v194
	v_mul_f32_e32 v182, 0xbfb8aa3b, v182
	v_exp_f32_e32 v182, v182
	v_cvt_pk_f16_f32 v193, v189, v136
	v_cvt_pk_f16_f32 v192, v184, v187
	v_sub_f32_e32 v184, 1.0, v161
	v_add_f32_e32 v136, 1.0, v182
	v_rcp_f32_e32 v182, v136
	v_lshlrev_b32_e32 v136, 1, v181
	v_lshl_add_u64 v[152:153], v[152:153], 0, v[136:137]
	global_store_dwordx4 v[152:153], v[190:193], off
	v_fma_f32 v181, v184, v182, v161
	v_cmp_gt_f32_e32 vcc, s90, v181
	s_nop 1
	v_cndmask_b32_e64 v182, 0, 32, vcc
	v_ldexp_f32 v181, v181, v182
	v_log_f32_e32 v182, v181
	v_mul_f32_e32 v181, v117, v194
	v_mul_f32_e32 v181, 0xbfb8aa3b, v181
	v_exp_f32_e32 v181, v181
	v_mul_f32_e32 v185, 0x3f317217, v182
	v_fma_f32 v185, v182, s95, -v185
	v_fmac_f32_e32 v185, 0x3377d1cf, v182
	v_add_f32_e32 v181, 1.0, v181
	v_rcp_f32_e32 v186, v181
	v_sub_f32_e32 v181, 1.0, v160
	v_fmac_f32_e32 v185, 0x3f317217, v182
	v_cmp_lt_f32_e64 s[8:9], |v182|, s96
	v_fma_f32 v186, v181, v186, v160
	v_cmp_gt_f32_e64 s[6:7], s90, v186
	v_cndmask_b32_e64 v182, v182, v185, s[8:9]
	v_cndmask_b32_e32 v185, 0, v171, vcc
	v_cndmask_b32_e64 v187, 0, 32, s[6:7]
	v_ldexp_f32 v186, v186, v187
	v_mul_f32_e32 v187, v118, v194
	v_mul_f32_e32 v187, 0xbfb8aa3b, v187
	v_log_f32_e32 v186, v186
	v_exp_f32_e32 v187, v187
	v_sub_f32_e32 v182, v182, v185
	v_cndmask_b32_e64 v189, 0, v171, s[6:7]
	v_mul_f32_e32 v185, 0x3f317217, v186
	v_add_f32_e32 v187, 1.0, v187
	v_fma_f32 v185, v186, s95, -v185
	v_rcp_f32_e32 v187, v187
	v_fmac_f32_e32 v185, 0x3377d1cf, v186
	v_fmac_f32_e32 v185, 0x3f317217, v186
	v_cmp_lt_f32_e64 vcc, |v186|, s96
	s_nop 1
	v_cndmask_b32_e32 v186, v186, v185, vcc
	v_sub_f32_e32 v185, 1.0, v159
	v_fma_f32 v187, v185, v187, v159
	v_cmp_gt_f32_e32 vcc, s90, v187
	v_sub_f32_e32 v189, v186, v189
	s_nop 0
	v_cndmask_b32_e64 v190, 0, 32, vcc
	v_ldexp_f32 v187, v187, v190
	v_mul_f32_e32 v190, v119, v194
	v_log_f32_e32 v187, v187
	v_mul_f32_e32 v190, 0xbfb8aa3b, v190
	v_exp_f32_e32 v190, v190
	v_mul_f32_e32 v186, 0x3f317217, v187
	v_fma_f32 v191, v187, s95, -v186
	v_add_f32_e32 v186, 1.0, v190
	v_rcp_f32_e32 v190, v186
; __device__ __forceinline__ float fsigm(float x) { return __builtin_amdgcn_rcpf(1.f + __expf(-x)); }
; __device__ __forceinline__ float row_rs(const float* ssq, int row) { return ssq ? rsqrtf(ssq[row] * (1.f / 1024.f) + RMS_EPS) : 1.f; }
;     __device__ __forceinline__ void operator()(const f32x4 (&acc)[2][2][4][2], const Unit& u, int wr, int wc, int fr, int fq) const {
;     ...
;                 for (int m = 0; m < 4; ++m) { const int row = row0 + ai * HALF + m * 16; const float rs = row_rs(ssq, row);
; #pragma unroll
;                     for (int bj = 0; bj < 2; ++bj) { f16x4 o[2];
; #pragma unroll
;                         for (int n = 0; n < 2; ++n) { const f32x4 p = acc[ai][bj][m][n] * rs;
; #pragma unroll
;                             for (int j = 0; j < 4; ++j) { const float l = lb[bj][n][j]; const float f = l + (1.f - l) * fsigm(p[j]); o[n][j] = (_Float16)__logf(f); } }
;                         const u32x2 a0 = __builtin_bit_cast(u32x2, o[0]), a1 = __builtin_bit_cast(u32x2, o[1]); u32x4 w; w.x = a0.x; w.y = a0.y; w.z = a1.x; w.w = a1.y;
;                         *(u32x4*)(LF + (size_t)row * 512 + cbase + bj * HALF) = w; } }
	v_sub_f32_e32 v186, 1.0, v158
	v_fmac_f32_e32 v191, 0x3377d1cf, v187
	v_fmac_f32_e32 v191, 0x3f317217, v187
	v_fma_f32 v190, v186, v190, v158
	v_cmp_gt_f32_e64 s[6:7], s90, v190
	v_cmp_lt_f32_e64 s[8:9], |v187|, s96
	s_nop 0
	v_cndmask_b32_e64 v192, 0, 32, s[6:7]
	v_ldexp_f32 v190, v190, v192
	v_log_f32_e32 v190, v190
	v_mul_f32_e32 v192, v112, v194
	v_mul_f32_e32 v192, 0xbfb8aa3b, v192
	v_exp_f32_e32 v192, v192
	v_cndmask_b32_e64 v187, v187, v191, s[8:9]
	v_cndmask_b32_e32 v191, 0, v171, vcc
	v_sub_f32_e32 v187, v187, v191
	v_mul_f32_e32 v191, 0x3f317217, v190
	v_fma_f32 v191, v190, s95, -v191
	v_fmac_f32_e32 v191, 0x3377d1cf, v190
	v_add_f32_e32 v192, 1.0, v192
	v_fmac_f32_e32 v191, 0x3f317217, v190
	v_cmp_lt_f32_e64 vcc, |v190|, s96
	v_rcp_f32_e32 v192, v192
	s_nop 0
	v_cndmask_b32_e32 v190, v190, v191, vcc
	v_cndmask_b32_e64 v191, 0, v171, s[6:7]
	v_sub_f32_e32 v190, v190, v191
	v_cvt_pk_f16_f32 v193, v187, v190
	v_sub_f32_e32 v187, 1.0, v157
	v_fma_f32 v190, v187, v192, v157
	v_cmp_gt_f32_e32 vcc, s90, v190
	v_cvt_pk_f16_f32 v192, v182, v189
	s_nop 0
	v_cndmask_b32_e64 v191, 0, 32, vcc
	v_ldexp_f32 v190, v190, v191
	v_mul_f32_e32 v191, v113, v194
	v_log_f32_e32 v190, v190
	v_mul_f32_e32 v191, 0xbfb8aa3b, v191
	v_exp_f32_e32 v191, v191
	v_mul_f32_e32 v182, 0x3f317217, v190
	v_fma_f32 v189, v190, s95, -v182
	v_add_f32_e32 v182, 1.0, v191
	v_rcp_f32_e32 v191, v182
	v_fmac_f32_e32 v189, 0x3377d1cf, v190
	v_sub_f32_e32 v182, 1.0, v156
	v_fmac_f32_e32 v189, 0x3f317217, v190
	v_fma_f32 v191, v182, v191, v156
	v_cmp_lt_f32_e64 s[8:9], |v190|, s96
	v_cmp_gt_f32_e64 s[6:7], s90, v191
	s_nop 0
	v_cndmask_b32_e64 v189, v190, v189, s[8:9]
	v_cndmask_b32_e32 v190, 0, v171, vcc
	v_cndmask_b32_e64 v195, 0, 32, s[6:7]
	v_sub_f32_e32 v196, v189, v190
	v_mul_f32_e32 v190, v114, v194
	v_ldexp_f32 v191, v191, v195
	v_mul_f32_e32 v190, 0xbfb8aa3b, v190
	v_log_f32_e32 v191, v191
	v_exp_f32_e32 v190, v190
	v_cndmask_b32_e64 v195, 0, v171, s[6:7]
	v_mul_f32_e32 v189, 0x3f317217, v191
	v_add_f32_e32 v190, 1.0, v190
	v_fma_f32 v189, v191, s95, -v189
	v_rcp_f32_e32 v190, v190
	v_fmac_f32_e32 v189, 0x3377d1cf, v191
	v_fmac_f32_e32 v189, 0x3f317217, v191
	v_cmp_lt_f32_e64 vcc, |v191|, s96
	s_nop 1
	v_cndmask_b32_e32 v191, v191, v189, vcc
	v_sub_f32_e32 v189, 1.0, v155
	v_fma_f32 v190, v189, v190, v155
	v_cmp_gt_f32_e32 vcc, s90, v190
	v_sub_f32_e32 v191, v191, v195
	s_nop 0
	v_cndmask_b32_e64 v197, 0, 32, vcc
	v_ldexp_f32 v190, v190, v197
	v_log_f32_e32 v197, v190
	v_mul_f32_e32 v190, v115, v194
	v_mul_f32_e32 v190, 0xbfb8aa3b, v190
	v_exp_f32_e32 v190, v190
	v_mul_f32_e32 v194, 0x3f317217, v197
	v_fma_f32 v194, v197, s95, -v194
	v_fmac_f32_e32 v194, 0x3377d1cf, v197
	v_add_f32_e32 v190, 1.0, v190
	v_rcp_f32_e32 v195, v190
	v_sub_f32_e32 v190, 1.0, v154
	v_fmac_f32_e32 v194, 0x3f317217, v197
	v_cmp_lt_f32_e64 s[8:9], |v197|, s96
	v_fma_f32 v195, v190, v195, v154
	v_cmp_gt_f32_e64 s[6:7], s90, v195
	v_cndmask_b32_e64 v194, v197, v194, s[8:9]
	v_cndmask_b32_e32 v197, 0, v171, vcc
	v_cndmask_b32_e64 v198, 0, 32, s[6:7]
	v_ldexp_f32 v195, v195, v198
	v_log_f32_e32 v195, v195
	v_sub_f32_e32 v194, v194, v197
	v_mul_f32_e32 v197, 0x3f317217, v195
	v_fma_f32 v197, v195, s95, -v197
	v_fmac_f32_e32 v197, 0x3377d1cf, v195
	v_fmac_f32_e32 v197, 0x3f317217, v195
	v_cmp_lt_f32_e64 vcc, |v195|, s96
	s_nop 1
	v_cndmask_b32_e32 v195, v195, v197, vcc
	v_cndmask_b32_e64 v197, 0, v171, s[6:7]
	v_sub_f32_e32 v195, v195, v197
	v_cvt_pk_f16_f32 v195, v194, v195
	v_cvt_pk_f16_f32 v194, v196, v191
	global_store_dwordx4 v[152:153], v[192:195], off offset:256
	s_nop 1
	v_or_b32_e32 v192, 16, v148
	v_ashrrev_i32_e32 v193, 31, v192
	v_lshl_add_u64 v[194:195], v[192:193], 2, s[30:31]
	v_lshlrev_b64 v[196:197], 10, v[192:193]
	v_lshl_add_u64 v[196:197], s[10:11], 0, v[196:197]
	v_lshl_add_u64 v[196:197], v[196:197], 0, v[136:137]
	v_fmamk_f32 v191, v210, 0x3a800000, v170
	v_mul_f32_e32 v194, 0x4b800000, v191
	v_cmp_gt_f32_e32 vcc, s90, v191
	s_nop 1
	v_cndmask_b32_e32 v191, v191, v194, vcc
	v_rsq_f32_e32 v191, v191
	s_nop 0
	v_mul_f32_e32 v194, 0x45800000, v191
	v_cndmask_b32_e32 v191, v191, v194, vcc
	v_mul_f32_e32 v194, v108, v191
	v_mul_f32_e32 v194, 0xbfb8aa3b, v194
	v_exp_f32_e32 v194, v194
	v_mul_f32_e32 v193, v109, v191
	v_mul_f32_e32 v193, 0xbfb8aa3b, v193
	v_exp_f32_e32 v193, v193
	v_add_f32_e32 v194, 1.0, v194
	v_rcp_f32_e32 v194, v194
	v_add_f32_e32 v193, 1.0, v193
	v_rcp_f32_e32 v193, v193
	v_fma_f32 v194, v176, v194, v175
	v_cmp_gt_f32_e32 vcc, s90, v194
	v_fma_f32 v193, v177, v193, v174
	s_nop 0
	v_cndmask_b32_e64 v195, 0, 32, vcc
	v_ldexp_f32 v194, v194, v195
	v_log_f32_e32 v194, v194
	s_nop 0
	v_mul_f32_e32 v192, 0x3f317217, v194
	v_fma_f32 v192, v194, s95, -v192
	v_fmac_f32_e32 v192, 0x3377d1cf, v194
	v_fmac_f32_e32 v192, 0x3f317217, v194
	v_cmp_lt_f32_e64 s[6:7], |v194|, s96
	s_nop 1
	v_cndmask_b32_e64 v192, v194, v192, s[6:7]
	v_cndmask_b32_e32 v194, 0, v171, vcc
	v_cmp_gt_f32_e32 vcc, s90, v193
	v_sub_f32_e32 v192, v192, v194
	s_nop 0
	v_cndmask_b32_e64 v194, 0, 32, vcc
	v_ldexp_f32 v193, v193, v194
	v_mul_f32_e32 v194, v110, v191
	v_mul_f32_e32 v194, 0xbfb8aa3b, v194
	v_exp_f32_e32 v194, v194
	v_log_f32_e32 v193, v193
	v_cndmask_b32_e32 v198, 0, v171, vcc
	v_add_f32_e32 v194, 1.0, v194
	v_rcp_f32_e32 v194, v194
	v_mul_f32_e32 v195, 0x3f317217, v193
	v_fma_f32 v195, v193, s95, -v195
	v_fmac_f32_e32 v195, 0x3377d1cf, v193
	v_fmac_f32_e32 v195, 0x3f317217, v193
	v_cmp_lt_f32_e64 s[6:7], |v193|, s96
	v_fma_f32 v194, v178, v194, v173
	s_nop 0
	v_cndmask_b32_e64 v193, v193, v195, s[6:7]
	v_cmp_gt_f32_e64 s[6:7], s90, v194
	v_sub_f32_e32 v198, v193, v198
	v_cvt_pk_f16_f32 v192, v192, v198
; __device__ __forceinline__ float fsigm(float x) { return __builtin_amdgcn_rcpf(1.f + __expf(-x)); }
; __device__ __forceinline__ float row_rs(const float* ssq, int row) { return ssq ? rsqrtf(ssq[row] * (1.f / 1024.f) + RMS_EPS) : 1.f; }
;     __device__ __forceinline__ void operator()(const f32x4 (&acc)[2][2][4][2], const Unit& u, int wr, int wc, int fr, int fq) const {
;     ...
;                 for (int m = 0; m < 4; ++m) { const int row = row0 + ai * HALF + m * 16; const float rs = row_rs(ssq, row);
; #pragma unroll
;                     for (int bj = 0; bj < 2; ++bj) { f16x4 o[2];
; #pragma unroll
;                         for (int n = 0; n < 2; ++n) { const f32x4 p = acc[ai][bj][m][n] * rs;
; #pragma unroll
;                             for (int j = 0; j < 4; ++j) { const float l = lb[bj][n][j]; const float f = l + (1.f - l) * fsigm(p[j]); o[n][j] = (_Float16)__logf(f); } }
;                         const u32x2 a0 = __builtin_bit_cast(u32x2, o[0]), a1 = __builtin_bit_cast(u32x2, o[1]); u32x4 w; w.x = a0.x; w.y = a0.y; w.z = a1.x; w.w = a1.y;
;                         *(u32x4*)(LF + (size_t)row * 512 + cbase + bj * HALF) = w; } }
	v_cndmask_b32_e64 v195, 0, 32, s[6:7]
	v_ldexp_f32 v194, v194, v195
	v_mul_f32_e32 v195, v111, v191
	v_mul_f32_e32 v195, 0xbfb8aa3b, v195
	v_exp_f32_e32 v195, v195
	v_log_f32_e32 v194, v194
	v_add_f32_e32 v195, 1.0, v195
	v_rcp_f32_e32 v195, v195
	v_mul_f32_e32 v193, 0x3f317217, v194
	v_fma_f32 v193, v194, s95, -v193
	v_fmac_f32_e32 v193, 0x3377d1cf, v194
	v_fma_f32 v195, v183, v195, v172
	v_cmp_gt_f32_e32 vcc, s90, v195
	v_fmac_f32_e32 v193, 0x3f317217, v194
	v_cmp_lt_f32_e64 s[8:9], |v194|, s96
	v_cndmask_b32_e64 v199, 0, 32, vcc
	v_ldexp_f32 v195, v195, v199
	v_mul_f32_e32 v199, v104, v191
	v_mul_f32_e32 v199, 0xbfb8aa3b, v199
	v_log_f32_e32 v195, v195
	v_exp_f32_e32 v199, v199
	v_cndmask_b32_e64 v193, v194, v193, s[8:9]
	v_cndmask_b32_e64 v194, 0, v171, s[6:7]
	v_sub_f32_e32 v193, v193, v194
	v_mul_f32_e32 v194, 0x3f317217, v195
	v_add_f32_e32 v199, 1.0, v199
	v_fma_f32 v194, v195, s95, -v194
	v_rcp_f32_e32 v199, v199
	v_fmac_f32_e32 v194, 0x3377d1cf, v195
	v_fmac_f32_e32 v194, 0x3f317217, v195
	v_cmp_lt_f32_e64 s[6:7], |v195|, s96
	v_fma_f32 v199, v149, v199, v165
	s_nop 0
	v_cndmask_b32_e64 v194, v195, v194, s[6:7]
	v_cndmask_b32_e32 v195, 0, v171, vcc
	v_sub_f32_e32 v194, v194, v195
	v_mul_f32_e32 v195, v105, v191
	v_cmp_gt_f32_e32 vcc, s90, v199
	v_mul_f32_e32 v195, 0xbfb8aa3b, v195
	v_exp_f32_e32 v195, v195
	v_cndmask_b32_e64 v200, 0, 32, vcc
	v_ldexp_f32 v199, v199, v200
	v_log_f32_e32 v199, v199
	v_add_f32_e32 v195, 1.0, v195
	v_rcp_f32_e32 v195, v195
	v_cvt_pk_f16_f32 v193, v193, v194
	v_mul_f32_e32 v194, 0x3f317217, v199
	v_fma_f32 v194, v199, s95, -v194
	v_fmac_f32_e32 v194, 0x3377d1cf, v199
	v_fmac_f32_e32 v194, 0x3f317217, v199
	v_cmp_lt_f32_e64 s[6:7], |v199|, s96
	v_fma_f32 v195, v179, v195, v164
	v_cndmask_b32_e32 v198, 0, v171, vcc
	v_cndmask_b32_e64 v194, v199, v194, s[6:7]
	v_cmp_gt_f32_e32 vcc, s90, v195
	v_sub_f32_e32 v194, v194, v198
	s_nop 0
	v_cndmask_b32_e64 v198, 0, 32, vcc
	v_ldexp_f32 v195, v195, v198
	v_mul_f32_e32 v198, v106, v191
	v_mul_f32_e32 v198, 0xbfb8aa3b, v198
	v_exp_f32_e32 v198, v198
	v_log_f32_e32 v195, v195
	v_cndmask_b32_e32 v200, 0, v171, vcc
	v_add_f32_e32 v198, 1.0, v198
	v_rcp_f32_e32 v198, v198
	v_mul_f32_e32 v199, 0x3f317217, v195
	v_fma_f32 v199, v195, s95, -v199
	v_fmac_f32_e32 v199, 0x3377d1cf, v195
	v_fmac_f32_e32 v199, 0x3f317217, v195
	v_cmp_lt_f32_e64 s[6:7], |v195|, s96
	v_fma_f32 v198, v180, v198, v163
	s_nop 0
	v_cndmask_b32_e64 v195, v195, v199, s[6:7]
	v_cmp_gt_f32_e64 s[6:7], s90, v198
	v_sub_f32_e32 v200, v195, v200
	v_cvt_pk_f16_f32 v194, v194, v200
	v_cndmask_b32_e64 v199, 0, 32, s[6:7]
	v_ldexp_f32 v198, v198, v199
	v_mul_f32_e32 v199, v107, v191
	v_mul_f32_e32 v199, 0xbfb8aa3b, v199
	v_exp_f32_e32 v199, v199
	v_log_f32_e32 v198, v198
	v_add_f32_e32 v199, 1.0, v199
	v_rcp_f32_e32 v199, v199
	v_mul_f32_e32 v195, 0x3f317217, v198
	v_fma_f32 v195, v198, s95, -v195
	v_fmac_f32_e32 v195, 0x3377d1cf, v198
	v_fma_f32 v199, v188, v199, v162
	v_cmp_gt_f32_e32 vcc, s90, v199
	v_fmac_f32_e32 v195, 0x3f317217, v198
	v_cmp_lt_f32_e64 s[8:9], |v198|, s96
	v_cndmask_b32_e64 v201, 0, 32, vcc
	v_ldexp_f32 v199, v199, v201
	v_log_f32_e32 v199, v199
	v_mul_f32_e32 v201, v100, v191
	v_mul_f32_e32 v201, 0xbfb8aa3b, v201
	v_exp_f32_e32 v201, v201
	v_cndmask_b32_e64 v195, v198, v195, s[8:9]
	v_cndmask_b32_e64 v198, 0, v171, s[6:7]
	v_sub_f32_e32 v195, v195, v198
	v_mul_f32_e32 v198, 0x3f317217, v199
	v_fma_f32 v198, v199, s95, -v198
	v_fmac_f32_e32 v198, 0x3377d1cf, v199
	v_add_f32_e32 v201, 1.0, v201
	v_fmac_f32_e32 v198, 0x3f317217, v199
	v_cmp_lt_f32_e64 s[6:7], |v199|, s96
	v_rcp_f32_e32 v201, v201
	s_nop 0
	v_cndmask_b32_e64 v198, v199, v198, s[6:7]
	v_cndmask_b32_e32 v199, 0, v171, vcc
	v_sub_f32_e32 v198, v198, v199
	v_cvt_pk_f16_f32 v195, v195, v198
	v_fma_f32 v198, v184, v201, v161
	global_store_dwordx4 v[196:197], v[192:195], off
	v_cmp_gt_f32_e32 vcc, s90, v198
	s_nop 0
	v_mul_f32_e32 v193, v101, v191
	v_mul_f32_e32 v193, 0xbfb8aa3b, v193
	v_cndmask_b32_e64 v199, 0, 32, vcc
	v_exp_f32_e32 v193, v193
	v_ldexp_f32 v198, v198, v199
	v_log_f32_e32 v198, v198
	v_cndmask_b32_e32 v194, 0, v171, vcc
	v_add_f32_e32 v193, 1.0, v193
	v_rcp_f32_e32 v193, v193
	v_mul_f32_e32 v192, 0x3f317217, v198
	v_fma_f32 v192, v198, s95, -v192
	v_fmac_f32_e32 v192, 0x3377d1cf, v198
	v_fmac_f32_e32 v192, 0x3f317217, v198
	v_cmp_lt_f32_e64 s[6:7], |v198|, s96
	v_fma_f32 v193, v181, v193, v160
	v_cmp_gt_f32_e32 vcc, s90, v193
	v_cndmask_b32_e64 v192, v198, v192, s[6:7]
	v_sub_f32_e32 v192, v192, v194
	v_cndmask_b32_e64 v194, 0, 32, vcc
	v_ldexp_f32 v193, v193, v194
	v_mul_f32_e32 v194, v102, v191
	v_mul_f32_e32 v194, 0xbfb8aa3b, v194
	v_exp_f32_e32 v194, v194
	v_log_f32_e32 v193, v193
	v_cndmask_b32_e32 v198, 0, v171, vcc
	v_add_f32_e32 v194, 1.0, v194
	v_rcp_f32_e32 v194, v194
	v_mul_f32_e32 v195, 0x3f317217, v193
	v_fma_f32 v195, v193, s95, -v195
	v_fmac_f32_e32 v195, 0x3377d1cf, v193
	v_fmac_f32_e32 v195, 0x3f317217, v193
	v_cmp_lt_f32_e64 s[6:7], |v193|, s96
	v_fma_f32 v194, v185, v194, v159
	s_nop 0
	v_cndmask_b32_e64 v193, v193, v195, s[6:7]
	v_cmp_gt_f32_e64 s[6:7], s90, v194
	v_sub_f32_e32 v198, v193, v198
	v_cvt_pk_f16_f32 v192, v192, v198
	v_cndmask_b32_e64 v195, 0, 32, s[6:7]
	v_ldexp_f32 v194, v194, v195
	v_mul_f32_e32 v195, v103, v191
	v_mul_f32_e32 v195, 0xbfb8aa3b, v195
	v_exp_f32_e32 v195, v195
	v_log_f32_e32 v194, v194
	v_add_f32_e32 v195, 1.0, v195
	v_rcp_f32_e32 v195, v195
	v_mul_f32_e32 v193, 0x3f317217, v194
	v_fma_f32 v193, v194, s95, -v193
	v_fmac_f32_e32 v193, 0x3377d1cf, v194
	v_fma_f32 v195, v186, v195, v158
	v_cmp_gt_f32_e32 vcc, s90, v195
	v_fmac_f32_e32 v193, 0x3f317217, v194
; __device__ __forceinline__ float fsigm(float x) { return __builtin_amdgcn_rcpf(1.f + __expf(-x)); }
; __device__ __forceinline__ float row_rs(const float* ssq, int row) { return ssq ? rsqrtf(ssq[row] * (1.f / 1024.f) + RMS_EPS) : 1.f; }
;     __device__ __forceinline__ void operator()(const f32x4 (&acc)[2][2][4][2], const Unit& u, int wr, int wc, int fr, int fq) const {
;     ...
;                 for (int m = 0; m < 4; ++m) { const int row = row0 + ai * HALF + m * 16; const float rs = row_rs(ssq, row);
; #pragma unroll
;                     for (int bj = 0; bj < 2; ++bj) { f16x4 o[2];
; #pragma unroll
;                         for (int n = 0; n < 2; ++n) { const f32x4 p = acc[ai][bj][m][n] * rs;
; #pragma unroll
;                             for (int j = 0; j < 4; ++j) { const float l = lb[bj][n][j]; const float f = l + (1.f - l) * fsigm(p[j]); o[n][j] = (_Float16)__logf(f); } }
;                         const u32x2 a0 = __builtin_bit_cast(u32x2, o[0]), a1 = __builtin_bit_cast(u32x2, o[1]); u32x4 w; w.x = a0.x; w.y = a0.y; w.z = a1.x; w.w = a1.y;
;                         *(u32x4*)(LF + (size_t)row * 512 + cbase + bj * HALF) = w; } }
	v_cmp_lt_f32_e64 s[8:9], |v194|, s96
	v_cndmask_b32_e64 v199, 0, 32, vcc
	v_ldexp_f32 v195, v195, v199
	v_mul_f32_e32 v199, v96, v191
	v_mul_f32_e32 v199, 0xbfb8aa3b, v199
	v_log_f32_e32 v195, v195
	v_exp_f32_e32 v199, v199
	v_cndmask_b32_e64 v193, v194, v193, s[8:9]
	v_cndmask_b32_e64 v194, 0, v171, s[6:7]
	v_sub_f32_e32 v193, v193, v194
	v_mul_f32_e32 v194, 0x3f317217, v195
	v_add_f32_e32 v199, 1.0, v199
	v_fma_f32 v194, v195, s95, -v194
	v_rcp_f32_e32 v199, v199
	v_fmac_f32_e32 v194, 0x3377d1cf, v195
	v_fmac_f32_e32 v194, 0x3f317217, v195
	v_cmp_lt_f32_e64 s[6:7], |v195|, s96
	v_fma_f32 v199, v187, v199, v157
	s_nop 0
	v_cndmask_b32_e64 v194, v195, v194, s[6:7]
	v_cndmask_b32_e32 v195, 0, v171, vcc
	v_sub_f32_e32 v194, v194, v195
	v_mul_f32_e32 v195, v97, v191
	v_cmp_gt_f32_e32 vcc, s90, v199
	v_mul_f32_e32 v195, 0xbfb8aa3b, v195
	v_exp_f32_e32 v195, v195
	v_cndmask_b32_e64 v200, 0, 32, vcc
	v_ldexp_f32 v199, v199, v200
	v_log_f32_e32 v199, v199
	v_add_f32_e32 v195, 1.0, v195
	v_rcp_f32_e32 v195, v195
	v_cvt_pk_f16_f32 v193, v193, v194
	v_mul_f32_e32 v194, 0x3f317217, v199
	v_fma_f32 v194, v199, s95, -v194
	v_fmac_f32_e32 v194, 0x3377d1cf, v199
	v_fmac_f32_e32 v194, 0x3f317217, v199
	v_cmp_lt_f32_e64 s[6:7], |v199|, s96
	v_fma_f32 v195, v182, v195, v156
	v_cndmask_b32_e32 v198, 0, v171, vcc
	v_cndmask_b32_e64 v194, v199, v194, s[6:7]
	v_cmp_gt_f32_e32 vcc, s90, v195
	v_sub_f32_e32 v194, v194, v198
	s_nop 0
	v_cndmask_b32_e64 v198, 0, 32, vcc
	v_ldexp_f32 v195, v195, v198
	v_mul_f32_e32 v198, v98, v191
	v_mul_f32_e32 v198, 0xbfb8aa3b, v198
	v_exp_f32_e32 v198, v198
	v_log_f32_e32 v195, v195
	v_mul_f32_e32 v191, v99, v191
	v_mul_f32_e32 v191, 0xbfb8aa3b, v191
	v_add_f32_e32 v198, 1.0, v198
	v_rcp_f32_e32 v198, v198
	v_exp_f32_e32 v191, v191
	v_mul_f32_e32 v199, 0x3f317217, v195
	v_fma_f32 v199, v195, s95, -v199
	v_fmac_f32_e32 v199, 0x3377d1cf, v195
	v_fmac_f32_e32 v199, 0x3f317217, v195
	v_cmp_lt_f32_e64 s[6:7], |v195|, s96
	v_fma_f32 v198, v189, v198, v155
	v_add_f32_e32 v191, 1.0, v191
	v_cndmask_b32_e64 v195, v195, v199, s[6:7]
	v_cmp_gt_f32_e64 s[6:7], s90, v198
	v_rcp_f32_e32 v191, v191
	s_nop 0
	v_cndmask_b32_e64 v199, 0, 32, s[6:7]
	v_ldexp_f32 v198, v198, v199
	v_log_f32_e32 v198, v198
	v_fma_f32 v191, v190, v191, v154
	v_cndmask_b32_e32 v199, 0, v171, vcc
	v_cmp_gt_f32_e32 vcc, s90, v191
	v_sub_f32_e32 v199, v195, v199
	v_mul_f32_e32 v195, 0x3f317217, v198
	v_cndmask_b32_e64 v200, 0, 32, vcc
	v_ldexp_f32 v191, v191, v200
	v_fma_f32 v195, v198, s95, -v195
	v_log_f32_e32 v191, v191
	v_fmac_f32_e32 v195, 0x3377d1cf, v198
	v_fmac_f32_e32 v195, 0x3f317217, v198
	v_cmp_lt_f32_e64 s[8:9], |v198|, s96
	v_cvt_pk_f16_f32 v194, v194, v199
	s_nop 0
	v_cndmask_b32_e64 v195, v198, v195, s[8:9]
	v_cndmask_b32_e64 v198, 0, v171, s[6:7]
	v_sub_f32_e32 v195, v195, v198
	v_mul_f32_e32 v198, 0x3f317217, v191
	v_fma_f32 v198, v191, s95, -v198
	v_fmac_f32_e32 v198, 0x3377d1cf, v191
	v_fmac_f32_e32 v198, 0x3f317217, v191
	v_cmp_lt_f32_e64 s[6:7], |v191|, s96
	s_nop 1
	v_cndmask_b32_e64 v191, v191, v198, s[6:7]
	v_cndmask_b32_e32 v198, 0, v171, vcc
	v_sub_f32_e32 v191, v191, v198
	v_cvt_pk_f16_f32 v195, v195, v191
	global_store_dwordx4 v[196:197], v[192:195], off offset:256
	s_nop 1
	v_or_b32_e32 v192, 32, v148
	v_ashrrev_i32_e32 v193, 31, v192
	v_lshl_add_u64 v[194:195], v[192:193], 2, s[30:31]
	v_lshlrev_b64 v[196:197], 10, v[192:193]
	v_lshl_add_u64 v[196:197], s[10:11], 0, v[196:197]
	v_lshl_add_u64 v[196:197], v[196:197], 0, v[136:137]
	v_fmamk_f32 v191, v211, 0x3a800000, v170
	v_mul_f32_e32 v194, 0x4b800000, v191
	v_cmp_gt_f32_e32 vcc, s90, v191
	s_nop 1
	v_cndmask_b32_e32 v191, v191, v194, vcc
	v_rsq_f32_e32 v191, v191
	s_nop 0
	v_mul_f32_e32 v194, 0x45800000, v191
	v_cndmask_b32_e32 v191, v191, v194, vcc
	v_mul_f32_e32 v194, v92, v191
	v_mul_f32_e32 v194, 0xbfb8aa3b, v194
	v_exp_f32_e32 v194, v194
	v_mul_f32_e32 v193, v93, v191
	v_mul_f32_e32 v193, 0xbfb8aa3b, v193
	v_exp_f32_e32 v193, v193
	v_add_f32_e32 v194, 1.0, v194
	v_rcp_f32_e32 v194, v194
	v_add_f32_e32 v193, 1.0, v193
	v_rcp_f32_e32 v193, v193
	v_fma_f32 v194, v176, v194, v175
	v_cmp_gt_f32_e32 vcc, s90, v194
	v_fma_f32 v193, v177, v193, v174
	s_nop 0
	v_cndmask_b32_e64 v195, 0, 32, vcc
	v_ldexp_f32 v194, v194, v195
	v_log_f32_e32 v194, v194
	s_nop 0
	v_mul_f32_e32 v192, 0x3f317217, v194
	v_fma_f32 v192, v194, s95, -v192
	v_fmac_f32_e32 v192, 0x3377d1cf, v194
	v_fmac_f32_e32 v192, 0x3f317217, v194
	v_cmp_lt_f32_e64 s[6:7], |v194|, s96
	s_nop 1
	v_cndmask_b32_e64 v192, v194, v192, s[6:7]
	v_cndmask_b32_e32 v194, 0, v171, vcc
	v_cmp_gt_f32_e32 vcc, s90, v193
	v_sub_f32_e32 v192, v192, v194
	s_nop 0
	v_cndmask_b32_e64 v194, 0, 32, vcc
	v_ldexp_f32 v193, v193, v194
	v_mul_f32_e32 v194, v94, v191
	v_mul_f32_e32 v194, 0xbfb8aa3b, v194
	v_exp_f32_e32 v194, v194
	v_log_f32_e32 v193, v193
	v_cndmask_b32_e32 v198, 0, v171, vcc
	v_add_f32_e32 v194, 1.0, v194
	v_rcp_f32_e32 v194, v194
	v_mul_f32_e32 v195, 0x3f317217, v193
	v_fma_f32 v195, v193, s95, -v195
	v_fmac_f32_e32 v195, 0x3377d1cf, v193
	v_fmac_f32_e32 v195, 0x3f317217, v193
	v_cmp_lt_f32_e64 s[6:7], |v193|, s96
	v_fma_f32 v194, v178, v194, v173
	s_nop 0
	v_cndmask_b32_e64 v193, v193, v195, s[6:7]
	v_cmp_gt_f32_e64 s[6:7], s90, v194
	v_sub_f32_e32 v198, v193, v198
	v_cvt_pk_f16_f32 v192, v192, v198
	v_cndmask_b32_e64 v195, 0, 32, s[6:7]
	v_ldexp_f32 v194, v194, v195
	v_mul_f32_e32 v195, v95, v191
	v_mul_f32_e32 v195, 0xbfb8aa3b, v195
	v_exp_f32_e32 v195, v195
	v_log_f32_e32 v194, v194
	v_add_f32_e32 v195, 1.0, v195
	v_rcp_f32_e32 v195, v195
	v_mul_f32_e32 v193, 0x3f317217, v194
	v_fma_f32 v193, v194, s95, -v193
	v_fmac_f32_e32 v193, 0x3377d1cf, v194
; __device__ __forceinline__ float fsigm(float x) { return __builtin_amdgcn_rcpf(1.f + __expf(-x)); }
; __device__ __forceinline__ float row_rs(const float* ssq, int row) { return ssq ? rsqrtf(ssq[row] * (1.f / 1024.f) + RMS_EPS) : 1.f; }
;     __device__ __forceinline__ void operator()(const f32x4 (&acc)[2][2][4][2], const Unit& u, int wr, int wc, int fr, int fq) const {
;     ...
;                 for (int m = 0; m < 4; ++m) { const int row = row0 + ai * HALF + m * 16; const float rs = row_rs(ssq, row);
; #pragma unroll
;                     for (int bj = 0; bj < 2; ++bj) { f16x4 o[2];
; #pragma unroll
;                         for (int n = 0; n < 2; ++n) { const f32x4 p = acc[ai][bj][m][n] * rs;
; #pragma unroll
;                             for (int j = 0; j < 4; ++j) { const float l = lb[bj][n][j]; const float f = l + (1.f - l) * fsigm(p[j]); o[n][j] = (_Float16)__logf(f); } }
;                         const u32x2 a0 = __builtin_bit_cast(u32x2, o[0]), a1 = __builtin_bit_cast(u32x2, o[1]); u32x4 w; w.x = a0.x; w.y = a0.y; w.z = a1.x; w.w = a1.y;
;                         *(u32x4*)(LF + (size_t)row * 512 + cbase + bj * HALF) = w; } }
	v_fma_f32 v195, v183, v195, v172
	v_cmp_gt_f32_e32 vcc, s90, v195
	v_fmac_f32_e32 v193, 0x3f317217, v194
	v_cmp_lt_f32_e64 s[8:9], |v194|, s96
	v_cndmask_b32_e64 v199, 0, 32, vcc
	v_ldexp_f32 v195, v195, v199
	v_mul_f32_e32 v199, v88, v191
	v_mul_f32_e32 v199, 0xbfb8aa3b, v199
	v_log_f32_e32 v195, v195
	v_exp_f32_e32 v199, v199
	v_cndmask_b32_e64 v193, v194, v193, s[8:9]
	v_cndmask_b32_e64 v194, 0, v171, s[6:7]
	v_sub_f32_e32 v193, v193, v194
	v_mul_f32_e32 v194, 0x3f317217, v195
	v_add_f32_e32 v199, 1.0, v199
	v_fma_f32 v194, v195, s95, -v194
	v_rcp_f32_e32 v199, v199
	v_fmac_f32_e32 v194, 0x3377d1cf, v195
	v_fmac_f32_e32 v194, 0x3f317217, v195
	v_cmp_lt_f32_e64 s[6:7], |v195|, s96
	v_fma_f32 v199, v149, v199, v165
	s_nop 0
	v_cndmask_b32_e64 v194, v195, v194, s[6:7]
	v_cndmask_b32_e32 v195, 0, v171, vcc
	v_sub_f32_e32 v194, v194, v195
	v_mul_f32_e32 v195, v89, v191
	v_cmp_gt_f32_e32 vcc, s90, v199
	v_mul_f32_e32 v195, 0xbfb8aa3b, v195
	v_exp_f32_e32 v195, v195
	v_cndmask_b32_e64 v200, 0, 32, vcc
	v_ldexp_f32 v199, v199, v200
	v_log_f32_e32 v199, v199
	v_add_f32_e32 v195, 1.0, v195
	v_rcp_f32_e32 v195, v195
	v_cvt_pk_f16_f32 v193, v193, v194
	v_mul_f32_e32 v194, 0x3f317217, v199
	v_fma_f32 v194, v199, s95, -v194
	v_fmac_f32_e32 v194, 0x3377d1cf, v199
	v_fmac_f32_e32 v194, 0x3f317217, v199
	v_cmp_lt_f32_e64 s[6:7], |v199|, s96
	v_fma_f32 v195, v179, v195, v164
	v_cndmask_b32_e32 v198, 0, v171, vcc
	v_cndmask_b32_e64 v194, v199, v194, s[6:7]
	v_cmp_gt_f32_e32 vcc, s90, v195
	v_sub_f32_e32 v194, v194, v198
	s_nop 0
	v_cndmask_b32_e64 v198, 0, 32, vcc
	v_ldexp_f32 v195, v195, v198
	v_mul_f32_e32 v198, v90, v191
	v_mul_f32_e32 v198, 0xbfb8aa3b, v198
	v_exp_f32_e32 v198, v198
	v_log_f32_e32 v195, v195
	v_cndmask_b32_e32 v200, 0, v171, vcc
	v_add_f32_e32 v198, 1.0, v198
	v_rcp_f32_e32 v198, v198
	v_mul_f32_e32 v199, 0x3f317217, v195
	v_fma_f32 v199, v195, s95, -v199
	v_fmac_f32_e32 v199, 0x3377d1cf, v195
	v_fmac_f32_e32 v199, 0x3f317217, v195
	v_cmp_lt_f32_e64 s[6:7], |v195|, s96
	v_fma_f32 v198, v180, v198, v163
	s_nop 0
	v_cndmask_b32_e64 v195, v195, v199, s[6:7]
	v_cmp_gt_f32_e64 s[6:7], s90, v198
	v_sub_f32_e32 v200, v195, v200
	v_cvt_pk_f16_f32 v194, v194, v200
	v_cndmask_b32_e64 v199, 0, 32, s[6:7]
	v_ldexp_f32 v198, v198, v199
	v_mul_f32_e32 v199, v91, v191
	v_mul_f32_e32 v199, 0xbfb8aa3b, v199
	v_exp_f32_e32 v199, v199
	v_log_f32_e32 v198, v198
	v_add_f32_e32 v199, 1.0, v199
	v_rcp_f32_e32 v199, v199
	v_mul_f32_e32 v195, 0x3f317217, v198
	v_fma_f32 v195, v198, s95, -v195
	v_fmac_f32_e32 v195, 0x3377d1cf, v198
	v_fma_f32 v199, v188, v199, v162
	v_cmp_gt_f32_e32 vcc, s90, v199
	v_fmac_f32_e32 v195, 0x3f317217, v198
	v_cmp_lt_f32_e64 s[8:9], |v198|, s96
	v_cndmask_b32_e64 v201, 0, 32, vcc
	v_ldexp_f32 v199, v199, v201
	v_log_f32_e32 v199, v199
	v_mul_f32_e32 v201, v84, v191
	v_mul_f32_e32 v201, 0xbfb8aa3b, v201
	v_exp_f32_e32 v201, v201
	v_cndmask_b32_e64 v195, v198, v195, s[8:9]
	v_cndmask_b32_e64 v198, 0, v171, s[6:7]
	v_sub_f32_e32 v195, v195, v198
	v_mul_f32_e32 v198, 0x3f317217, v199
	v_fma_f32 v198, v199, s95, -v198
	v_fmac_f32_e32 v198, 0x3377d1cf, v199
	v_add_f32_e32 v201, 1.0, v201
	v_fmac_f32_e32 v198, 0x3f317217, v199
	v_cmp_lt_f32_e64 s[6:7], |v199|, s96
	v_rcp_f32_e32 v201, v201
	s_nop 0
	v_cndmask_b32_e64 v198, v199, v198, s[6:7]
	v_cndmask_b32_e32 v199, 0, v171, vcc
	v_sub_f32_e32 v198, v198, v199
	v_cvt_pk_f16_f32 v195, v195, v198
	v_fma_f32 v198, v184, v201, v161
	global_store_dwordx4 v[196:197], v[192:195], off
	v_cmp_gt_f32_e32 vcc, s90, v198
	s_nop 0
	v_mul_f32_e32 v193, v85, v191
	v_mul_f32_e32 v193, 0xbfb8aa3b, v193
	v_cndmask_b32_e64 v199, 0, 32, vcc
	v_exp_f32_e32 v193, v193
	v_ldexp_f32 v198, v198, v199
	v_log_f32_e32 v198, v198
	v_cndmask_b32_e32 v194, 0, v171, vcc
	v_add_f32_e32 v193, 1.0, v193
	v_rcp_f32_e32 v193, v193
	v_mul_f32_e32 v192, 0x3f317217, v198
	v_fma_f32 v192, v198, s95, -v192
	v_fmac_f32_e32 v192, 0x3377d1cf, v198
	v_fmac_f32_e32 v192, 0x3f317217, v198
	v_cmp_lt_f32_e64 s[6:7], |v198|, s96
	v_fma_f32 v193, v181, v193, v160
	v_cmp_gt_f32_e32 vcc, s90, v193
	v_cndmask_b32_e64 v192, v198, v192, s[6:7]
	v_sub_f32_e32 v192, v192, v194
	v_cndmask_b32_e64 v194, 0, 32, vcc
	v_ldexp_f32 v193, v193, v194
	v_mul_f32_e32 v194, v86, v191
	v_mul_f32_e32 v194, 0xbfb8aa3b, v194
	v_exp_f32_e32 v194, v194
	v_log_f32_e32 v193, v193
	v_cndmask_b32_e32 v198, 0, v171, vcc
	v_add_f32_e32 v194, 1.0, v194
	v_rcp_f32_e32 v194, v194
	v_mul_f32_e32 v195, 0x3f317217, v193
	v_fma_f32 v195, v193, s95, -v195
	v_fmac_f32_e32 v195, 0x3377d1cf, v193
	v_fmac_f32_e32 v195, 0x3f317217, v193
	v_cmp_lt_f32_e64 s[6:7], |v193|, s96
	v_fma_f32 v194, v185, v194, v159
	s_nop 0
	v_cndmask_b32_e64 v193, v193, v195, s[6:7]
	v_cmp_gt_f32_e64 s[6:7], s90, v194
	v_sub_f32_e32 v198, v193, v198
	v_cvt_pk_f16_f32 v192, v192, v198
	v_cndmask_b32_e64 v195, 0, 32, s[6:7]
	v_ldexp_f32 v194, v194, v195
	v_mul_f32_e32 v195, v87, v191
	v_mul_f32_e32 v195, 0xbfb8aa3b, v195
	v_exp_f32_e32 v195, v195
	v_log_f32_e32 v194, v194
	v_add_f32_e32 v195, 1.0, v195
	v_rcp_f32_e32 v195, v195
	v_mul_f32_e32 v193, 0x3f317217, v194
	v_fma_f32 v193, v194, s95, -v193
	v_fmac_f32_e32 v193, 0x3377d1cf, v194
	v_fma_f32 v195, v186, v195, v158
	v_cmp_gt_f32_e32 vcc, s90, v195
	v_fmac_f32_e32 v193, 0x3f317217, v194
	v_cmp_lt_f32_e64 s[8:9], |v194|, s96
	v_cndmask_b32_e64 v199, 0, 32, vcc
	v_ldexp_f32 v195, v195, v199
	v_mul_f32_e32 v199, v80, v191
	v_mul_f32_e32 v199, 0xbfb8aa3b, v199
	v_log_f32_e32 v195, v195
	v_exp_f32_e32 v199, v199
	v_cndmask_b32_e64 v193, v194, v193, s[8:9]
	v_cndmask_b32_e64 v194, 0, v171, s[6:7]
	v_sub_f32_e32 v193, v193, v194
	v_mul_f32_e32 v194, 0x3f317217, v195
; __device__ __forceinline__ float fsigm(float x) { return __builtin_amdgcn_rcpf(1.f + __expf(-x)); }
; __device__ __forceinline__ float row_rs(const float* ssq, int row) { return ssq ? rsqrtf(ssq[row] * (1.f / 1024.f) + RMS_EPS) : 1.f; }
;     __device__ __forceinline__ void operator()(const f32x4 (&acc)[2][2][4][2], const Unit& u, int wr, int wc, int fr, int fq) const {
;     ...
;                 for (int m = 0; m < 4; ++m) { const int row = row0 + ai * HALF + m * 16; const float rs = row_rs(ssq, row);
; #pragma unroll
;                     for (int bj = 0; bj < 2; ++bj) { f16x4 o[2];
; #pragma unroll
;                         for (int n = 0; n < 2; ++n) { const f32x4 p = acc[ai][bj][m][n] * rs;
; #pragma unroll
;                             for (int j = 0; j < 4; ++j) { const float l = lb[bj][n][j]; const float f = l + (1.f - l) * fsigm(p[j]); o[n][j] = (_Float16)__logf(f); } }
;                         const u32x2 a0 = __builtin_bit_cast(u32x2, o[0]), a1 = __builtin_bit_cast(u32x2, o[1]); u32x4 w; w.x = a0.x; w.y = a0.y; w.z = a1.x; w.w = a1.y;
;                         *(u32x4*)(LF + (size_t)row * 512 + cbase + bj * HALF) = w; } }
	v_add_f32_e32 v199, 1.0, v199
	v_fma_f32 v194, v195, s95, -v194
	v_rcp_f32_e32 v199, v199
	v_fmac_f32_e32 v194, 0x3377d1cf, v195
	v_fmac_f32_e32 v194, 0x3f317217, v195
	v_cmp_lt_f32_e64 s[6:7], |v195|, s96
	v_fma_f32 v199, v187, v199, v157
	s_nop 0
	v_cndmask_b32_e64 v194, v195, v194, s[6:7]
	v_cndmask_b32_e32 v195, 0, v171, vcc
	v_sub_f32_e32 v194, v194, v195
	v_mul_f32_e32 v195, v81, v191
	v_cmp_gt_f32_e32 vcc, s90, v199
	v_mul_f32_e32 v195, 0xbfb8aa3b, v195
	v_exp_f32_e32 v195, v195
	v_cndmask_b32_e64 v200, 0, 32, vcc
	v_ldexp_f32 v199, v199, v200
	v_log_f32_e32 v199, v199
	v_add_f32_e32 v195, 1.0, v195
	v_rcp_f32_e32 v195, v195
	v_cvt_pk_f16_f32 v193, v193, v194
	v_mul_f32_e32 v194, 0x3f317217, v199
	v_fma_f32 v194, v199, s95, -v194
	v_fmac_f32_e32 v194, 0x3377d1cf, v199
	v_fmac_f32_e32 v194, 0x3f317217, v199
	v_cmp_lt_f32_e64 s[6:7], |v199|, s96
	v_fma_f32 v195, v182, v195, v156
	v_cndmask_b32_e32 v198, 0, v171, vcc
	v_cndmask_b32_e64 v194, v199, v194, s[6:7]
	v_cmp_gt_f32_e32 vcc, s90, v195
	v_sub_f32_e32 v194, v194, v198
	s_nop 0
	v_cndmask_b32_e64 v198, 0, 32, vcc
	v_ldexp_f32 v195, v195, v198
	v_mul_f32_e32 v198, v82, v191
	v_mul_f32_e32 v198, 0xbfb8aa3b, v198
	v_exp_f32_e32 v198, v198
	v_log_f32_e32 v195, v195
	v_mul_f32_e32 v191, v83, v191
	v_mul_f32_e32 v191, 0xbfb8aa3b, v191
	v_add_f32_e32 v198, 1.0, v198
	v_rcp_f32_e32 v198, v198
	v_exp_f32_e32 v191, v191
	v_mul_f32_e32 v199, 0x3f317217, v195
	v_fma_f32 v199, v195, s95, -v199
	v_fmac_f32_e32 v199, 0x3377d1cf, v195
	v_fmac_f32_e32 v199, 0x3f317217, v195
	v_cmp_lt_f32_e64 s[6:7], |v195|, s96
	v_fma_f32 v198, v189, v198, v155
	v_add_f32_e32 v191, 1.0, v191
	v_cndmask_b32_e64 v195, v195, v199, s[6:7]
	v_cmp_gt_f32_e64 s[6:7], s90, v198
	v_rcp_f32_e32 v191, v191
	s_nop 0
	v_cndmask_b32_e64 v199, 0, 32, s[6:7]
	v_ldexp_f32 v198, v198, v199
	v_log_f32_e32 v198, v198
	v_fma_f32 v191, v190, v191, v154
	v_cndmask_b32_e32 v199, 0, v171, vcc
	v_cmp_gt_f32_e32 vcc, s90, v191
	v_sub_f32_e32 v199, v195, v199
	v_mul_f32_e32 v195, 0x3f317217, v198
	v_cndmask_b32_e64 v200, 0, 32, vcc
	v_ldexp_f32 v191, v191, v200
	v_fma_f32 v195, v198, s95, -v195
	v_log_f32_e32 v191, v191
	v_fmac_f32_e32 v195, 0x3377d1cf, v198
	v_fmac_f32_e32 v195, 0x3f317217, v198
	v_cmp_lt_f32_e64 s[8:9], |v198|, s96
	v_cvt_pk_f16_f32 v194, v194, v199
	s_nop 0
	v_cndmask_b32_e64 v195, v198, v195, s[8:9]
	v_cndmask_b32_e64 v198, 0, v171, s[6:7]
	v_sub_f32_e32 v195, v195, v198
	v_mul_f32_e32 v198, 0x3f317217, v191
	v_fma_f32 v198, v191, s95, -v198
	v_fmac_f32_e32 v198, 0x3377d1cf, v191
	v_fmac_f32_e32 v198, 0x3f317217, v191
	v_cmp_lt_f32_e64 s[6:7], |v191|, s96
	s_nop 1
	v_cndmask_b32_e64 v191, v191, v198, s[6:7]
	v_cndmask_b32_e32 v198, 0, v171, vcc
	v_sub_f32_e32 v191, v191, v198
	v_cvt_pk_f16_f32 v195, v195, v191
	global_store_dwordx4 v[196:197], v[192:195], off offset:256
	s_nop 1
	v_or_b32_e32 v192, 48, v148
	v_ashrrev_i32_e32 v193, 31, v192
	v_lshl_add_u64 v[194:195], v[192:193], 2, s[30:31]
	v_lshlrev_b64 v[196:197], 10, v[192:193]
	v_lshl_add_u64 v[196:197], s[10:11], 0, v[196:197]
	v_lshl_add_u64 v[196:197], v[196:197], 0, v[136:137]
	v_fmamk_f32 v191, v212, 0x3a800000, v170
	v_mul_f32_e32 v194, 0x4b800000, v191
	v_cmp_gt_f32_e32 vcc, s90, v191
	s_nop 1
	v_cndmask_b32_e32 v191, v191, v194, vcc
	v_rsq_f32_e32 v191, v191
	s_nop 0
	v_mul_f32_e32 v194, 0x45800000, v191
	v_cndmask_b32_e32 v191, v191, v194, vcc
	v_mul_f32_e32 v194, v76, v191
	v_mul_f32_e32 v194, 0xbfb8aa3b, v194
	v_exp_f32_e32 v194, v194
	v_mul_f32_e32 v193, v77, v191
	v_mul_f32_e32 v193, 0xbfb8aa3b, v193
	v_exp_f32_e32 v193, v193
	v_add_f32_e32 v194, 1.0, v194
	v_rcp_f32_e32 v194, v194
	v_add_f32_e32 v193, 1.0, v193
	v_rcp_f32_e32 v193, v193
	v_fma_f32 v194, v176, v194, v175
	v_cmp_gt_f32_e32 vcc, s90, v194
	v_fma_f32 v193, v177, v193, v174
	s_nop 0
	v_cndmask_b32_e64 v195, 0, 32, vcc
	v_ldexp_f32 v194, v194, v195
	v_log_f32_e32 v194, v194
	s_nop 0
	v_mul_f32_e32 v192, 0x3f317217, v194
	v_fma_f32 v192, v194, s95, -v192
	v_fmac_f32_e32 v192, 0x3377d1cf, v194
	v_fmac_f32_e32 v192, 0x3f317217, v194
	v_cmp_lt_f32_e64 s[6:7], |v194|, s96
	s_nop 1
	v_cndmask_b32_e64 v192, v194, v192, s[6:7]
	v_cndmask_b32_e32 v194, 0, v171, vcc
	v_cmp_gt_f32_e32 vcc, s90, v193
	v_sub_f32_e32 v192, v192, v194
	s_nop 0
	v_cndmask_b32_e64 v194, 0, 32, vcc
	v_ldexp_f32 v193, v193, v194
	v_mul_f32_e32 v194, v78, v191
	v_mul_f32_e32 v194, 0xbfb8aa3b, v194
	v_exp_f32_e32 v194, v194
	v_log_f32_e32 v193, v193
	v_cndmask_b32_e32 v198, 0, v171, vcc
	v_add_f32_e32 v194, 1.0, v194
	v_rcp_f32_e32 v194, v194
	v_mul_f32_e32 v195, 0x3f317217, v193
	v_fma_f32 v195, v193, s95, -v195
	v_fmac_f32_e32 v195, 0x3377d1cf, v193
	v_fmac_f32_e32 v195, 0x3f317217, v193
	v_cmp_lt_f32_e64 s[6:7], |v193|, s96
	v_fma_f32 v194, v178, v194, v173
	s_nop 0
	v_cndmask_b32_e64 v193, v193, v195, s[6:7]
	v_cmp_gt_f32_e64 s[6:7], s90, v194
	v_sub_f32_e32 v198, v193, v198
	v_cvt_pk_f16_f32 v192, v192, v198
	v_cndmask_b32_e64 v195, 0, 32, s[6:7]
	v_ldexp_f32 v194, v194, v195
	v_mul_f32_e32 v195, v79, v191
	v_mul_f32_e32 v195, 0xbfb8aa3b, v195
	v_exp_f32_e32 v195, v195
	v_log_f32_e32 v194, v194
	v_add_f32_e32 v195, 1.0, v195
	v_rcp_f32_e32 v195, v195
	v_mul_f32_e32 v193, 0x3f317217, v194
	v_fma_f32 v193, v194, s95, -v193
	v_fmac_f32_e32 v193, 0x3377d1cf, v194
	v_fma_f32 v195, v183, v195, v172
	v_cmp_gt_f32_e32 vcc, s90, v195
	v_fmac_f32_e32 v193, 0x3f317217, v194
	v_cmp_lt_f32_e64 s[8:9], |v194|, s96
	v_cndmask_b32_e64 v199, 0, 32, vcc
	v_ldexp_f32 v195, v195, v199
	v_mul_f32_e32 v199, v72, v191
	v_mul_f32_e32 v199, 0xbfb8aa3b, v199
	v_log_f32_e32 v195, v195
	v_exp_f32_e32 v199, v199
	v_cndmask_b32_e64 v193, v194, v193, s[8:9]
; __device__ __forceinline__ float fsigm(float x) { return __builtin_amdgcn_rcpf(1.f + __expf(-x)); }
; __device__ __forceinline__ float row_rs(const float* ssq, int row) { return ssq ? rsqrtf(ssq[row] * (1.f / 1024.f) + RMS_EPS) : 1.f; }
;     __device__ __forceinline__ void operator()(const f32x4 (&acc)[2][2][4][2], const Unit& u, int wr, int wc, int fr, int fq) const {
;     ...
;                 for (int m = 0; m < 4; ++m) { const int row = row0 + ai * HALF + m * 16; const float rs = row_rs(ssq, row);
; #pragma unroll
;                     for (int bj = 0; bj < 2; ++bj) { f16x4 o[2];
; #pragma unroll
;                         for (int n = 0; n < 2; ++n) { const f32x4 p = acc[ai][bj][m][n] * rs;
; #pragma unroll
;                             for (int j = 0; j < 4; ++j) { const float l = lb[bj][n][j]; const float f = l + (1.f - l) * fsigm(p[j]); o[n][j] = (_Float16)__logf(f); } }
;                         const u32x2 a0 = __builtin_bit_cast(u32x2, o[0]), a1 = __builtin_bit_cast(u32x2, o[1]); u32x4 w; w.x = a0.x; w.y = a0.y; w.z = a1.x; w.w = a1.y;
;                         *(u32x4*)(LF + (size_t)row * 512 + cbase + bj * HALF) = w; } }
	v_cndmask_b32_e64 v194, 0, v171, s[6:7]
	v_sub_f32_e32 v193, v193, v194
	v_mul_f32_e32 v194, 0x3f317217, v195
	v_add_f32_e32 v199, 1.0, v199
	v_fma_f32 v194, v195, s95, -v194
	v_rcp_f32_e32 v199, v199
	v_fmac_f32_e32 v194, 0x3377d1cf, v195
	v_fmac_f32_e32 v194, 0x3f317217, v195
	v_cmp_lt_f32_e64 s[6:7], |v195|, s96
	v_fma_f32 v199, v149, v199, v165
	s_nop 0
	v_cndmask_b32_e64 v194, v195, v194, s[6:7]
	v_cndmask_b32_e32 v195, 0, v171, vcc
	v_sub_f32_e32 v194, v194, v195
	v_mul_f32_e32 v195, v73, v191
	v_cmp_gt_f32_e32 vcc, s90, v199
	v_mul_f32_e32 v195, 0xbfb8aa3b, v195
	v_exp_f32_e32 v195, v195
	v_cndmask_b32_e64 v200, 0, 32, vcc
	v_ldexp_f32 v199, v199, v200
	v_log_f32_e32 v199, v199
	v_add_f32_e32 v195, 1.0, v195
	v_rcp_f32_e32 v195, v195
	v_cvt_pk_f16_f32 v193, v193, v194
	v_mul_f32_e32 v194, 0x3f317217, v199
	v_fma_f32 v194, v199, s95, -v194
	v_fmac_f32_e32 v194, 0x3377d1cf, v199
	v_fmac_f32_e32 v194, 0x3f317217, v199
	v_cmp_lt_f32_e64 s[6:7], |v199|, s96
	v_fma_f32 v195, v179, v195, v164
	v_cndmask_b32_e32 v198, 0, v171, vcc
	v_cndmask_b32_e64 v194, v199, v194, s[6:7]
	v_cmp_gt_f32_e32 vcc, s90, v195
	v_sub_f32_e32 v194, v194, v198
	s_nop 0
	v_cndmask_b32_e64 v198, 0, 32, vcc
	v_ldexp_f32 v195, v195, v198
	v_mul_f32_e32 v198, v74, v191
	v_mul_f32_e32 v198, 0xbfb8aa3b, v198
	v_exp_f32_e32 v198, v198
	v_log_f32_e32 v195, v195
	v_cndmask_b32_e32 v200, 0, v171, vcc
	v_add_f32_e32 v198, 1.0, v198
	v_rcp_f32_e32 v198, v198
	v_mul_f32_e32 v199, 0x3f317217, v195
	v_fma_f32 v199, v195, s95, -v199
	v_fmac_f32_e32 v199, 0x3377d1cf, v195
	v_fmac_f32_e32 v199, 0x3f317217, v195
	v_cmp_lt_f32_e64 s[6:7], |v195|, s96
	v_fma_f32 v198, v180, v198, v163
	s_nop 0
	v_cndmask_b32_e64 v195, v195, v199, s[6:7]
	v_cmp_gt_f32_e64 s[6:7], s90, v198
	v_sub_f32_e32 v200, v195, v200
	v_cvt_pk_f16_f32 v194, v194, v200
	v_cndmask_b32_e64 v199, 0, 32, s[6:7]
	v_ldexp_f32 v198, v198, v199
	v_mul_f32_e32 v199, v75, v191
	v_mul_f32_e32 v199, 0xbfb8aa3b, v199
	v_exp_f32_e32 v199, v199
	v_log_f32_e32 v198, v198
	v_add_f32_e32 v199, 1.0, v199
	v_rcp_f32_e32 v199, v199
	v_mul_f32_e32 v195, 0x3f317217, v198
	v_fma_f32 v195, v198, s95, -v195
	v_fmac_f32_e32 v195, 0x3377d1cf, v198
	v_fma_f32 v199, v188, v199, v162
	v_cmp_gt_f32_e32 vcc, s90, v199
	v_fmac_f32_e32 v195, 0x3f317217, v198
	v_cmp_lt_f32_e64 s[8:9], |v198|, s96
	v_cndmask_b32_e64 v201, 0, 32, vcc
	v_ldexp_f32 v199, v199, v201
	v_log_f32_e32 v199, v199
	v_mul_f32_e32 v201, v68, v191
	v_mul_f32_e32 v201, 0xbfb8aa3b, v201
	v_exp_f32_e32 v201, v201
	v_cndmask_b32_e64 v195, v198, v195, s[8:9]
	v_cndmask_b32_e64 v198, 0, v171, s[6:7]
	v_sub_f32_e32 v195, v195, v198
	v_mul_f32_e32 v198, 0x3f317217, v199
	v_fma_f32 v198, v199, s95, -v198
	v_fmac_f32_e32 v198, 0x3377d1cf, v199
	v_add_f32_e32 v201, 1.0, v201
	v_fmac_f32_e32 v198, 0x3f317217, v199
	v_cmp_lt_f32_e64 s[6:7], |v199|, s96
	v_rcp_f32_e32 v201, v201
	s_nop 0
	v_cndmask_b32_e64 v198, v199, v198, s[6:7]
	v_cndmask_b32_e32 v199, 0, v171, vcc
	v_sub_f32_e32 v198, v198, v199
	v_cvt_pk_f16_f32 v195, v195, v198
	v_fma_f32 v198, v184, v201, v161
	global_store_dwordx4 v[196:197], v[192:195], off
	v_cmp_gt_f32_e32 vcc, s90, v198
	s_nop 0
	v_mul_f32_e32 v192, v69, v191
	v_mul_f32_e32 v192, 0xbfb8aa3b, v192
	v_cndmask_b32_e64 v199, 0, 32, vcc
	v_exp_f32_e32 v192, v192
	v_ldexp_f32 v198, v198, v199
	v_log_f32_e32 v198, v198
	v_cndmask_b32_e32 v193, 0, v171, vcc
	v_add_f32_e32 v192, 1.0, v192
	v_rcp_f32_e32 v192, v192
	v_mul_f32_e32 v136, 0x3f317217, v198
	v_fma_f32 v136, v198, s95, -v136
	v_fmac_f32_e32 v136, 0x3377d1cf, v198
	v_fmac_f32_e32 v136, 0x3f317217, v198
	v_cmp_lt_f32_e64 s[6:7], |v198|, s96
	v_fma_f32 v192, v181, v192, v160
	v_cmp_gt_f32_e32 vcc, s90, v192
	v_cndmask_b32_e64 v136, v198, v136, s[6:7]
	v_sub_f32_e32 v136, v136, v193
	v_cndmask_b32_e64 v193, 0, 32, vcc
	v_ldexp_f32 v192, v192, v193
	v_mul_f32_e32 v193, v70, v191
	v_mul_f32_e32 v193, 0xbfb8aa3b, v193
	v_exp_f32_e32 v193, v193
	v_log_f32_e32 v192, v192
	v_cndmask_b32_e32 v195, 0, v171, vcc
	v_add_f32_e32 v193, 1.0, v193
	v_rcp_f32_e32 v193, v193
	v_mul_f32_e32 v194, 0x3f317217, v192
	v_fma_f32 v194, v192, s95, -v194
	v_fmac_f32_e32 v194, 0x3377d1cf, v192
	v_fmac_f32_e32 v194, 0x3f317217, v192
	v_cmp_lt_f32_e64 s[6:7], |v192|, s96
	v_fma_f32 v193, v185, v193, v159
	s_nop 0
	v_cndmask_b32_e64 v192, v192, v194, s[6:7]
	v_cmp_gt_f32_e64 s[6:7], s90, v193
	v_sub_f32_e32 v192, v192, v195
	v_cvt_pk_f16_f32 v192, v136, v192
	v_cndmask_b32_e64 v194, 0, 32, s[6:7]
	v_ldexp_f32 v193, v193, v194
	v_mul_f32_e32 v194, v71, v191
	v_mul_f32_e32 v194, 0xbfb8aa3b, v194
	v_exp_f32_e32 v194, v194
	v_log_f32_e32 v193, v193
	v_add_f32_e32 v194, 1.0, v194
	v_rcp_f32_e32 v194, v194
	v_mul_f32_e32 v195, 0x3f317217, v193
	v_fma_f32 v195, v193, s95, -v195
	v_fmac_f32_e32 v195, 0x3377d1cf, v193
	v_fma_f32 v194, v186, v194, v158
	v_cmp_gt_f32_e32 vcc, s90, v194
	v_fmac_f32_e32 v195, 0x3f317217, v193
	v_cmp_lt_f32_e64 s[8:9], |v193|, s96
	v_cndmask_b32_e64 v198, 0, 32, vcc
	v_ldexp_f32 v194, v194, v198
	v_mul_f32_e32 v198, v64, v191
	v_log_f32_e32 v194, v194
	v_mul_f32_e32 v198, 0xbfb8aa3b, v198
	v_exp_f32_e32 v198, v198
	v_cndmask_b32_e64 v193, v193, v195, s[8:9]
	v_cndmask_b32_e64 v195, 0, v171, s[6:7]
	v_sub_f32_e32 v193, v193, v195
	v_mul_f32_e32 v195, 0x3f317217, v194
	v_fma_f32 v195, v194, s95, -v195
	v_add_f32_e32 v198, 1.0, v198
	v_fmac_f32_e32 v195, 0x3377d1cf, v194
	v_rcp_f32_e32 v198, v198
	v_fmac_f32_e32 v195, 0x3f317217, v194
	v_cmp_lt_f32_e64 s[6:7], |v194|, s96
	v_fma_f32 v198, v187, v198, v157
	s_nop 0
	v_cndmask_b32_e64 v194, v194, v195, s[6:7]
	v_cndmask_b32_e32 v195, 0, v171, vcc
	v_sub_f32_e32 v194, v194, v195
; __device__ __forceinline__ float fsigm(float x) { return __builtin_amdgcn_rcpf(1.f + __expf(-x)); }
; __device__ __forceinline__ float row_rs(const float* ssq, int row) { return ssq ? rsqrtf(ssq[row] * (1.f / 1024.f) + RMS_EPS) : 1.f; }
;     __device__ __forceinline__ void operator()(const f32x4 (&acc)[2][2][4][2], const Unit& u, int wr, int wc, int fr, int fq) const {
;     ...
;                 for (int m = 0; m < 4; ++m) { const int row = row0 + ai * HALF + m * 16; const float rs = row_rs(ssq, row);
; #pragma unroll
;                     for (int bj = 0; bj < 2; ++bj) { f16x4 o[2];
; #pragma unroll
;                         for (int n = 0; n < 2; ++n) { const f32x4 p = acc[ai][bj][m][n] * rs;
; #pragma unroll
;                             for (int j = 0; j < 4; ++j) { const float l = lb[bj][n][j]; const float f = l + (1.f - l) * fsigm(p[j]); o[n][j] = (_Float16)__logf(f); } }
;                         const u32x2 a0 = __builtin_bit_cast(u32x2, o[0]), a1 = __builtin_bit_cast(u32x2, o[1]); u32x4 w; w.x = a0.x; w.y = a0.y; w.z = a1.x; w.w = a1.y;
;                         *(u32x4*)(LF + (size_t)row * 512 + cbase + bj * HALF) = w; } }
	v_cvt_pk_f16_f32 v193, v193, v194
	v_mul_f32_e32 v194, v65, v191
	v_cmp_gt_f32_e32 vcc, s90, v198
	v_mul_f32_e32 v194, 0xbfb8aa3b, v194
	v_exp_f32_e32 v194, v194
	v_cndmask_b32_e64 v199, 0, 32, vcc
	v_ldexp_f32 v198, v198, v199
	v_log_f32_e32 v198, v198
	v_add_f32_e32 v194, 1.0, v194
	v_rcp_f32_e32 v194, v194
	v_cndmask_b32_e32 v195, 0, v171, vcc
	v_mul_f32_e32 v136, 0x3f317217, v198
	v_fma_f32 v136, v198, s95, -v136
	v_fmac_f32_e32 v136, 0x3377d1cf, v198
	v_fmac_f32_e32 v136, 0x3f317217, v198
	v_cmp_lt_f32_e64 s[6:7], |v198|, s96
	v_fma_f32 v194, v182, v194, v156
	v_cmp_gt_f32_e32 vcc, s90, v194
	v_cndmask_b32_e64 v136, v198, v136, s[6:7]
	v_sub_f32_e32 v136, v136, v195
	v_cndmask_b32_e64 v195, 0, 32, vcc
	v_ldexp_f32 v194, v194, v195
	v_mul_f32_e32 v195, v66, v191
	v_mul_f32_e32 v195, 0xbfb8aa3b, v195
	v_exp_f32_e32 v195, v195
	v_log_f32_e32 v194, v194
	v_mul_f32_e32 v191, v67, v191
	v_mul_f32_e32 v191, 0xbfb8aa3b, v191
	v_add_f32_e32 v195, 1.0, v195
	v_rcp_f32_e32 v195, v195
	v_exp_f32_e32 v191, v191
	v_mul_f32_e32 v198, 0x3f317217, v194
	v_fma_f32 v198, v194, s95, -v198
	v_fmac_f32_e32 v198, 0x3377d1cf, v194
	v_fmac_f32_e32 v198, 0x3f317217, v194
	v_cmp_lt_f32_e64 s[6:7], |v194|, s96
	v_fma_f32 v195, v189, v195, v155
	v_add_f32_e32 v191, 1.0, v191
	v_cndmask_b32_e64 v194, v194, v198, s[6:7]
	v_cmp_gt_f32_e64 s[6:7], s90, v195
	v_rcp_f32_e32 v191, v191
	s_nop 0
	v_cndmask_b32_e64 v198, 0, 32, s[6:7]
	v_ldexp_f32 v195, v195, v198
	v_log_f32_e32 v195, v195
	v_fma_f32 v191, v190, v191, v154
	v_cndmask_b32_e32 v198, 0, v171, vcc
	v_cmp_gt_f32_e32 vcc, s90, v191
	v_sub_f32_e32 v194, v194, v198
	v_mul_f32_e32 v198, 0x3f317217, v195
	v_cndmask_b32_e64 v199, 0, 32, vcc
	v_ldexp_f32 v191, v191, v199
	v_fma_f32 v198, v195, s95, -v198
	v_log_f32_e32 v191, v191
	v_fmac_f32_e32 v198, 0x3377d1cf, v195
	v_fmac_f32_e32 v198, 0x3f317217, v195
	v_cmp_lt_f32_e64 s[8:9], |v195|, s96
	v_cvt_pk_f16_f32 v194, v136, v194
	s_nop 0
	v_cndmask_b32_e64 v195, v195, v198, s[8:9]
	v_cndmask_b32_e64 v198, 0, v171, s[6:7]
	v_sub_f32_e32 v195, v195, v198
	v_mul_f32_e32 v198, 0x3f317217, v191
	v_fma_f32 v198, v191, s95, -v198
	v_fmac_f32_e32 v198, 0x3377d1cf, v191
	v_fmac_f32_e32 v198, 0x3f317217, v191
	v_cmp_lt_f32_e64 s[6:7], |v191|, s96
	s_nop 1
	v_cndmask_b32_e64 v191, v191, v198, s[6:7]
	v_cndmask_b32_e32 v198, 0, v171, vcc
	v_sub_f32_e32 v191, v191, v198
	v_cvt_pk_f16_f32 v195, v195, v191
	global_store_dwordx4 v[196:197], v[192:195], off offset:256
	v_fmamk_f32 v136, v213, 0x3a800000, v170
	v_mul_f32_e32 v191, 0x4b800000, v136
	v_cmp_gt_f32_e32 vcc, s90, v136
	s_nop 1
	v_cndmask_b32_e32 v136, v136, v191, vcc
	v_rsq_f32_e32 v136, v136
	s_nop 0
	v_mul_f32_e32 v191, 0x45800000, v136
	v_cndmask_b32_e32 v136, v136, v191, vcc
	v_mul_f32_e32 v191, v60, v136
	v_mul_f32_e32 v191, 0xbfb8aa3b, v191
	v_exp_f32_e32 v191, v191
	v_mul_f32_e32 v193, v61, v136
	v_mul_f32_e32 v193, 0xbfb8aa3b, v193
	v_exp_f32_e32 v193, v193
	v_add_f32_e32 v191, 1.0, v191
	v_rcp_f32_e32 v191, v191
	v_add_f32_e32 v193, 1.0, v193
	v_rcp_f32_e32 v193, v193
	v_fma_f32 v191, v176, v191, v175
	v_cmp_gt_f32_e32 vcc, s90, v191
	s_nop 1
	v_cndmask_b32_e64 v192, 0, 32, vcc
	v_ldexp_f32 v191, v191, v192
	v_log_f32_e32 v191, v191
	s_nop 0
	v_mul_f32_e32 v192, 0x3f317217, v191
	v_fma_f32 v192, v191, s95, -v192
	v_fmac_f32_e32 v192, 0x3377d1cf, v191
	v_fmac_f32_e32 v192, 0x3f317217, v191
	v_cmp_lt_f32_e64 s[6:7], |v191|, s96
	s_nop 1
	v_cndmask_b32_e64 v191, v191, v192, s[6:7]
	v_cndmask_b32_e32 v192, 0, v171, vcc
	v_sub_f32_e32 v191, v191, v192
	v_fma_f32 v192, v177, v193, v174
	v_cmp_gt_f32_e32 vcc, s90, v192
	s_nop 1
	v_cndmask_b32_e64 v193, 0, 32, vcc
	v_ldexp_f32 v192, v192, v193
	v_mul_f32_e32 v193, v62, v136
	v_mul_f32_e32 v193, 0xbfb8aa3b, v193
	v_exp_f32_e32 v193, v193
	v_log_f32_e32 v192, v192
	v_cndmask_b32_e32 v195, 0, v171, vcc
	v_add_f32_e32 v193, 1.0, v193
	v_rcp_f32_e32 v193, v193
	v_mul_f32_e32 v194, 0x3f317217, v192
	v_fma_f32 v194, v192, s95, -v194
	v_fmac_f32_e32 v194, 0x3377d1cf, v192
	v_fmac_f32_e32 v194, 0x3f317217, v192
	v_cmp_lt_f32_e64 s[6:7], |v192|, s96
	v_fma_f32 v193, v178, v193, v173
	s_nop 0
	v_cndmask_b32_e64 v192, v192, v194, s[6:7]
	v_cmp_gt_f32_e64 s[6:7], s90, v193
	v_sub_f32_e32 v192, v192, v195
	v_cvt_pk_f16_f32 v192, v191, v192
	v_cndmask_b32_e64 v194, 0, 32, s[6:7]
	v_ldexp_f32 v193, v193, v194
	v_mul_f32_e32 v194, v63, v136
	v_mul_f32_e32 v194, 0xbfb8aa3b, v194
	v_exp_f32_e32 v194, v194
	v_log_f32_e32 v193, v193
	v_add_f32_e32 v194, 1.0, v194
	v_rcp_f32_e32 v194, v194
	v_mul_f32_e32 v195, 0x3f317217, v193
	v_fma_f32 v195, v193, s95, -v195
	v_fmac_f32_e32 v195, 0x3377d1cf, v193
	v_fma_f32 v194, v183, v194, v172
	v_cmp_gt_f32_e32 vcc, s90, v194
	v_fmac_f32_e32 v195, 0x3f317217, v193
	v_cmp_lt_f32_e64 s[8:9], |v193|, s96
	v_cndmask_b32_e64 v196, 0, 32, vcc
	v_ldexp_f32 v194, v194, v196
	v_mul_f32_e32 v196, v56, v136
	v_log_f32_e32 v194, v194
	v_mul_f32_e32 v196, 0xbfb8aa3b, v196
	v_exp_f32_e32 v196, v196
	v_cndmask_b32_e64 v193, v193, v195, s[8:9]
	v_cndmask_b32_e64 v195, 0, v171, s[6:7]
	v_sub_f32_e32 v193, v193, v195
	v_mul_f32_e32 v195, 0x3f317217, v194
	v_fma_f32 v195, v194, s95, -v195
	v_add_f32_e32 v196, 1.0, v196
	v_fmac_f32_e32 v195, 0x3377d1cf, v194
	v_rcp_f32_e32 v196, v196
	v_fmac_f32_e32 v195, 0x3f317217, v194
	v_cmp_lt_f32_e64 s[6:7], |v194|, s96
	v_fma_f32 v196, v149, v196, v165
	s_nop 0
	v_cndmask_b32_e64 v194, v194, v195, s[6:7]
	v_cndmask_b32_e32 v195, 0, v171, vcc
	v_sub_f32_e32 v194, v194, v195
	v_cvt_pk_f16_f32 v193, v193, v194
	v_mul_f32_e32 v194, v57, v136
	v_cmp_gt_f32_e32 vcc, s90, v196
	v_mul_f32_e32 v194, 0xbfb8aa3b, v194
	v_exp_f32_e32 v194, v194
; __device__ __forceinline__ float fsigm(float x) { return __builtin_amdgcn_rcpf(1.f + __expf(-x)); }
; __device__ __forceinline__ float row_rs(const float* ssq, int row) { return ssq ? rsqrtf(ssq[row] * (1.f / 1024.f) + RMS_EPS) : 1.f; }
;     __device__ __forceinline__ void operator()(const f32x4 (&acc)[2][2][4][2], const Unit& u, int wr, int wc, int fr, int fq) const {
;     ...
;                 for (int m = 0; m < 4; ++m) { const int row = row0 + ai * HALF + m * 16; const float rs = row_rs(ssq, row);
; #pragma unroll
;                     for (int bj = 0; bj < 2; ++bj) { f16x4 o[2];
; #pragma unroll
;                         for (int n = 0; n < 2; ++n) { const f32x4 p = acc[ai][bj][m][n] * rs;
; #pragma unroll
;                             for (int j = 0; j < 4; ++j) { const float l = lb[bj][n][j]; const float f = l + (1.f - l) * fsigm(p[j]); o[n][j] = (_Float16)__logf(f); } }
;                         const u32x2 a0 = __builtin_bit_cast(u32x2, o[0]), a1 = __builtin_bit_cast(u32x2, o[1]); u32x4 w; w.x = a0.x; w.y = a0.y; w.z = a1.x; w.w = a1.y;
;                         *(u32x4*)(LF + (size_t)row * 512 + cbase + bj * HALF) = w; } }
	v_cndmask_b32_e64 v197, 0, 32, vcc
	v_ldexp_f32 v196, v196, v197
	v_log_f32_e32 v196, v196
	v_add_f32_e32 v194, 1.0, v194
	v_rcp_f32_e32 v194, v194
	v_cndmask_b32_e32 v195, 0, v171, vcc
	v_mul_f32_e32 v191, 0x3f317217, v196
	v_fma_f32 v191, v196, s95, -v191
	v_fmac_f32_e32 v191, 0x3377d1cf, v196
	v_fmac_f32_e32 v191, 0x3f317217, v196
	v_cmp_lt_f32_e64 s[6:7], |v196|, s96
	v_fma_f32 v194, v179, v194, v164
	v_cmp_gt_f32_e32 vcc, s90, v194
	v_cndmask_b32_e64 v191, v196, v191, s[6:7]
	v_sub_f32_e32 v191, v191, v195
	v_cndmask_b32_e64 v195, 0, 32, vcc
	v_ldexp_f32 v194, v194, v195
	v_mul_f32_e32 v195, v58, v136
	v_mul_f32_e32 v195, 0xbfb8aa3b, v195
	v_exp_f32_e32 v195, v195
	v_log_f32_e32 v194, v194
	v_cndmask_b32_e32 v197, 0, v171, vcc
	v_add_f32_e32 v195, 1.0, v195
	v_rcp_f32_e32 v195, v195
	v_mul_f32_e32 v196, 0x3f317217, v194
	v_fma_f32 v196, v194, s95, -v196
	v_fmac_f32_e32 v196, 0x3377d1cf, v194
	v_fmac_f32_e32 v196, 0x3f317217, v194
	v_cmp_lt_f32_e64 s[6:7], |v194|, s96
	v_fma_f32 v195, v180, v195, v163
	s_nop 0
	v_cndmask_b32_e64 v194, v194, v196, s[6:7]
	v_cmp_gt_f32_e64 s[6:7], s90, v195
	v_sub_f32_e32 v194, v194, v197
	v_cvt_pk_f16_f32 v194, v191, v194
	v_cndmask_b32_e64 v196, 0, 32, s[6:7]
	v_ldexp_f32 v195, v195, v196
	v_mul_f32_e32 v196, v59, v136
	v_mul_f32_e32 v196, 0xbfb8aa3b, v196
	v_exp_f32_e32 v196, v196
	v_log_f32_e32 v195, v195
	v_add_f32_e32 v196, 1.0, v196
	v_rcp_f32_e32 v196, v196
	v_mul_f32_e32 v197, 0x3f317217, v195
	v_fma_f32 v197, v195, s95, -v197
	v_fmac_f32_e32 v197, 0x3377d1cf, v195
	v_fma_f32 v196, v188, v196, v162
	v_cmp_gt_f32_e32 vcc, s90, v196
	v_fmac_f32_e32 v197, 0x3f317217, v195
	v_cmp_lt_f32_e64 s[8:9], |v195|, s96
	v_cndmask_b32_e64 v198, 0, 32, vcc
	v_ldexp_f32 v196, v196, v198
	v_log_f32_e32 v196, v196
	v_cndmask_b32_e64 v195, v195, v197, s[8:9]
	v_cndmask_b32_e64 v197, 0, v171, s[6:7]
	v_mul_f32_e32 v198, v52, v136
	v_sub_f32_e32 v195, v195, v197
	v_mul_f32_e32 v197, 0x3f317217, v196
	v_mul_f32_e32 v198, 0xbfb8aa3b, v198
	v_fma_f32 v197, v196, s95, -v197
	v_exp_f32_e32 v198, v198
	v_fmac_f32_e32 v197, 0x3377d1cf, v196
	v_fmac_f32_e32 v197, 0x3f317217, v196
	v_cmp_lt_f32_e64 s[6:7], |v196|, s96
	s_nop 1
	v_cndmask_b32_e64 v196, v196, v197, s[6:7]
	v_cndmask_b32_e32 v197, 0, v171, vcc
	v_sub_f32_e32 v196, v196, v197
	v_add_f32_e32 v197, 1.0, v198
	v_rcp_f32_e32 v198, v197
	v_cvt_pk_f16_f32 v195, v195, v196
	v_lshl_add_u64 v[196:197], v[152:153], 0, s[38:39]
	v_fma_f32 v191, v184, v198, v161
	v_cmp_gt_f32_e32 vcc, s90, v191
	s_nop 1
	v_cndmask_b32_e64 v198, 0, 32, vcc
	v_ldexp_f32 v191, v191, v198
	v_add_co_u32_e64 v198, s[6:7], s91, v152
	v_log_f32_e32 v191, v191
	s_nop 0
	v_addc_co_u32_e64 v199, s[6:7], 0, v153, s[6:7]
	global_store_dwordx4 v[198:199], v[192:195], off
	v_cmp_lt_f32_e64 s[6:7], |v191|, s96
	s_nop 0
	v_mul_f32_e32 v193, v53, v136
	v_mul_f32_e32 v193, 0xbfb8aa3b, v193
	v_exp_f32_e32 v193, v193
	v_mul_f32_e32 v192, 0x3f317217, v191
	v_fma_f32 v192, v191, s95, -v192
	v_fmac_f32_e32 v192, 0x3377d1cf, v191
	v_add_f32_e32 v193, 1.0, v193
	v_rcp_f32_e32 v193, v193
	v_fmac_f32_e32 v192, 0x3f317217, v191
	v_cndmask_b32_e64 v191, v191, v192, s[6:7]
	v_cndmask_b32_e32 v192, 0, v171, vcc
	v_sub_f32_e32 v191, v191, v192
	v_fma_f32 v192, v181, v193, v160
	v_cmp_gt_f32_e32 vcc, s90, v192
	s_nop 1
	v_cndmask_b32_e64 v193, 0, 32, vcc
	v_ldexp_f32 v192, v192, v193
	v_mul_f32_e32 v193, v54, v136
	v_mul_f32_e32 v193, 0xbfb8aa3b, v193
	v_exp_f32_e32 v193, v193
	v_log_f32_e32 v192, v192
	v_cndmask_b32_e32 v195, 0, v171, vcc
	v_add_f32_e32 v193, 1.0, v193
	v_rcp_f32_e32 v193, v193
	v_mul_f32_e32 v194, 0x3f317217, v192
	v_fma_f32 v194, v192, s95, -v194
	v_fmac_f32_e32 v194, 0x3377d1cf, v192
	v_fmac_f32_e32 v194, 0x3f317217, v192
	v_cmp_lt_f32_e64 s[6:7], |v192|, s96
	v_fma_f32 v193, v185, v193, v159
	s_nop 0
	v_cndmask_b32_e64 v192, v192, v194, s[6:7]
	v_cmp_gt_f32_e64 s[6:7], s90, v193
	v_sub_f32_e32 v192, v192, v195
	v_cvt_pk_f16_f32 v192, v191, v192
	v_cndmask_b32_e64 v194, 0, 32, s[6:7]
	v_ldexp_f32 v193, v193, v194
	v_mul_f32_e32 v194, v55, v136
	v_mul_f32_e32 v194, 0xbfb8aa3b, v194
	v_exp_f32_e32 v194, v194
	v_log_f32_e32 v193, v193
	v_add_f32_e32 v194, 1.0, v194
	v_rcp_f32_e32 v194, v194
	v_mul_f32_e32 v195, 0x3f317217, v193
	v_fma_f32 v195, v193, s95, -v195
	v_fmac_f32_e32 v195, 0x3377d1cf, v193
	v_fma_f32 v194, v186, v194, v158
	v_cmp_gt_f32_e32 vcc, s90, v194
	v_fmac_f32_e32 v195, 0x3f317217, v193
	v_cmp_lt_f32_e64 s[8:9], |v193|, s96
	v_cndmask_b32_e64 v198, 0, 32, vcc
	v_ldexp_f32 v194, v194, v198
	v_mul_f32_e32 v198, v48, v136
	v_log_f32_e32 v194, v194
	v_mul_f32_e32 v198, 0xbfb8aa3b, v198
	v_exp_f32_e32 v198, v198
	v_cndmask_b32_e64 v193, v193, v195, s[8:9]
	v_cndmask_b32_e64 v195, 0, v171, s[6:7]
	v_sub_f32_e32 v193, v193, v195
	v_mul_f32_e32 v195, 0x3f317217, v194
	v_fma_f32 v195, v194, s95, -v195
	v_add_f32_e32 v198, 1.0, v198
	v_fmac_f32_e32 v195, 0x3377d1cf, v194
	v_rcp_f32_e32 v198, v198
	v_fmac_f32_e32 v195, 0x3f317217, v194
	v_cmp_lt_f32_e64 s[6:7], |v194|, s96
	v_fma_f32 v198, v187, v198, v157
	s_nop 0
	v_cndmask_b32_e64 v194, v194, v195, s[6:7]
	v_cndmask_b32_e32 v195, 0, v171, vcc
	v_sub_f32_e32 v194, v194, v195
	v_cvt_pk_f16_f32 v193, v193, v194
	v_mul_f32_e32 v194, v49, v136
	v_cmp_gt_f32_e32 vcc, s90, v198
	v_mul_f32_e32 v194, 0xbfb8aa3b, v194
	v_exp_f32_e32 v194, v194
	v_cndmask_b32_e64 v199, 0, 32, vcc
	v_ldexp_f32 v198, v198, v199
	v_log_f32_e32 v198, v198
	v_add_f32_e32 v194, 1.0, v194
	v_rcp_f32_e32 v194, v194
	v_cndmask_b32_e32 v195, 0, v171, vcc
	v_mul_f32_e32 v191, 0x3f317217, v198
	v_fma_f32 v191, v198, s95, -v191
	v_fmac_f32_e32 v191, 0x3377d1cf, v198
; __device__ __forceinline__ float fsigm(float x) { return __builtin_amdgcn_rcpf(1.f + __expf(-x)); }
; __device__ __forceinline__ float row_rs(const float* ssq, int row) { return ssq ? rsqrtf(ssq[row] * (1.f / 1024.f) + RMS_EPS) : 1.f; }
;     __device__ __forceinline__ void operator()(const f32x4 (&acc)[2][2][4][2], const Unit& u, int wr, int wc, int fr, int fq) const {
;     ...
;                 for (int m = 0; m < 4; ++m) { const int row = row0 + ai * HALF + m * 16; const float rs = row_rs(ssq, row);
; #pragma unroll
;                     for (int bj = 0; bj < 2; ++bj) { f16x4 o[2];
; #pragma unroll
;                         for (int n = 0; n < 2; ++n) { const f32x4 p = acc[ai][bj][m][n] * rs;
; #pragma unroll
;                             for (int j = 0; j < 4; ++j) { const float l = lb[bj][n][j]; const float f = l + (1.f - l) * fsigm(p[j]); o[n][j] = (_Float16)__logf(f); } }
;                         const u32x2 a0 = __builtin_bit_cast(u32x2, o[0]), a1 = __builtin_bit_cast(u32x2, o[1]); u32x4 w; w.x = a0.x; w.y = a0.y; w.z = a1.x; w.w = a1.y;
;                         *(u32x4*)(LF + (size_t)row * 512 + cbase + bj * HALF) = w; } }
	v_fmac_f32_e32 v191, 0x3f317217, v198
	v_cmp_lt_f32_e64 s[6:7], |v198|, s96
	v_fma_f32 v194, v182, v194, v156
	v_cmp_gt_f32_e32 vcc, s90, v194
	v_cndmask_b32_e64 v191, v198, v191, s[6:7]
	v_sub_f32_e32 v191, v191, v195
	v_cndmask_b32_e64 v195, 0, 32, vcc
	v_ldexp_f32 v194, v194, v195
	v_mul_f32_e32 v195, v50, v136
	v_mul_f32_e32 v195, 0xbfb8aa3b, v195
	v_exp_f32_e32 v195, v195
	v_log_f32_e32 v194, v194
	v_mul_f32_e32 v136, v51, v136
	v_mul_f32_e32 v136, 0xbfb8aa3b, v136
	v_add_f32_e32 v195, 1.0, v195
	v_rcp_f32_e32 v195, v195
	v_exp_f32_e32 v136, v136
	v_mul_f32_e32 v198, 0x3f317217, v194
	v_fma_f32 v198, v194, s95, -v198
	v_fmac_f32_e32 v198, 0x3377d1cf, v194
	v_fmac_f32_e32 v198, 0x3f317217, v194
	v_cmp_lt_f32_e64 s[6:7], |v194|, s96
	v_fma_f32 v195, v189, v195, v155
	v_add_f32_e32 v136, 1.0, v136
	v_cndmask_b32_e64 v194, v194, v198, s[6:7]
	v_cmp_gt_f32_e64 s[6:7], s90, v195
	v_rcp_f32_e32 v136, v136
	s_nop 0
	v_cndmask_b32_e64 v198, 0, 32, s[6:7]
	v_ldexp_f32 v195, v195, v198
	v_log_f32_e32 v195, v195
	v_fma_f32 v136, v190, v136, v154
	v_cndmask_b32_e32 v198, 0, v171, vcc
	v_cmp_gt_f32_e32 vcc, s90, v136
	v_sub_f32_e32 v194, v194, v198
	v_mul_f32_e32 v198, 0x3f317217, v195
	v_cndmask_b32_e64 v199, 0, 32, vcc
	v_ldexp_f32 v136, v136, v199
	v_fma_f32 v198, v195, s95, -v198
	v_log_f32_e32 v136, v136
	v_fmac_f32_e32 v198, 0x3377d1cf, v195
	v_fmac_f32_e32 v198, 0x3f317217, v195
	v_cmp_lt_f32_e64 s[8:9], |v195|, s96
	v_cvt_pk_f16_f32 v194, v191, v194
	s_nop 0
	v_cndmask_b32_e64 v195, v195, v198, s[8:9]
	v_cndmask_b32_e64 v198, 0, v171, s[6:7]
	v_sub_f32_e32 v195, v195, v198
	v_mul_f32_e32 v198, 0x3f317217, v136
	v_fma_f32 v198, v136, s95, -v198
	v_fmac_f32_e32 v198, 0x3377d1cf, v136
	v_fmac_f32_e32 v198, 0x3f317217, v136
	v_cmp_lt_f32_e64 s[6:7], |v136|, s96
	s_nop 1
	v_cndmask_b32_e64 v136, v136, v198, s[6:7]
	v_cndmask_b32_e32 v198, 0, v171, vcc
	v_sub_f32_e32 v136, v136, v198
	v_cvt_pk_f16_f32 v195, v195, v136
	global_store_dwordx4 v[196:197], v[192:195], off offset:256
	v_fmamk_f32 v136, v214, 0x3a800000, v170
	v_mul_f32_e32 v191, 0x4b800000, v136
	v_cmp_gt_f32_e32 vcc, s90, v136
	s_nop 1
	v_cndmask_b32_e32 v136, v136, v191, vcc
	v_rsq_f32_e32 v136, v136
	s_nop 0
	v_mul_f32_e32 v191, 0x45800000, v136
	v_cndmask_b32_e32 v136, v136, v191, vcc
	v_mul_f32_e32 v191, v44, v136
	v_mul_f32_e32 v191, 0xbfb8aa3b, v191
	v_exp_f32_e32 v191, v191
	v_mul_f32_e32 v193, v45, v136
	v_mul_f32_e32 v193, 0xbfb8aa3b, v193
	v_exp_f32_e32 v193, v193
	v_add_f32_e32 v191, 1.0, v191
	v_rcp_f32_e32 v191, v191
	v_add_f32_e32 v193, 1.0, v193
	v_rcp_f32_e32 v193, v193
	v_fma_f32 v191, v176, v191, v175
	v_cmp_gt_f32_e32 vcc, s90, v191
	s_nop 1
	v_cndmask_b32_e64 v192, 0, 32, vcc
	v_ldexp_f32 v191, v191, v192
	v_log_f32_e32 v191, v191
	s_nop 0
	v_mul_f32_e32 v192, 0x3f317217, v191
	v_fma_f32 v192, v191, s95, -v192
	v_fmac_f32_e32 v192, 0x3377d1cf, v191
	v_fmac_f32_e32 v192, 0x3f317217, v191
	v_cmp_lt_f32_e64 s[6:7], |v191|, s96
	s_nop 1
	v_cndmask_b32_e64 v191, v191, v192, s[6:7]
	v_cndmask_b32_e32 v192, 0, v171, vcc
	v_sub_f32_e32 v191, v191, v192
	v_fma_f32 v192, v177, v193, v174
	v_cmp_gt_f32_e32 vcc, s90, v192
	s_nop 1
	v_cndmask_b32_e64 v193, 0, 32, vcc
	v_ldexp_f32 v192, v192, v193
	v_mul_f32_e32 v193, v46, v136
	v_mul_f32_e32 v193, 0xbfb8aa3b, v193
	v_exp_f32_e32 v193, v193
	v_log_f32_e32 v192, v192
	v_cndmask_b32_e32 v195, 0, v171, vcc
	v_add_f32_e32 v193, 1.0, v193
	v_rcp_f32_e32 v193, v193
	v_mul_f32_e32 v194, 0x3f317217, v192
	v_fma_f32 v194, v192, s95, -v194
	v_fmac_f32_e32 v194, 0x3377d1cf, v192
	v_fmac_f32_e32 v194, 0x3f317217, v192
	v_cmp_lt_f32_e64 s[6:7], |v192|, s96
	v_fma_f32 v193, v178, v193, v173
	s_nop 0
	v_cndmask_b32_e64 v192, v192, v194, s[6:7]
	v_cmp_gt_f32_e64 s[6:7], s90, v193
	v_sub_f32_e32 v192, v192, v195
	v_cvt_pk_f16_f32 v192, v191, v192
	v_cndmask_b32_e64 v194, 0, 32, s[6:7]
	v_ldexp_f32 v193, v193, v194
	v_mul_f32_e32 v194, v47, v136
	v_mul_f32_e32 v194, 0xbfb8aa3b, v194
	v_exp_f32_e32 v194, v194
	v_log_f32_e32 v193, v193
	v_add_f32_e32 v194, 1.0, v194
	v_rcp_f32_e32 v194, v194
	v_mul_f32_e32 v195, 0x3f317217, v193
	v_fma_f32 v195, v193, s95, -v195
	v_fmac_f32_e32 v195, 0x3377d1cf, v193
	v_fma_f32 v194, v183, v194, v172
	v_cmp_gt_f32_e32 vcc, s90, v194
	v_fmac_f32_e32 v195, 0x3f317217, v193
	v_cmp_lt_f32_e64 s[8:9], |v193|, s96
	v_cndmask_b32_e64 v196, 0, 32, vcc
	v_ldexp_f32 v194, v194, v196
	v_mul_f32_e32 v196, v40, v136
	v_log_f32_e32 v194, v194
	v_mul_f32_e32 v196, 0xbfb8aa3b, v196
	v_exp_f32_e32 v196, v196
	v_cndmask_b32_e64 v193, v193, v195, s[8:9]
	v_cndmask_b32_e64 v195, 0, v171, s[6:7]
	v_sub_f32_e32 v193, v193, v195
	v_mul_f32_e32 v195, 0x3f317217, v194
	v_fma_f32 v195, v194, s95, -v195
	v_add_f32_e32 v196, 1.0, v196
	v_fmac_f32_e32 v195, 0x3377d1cf, v194
	v_rcp_f32_e32 v196, v196
	v_fmac_f32_e32 v195, 0x3f317217, v194
	v_cmp_lt_f32_e64 s[6:7], |v194|, s96
	v_fma_f32 v196, v149, v196, v165
	s_nop 0
	v_cndmask_b32_e64 v194, v194, v195, s[6:7]
	v_cndmask_b32_e32 v195, 0, v171, vcc
	v_sub_f32_e32 v194, v194, v195
	v_cvt_pk_f16_f32 v193, v193, v194
	v_mul_f32_e32 v194, v41, v136
	v_cmp_gt_f32_e32 vcc, s90, v196
	v_mul_f32_e32 v194, 0xbfb8aa3b, v194
	v_exp_f32_e32 v194, v194
	v_cndmask_b32_e64 v197, 0, 32, vcc
	v_ldexp_f32 v196, v196, v197
	v_log_f32_e32 v196, v196
	v_add_f32_e32 v194, 1.0, v194
	v_rcp_f32_e32 v194, v194
	v_cndmask_b32_e32 v195, 0, v171, vcc
	v_mul_f32_e32 v191, 0x3f317217, v196
	v_fma_f32 v191, v196, s95, -v191
	v_fmac_f32_e32 v191, 0x3377d1cf, v196
	v_fmac_f32_e32 v191, 0x3f317217, v196
	v_cmp_lt_f32_e64 s[6:7], |v196|, s96
	v_fma_f32 v194, v179, v194, v164
	v_cmp_gt_f32_e32 vcc, s90, v194
; __device__ __forceinline__ float fsigm(float x) { return __builtin_amdgcn_rcpf(1.f + __expf(-x)); }
; __device__ __forceinline__ float row_rs(const float* ssq, int row) { return ssq ? rsqrtf(ssq[row] * (1.f / 1024.f) + RMS_EPS) : 1.f; }
;     __device__ __forceinline__ void operator()(const f32x4 (&acc)[2][2][4][2], const Unit& u, int wr, int wc, int fr, int fq) const {
;     ...
;                 for (int m = 0; m < 4; ++m) { const int row = row0 + ai * HALF + m * 16; const float rs = row_rs(ssq, row);
; #pragma unroll
;                     for (int bj = 0; bj < 2; ++bj) { f16x4 o[2];
; #pragma unroll
;                         for (int n = 0; n < 2; ++n) { const f32x4 p = acc[ai][bj][m][n] * rs;
; #pragma unroll
;                             for (int j = 0; j < 4; ++j) { const float l = lb[bj][n][j]; const float f = l + (1.f - l) * fsigm(p[j]); o[n][j] = (_Float16)__logf(f); } }
;                         const u32x2 a0 = __builtin_bit_cast(u32x2, o[0]), a1 = __builtin_bit_cast(u32x2, o[1]); u32x4 w; w.x = a0.x; w.y = a0.y; w.z = a1.x; w.w = a1.y;
;                         *(u32x4*)(LF + (size_t)row * 512 + cbase + bj * HALF) = w; } }
	v_cndmask_b32_e64 v191, v196, v191, s[6:7]
	v_sub_f32_e32 v191, v191, v195
	v_cndmask_b32_e64 v195, 0, 32, vcc
	v_ldexp_f32 v194, v194, v195
	v_mul_f32_e32 v195, v42, v136
	v_mul_f32_e32 v195, 0xbfb8aa3b, v195
	v_exp_f32_e32 v195, v195
	v_log_f32_e32 v194, v194
	v_cndmask_b32_e32 v197, 0, v171, vcc
	v_add_f32_e32 v195, 1.0, v195
	v_rcp_f32_e32 v195, v195
	v_mul_f32_e32 v196, 0x3f317217, v194
	v_fma_f32 v196, v194, s95, -v196
	v_fmac_f32_e32 v196, 0x3377d1cf, v194
	v_fmac_f32_e32 v196, 0x3f317217, v194
	v_cmp_lt_f32_e64 s[6:7], |v194|, s96
	v_fma_f32 v195, v180, v195, v163
	s_nop 0
	v_cndmask_b32_e64 v194, v194, v196, s[6:7]
	v_cmp_gt_f32_e64 s[6:7], s90, v195
	v_sub_f32_e32 v194, v194, v197
	v_cvt_pk_f16_f32 v194, v191, v194
	v_cndmask_b32_e64 v196, 0, 32, s[6:7]
	v_ldexp_f32 v195, v195, v196
	v_mul_f32_e32 v196, v43, v136
	v_mul_f32_e32 v196, 0xbfb8aa3b, v196
	v_exp_f32_e32 v196, v196
	v_log_f32_e32 v195, v195
	v_add_f32_e32 v196, 1.0, v196
	v_rcp_f32_e32 v196, v196
	v_mul_f32_e32 v197, 0x3f317217, v195
	v_fma_f32 v197, v195, s95, -v197
	v_fmac_f32_e32 v197, 0x3377d1cf, v195
	v_fma_f32 v196, v188, v196, v162
	v_cmp_gt_f32_e32 vcc, s90, v196
	v_fmac_f32_e32 v197, 0x3f317217, v195
	v_cmp_lt_f32_e64 s[8:9], |v195|, s96
	v_cndmask_b32_e64 v198, 0, 32, vcc
	v_ldexp_f32 v196, v196, v198
	v_log_f32_e32 v196, v196
	v_cndmask_b32_e64 v195, v195, v197, s[8:9]
	v_cndmask_b32_e64 v197, 0, v171, s[6:7]
	v_mul_f32_e32 v198, v36, v136
	v_sub_f32_e32 v195, v195, v197
	v_mul_f32_e32 v197, 0x3f317217, v196
	v_mul_f32_e32 v198, 0xbfb8aa3b, v198
	v_fma_f32 v197, v196, s95, -v197
	v_exp_f32_e32 v198, v198
	v_fmac_f32_e32 v197, 0x3377d1cf, v196
	v_fmac_f32_e32 v197, 0x3f317217, v196
	v_cmp_lt_f32_e64 s[6:7], |v196|, s96
	s_nop 1
	v_cndmask_b32_e64 v196, v196, v197, s[6:7]
	v_cndmask_b32_e32 v197, 0, v171, vcc
	v_sub_f32_e32 v196, v196, v197
	v_add_f32_e32 v197, 1.0, v198
	v_rcp_f32_e32 v198, v197
	v_cvt_pk_f16_f32 v195, v195, v196
	v_lshl_add_u64 v[196:197], v[152:153], 0, s[40:41]
	v_fma_f32 v191, v184, v198, v161
	v_cmp_gt_f32_e32 vcc, s90, v191
	s_nop 1
	v_cndmask_b32_e64 v198, 0, 32, vcc
	v_ldexp_f32 v191, v191, v198
	v_add_co_u32_e64 v198, s[6:7], s92, v152
	v_log_f32_e32 v191, v191
	s_nop 0
	v_addc_co_u32_e64 v199, s[6:7], 0, v153, s[6:7]
	global_store_dwordx4 v[198:199], v[192:195], off
	v_cmp_lt_f32_e64 s[6:7], |v191|, s96
	s_nop 0
	v_mul_f32_e32 v193, v37, v136
	v_mul_f32_e32 v193, 0xbfb8aa3b, v193
	v_exp_f32_e32 v193, v193
	v_mul_f32_e32 v192, 0x3f317217, v191
	v_fma_f32 v192, v191, s95, -v192
	v_fmac_f32_e32 v192, 0x3377d1cf, v191
	v_add_f32_e32 v193, 1.0, v193
	v_rcp_f32_e32 v193, v193
	v_fmac_f32_e32 v192, 0x3f317217, v191
	v_cndmask_b32_e64 v191, v191, v192, s[6:7]
	v_cndmask_b32_e32 v192, 0, v171, vcc
	v_sub_f32_e32 v191, v191, v192
	v_fma_f32 v192, v181, v193, v160
	v_cmp_gt_f32_e32 vcc, s90, v192
	s_nop 1
	v_cndmask_b32_e64 v193, 0, 32, vcc
	v_ldexp_f32 v192, v192, v193
	v_mul_f32_e32 v193, v38, v136
	v_mul_f32_e32 v193, 0xbfb8aa3b, v193
	v_exp_f32_e32 v193, v193
	v_log_f32_e32 v192, v192
	v_cndmask_b32_e32 v195, 0, v171, vcc
	v_add_f32_e32 v193, 1.0, v193
	v_rcp_f32_e32 v193, v193
	v_mul_f32_e32 v194, 0x3f317217, v192
	v_fma_f32 v194, v192, s95, -v194
	v_fmac_f32_e32 v194, 0x3377d1cf, v192
	v_fmac_f32_e32 v194, 0x3f317217, v192
	v_cmp_lt_f32_e64 s[6:7], |v192|, s96
	v_fma_f32 v193, v185, v193, v159
	s_nop 0
	v_cndmask_b32_e64 v192, v192, v194, s[6:7]
	v_cmp_gt_f32_e64 s[6:7], s90, v193
	v_sub_f32_e32 v192, v192, v195
	v_cvt_pk_f16_f32 v192, v191, v192
	v_cndmask_b32_e64 v194, 0, 32, s[6:7]
	v_ldexp_f32 v193, v193, v194
	v_mul_f32_e32 v194, v39, v136
	v_mul_f32_e32 v194, 0xbfb8aa3b, v194
	v_exp_f32_e32 v194, v194
	v_log_f32_e32 v193, v193
	v_add_f32_e32 v194, 1.0, v194
	v_rcp_f32_e32 v194, v194
	v_mul_f32_e32 v195, 0x3f317217, v193
	v_fma_f32 v195, v193, s95, -v195
	v_fmac_f32_e32 v195, 0x3377d1cf, v193
	v_fma_f32 v194, v186, v194, v158
	v_cmp_gt_f32_e32 vcc, s90, v194
	v_fmac_f32_e32 v195, 0x3f317217, v193
	v_cmp_lt_f32_e64 s[8:9], |v193|, s96
	v_cndmask_b32_e64 v198, 0, 32, vcc
	v_ldexp_f32 v194, v194, v198
	v_mul_f32_e32 v198, v32, v136
	v_log_f32_e32 v194, v194
	v_mul_f32_e32 v198, 0xbfb8aa3b, v198
	v_exp_f32_e32 v198, v198
	v_cndmask_b32_e64 v193, v193, v195, s[8:9]
	v_cndmask_b32_e64 v195, 0, v171, s[6:7]
	v_sub_f32_e32 v193, v193, v195
	v_mul_f32_e32 v195, 0x3f317217, v194
	v_fma_f32 v195, v194, s95, -v195
	v_add_f32_e32 v198, 1.0, v198
	v_fmac_f32_e32 v195, 0x3377d1cf, v194
	v_rcp_f32_e32 v198, v198
	v_fmac_f32_e32 v195, 0x3f317217, v194
	v_cmp_lt_f32_e64 s[6:7], |v194|, s96
	v_fma_f32 v198, v187, v198, v157
	s_nop 0
	v_cndmask_b32_e64 v194, v194, v195, s[6:7]
	v_cndmask_b32_e32 v195, 0, v171, vcc
	v_sub_f32_e32 v194, v194, v195
	v_cvt_pk_f16_f32 v193, v193, v194
	v_mul_f32_e32 v194, v33, v136
	v_cmp_gt_f32_e32 vcc, s90, v198
	v_mul_f32_e32 v194, 0xbfb8aa3b, v194
	v_exp_f32_e32 v194, v194
	v_cndmask_b32_e64 v199, 0, 32, vcc
	v_ldexp_f32 v198, v198, v199
	v_log_f32_e32 v198, v198
	v_add_f32_e32 v194, 1.0, v194
	v_rcp_f32_e32 v194, v194
	v_cndmask_b32_e32 v195, 0, v171, vcc
	v_mul_f32_e32 v191, 0x3f317217, v198
	v_fma_f32 v191, v198, s95, -v191
	v_fmac_f32_e32 v191, 0x3377d1cf, v198
	v_fmac_f32_e32 v191, 0x3f317217, v198
	v_cmp_lt_f32_e64 s[6:7], |v198|, s96
	v_fma_f32 v194, v182, v194, v156
	v_cmp_gt_f32_e32 vcc, s90, v194
	v_cndmask_b32_e64 v191, v198, v191, s[6:7]
	v_sub_f32_e32 v191, v191, v195
	v_cndmask_b32_e64 v195, 0, 32, vcc
	v_ldexp_f32 v194, v194, v195
	v_mul_f32_e32 v195, v34, v136
	v_mul_f32_e32 v195, 0xbfb8aa3b, v195
	v_exp_f32_e32 v195, v195
	v_log_f32_e32 v194, v194
	v_mul_f32_e32 v136, v35, v136
; __device__ __forceinline__ float fsigm(float x) { return __builtin_amdgcn_rcpf(1.f + __expf(-x)); }
; __device__ __forceinline__ float row_rs(const float* ssq, int row) { return ssq ? rsqrtf(ssq[row] * (1.f / 1024.f) + RMS_EPS) : 1.f; }
;     __device__ __forceinline__ void operator()(const f32x4 (&acc)[2][2][4][2], const Unit& u, int wr, int wc, int fr, int fq) const {
;     ...
;                 for (int m = 0; m < 4; ++m) { const int row = row0 + ai * HALF + m * 16; const float rs = row_rs(ssq, row);
; #pragma unroll
;                     for (int bj = 0; bj < 2; ++bj) { f16x4 o[2];
; #pragma unroll
;                         for (int n = 0; n < 2; ++n) { const f32x4 p = acc[ai][bj][m][n] * rs;
; #pragma unroll
;                             for (int j = 0; j < 4; ++j) { const float l = lb[bj][n][j]; const float f = l + (1.f - l) * fsigm(p[j]); o[n][j] = (_Float16)__logf(f); } }
;                         const u32x2 a0 = __builtin_bit_cast(u32x2, o[0]), a1 = __builtin_bit_cast(u32x2, o[1]); u32x4 w; w.x = a0.x; w.y = a0.y; w.z = a1.x; w.w = a1.y;
;                         *(u32x4*)(LF + (size_t)row * 512 + cbase + bj * HALF) = w; } }
	v_mul_f32_e32 v136, 0xbfb8aa3b, v136
	v_add_f32_e32 v195, 1.0, v195
	v_rcp_f32_e32 v195, v195
	v_exp_f32_e32 v136, v136
	v_mul_f32_e32 v198, 0x3f317217, v194
	v_fma_f32 v198, v194, s95, -v198
	v_fmac_f32_e32 v198, 0x3377d1cf, v194
	v_fmac_f32_e32 v198, 0x3f317217, v194
	v_cmp_lt_f32_e64 s[6:7], |v194|, s96
	v_fma_f32 v195, v189, v195, v155
	v_add_f32_e32 v136, 1.0, v136
	v_cndmask_b32_e64 v194, v194, v198, s[6:7]
	v_cmp_gt_f32_e64 s[6:7], s90, v195
	v_rcp_f32_e32 v136, v136
	s_nop 0
	v_cndmask_b32_e64 v198, 0, 32, s[6:7]
	v_ldexp_f32 v195, v195, v198
	v_log_f32_e32 v195, v195
	v_fma_f32 v136, v190, v136, v154
	v_cndmask_b32_e32 v198, 0, v171, vcc
	v_cmp_gt_f32_e32 vcc, s90, v136
	v_sub_f32_e32 v194, v194, v198
	v_mul_f32_e32 v198, 0x3f317217, v195
	v_cndmask_b32_e64 v199, 0, 32, vcc
	v_ldexp_f32 v136, v136, v199
	v_fma_f32 v198, v195, s95, -v198
	v_log_f32_e32 v136, v136
	v_fmac_f32_e32 v198, 0x3377d1cf, v195
	v_fmac_f32_e32 v198, 0x3f317217, v195
	v_cmp_lt_f32_e64 s[8:9], |v195|, s96
	v_cvt_pk_f16_f32 v194, v191, v194
	s_nop 0
	v_cndmask_b32_e64 v195, v195, v198, s[8:9]
	v_cndmask_b32_e64 v198, 0, v171, s[6:7]
	v_sub_f32_e32 v195, v195, v198
	v_mul_f32_e32 v198, 0x3f317217, v136
	v_fma_f32 v198, v136, s95, -v198
	v_fmac_f32_e32 v198, 0x3377d1cf, v136
	v_fmac_f32_e32 v198, 0x3f317217, v136
	v_cmp_lt_f32_e64 s[6:7], |v136|, s96
	s_nop 1
	v_cndmask_b32_e64 v136, v136, v198, s[6:7]
	v_cndmask_b32_e32 v198, 0, v171, vcc
	v_sub_f32_e32 v136, v136, v198
	v_cvt_pk_f16_f32 v195, v195, v136
	global_store_dwordx4 v[196:197], v[192:195], off offset:256
	v_fmamk_f32 v136, v215, 0x3a800000, v170
	v_mul_f32_e32 v191, 0x4b800000, v136
	v_cmp_gt_f32_e32 vcc, s90, v136
	s_nop 1
	v_cndmask_b32_e32 v136, v136, v191, vcc
	v_rsq_f32_e32 v136, v136
	s_nop 0
	v_mul_f32_e32 v191, 0x45800000, v136
	v_cndmask_b32_e32 v136, v136, v191, vcc
	v_mul_f32_e32 v191, v28, v136
	v_mul_f32_e32 v191, 0xbfb8aa3b, v191
	v_exp_f32_e32 v191, v191
	v_mul_f32_e32 v193, v29, v136
	v_mul_f32_e32 v193, 0xbfb8aa3b, v193
	v_exp_f32_e32 v193, v193
	v_add_f32_e32 v191, 1.0, v191
	v_rcp_f32_e32 v191, v191
	v_add_f32_e32 v193, 1.0, v193
	v_rcp_f32_e32 v193, v193
	v_fma_f32 v191, v176, v191, v175
	v_cmp_gt_f32_e32 vcc, s90, v191
	s_nop 1
	v_cndmask_b32_e64 v192, 0, 32, vcc
	v_ldexp_f32 v191, v191, v192
	v_log_f32_e32 v191, v191
	s_nop 0
	v_mul_f32_e32 v192, 0x3f317217, v191
	v_fma_f32 v192, v191, s95, -v192
	v_fmac_f32_e32 v192, 0x3377d1cf, v191
	v_fmac_f32_e32 v192, 0x3f317217, v191
	v_cmp_lt_f32_e64 s[6:7], |v191|, s96
	s_nop 1
	v_cndmask_b32_e64 v191, v191, v192, s[6:7]
	v_cndmask_b32_e32 v192, 0, v171, vcc
	v_sub_f32_e32 v191, v191, v192
	v_fma_f32 v192, v177, v193, v174
	v_cmp_gt_f32_e32 vcc, s90, v192
	s_nop 1
	v_cndmask_b32_e64 v193, 0, 32, vcc
	v_ldexp_f32 v192, v192, v193
	v_mul_f32_e32 v193, v30, v136
	v_mul_f32_e32 v193, 0xbfb8aa3b, v193
	v_exp_f32_e32 v193, v193
	v_log_f32_e32 v192, v192
	v_cndmask_b32_e32 v195, 0, v171, vcc
	v_add_f32_e32 v193, 1.0, v193
	v_rcp_f32_e32 v193, v193
	v_mul_f32_e32 v194, 0x3f317217, v192
	v_fma_f32 v194, v192, s95, -v194
	v_fmac_f32_e32 v194, 0x3377d1cf, v192
	v_fmac_f32_e32 v194, 0x3f317217, v192
	v_cmp_lt_f32_e64 s[6:7], |v192|, s96
	v_fma_f32 v193, v178, v193, v173
	s_nop 0
	v_cndmask_b32_e64 v192, v192, v194, s[6:7]
	v_cmp_gt_f32_e64 s[6:7], s90, v193
	v_sub_f32_e32 v192, v192, v195
	v_cvt_pk_f16_f32 v192, v191, v192
	v_cndmask_b32_e64 v194, 0, 32, s[6:7]
	v_ldexp_f32 v193, v193, v194
	v_mul_f32_e32 v194, v31, v136
	v_mul_f32_e32 v194, 0xbfb8aa3b, v194
	v_exp_f32_e32 v194, v194
	v_log_f32_e32 v193, v193
	v_add_f32_e32 v194, 1.0, v194
	v_rcp_f32_e32 v194, v194
	v_mul_f32_e32 v195, 0x3f317217, v193
	v_fma_f32 v195, v193, s95, -v195
	v_fmac_f32_e32 v195, 0x3377d1cf, v193
	v_fma_f32 v194, v183, v194, v172
	v_cmp_gt_f32_e32 vcc, s90, v194
	v_fmac_f32_e32 v195, 0x3f317217, v193
	v_cmp_lt_f32_e64 s[8:9], |v193|, s96
	v_cndmask_b32_e64 v196, 0, 32, vcc
	v_ldexp_f32 v194, v194, v196
	v_mul_f32_e32 v196, v24, v136
	v_log_f32_e32 v194, v194
	v_mul_f32_e32 v196, 0xbfb8aa3b, v196
	v_exp_f32_e32 v196, v196
	v_cndmask_b32_e64 v193, v193, v195, s[8:9]
	v_cndmask_b32_e64 v195, 0, v171, s[6:7]
	v_sub_f32_e32 v193, v193, v195
	v_mul_f32_e32 v195, 0x3f317217, v194
	v_fma_f32 v195, v194, s95, -v195
	v_add_f32_e32 v196, 1.0, v196
	v_fmac_f32_e32 v195, 0x3377d1cf, v194
	v_rcp_f32_e32 v196, v196
	v_fmac_f32_e32 v195, 0x3f317217, v194
	v_cmp_lt_f32_e64 s[6:7], |v194|, s96
	v_fma_f32 v196, v149, v196, v165
	s_nop 0
	v_cndmask_b32_e64 v194, v194, v195, s[6:7]
	v_cndmask_b32_e32 v195, 0, v171, vcc
	v_sub_f32_e32 v194, v194, v195
	v_cvt_pk_f16_f32 v193, v193, v194
	v_mul_f32_e32 v194, v25, v136
	v_cmp_gt_f32_e32 vcc, s90, v196
	v_mul_f32_e32 v194, 0xbfb8aa3b, v194
	v_exp_f32_e32 v194, v194
	v_cndmask_b32_e64 v197, 0, 32, vcc
	v_ldexp_f32 v196, v196, v197
	v_log_f32_e32 v196, v196
	v_add_f32_e32 v194, 1.0, v194
	v_rcp_f32_e32 v194, v194
	v_cndmask_b32_e32 v195, 0, v171, vcc
	v_mul_f32_e32 v191, 0x3f317217, v196
	v_fma_f32 v191, v196, s95, -v191
	v_fmac_f32_e32 v191, 0x3377d1cf, v196
	v_fmac_f32_e32 v191, 0x3f317217, v196
	v_cmp_lt_f32_e64 s[6:7], |v196|, s96
	v_fma_f32 v194, v179, v194, v164
	v_cmp_gt_f32_e32 vcc, s90, v194
	v_cndmask_b32_e64 v191, v196, v191, s[6:7]
	v_sub_f32_e32 v191, v191, v195
	v_cndmask_b32_e64 v195, 0, 32, vcc
	v_ldexp_f32 v194, v194, v195
	v_mul_f32_e32 v195, v26, v136
	v_mul_f32_e32 v195, 0xbfb8aa3b, v195
	v_exp_f32_e32 v195, v195
	v_log_f32_e32 v194, v194
	v_cndmask_b32_e32 v197, 0, v171, vcc
	v_add_f32_e32 v195, 1.0, v195
	v_rcp_f32_e32 v195, v195
	v_mul_f32_e32 v196, 0x3f317217, v194
	v_fma_f32 v196, v194, s95, -v196
	v_fmac_f32_e32 v196, 0x3377d1cf, v194
; __device__ __forceinline__ float fsigm(float x) { return __builtin_amdgcn_rcpf(1.f + __expf(-x)); }
; __device__ __forceinline__ float row_rs(const float* ssq, int row) { return ssq ? rsqrtf(ssq[row] * (1.f / 1024.f) + RMS_EPS) : 1.f; }
;     __device__ __forceinline__ void operator()(const f32x4 (&acc)[2][2][4][2], const Unit& u, int wr, int wc, int fr, int fq) const {
;     ...
;                 for (int m = 0; m < 4; ++m) { const int row = row0 + ai * HALF + m * 16; const float rs = row_rs(ssq, row);
; #pragma unroll
;                     for (int bj = 0; bj < 2; ++bj) { f16x4 o[2];
; #pragma unroll
;                         for (int n = 0; n < 2; ++n) { const f32x4 p = acc[ai][bj][m][n] * rs;
; #pragma unroll
;                             for (int j = 0; j < 4; ++j) { const float l = lb[bj][n][j]; const float f = l + (1.f - l) * fsigm(p[j]); o[n][j] = (_Float16)__logf(f); } }
;                         const u32x2 a0 = __builtin_bit_cast(u32x2, o[0]), a1 = __builtin_bit_cast(u32x2, o[1]); u32x4 w; w.x = a0.x; w.y = a0.y; w.z = a1.x; w.w = a1.y;
;                         *(u32x4*)(LF + (size_t)row * 512 + cbase + bj * HALF) = w; } }
	v_fmac_f32_e32 v196, 0x3f317217, v194
	v_cmp_lt_f32_e64 s[6:7], |v194|, s96
	v_fma_f32 v195, v180, v195, v163
	s_nop 0
	v_cndmask_b32_e64 v194, v194, v196, s[6:7]
	v_cmp_gt_f32_e64 s[6:7], s90, v195
	v_sub_f32_e32 v194, v194, v197
	v_cvt_pk_f16_f32 v194, v191, v194
	v_cndmask_b32_e64 v196, 0, 32, s[6:7]
	v_ldexp_f32 v195, v195, v196
	v_mul_f32_e32 v196, v27, v136
	v_mul_f32_e32 v196, 0xbfb8aa3b, v196
	v_exp_f32_e32 v196, v196
	v_log_f32_e32 v195, v195
	v_add_f32_e32 v196, 1.0, v196
	v_rcp_f32_e32 v196, v196
	v_mul_f32_e32 v197, 0x3f317217, v195
	v_fma_f32 v197, v195, s95, -v197
	v_fmac_f32_e32 v197, 0x3377d1cf, v195
	v_fma_f32 v196, v188, v196, v162
	v_cmp_gt_f32_e32 vcc, s90, v196
	v_fmac_f32_e32 v197, 0x3f317217, v195
	v_cmp_lt_f32_e64 s[8:9], |v195|, s96
	v_cndmask_b32_e64 v198, 0, 32, vcc
	v_ldexp_f32 v196, v196, v198
	v_log_f32_e32 v196, v196
	v_cndmask_b32_e64 v195, v195, v197, s[8:9]
	v_cndmask_b32_e64 v197, 0, v171, s[6:7]
	v_mul_f32_e32 v198, v20, v136
	v_sub_f32_e32 v195, v195, v197
	v_mul_f32_e32 v197, 0x3f317217, v196
	v_mul_f32_e32 v198, 0xbfb8aa3b, v198
	v_fma_f32 v197, v196, s95, -v197
	v_exp_f32_e32 v198, v198
	v_fmac_f32_e32 v197, 0x3377d1cf, v196
	v_fmac_f32_e32 v197, 0x3f317217, v196
	v_cmp_lt_f32_e64 s[6:7], |v196|, s96
	s_nop 1
	v_cndmask_b32_e64 v196, v196, v197, s[6:7]
	v_cndmask_b32_e32 v197, 0, v171, vcc
	v_sub_f32_e32 v196, v196, v197
	v_add_f32_e32 v197, 1.0, v198
	v_rcp_f32_e32 v198, v197
	v_cvt_pk_f16_f32 v195, v195, v196
	v_lshl_add_u64 v[196:197], v[152:153], 0, s[42:43]
	v_fma_f32 v191, v184, v198, v161
	v_cmp_gt_f32_e32 vcc, s90, v191
	s_nop 1
	v_cndmask_b32_e64 v198, 0, 32, vcc
	v_ldexp_f32 v191, v191, v198
	v_add_co_u32_e64 v198, s[6:7], s93, v152
	v_log_f32_e32 v191, v191
	s_nop 0
	v_addc_co_u32_e64 v199, s[6:7], 0, v153, s[6:7]
	global_store_dwordx4 v[198:199], v[192:195], off
	v_cmp_lt_f32_e64 s[6:7], |v191|, s96
	s_nop 0
	v_mul_f32_e32 v193, v21, v136
	v_mul_f32_e32 v193, 0xbfb8aa3b, v193
	v_exp_f32_e32 v193, v193
	v_mul_f32_e32 v192, 0x3f317217, v191
	v_fma_f32 v192, v191, s95, -v192
	v_fmac_f32_e32 v192, 0x3377d1cf, v191
	v_add_f32_e32 v193, 1.0, v193
	v_rcp_f32_e32 v193, v193
	v_fmac_f32_e32 v192, 0x3f317217, v191
	v_cndmask_b32_e64 v191, v191, v192, s[6:7]
	v_cndmask_b32_e32 v192, 0, v171, vcc
	v_sub_f32_e32 v191, v191, v192
	v_fma_f32 v192, v181, v193, v160
	v_cmp_gt_f32_e32 vcc, s90, v192
	s_nop 1
	v_cndmask_b32_e64 v193, 0, 32, vcc
	v_ldexp_f32 v192, v192, v193
	v_mul_f32_e32 v193, v22, v136
	v_mul_f32_e32 v193, 0xbfb8aa3b, v193
	v_exp_f32_e32 v193, v193
	v_log_f32_e32 v192, v192
	v_cndmask_b32_e32 v195, 0, v171, vcc
	v_add_f32_e32 v193, 1.0, v193
	v_rcp_f32_e32 v193, v193
	v_mul_f32_e32 v194, 0x3f317217, v192
	v_fma_f32 v194, v192, s95, -v194
	v_fmac_f32_e32 v194, 0x3377d1cf, v192
	v_fmac_f32_e32 v194, 0x3f317217, v192
	v_cmp_lt_f32_e64 s[6:7], |v192|, s96
	v_fma_f32 v193, v185, v193, v159
	s_nop 0
	v_cndmask_b32_e64 v192, v192, v194, s[6:7]
	v_cmp_gt_f32_e64 s[6:7], s90, v193
	v_sub_f32_e32 v192, v192, v195
	v_cvt_pk_f16_f32 v192, v191, v192
	v_cndmask_b32_e64 v194, 0, 32, s[6:7]
	v_ldexp_f32 v193, v193, v194
	v_mul_f32_e32 v194, v23, v136
	v_mul_f32_e32 v194, 0xbfb8aa3b, v194
	v_exp_f32_e32 v194, v194
	v_log_f32_e32 v193, v193
	v_add_f32_e32 v194, 1.0, v194
	v_rcp_f32_e32 v194, v194
	v_mul_f32_e32 v195, 0x3f317217, v193
	v_fma_f32 v195, v193, s95, -v195
	v_fmac_f32_e32 v195, 0x3377d1cf, v193
	v_fma_f32 v194, v186, v194, v158
	v_cmp_gt_f32_e32 vcc, s90, v194
	v_fmac_f32_e32 v195, 0x3f317217, v193
	v_cmp_lt_f32_e64 s[8:9], |v193|, s96
	v_cndmask_b32_e64 v198, 0, 32, vcc
	v_ldexp_f32 v194, v194, v198
	v_mul_f32_e32 v198, v16, v136
	v_log_f32_e32 v194, v194
	v_mul_f32_e32 v198, 0xbfb8aa3b, v198
	v_exp_f32_e32 v198, v198
	v_cndmask_b32_e64 v193, v193, v195, s[8:9]
	v_cndmask_b32_e64 v195, 0, v171, s[6:7]
	v_sub_f32_e32 v193, v193, v195
	v_mul_f32_e32 v195, 0x3f317217, v194
	v_fma_f32 v195, v194, s95, -v195
	v_add_f32_e32 v198, 1.0, v198
	v_fmac_f32_e32 v195, 0x3377d1cf, v194
	v_rcp_f32_e32 v198, v198
	v_fmac_f32_e32 v195, 0x3f317217, v194
	v_cmp_lt_f32_e64 s[6:7], |v194|, s96
	v_fma_f32 v198, v187, v198, v157
	s_nop 0
	v_cndmask_b32_e64 v194, v194, v195, s[6:7]
	v_cndmask_b32_e32 v195, 0, v171, vcc
	v_sub_f32_e32 v194, v194, v195
	v_cvt_pk_f16_f32 v193, v193, v194
	v_mul_f32_e32 v194, v17, v136
	v_cmp_gt_f32_e32 vcc, s90, v198
	v_mul_f32_e32 v194, 0xbfb8aa3b, v194
	v_exp_f32_e32 v194, v194
	v_cndmask_b32_e64 v199, 0, 32, vcc
	v_ldexp_f32 v198, v198, v199
	v_log_f32_e32 v198, v198
	v_add_f32_e32 v194, 1.0, v194
	v_rcp_f32_e32 v194, v194
	v_cndmask_b32_e32 v195, 0, v171, vcc
	v_mul_f32_e32 v191, 0x3f317217, v198
	v_fma_f32 v191, v198, s95, -v191
	v_fmac_f32_e32 v191, 0x3377d1cf, v198
	v_fmac_f32_e32 v191, 0x3f317217, v198
	v_cmp_lt_f32_e64 s[6:7], |v198|, s96
	v_fma_f32 v194, v182, v194, v156
	v_cmp_gt_f32_e32 vcc, s90, v194
	v_cndmask_b32_e64 v191, v198, v191, s[6:7]
	v_sub_f32_e32 v191, v191, v195
	v_cndmask_b32_e64 v195, 0, 32, vcc
	v_ldexp_f32 v194, v194, v195
	v_mul_f32_e32 v195, v18, v136
	v_mul_f32_e32 v195, 0xbfb8aa3b, v195
	v_exp_f32_e32 v195, v195
	v_log_f32_e32 v194, v194
	v_mul_f32_e32 v136, v19, v136
	v_mul_f32_e32 v136, 0xbfb8aa3b, v136
	v_add_f32_e32 v195, 1.0, v195
	v_rcp_f32_e32 v195, v195
	v_exp_f32_e32 v136, v136
	v_mul_f32_e32 v198, 0x3f317217, v194
	v_fma_f32 v198, v194, s95, -v198
	v_fmac_f32_e32 v198, 0x3377d1cf, v194
	v_fmac_f32_e32 v198, 0x3f317217, v194
	v_cmp_lt_f32_e64 s[6:7], |v194|, s96
	v_fma_f32 v195, v189, v195, v155
	v_add_f32_e32 v136, 1.0, v136
	v_cndmask_b32_e64 v194, v194, v198, s[6:7]
	v_cmp_gt_f32_e64 s[6:7], s90, v195
	v_rcp_f32_e32 v136, v136
	s_nop 0
; __device__ __forceinline__ float fsigm(float x) { return __builtin_amdgcn_rcpf(1.f + __expf(-x)); }
; __device__ __forceinline__ float row_rs(const float* ssq, int row) { return ssq ? rsqrtf(ssq[row] * (1.f / 1024.f) + RMS_EPS) : 1.f; }
;     __device__ __forceinline__ void operator()(const f32x4 (&acc)[2][2][4][2], const Unit& u, int wr, int wc, int fr, int fq) const {
;     ...
;                 for (int m = 0; m < 4; ++m) { const int row = row0 + ai * HALF + m * 16; const float rs = row_rs(ssq, row);
; #pragma unroll
;                     for (int bj = 0; bj < 2; ++bj) { f16x4 o[2];
; #pragma unroll
;                         for (int n = 0; n < 2; ++n) { const f32x4 p = acc[ai][bj][m][n] * rs;
; #pragma unroll
;                             for (int j = 0; j < 4; ++j) { const float l = lb[bj][n][j]; const float f = l + (1.f - l) * fsigm(p[j]); o[n][j] = (_Float16)__logf(f); } }
;                         const u32x2 a0 = __builtin_bit_cast(u32x2, o[0]), a1 = __builtin_bit_cast(u32x2, o[1]); u32x4 w; w.x = a0.x; w.y = a0.y; w.z = a1.x; w.w = a1.y;
;                         *(u32x4*)(LF + (size_t)row * 512 + cbase + bj * HALF) = w; } }
	v_cndmask_b32_e64 v198, 0, 32, s[6:7]
	v_ldexp_f32 v195, v195, v198
	v_log_f32_e32 v195, v195
	v_fma_f32 v136, v190, v136, v154
	v_cndmask_b32_e32 v198, 0, v171, vcc
	v_cmp_gt_f32_e32 vcc, s90, v136
	v_sub_f32_e32 v194, v194, v198
	v_mul_f32_e32 v198, 0x3f317217, v195
	v_cndmask_b32_e64 v199, 0, 32, vcc
	v_ldexp_f32 v136, v136, v199
	v_fma_f32 v198, v195, s95, -v198
	v_log_f32_e32 v136, v136
	v_fmac_f32_e32 v198, 0x3377d1cf, v195
	v_fmac_f32_e32 v198, 0x3f317217, v195
	v_cmp_lt_f32_e64 s[8:9], |v195|, s96
	v_cvt_pk_f16_f32 v194, v191, v194
	s_nop 0
	v_cndmask_b32_e64 v195, v195, v198, s[8:9]
	v_cndmask_b32_e64 v198, 0, v171, s[6:7]
	v_sub_f32_e32 v195, v195, v198
	v_mul_f32_e32 v198, 0x3f317217, v136
	v_fma_f32 v198, v136, s95, -v198
	v_fmac_f32_e32 v198, 0x3377d1cf, v136
	v_fmac_f32_e32 v198, 0x3f317217, v136
	v_cmp_lt_f32_e64 s[6:7], |v136|, s96
	s_nop 1
	v_cndmask_b32_e64 v136, v136, v198, s[6:7]
	v_cndmask_b32_e32 v198, 0, v171, vcc
	v_sub_f32_e32 v136, v136, v198
	v_cvt_pk_f16_f32 v195, v195, v136
	global_store_dwordx4 v[196:197], v[192:195], off offset:256
	v_fmamk_f32 v136, v216, 0x3a800000, v170
	v_mul_f32_e32 v150, 0x4b800000, v136
	v_cmp_gt_f32_e32 vcc, s90, v136
	s_nop 1
	v_cndmask_b32_e32 v136, v136, v150, vcc
	v_rsq_f32_e32 v136, v136
	s_nop 0
	v_mul_f32_e32 v150, 0x45800000, v136
	v_cndmask_b32_e32 v136, v136, v150, vcc
	v_mul_f32_e32 v150, v12, v136
	v_mul_f32_e32 v150, 0xbfb8aa3b, v150
	v_exp_f32_e32 v150, v150
	s_nop 0
	v_add_f32_e32 v150, 1.0, v150
	v_rcp_f32_e32 v150, v150
	s_nop 0
	v_fmac_f32_e32 v175, v176, v150
	v_cmp_gt_f32_e32 vcc, s90, v175
	s_nop 1
	v_cndmask_b32_e64 v150, 0, 32, vcc
	v_ldexp_f32 v150, v175, v150
	v_mul_f32_e32 v175, v13, v136
	v_mul_f32_e32 v175, 0xbfb8aa3b, v175
	v_exp_f32_e32 v175, v175
	v_log_f32_e32 v150, v150
	v_add_f32_e32 v175, 1.0, v175
	v_rcp_f32_e32 v175, v175
	v_mul_f32_e32 v151, 0x3f317217, v150
	v_fma_f32 v151, v150, s95, -v151
	v_fmac_f32_e32 v151, 0x3377d1cf, v150
	v_fmac_f32_e32 v151, 0x3f317217, v150
	v_cmp_lt_f32_e64 s[6:7], |v150|, s96
	v_fmac_f32_e32 v174, v177, v175
	s_nop 0
	v_cndmask_b32_e64 v150, v150, v151, s[6:7]
	v_cndmask_b32_e32 v151, 0, v171, vcc
	v_cmp_gt_f32_e32 vcc, s90, v174
	v_sub_f32_e32 v150, v150, v151
	s_nop 0
	v_cndmask_b32_e64 v151, 0, 32, vcc
	v_ldexp_f32 v151, v174, v151
	v_mul_f32_e32 v174, v14, v136
	v_mul_f32_e32 v174, 0xbfb8aa3b, v174
	v_exp_f32_e32 v174, v174
	v_log_f32_e32 v151, v151
	v_add_f32_e32 v174, 1.0, v174
	v_rcp_f32_e32 v174, v174
	v_mul_f32_e32 v175, 0x3f317217, v151
	v_fma_f32 v175, v151, s95, -v175
	v_fmac_f32_e32 v175, 0x3377d1cf, v151
	v_fmac_f32_e32 v175, 0x3f317217, v151
	v_cmp_lt_f32_e64 s[6:7], |v151|, s96
	v_fmac_f32_e32 v173, v178, v174
	s_nop 0
	v_cndmask_b32_e64 v151, v151, v175, s[6:7]
	v_cmp_gt_f32_e64 s[6:7], s90, v173
	v_cndmask_b32_e32 v175, 0, v171, vcc
	v_sub_f32_e32 v151, v151, v175
	v_cndmask_b32_e64 v174, 0, 32, s[6:7]
	v_ldexp_f32 v173, v173, v174
	v_mul_f32_e32 v174, v15, v136
	v_mul_f32_e32 v174, 0xbfb8aa3b, v174
	v_exp_f32_e32 v174, v174
	v_log_f32_e32 v173, v173
	v_add_f32_e32 v174, 1.0, v174
	v_mul_f32_e32 v175, 0x3f317217, v173
	v_rcp_f32_e32 v174, v174
	v_fma_f32 v175, v173, s95, -v175
	v_fmac_f32_e32 v175, 0x3377d1cf, v173
	v_fmac_f32_e32 v175, 0x3f317217, v173
	v_cmp_lt_f32_e64 s[8:9], |v173|, s96
	v_fmac_f32_e32 v172, v183, v174
	v_cmp_gt_f32_e32 vcc, s90, v172
	v_cndmask_b32_e64 v173, v173, v175, s[8:9]
	v_mul_f32_e32 v175, v8, v136
	v_mul_f32_e32 v175, 0xbfb8aa3b, v175
	v_cndmask_b32_e64 v174, 0, 32, vcc
	v_exp_f32_e32 v175, v175
	v_ldexp_f32 v172, v172, v174
	v_log_f32_e32 v172, v172
	v_cndmask_b32_e64 v174, 0, v171, s[6:7]
	v_add_f32_e32 v175, 1.0, v175
	v_rcp_f32_e32 v175, v175
	v_sub_f32_e32 v173, v173, v174
	v_mul_f32_e32 v174, 0x3f317217, v172
	v_fma_f32 v174, v172, s95, -v174
	v_fmac_f32_e32 v174, 0x3377d1cf, v172
	v_fmac_f32_e32 v174, 0x3f317217, v172
	v_cmp_lt_f32_e64 s[6:7], |v172|, s96
	v_fmac_f32_e32 v165, v149, v175
	s_nop 0
	v_cndmask_b32_e64 v172, v172, v174, s[6:7]
	v_cndmask_b32_e32 v174, 0, v171, vcc
	v_cmp_gt_f32_e32 vcc, s90, v165
	s_nop 1
	v_cndmask_b32_e64 v149, 0, 32, vcc
	v_ldexp_f32 v149, v165, v149
	v_sub_f32_e32 v165, v172, v174
	v_cvt_pk_f16_f32 v172, v150, v151
	v_mul_f32_e32 v151, v9, v136
	v_mul_f32_e32 v151, 0xbfb8aa3b, v151
	v_exp_f32_e32 v151, v151
	v_log_f32_e32 v149, v149
	v_cvt_pk_f16_f32 v173, v173, v165
	v_add_f32_e32 v151, 1.0, v151
	v_rcp_f32_e32 v151, v151
	v_mul_f32_e32 v150, 0x3f317217, v149
	v_fma_f32 v150, v149, s95, -v150
	v_fmac_f32_e32 v150, 0x3377d1cf, v149
	v_fmac_f32_e32 v150, 0x3f317217, v149
	v_cmp_lt_f32_e64 s[6:7], |v149|, s96
	v_fmac_f32_e32 v164, v179, v151
	v_mul_f32_e32 v151, v10, v136
	v_cndmask_b32_e64 v149, v149, v150, s[6:7]
	v_cndmask_b32_e32 v150, 0, v171, vcc
	v_cmp_gt_f32_e32 vcc, s90, v164
	v_mul_f32_e32 v151, 0xbfb8aa3b, v151
	v_sub_f32_e32 v149, v149, v150
	v_cndmask_b32_e64 v150, 0, 32, vcc
	v_exp_f32_e32 v151, v151
	v_ldexp_f32 v150, v164, v150
	v_log_f32_e32 v150, v150
	v_add_f32_e32 v151, 1.0, v151
	v_rcp_f32_e32 v151, v151
	v_mul_f32_e32 v164, 0x3f317217, v150
	v_fma_f32 v164, v150, s95, -v164
	v_fmac_f32_e32 v164, 0x3377d1cf, v150
	v_fmac_f32_e32 v164, 0x3f317217, v150
	v_cmp_lt_f32_e64 s[6:7], |v150|, s96
	v_fmac_f32_e32 v163, v180, v151
	s_nop 0
	v_cndmask_b32_e64 v150, v150, v164, s[6:7]
	v_cmp_gt_f32_e64 s[6:7], s90, v163
	v_cndmask_b32_e32 v164, 0, v171, vcc
	v_sub_f32_e32 v150, v150, v164
	v_cndmask_b32_e64 v151, 0, 32, s[6:7]
	v_ldexp_f32 v151, v163, v151
	v_mul_f32_e32 v163, v11, v136
	v_mul_f32_e32 v163, 0xbfb8aa3b, v163
	v_exp_f32_e32 v163, v163
	v_log_f32_e32 v151, v151
	v_cvt_pk_f16_f32 v174, v149, v150
; __device__ __forceinline__ float fsigm(float x) { return __builtin_amdgcn_rcpf(1.f + __expf(-x)); }
;     __device__ __forceinline__ void operator()(const f32x4 (&acc)[2][2][4][2], const Unit& u, int wr, int wc, int fr, int fq) const {
;     ...
;                     for (int bj = 0; bj < 2; ++bj) { f16x4 o[2];
; #pragma unroll
;                         for (int n = 0; n < 2; ++n) { const f32x4 p = acc[ai][bj][m][n] * rs;
; #pragma unroll
;                             for (int j = 0; j < 4; ++j) { const float l = lb[bj][n][j]; const float f = l + (1.f - l) * fsigm(p[j]); o[n][j] = (_Float16)__logf(f); } }
;                         const u32x2 a0 = __builtin_bit_cast(u32x2, o[0]), a1 = __builtin_bit_cast(u32x2, o[1]); u32x4 w; w.x = a0.x; w.y = a0.y; w.z = a1.x; w.w = a1.y;
;                         *(u32x4*)(LF + (size_t)row * 512 + cbase + bj * HALF) = w; } }
	v_add_f32_e32 v163, 1.0, v163
	v_rcp_f32_e32 v163, v163
	v_mul_f32_e32 v164, 0x3f317217, v151
	v_fma_f32 v164, v151, s95, -v164
	v_fmac_f32_e32 v164, 0x3377d1cf, v151
	v_fmac_f32_e32 v162, v188, v163
	v_cmp_gt_f32_e32 vcc, s90, v162
	v_fmac_f32_e32 v164, 0x3f317217, v151
	v_cmp_lt_f32_e64 s[8:9], |v151|, s96
	v_cndmask_b32_e64 v163, 0, 32, vcc
	v_ldexp_f32 v162, v162, v163
	v_log_f32_e32 v162, v162
	v_cndmask_b32_e64 v151, v151, v164, s[8:9]
	v_cndmask_b32_e64 v163, 0, v171, s[6:7]
	v_mul_f32_e32 v164, v4, v136
	v_sub_f32_e32 v151, v151, v163
	v_mul_f32_e32 v163, 0x3f317217, v162
	v_mul_f32_e32 v164, 0xbfb8aa3b, v164
	v_fma_f32 v163, v162, s95, -v163
	v_exp_f32_e32 v164, v164
	v_fmac_f32_e32 v163, 0x3377d1cf, v162
	v_fmac_f32_e32 v163, 0x3f317217, v162
	v_cmp_lt_f32_e64 s[6:7], |v162|, s96
	s_nop 1
	v_cndmask_b32_e64 v162, v162, v163, s[6:7]
	v_cndmask_b32_e32 v163, 0, v171, vcc
	v_sub_f32_e32 v162, v162, v163
	v_add_f32_e32 v163, 1.0, v164
	v_rcp_f32_e32 v164, v163
	v_add_co_u32_e64 v150, s[6:7], s94, v152
	v_cvt_pk_f16_f32 v175, v151, v162
	s_nop 0
	v_addc_co_u32_e64 v151, s[6:7], 0, v153, s[6:7]
	v_fmac_f32_e32 v161, v184, v164
	global_store_dwordx4 v[150:151], v[172:175], off
	v_mul_f32_e32 v151, v5, v136
	v_cmp_gt_f32_e32 vcc, s90, v161
	v_mul_f32_e32 v151, 0xbfb8aa3b, v151
	v_exp_f32_e32 v151, v151
	v_cndmask_b32_e64 v149, 0, 32, vcc
	v_ldexp_f32 v149, v161, v149
	v_log_f32_e32 v149, v149
	v_add_f32_e32 v151, 1.0, v151
	v_rcp_f32_e32 v151, v151
	v_lshl_add_u64 v[162:163], v[152:153], 0, s[62:63]
	v_mul_f32_e32 v150, 0x3f317217, v149
	v_fma_f32 v150, v149, s95, -v150
	v_fmac_f32_e32 v150, 0x3377d1cf, v149
	v_fmac_f32_e32 v150, 0x3f317217, v149
	v_cmp_lt_f32_e64 s[6:7], |v149|, s96
	v_fmac_f32_e32 v160, v181, v151
	v_mul_f32_e32 v151, v6, v136
	v_cndmask_b32_e64 v149, v149, v150, s[6:7]
	v_cndmask_b32_e32 v150, 0, v171, vcc
	v_cmp_gt_f32_e32 vcc, s90, v160
	v_sub_f32_e32 v149, v149, v150
	v_mul_f32_e32 v151, 0xbfb8aa3b, v151
	v_cndmask_b32_e64 v150, 0, 32, vcc
	v_ldexp_f32 v150, v160, v150
	v_log_f32_e32 v150, v150
	v_exp_f32_e32 v151, v151
	v_cndmask_b32_e32 v153, 0, v171, vcc
	v_mul_f32_e32 v152, 0x3f317217, v150
	v_fma_f32 v152, v150, s95, -v152
	v_fmac_f32_e32 v152, 0x3377d1cf, v150
	v_fmac_f32_e32 v152, 0x3f317217, v150
	v_cmp_lt_f32_e64 s[6:7], |v150|, s96
	v_add_f32_e32 v151, 1.0, v151
	v_rcp_f32_e32 v151, v151
	v_cndmask_b32_e64 v150, v150, v152, s[6:7]
	v_mul_f32_e32 v152, v7, v136
	v_mul_f32_e32 v152, 0xbfb8aa3b, v152
	v_exp_f32_e32 v152, v152
	v_fmac_f32_e32 v159, v185, v151
	v_cmp_gt_f32_e64 s[6:7], s90, v159
	v_sub_f32_e32 v150, v150, v153
	v_add_f32_e32 v152, 1.0, v152
	v_rcp_f32_e32 v152, v152
	v_cndmask_b32_e64 v151, 0, 32, s[6:7]
	v_ldexp_f32 v151, v159, v151
	v_log_f32_e32 v151, v151
	v_fmac_f32_e32 v158, v186, v152
	v_cmp_gt_f32_e32 vcc, s90, v158
	v_cvt_pk_f16_f32 v150, v149, v150
	v_mul_f32_e32 v153, 0x3f317217, v151
	v_cndmask_b32_e64 v152, 0, 32, vcc
	v_ldexp_f32 v152, v158, v152
	v_mul_f32_e32 v158, v0, v136
	v_mul_f32_e32 v158, 0xbfb8aa3b, v158
	v_exp_f32_e32 v158, v158
	v_fma_f32 v153, v151, s95, -v153
	v_log_f32_e32 v152, v152
	v_fmac_f32_e32 v153, 0x3377d1cf, v151
	v_fmac_f32_e32 v153, 0x3f317217, v151
	v_cmp_lt_f32_e64 s[8:9], |v151|, s96
	v_add_f32_e32 v158, 1.0, v158
	v_rcp_f32_e32 v158, v158
	v_cndmask_b32_e64 v151, v151, v153, s[8:9]
	v_cndmask_b32_e64 v153, 0, v171, s[6:7]
	v_sub_f32_e32 v151, v151, v153
	v_mul_f32_e32 v153, 0x3f317217, v152
	v_fma_f32 v153, v152, s95, -v153
	v_fmac_f32_e32 v153, 0x3377d1cf, v152
	v_fmac_f32_e32 v153, 0x3f317217, v152
	v_cmp_lt_f32_e64 s[6:7], |v152|, s96
	v_fmac_f32_e32 v157, v187, v158
	s_nop 0
	v_cndmask_b32_e64 v152, v152, v153, s[6:7]
	v_cndmask_b32_e32 v153, 0, v171, vcc
	v_cmp_gt_f32_e32 vcc, s90, v157
	v_sub_f32_e32 v152, v152, v153
	v_cvt_pk_f16_f32 v151, v151, v152
	v_cndmask_b32_e64 v158, 0, 32, vcc
	v_mul_f32_e32 v152, v1, v136
	v_ldexp_f32 v157, v157, v158
	v_mul_f32_e32 v152, 0xbfb8aa3b, v152
	v_log_f32_e32 v157, v157
	v_exp_f32_e32 v152, v152
	v_cndmask_b32_e32 v153, 0, v171, vcc
	v_mul_f32_e32 v149, 0x3f317217, v157
	v_add_f32_e32 v152, 1.0, v152
	v_fma_f32 v149, v157, s95, -v149
	v_rcp_f32_e32 v152, v152
	v_fmac_f32_e32 v149, 0x3377d1cf, v157
	v_fmac_f32_e32 v149, 0x3f317217, v157
	v_cmp_lt_f32_e64 s[6:7], |v157|, s96
	v_fmac_f32_e32 v156, v182, v152
	v_cmp_gt_f32_e32 vcc, s90, v156
	v_cndmask_b32_e64 v149, v157, v149, s[6:7]
	v_sub_f32_e32 v149, v149, v153
	v_mul_f32_e32 v153, v2, v136
	v_mul_f32_e32 v153, 0xbfb8aa3b, v153
	v_cndmask_b32_e64 v152, 0, 32, vcc
	v_exp_f32_e32 v153, v153
	v_ldexp_f32 v152, v156, v152
	v_log_f32_e32 v152, v152
	v_mul_f32_e32 v136, v3, v136
	v_add_f32_e32 v153, 1.0, v153
	v_mul_f32_e32 v136, 0xbfb8aa3b, v136
	v_rcp_f32_e32 v153, v153
	v_exp_f32_e32 v136, v136
	v_mul_f32_e32 v156, 0x3f317217, v152
	v_fma_f32 v156, v152, s95, -v156
	v_fmac_f32_e32 v156, 0x3377d1cf, v152
	v_fmac_f32_e32 v156, 0x3f317217, v152
	v_cmp_lt_f32_e64 s[6:7], |v152|, s96
	v_fmac_f32_e32 v155, v189, v153
	v_add_f32_e32 v136, 1.0, v136
	v_cndmask_b32_e64 v152, v152, v156, s[6:7]
	v_cmp_gt_f32_e64 s[6:7], s90, v155
	v_rcp_f32_e32 v136, v136
	s_nop 0
	v_cndmask_b32_e64 v153, 0, 32, s[6:7]
	v_ldexp_f32 v153, v155, v153
	v_log_f32_e32 v153, v153
	v_fmac_f32_e32 v154, v190, v136
	v_cndmask_b32_e32 v155, 0, v171, vcc
	v_cmp_gt_f32_e32 vcc, s90, v154
	v_sub_f32_e32 v152, v152, v155
	v_mul_f32_e32 v155, 0x3f317217, v153
	v_cndmask_b32_e64 v136, 0, 32, vcc
	v_ldexp_f32 v136, v154, v136
	v_fma_f32 v155, v153, s95, -v155
	v_log_f32_e32 v136, v136
	v_fmac_f32_e32 v155, 0x3377d1cf, v153
	v_fmac_f32_e32 v155, 0x3f317217, v153
	v_cmp_lt_f32_e64 s[8:9], |v153|, s96
	v_cndmask_b32_e64 v154, 0, v171, s[6:7]
	v_cmp_lt_f32_e64 s[6:7], |v136|, s96
	v_cndmask_b32_e64 v153, v153, v155, s[8:9]
	v_sub_f32_e32 v153, v153, v154
	v_mul_f32_e32 v154, 0x3f317217, v136
	v_fma_f32 v154, v136, s95, -v154
	v_fmac_f32_e32 v154, 0x3377d1cf, v136
	v_fmac_f32_e32 v154, 0x3f317217, v136
	v_cndmask_b32_e64 v136, v136, v154, s[6:7]
	v_cndmask_b32_e32 v154, 0, v171, vcc
	v_sub_f32_e32 v136, v136, v154
	v_cvt_pk_f16_f32 v153, v153, v136
	v_cvt_pk_f16_f32 v152, v149, v152
	global_store_dwordx4 v[162:163], v[150:153], off offset:256

; __device__ __forceinline__ unsigned cvt_pk_bf16(float lo, float hi) { cvf32x2_t v = {lo, hi}; cvbf16x2_t b = __builtin_convertvector(v, cvbf16x2_t); return __builtin_bit_cast(unsigned, b); }
; __device__ __forceinline__ float row_rs(const float* ssq, int row) { return ssq ? rsqrtf(ssq[row] * (1.f / 1024.f) + RMS_EPS) : 1.f; }
;     __device__ __forceinline__ void operator()(const f32x4 (&acc)[2][2][4][2], const Unit& u, int wr, int wc, int fr, int fq) const {
;     ...
;                 for (int m = 0; m < 4; ++m) { const int row = row0 + ai * HALF + m * 16; const float rs = row_rs(ssq, row); const float rs2 = rs * rs;
;                     const f32x4 v0 = acc[ai][0][m][0] * acc[ai][1][m][0] * rs2, v1 = acc[ai][0][m][1] * acc[ai][1][m][1] * rs2; u32x4 w;
;                     w.x = cvt_pk_bf16(v0[0], v0[1]); w.y = cvt_pk_bf16(v0[2], v0[3]); w.z = cvt_pk_bf16(v1[0], v1[1]); w.w = cvt_pk_bf16(v1[2], v1[3]);
;                     *(u32x4*)(CU + (size_t)row * 512 + (pn - 10) * HALF + cw) = w; }
.LBB0_648:
	v_ashrrev_i32_e32 v149, 31, v148
	v_lshl_add_u64 v[150:151], v[148:149], 2, s[30:31]
	global_load_dword v152, v[150:151], off
	global_load_dword v210, v[150:151], off offset:64
	global_load_dword v211, v[150:151], off offset:128
	global_load_dword v212, v[150:151], off offset:192
	global_load_dword v213, v[150:151], off offset:512
	global_load_dword v214, v[150:151], off offset:576
	global_load_dword v215, v[150:151], off offset:640
	global_load_dword v216, v[150:151], off offset:704
	v_pk_mul_f32 v[116:117], v[124:125], v[116:117]
	v_pk_mul_f32 v[118:119], v[126:127], v[118:119]
	s_lshl_b32 s6, s18, 7
	v_pk_mul_f32 v[120:121], v[120:121], v[112:113]
	s_add_i32 s18, s6, 0xfffffb00
	v_lshlrev_b64 v[112:113], 10, v[148:149]
	v_pk_mul_f32 v[114:115], v[122:123], v[114:115]
	v_lshl_add_u64 v[112:113], s[28:29], 0, v[112:113]
	s_lshl_b64 s[6:7], s[18:19], 1
	v_lshlrev_b32_e32 v136, 1, v138
	v_or_b32_e32 v122, 16, v148
	v_lshl_add_u64 v[112:113], v[112:113], 0, s[6:7]
	v_ashrrev_i32_e32 v123, 31, v122
	v_lshl_add_u64 v[112:113], v[112:113], 0, v[136:137]
	v_pk_mul_f32 v[102:103], v[110:111], v[102:103]
	v_pk_mul_f32 v[98:99], v[106:107], v[98:99]
	v_lshlrev_b64 v[106:107], 10, v[122:123]
	v_pk_mul_f32 v[100:101], v[108:109], v[100:101]
	v_pk_mul_f32 v[96:97], v[104:105], v[96:97]
	v_lshl_add_u64 v[106:107], s[28:29], 0, v[106:107]
	v_or_b32_e32 v104, 32, v148
	v_lshl_add_u64 v[106:107], v[106:107], 0, s[6:7]
	v_ashrrev_i32_e32 v105, 31, v104
	v_lshl_add_u64 v[106:107], v[106:107], 0, v[136:137]
	v_lshl_add_u64 v[108:109], v[104:105], 2, s[30:31]
	v_pk_mul_f32 v[86:87], v[94:95], v[86:87]
	v_pk_mul_f32 v[82:83], v[90:91], v[82:83]
	v_lshlrev_b64 v[90:91], 10, v[104:105]
	v_pk_mul_f32 v[84:85], v[92:93], v[84:85]
	v_pk_mul_f32 v[80:81], v[88:89], v[80:81]
	v_lshl_add_u64 v[90:91], s[28:29], 0, v[90:91]
	v_or_b32_e32 v88, 48, v148
	v_lshl_add_u64 v[90:91], v[90:91], 0, s[6:7]
	v_ashrrev_i32_e32 v89, 31, v88
	v_lshl_add_u64 v[90:91], v[90:91], 0, v[136:137]
	v_lshl_add_u64 v[92:93], v[88:89], 2, s[30:31]
	v_pk_mul_f32 v[66:67], v[74:75], v[66:67]
	v_pk_mul_f32 v[64:65], v[72:73], v[64:65]
	v_lshlrev_b64 v[72:73], 10, v[88:89]
	v_pk_mul_f32 v[70:71], v[78:79], v[70:71]
	v_pk_mul_f32 v[68:69], v[76:77], v[68:69]
	v_lshl_add_u64 v[72:73], s[28:29], 0, v[72:73]
	v_lshl_add_u64 v[72:73], v[72:73], 0, s[6:7]
	v_lshl_add_u64 v[72:73], v[72:73], 0, v[136:137]
	v_pk_mul_f32 v[48:49], v[56:57], v[48:49]
	v_pk_mul_f32 v[50:51], v[58:59], v[50:51]
	v_pk_mul_f32 v[54:55], v[62:63], v[54:55]
	v_pk_mul_f32 v[52:53], v[60:61], v[52:53]
	v_pk_mul_f32 v[32:33], v[40:41], v[32:33]
	v_pk_mul_f32 v[34:35], v[42:43], v[34:35]
	v_pk_mul_f32 v[38:39], v[46:47], v[38:39]
	v_pk_mul_f32 v[36:37], v[44:45], v[36:37]
	v_pk_mul_f32 v[16:17], v[24:25], v[16:17]
	v_pk_mul_f32 v[18:19], v[26:27], v[18:19]
	v_pk_mul_f32 v[22:23], v[30:31], v[22:23]
	v_pk_mul_f32 v[20:21], v[28:29], v[20:21]
	v_pk_mul_f32 v[2:3], v[10:11], v[2:3]
	v_pk_mul_f32 v[0:1], v[8:9], v[0:1]
	v_pk_mul_f32 v[6:7], v[14:15], v[6:7]
	v_pk_mul_f32 v[4:5], v[12:13], v[4:5]
	s_waitcnt vmcnt(0)
; __device__ __forceinline__ unsigned cvt_pk_bf16(float lo, float hi) { cvf32x2_t v = {lo, hi}; cvbf16x2_t b = __builtin_convertvector(v, cvbf16x2_t); return __builtin_bit_cast(unsigned, b); }
; __device__ __forceinline__ float row_rs(const float* ssq, int row) { return ssq ? rsqrtf(ssq[row] * (1.f / 1024.f) + RMS_EPS) : 1.f; }
;     __device__ __forceinline__ void operator()(const f32x4 (&acc)[2][2][4][2], const Unit& u, int wr, int wc, int fr, int fq) const {
;     ...
;                 for (int m = 0; m < 4; ++m) { const int row = row0 + ai * HALF + m * 16; const float rs = row_rs(ssq, row); const float rs2 = rs * rs;
;                     const f32x4 v0 = acc[ai][0][m][0] * acc[ai][1][m][0] * rs2, v1 = acc[ai][0][m][1] * acc[ai][1][m][1] * rs2; u32x4 w;
;                     w.x = cvt_pk_bf16(v0[0], v0[1]); w.y = cvt_pk_bf16(v0[2], v0[3]); w.z = cvt_pk_bf16(v1[0], v1[1]); w.w = cvt_pk_bf16(v1[2], v1[3]);
;                     *(u32x4*)(CU + (size_t)row * 512 + (pn - 10) * HALF + cw) = w; }
	v_fmamk_f32 v124, v152, 0x3a800000, v170
	v_mul_f32_e32 v125, 0x4b800000, v124
	v_cmp_gt_f32_e32 vcc, s90, v124
	s_nop 1
	v_cndmask_b32_e32 v124, v124, v125, vcc
	v_rsq_f32_e32 v126, v124
	v_lshl_add_u64 v[124:125], v[122:123], 2, s[30:31]
	v_mul_f32_e32 v127, 0x45800000, v126
	v_cndmask_b32_e32 v126, v126, v127, vcc
	v_mul_f32_e32 v126, v126, v126
	v_pk_mul_f32 v[118:119], v[118:119], v[126:127] op_sel_hi:[1,0]
	v_pk_mul_f32 v[116:117], v[116:117], v[126:127] op_sel_hi:[1,0]
	v_pk_mul_f32 v[152:153], v[114:115], v[126:127] op_sel_hi:[1,0]
	v_pk_mul_f32 v[120:121], v[120:121], v[126:127] op_sel_hi:[1,0]
	v_cvt_pk_bf16_f32 v114, v116, v117
	v_cvt_pk_bf16_f32 v115, v118, v119
	v_cvt_pk_bf16_f32 v116, v120, v121
	v_cvt_pk_bf16_f32 v117, v152, v153
	global_store_dwordx4 v[112:113], v[114:117], off
	v_fmamk_f32 v110, v210, 0x3a800000, v170
	v_mul_f32_e32 v111, 0x4b800000, v110
	v_cmp_gt_f32_e32 vcc, s90, v110
	s_nop 1
	v_cndmask_b32_e32 v110, v110, v111, vcc
	v_rsq_f32_e32 v110, v110
	s_nop 0
	v_mul_f32_e32 v111, 0x45800000, v110
	v_cndmask_b32_e32 v110, v110, v111, vcc
	v_mul_f32_e32 v110, v110, v110
	v_pk_mul_f32 v[102:103], v[102:103], v[110:111] op_sel_hi:[1,0]
	v_pk_mul_f32 v[100:101], v[100:101], v[110:111] op_sel_hi:[1,0]
	v_pk_mul_f32 v[114:115], v[98:99], v[110:111] op_sel_hi:[1,0]
	v_pk_mul_f32 v[98:99], v[96:97], v[110:111] op_sel_hi:[1,0]
	v_cvt_pk_bf16_f32 v96, v100, v101
	v_cvt_pk_bf16_f32 v97, v102, v103
	v_cvt_pk_bf16_f32 v98, v98, v99
	v_cvt_pk_bf16_f32 v99, v114, v115
	global_store_dwordx4 v[106:107], v[96:99], off
	v_fmamk_f32 v94, v211, 0x3a800000, v170
	v_mul_f32_e32 v95, 0x4b800000, v94
	v_cmp_gt_f32_e32 vcc, s90, v94
	s_nop 1
	v_cndmask_b32_e32 v94, v94, v95, vcc
	v_rsq_f32_e32 v94, v94
	s_nop 0
	v_mul_f32_e32 v95, 0x45800000, v94
	v_cndmask_b32_e32 v94, v94, v95, vcc
	v_mul_f32_e32 v94, v94, v94
	v_pk_mul_f32 v[86:87], v[86:87], v[94:95] op_sel_hi:[1,0]
	v_pk_mul_f32 v[84:85], v[84:85], v[94:95] op_sel_hi:[1,0]
	v_pk_mul_f32 v[96:97], v[82:83], v[94:95] op_sel_hi:[1,0]
	v_pk_mul_f32 v[82:83], v[80:81], v[94:95] op_sel_hi:[1,0]
	v_cvt_pk_bf16_f32 v80, v84, v85
	v_cvt_pk_bf16_f32 v81, v86, v87
	v_cvt_pk_bf16_f32 v82, v82, v83
	v_cvt_pk_bf16_f32 v83, v96, v97
	global_store_dwordx4 v[90:91], v[80:83], off
	v_fmamk_f32 v74, v212, 0x3a800000, v170
	v_mul_f32_e32 v75, 0x4b800000, v74
	v_cmp_gt_f32_e32 vcc, s90, v74
	s_nop 1
	v_cndmask_b32_e32 v74, v74, v75, vcc
	v_rsq_f32_e32 v74, v74
	s_nop 0
	v_mul_f32_e32 v75, 0x45800000, v74
	v_cndmask_b32_e32 v74, v74, v75, vcc
	v_mul_f32_e32 v74, v74, v74
	v_pk_mul_f32 v[70:71], v[70:71], v[74:75] op_sel_hi:[1,0]
	v_pk_mul_f32 v[68:69], v[68:69], v[74:75] op_sel_hi:[1,0]
	v_pk_mul_f32 v[76:77], v[66:67], v[74:75] op_sel_hi:[1,0]
	v_pk_mul_f32 v[66:67], v[64:65], v[74:75] op_sel_hi:[1,0]
	v_cvt_pk_bf16_f32 v64, v68, v69
	v_cvt_pk_bf16_f32 v65, v70, v71
	v_cvt_pk_bf16_f32 v66, v66, v67
	v_cvt_pk_bf16_f32 v67, v76, v77
	global_store_dwordx4 v[72:73], v[64:67], off
	v_fmamk_f32 v56, v213, 0x3a800000, v170
	v_mul_f32_e32 v57, 0x4b800000, v56
	v_cmp_gt_f32_e32 vcc, s90, v56
	s_nop 1
	v_cndmask_b32_e32 v56, v56, v57, vcc
	v_rsq_f32_e32 v58, v56
	v_add_co_u32_e64 v56, s[6:7], s91, v112
	v_mul_f32_e32 v59, 0x45800000, v58
	v_cndmask_b32_e32 v58, v58, v59, vcc
	v_mul_f32_e32 v58, v58, v58
	v_pk_mul_f32 v[54:55], v[54:55], v[58:59] op_sel_hi:[1,0]
	v_pk_mul_f32 v[52:53], v[52:53], v[58:59] op_sel_hi:[1,0]
	v_pk_mul_f32 v[60:61], v[50:51], v[58:59] op_sel_hi:[1,0]
	v_pk_mul_f32 v[50:51], v[48:49], v[58:59] op_sel_hi:[1,0]
	v_addc_co_u32_e64 v57, s[6:7], 0, v113, s[6:7]
	v_cvt_pk_bf16_f32 v48, v52, v53
	v_cvt_pk_bf16_f32 v49, v54, v55
	v_cvt_pk_bf16_f32 v50, v50, v51
	v_cvt_pk_bf16_f32 v51, v60, v61
	global_store_dwordx4 v[56:57], v[48:51], off
	v_fmamk_f32 v40, v214, 0x3a800000, v170
	v_mul_f32_e32 v41, 0x4b800000, v40
	v_cmp_gt_f32_e32 vcc, s90, v40
	s_nop 1
	v_cndmask_b32_e32 v40, v40, v41, vcc
	v_rsq_f32_e32 v42, v40
	v_add_co_u32_e64 v40, s[6:7], s92, v112
	v_mul_f32_e32 v43, 0x45800000, v42
	v_cndmask_b32_e32 v42, v42, v43, vcc
	v_mul_f32_e32 v42, v42, v42
	v_pk_mul_f32 v[38:39], v[38:39], v[42:43] op_sel_hi:[1,0]
	v_pk_mul_f32 v[36:37], v[36:37], v[42:43] op_sel_hi:[1,0]
	v_pk_mul_f32 v[44:45], v[34:35], v[42:43] op_sel_hi:[1,0]
	v_pk_mul_f32 v[34:35], v[32:33], v[42:43] op_sel_hi:[1,0]
	v_addc_co_u32_e64 v41, s[6:7], 0, v113, s[6:7]
	v_cvt_pk_bf16_f32 v32, v36, v37
	v_cvt_pk_bf16_f32 v33, v38, v39
	v_cvt_pk_bf16_f32 v34, v34, v35
	v_cvt_pk_bf16_f32 v35, v44, v45
	global_store_dwordx4 v[40:41], v[32:35], off
	v_fmamk_f32 v24, v215, 0x3a800000, v170
	v_mul_f32_e32 v25, 0x4b800000, v24
	v_cmp_gt_f32_e32 vcc, s90, v24
	s_nop 1
	v_cndmask_b32_e32 v24, v24, v25, vcc
	v_rsq_f32_e32 v26, v24
	v_add_co_u32_e64 v24, s[6:7], s93, v112
	v_mul_f32_e32 v27, 0x45800000, v26
	v_cndmask_b32_e32 v26, v26, v27, vcc
	v_mul_f32_e32 v26, v26, v26
	v_pk_mul_f32 v[22:23], v[22:23], v[26:27] op_sel_hi:[1,0]
	v_pk_mul_f32 v[20:21], v[20:21], v[26:27] op_sel_hi:[1,0]
	v_pk_mul_f32 v[28:29], v[18:19], v[26:27] op_sel_hi:[1,0]
	v_pk_mul_f32 v[18:19], v[16:17], v[26:27] op_sel_hi:[1,0]
	v_addc_co_u32_e64 v25, s[6:7], 0, v113, s[6:7]
	v_cvt_pk_bf16_f32 v16, v20, v21
	v_cvt_pk_bf16_f32 v17, v22, v23
	v_cvt_pk_bf16_f32 v18, v18, v19
	v_cvt_pk_bf16_f32 v19, v28, v29
	global_store_dwordx4 v[24:25], v[16:19], off
	v_add_co_u32_e32 v8, vcc, 0x2c000, v112
	v_fmamk_f32 v10, v216, 0x3a800000, v170
	v_mul_f32_e32 v11, 0x4b800000, v10
	v_cmp_gt_f32_e64 s[6:7], s90, v10
	s_nop 1
	v_cndmask_b32_e64 v10, v10, v11, s[6:7]
	v_rsq_f32_e32 v10, v10
	s_nop 0
	v_mul_f32_e32 v9, 0x45800000, v10
	v_cndmask_b32_e64 v9, v10, v9, s[6:7]
	v_mul_f32_e32 v10, v9, v9
	v_pk_mul_f32 v[6:7], v[6:7], v[10:11] op_sel_hi:[1,0]
	v_pk_mul_f32 v[4:5], v[4:5], v[10:11] op_sel_hi:[1,0]
	v_pk_mul_f32 v[12:13], v[2:3], v[10:11] op_sel_hi:[1,0]
	v_pk_mul_f32 v[2:3], v[0:1], v[10:11] op_sel_hi:[1,0]
	v_cvt_pk_bf16_f32 v0, v4, v5
	v_cvt_pk_bf16_f32 v1, v6, v7
	v_cvt_pk_bf16_f32 v2, v2, v3
	v_cvt_pk_bf16_f32 v3, v12, v13
	v_addc_co_u32_e32 v9, vcc, 0, v113, vcc
	global_store_dwordx4 v[8:9], v[0:3], off
	s_andn2_b64 vcc, exec, s[4:5]
	s_mov_b64 s[4:5], -1
	s_cbranch_vccnz .LBB0_592
